# GEMM phases: per-phase s_setprio flips in the K-loops deleted; one static s_setprio 1 for waves 0-3 for the duration of each GEMM phase (reset to 0 at phase end)
# speedup vs baseline: 1.0063x; 1.0054x over previous
;     __host__ __device__ bool next(int i, Unit& u) const {
;         const long L = (long)i * G + c; if (L >= nwg) return false;
;         int wgid = (int)L; { const int q = nwg / NXCD, r = nwg % NXCD, xcd = wgid % NXCD, off = wgid / NXCD; wgid = (xcd < r ? xcd * (q + 1) : r * (q + 1) + (xcd - r) * q) + off; }
;         const int nig = WGM * nN, gid = wgid / nig, fm = gid * WGM, gsz = (nM - fm) < WGM ? (nM - fm) : WGM;
;         u.pm = fm + ((wgid % nig) % gsz); u.pn = (wgid % nig) / gsz; return true;
; __global__ void __launch_bounds__(NTHREADS, 2) mk_fwd(Args args) {
;     ...
;     if (IN(2)) { pg8::Gemm g{(const pg8::bf16_t*)WSB(WS_H), (const pg8::bf16_t*)WSB(WS_WAIN), NTOK, A_IN, DM, DM, DM};
;         pg8::StaticOrder S; S.init(NTOK, A_IN, G, bx); pg8::EpiAin E{(pg8::bf16_t*)WSB(WS_P), (pg8::bf16_t*)WSB(WS_VFIRST), WSF(WS_ROPE), (pg8::bf16_t*)WSB(WS_Y)};
;         pg8::gemm_phase<pg8::EpiAin, pg8::StaticOrder, true>(ldsb + RING_OFF, g, S, E); }
.LBB0_186:
	s_cmp_lt_i32 s58, 3
	s_cselect_b64 s[0:1], -1, 0
	s_cmp_gt_i32 s59, 2
	s_cselect_b64 s[2:3], -1, 0
	s_and_b64 s[10:11], s[0:1], s[2:3]
	s_andn2_b64 vcc, exec, s[10:11]
	s_cbranch_vccnz .LBB0_317
	v_readfirstlane_b32 s98, v0
	s_nop 3
	s_lshr_b32 s98, s98, 8
	s_cmp_eq_u32 s98, 0
	s_cbranch_scc0 .Lmy_prio0
	s_setprio 1
.Lmy_prio0:
	v_mov_b32_e32 v1, v0
	s_cmpk_lt_i32 s33, 0x500
	s_cselect_b64 s[2:3], -1, 0
	s_cmpk_gt_i32 s33, 0x4ff
	v_readfirstlane_b32 s14, v1
	s_cbranch_scc1 .LBB0_189
	s_ashr_i32 s0, s33, 31
	s_lshr_b32 s0, s0, 29
	s_add_i32 s0, s33, s0
	s_ashr_i32 s1, s0, 3
	s_and_b32 s0, s0, -8
	s_sub_i32 s0, s33, s0
	s_cmp_lt_i32 s0, 0
	s_movk_i32 s4, 0xa1
	s_cselect_b32 s4, s4, 0xa0
	s_mul_i32 s0, s0, s4
	s_add_i32 s0, s0, s1
	s_mul_hi_i32 s1, s0, 0x66666667
	s_lshr_b32 s4, s1, 31
	s_ashr_i32 s1, s1, 7
	s_add_i32 s1, s1, s4
	s_lshl_b32 s4, s1, 3
	s_mulk_i32 s1, 0x140
	s_sub_i32 s0, s0, s1
	s_sext_i32_i16 s1, s0
	s_bfe_u32 s1, s1, 0x3001c
	s_add_i32 s1, s0, s1
	s_sext_i32_i16 s5, s1
	s_and_b32 s1, s1, 0xfff8
	s_sub_i32 s0, s0, s1
	s_sext_i32_i16 s0, s0
	s_add_i32 s4, s4, s0
	s_ashr_i32 s12, s5, 3

; #define PG8_STAGE(bufoff, gbase, voff) do { _Pragma("unroll") for (int _i = 0; _i < 2; ++_i) \
;         __builtin_amdgcn_global_load_lds((const unsigned*)((const char*)(gbase) + (voff)[_i]), (PG8_LAS unsigned*)(lds + (bufoff) + ldsw + _i * 8192), 16, 0, 0); } while (0)
; #define PG8_LDA(dst, b, h) do { _Pragma("unroll") for (int m = 0; m < 4; ++m) _Pragma("unroll") for (int k = 0; k < 2; ++k) dst[m][k] = *(const PG8_LAS bf16x8*)(lds + PG8_SA(b, h) + aoff + m * 2048 + k * 1024); } while (0)
; #define PG8_LDB(dst, b, h) do { _Pragma("unroll") for (int n = 0; n < 2; ++n) _Pragma("unroll") for (int k = 0; k < 2; ++k) dst[n][k] = *(const PG8_LAS bf16x8*)(lds + PG8_SB(b, h) + boff + n * 2048 + k * 1024); } while (0)
; #define PG8_MMA(ai, bj, At, Bt) do { __builtin_amdgcn_s_setprio(1); _Pragma("unroll") for (int m = 0; m < 4; ++m) _Pragma("unroll") for (int n = 0; n < 2; ++n) _Pragma("unroll") for (int k = 0; k < 2; ++k) \
;         acc[ai][bj][m][n] = __builtin_amdgcn_mfma_f32_16x16x32_bf16(Bt[n][k], At[m][k], acc[ai][bj][m][n], 0, 0, 0); __builtin_amdgcn_s_setprio(0); } while (0)
; #define PG8_WAIT_V(n) asm volatile("s_waitcnt vmcnt(" #n ")" ::: "memory")
; template <class Epi, class Sched, bool ALIGN_EPI = false>
; __device__ __forceinline__ void gemm_phase(PG8_LAS unsigned char* lds, const Gemm g, const Sched& S, const Epi& E) {
;     ...
;             PG8_LDB(B0, 0, 0); PG8_LDB(B1, 0, 1); PG8_SCHED; PG8_LDA(At, 0, 0); PG8_STAGE(PG8_SA(1, 1), a1 + hstepA, voffA);
;             PG8_WAIT_V(8); PG8_WAIT_L(0); PG8_BAR; PG8_MMA(0, 0, At, B0); PG8_MMA(0, 1, At, B1); PG8_BAR; PG8_SCHED;
;             PG8_LDA(At, 0, 1); PG8_STAGE(PG8_SB(0, 0), b2, voffB); PG8_STAGE(PG8_SB(0, 1), b2 + hstepB, voffB); PG8_STAGE(PG8_SA(0, 0), a2, voffA);
;             PG8_WAIT_V(8); PG8_WAIT_L(0); PG8_BAR; PG8_MMA(1, 0, At, B0); PG8_MMA(1, 1, At, B1); PG8_BAR; PG8_SCHED;
;             PG8_LDB(B0, 1, 0); PG8_LDB(B1, 1, 1); PG8_SCHED; PG8_LDA(At, 1, 0); PG8_STAGE(PG8_SA(0, 1), a2 + hstepA, voffA);
;             PG8_WAIT_V(8); PG8_WAIT_L(0); PG8_BAR; PG8_MMA(0, 0, At, B0); PG8_MMA(0, 1, At, B1); PG8_BAR; PG8_SCHED;
;             PG8_LDA(At, 1, 1); PG8_STAGE(PG8_SB(1, 0), b3, voffB); PG8_STAGE(PG8_SB(1, 1), b3 + hstepB, voffB); PG8_STAGE(PG8_SA(1, 0), a3, voffA);
;             PG8_WAIT_V(8); PG8_WAIT_L(0); PG8_BAR; PG8_MMA(1, 0, At, B0); PG8_MMA(1, 1, At, B1); PG8_BAR; PG8_SCHED;
.LBB0_198:
	s_waitcnt vmcnt(0)
	ds_read_b128 v[42:45], v172
	ds_read_b128 v[46:49], v172 offset:1024
	ds_read_b128 v[50:53], v172 offset:2048
	ds_read_b128 v[58:61], v172 offset:3072
	ds_read_b128 v[164:167], v173
	ds_read_b128 v[168:171], v173 offset:1024
	ds_read_b128 v[176:179], v173 offset:2048
	ds_read_b128 v[180:183], v173 offset:3072
	s_add_u32 s8, s6, 0xfff00080
	s_addc_u32 s9, s7, -1
	s_cmp_eq_u32 s63, 60
	s_cselect_b32 s41, s5, s9
	s_cselect_b32 s40, s14, s8
	s_cselect_b32 s9, s31, s62
	s_cselect_b32 s8, s35, s61
	v_lshl_add_u64 v[216:217], s[6:7], 0, v[156:157]
	s_add_i32 m0, s13, 0xc000
	ds_read_b128 v[184:187], v174
	ds_read_b128 v[188:191], v174 offset:1024
	ds_read_b128 v[192:195], v174 offset:2048
	ds_read_b128 v[196:199], v174 offset:3072
	ds_read_b128 v[200:203], v174 offset:4096
	ds_read_b128 v[204:207], v174 offset:5120
	ds_read_b128 v[208:211], v174 offset:6144
	ds_read_b128 v[212:215], v174 offset:7168
	global_load_lds_dwordx4 v[216:217], off
	v_lshl_add_u64 v[216:217], s[6:7], 0, v[158:159]
	s_add_i32 m0, s13, 0xe000
	s_nop 0
	global_load_lds_dwordx4 v[216:217], off
	s_waitcnt vmcnt(8)
	s_waitcnt lgkmcnt(0)
	s_barrier
	s_waitcnt lgkmcnt(0)
	v_mfma_f32_16x16x32_bf16 v[142:145], v[42:45], v[184:187], v[142:145]
	v_mfma_f32_16x16x32_bf16 v[138:141], v[50:53], v[184:187], v[138:141]
	v_mfma_f32_16x16x32_bf16 v[126:129], v[42:45], v[192:195], v[126:129]
	v_mfma_f32_16x16x32_bf16 v[122:125], v[50:53], v[192:195], v[122:125]
	v_mfma_f32_16x16x32_bf16 v[110:113], v[42:45], v[200:203], v[110:113]
	v_mfma_f32_16x16x32_bf16 v[106:109], v[50:53], v[200:203], v[106:109]
	v_mfma_f32_16x16x32_bf16 v[94:97], v[42:45], v[208:211], v[94:97]
	v_mfma_f32_16x16x32_bf16 v[90:93], v[50:53], v[208:211], v[90:93]
	v_mfma_f32_16x16x32_bf16 v[142:145], v[46:49], v[188:191], v[142:145]
	v_mfma_f32_16x16x32_bf16 v[138:141], v[58:61], v[188:191], v[138:141]
	v_mfma_f32_16x16x32_bf16 v[126:129], v[46:49], v[196:199], v[126:129]
	v_mfma_f32_16x16x32_bf16 v[122:125], v[58:61], v[196:199], v[122:125]
	v_mfma_f32_16x16x32_bf16 v[110:113], v[46:49], v[204:207], v[110:113]
	v_mfma_f32_16x16x32_bf16 v[106:109], v[58:61], v[204:207], v[106:109]
	v_mfma_f32_16x16x32_bf16 v[94:97], v[46:49], v[212:215], v[94:97]
	v_mfma_f32_16x16x32_bf16 v[90:93], v[58:61], v[212:215], v[90:93]
	v_mfma_f32_16x16x32_bf16 v[134:137], v[164:167], v[184:187], v[134:137]
	v_mfma_f32_16x16x32_bf16 v[130:133], v[176:179], v[184:187], v[130:133]
	v_mfma_f32_16x16x32_bf16 v[118:121], v[164:167], v[192:195], v[118:121]
	v_mfma_f32_16x16x32_bf16 v[114:117], v[176:179], v[192:195], v[114:117]
	v_mfma_f32_16x16x32_bf16 v[102:105], v[164:167], v[200:203], v[102:105]
	v_mfma_f32_16x16x32_bf16 v[98:101], v[176:179], v[200:203], v[98:101]
	v_mfma_f32_16x16x32_bf16 v[86:89], v[164:167], v[208:211], v[86:89]
	v_mfma_f32_16x16x32_bf16 v[82:85], v[176:179], v[208:211], v[82:85]
	v_mfma_f32_16x16x32_bf16 v[134:137], v[168:171], v[188:191], v[134:137]
	v_mfma_f32_16x16x32_bf16 v[130:133], v[180:183], v[188:191], v[130:133]
	v_mfma_f32_16x16x32_bf16 v[118:121], v[168:171], v[196:199], v[118:121]
	v_mfma_f32_16x16x32_bf16 v[114:117], v[180:183], v[196:199], v[114:117]
	v_mfma_f32_16x16x32_bf16 v[102:105], v[168:171], v[204:207], v[102:105]
	v_mfma_f32_16x16x32_bf16 v[98:101], v[180:183], v[204:207], v[98:101]
	v_mfma_f32_16x16x32_bf16 v[86:89], v[168:171], v[212:215], v[86:89]
	v_mfma_f32_16x16x32_bf16 v[82:85], v[180:183], v[212:215], v[82:85]
	s_barrier
	s_add_i32 s64, s53, s46
	v_lshl_add_u64 v[216:217], s[8:9], 0, v[148:149]
	s_mov_b32 m0, s64
	ds_read_b128 v[184:187], v174 offset:16384
	ds_read_b128 v[188:191], v174 offset:17408
	ds_read_b128 v[192:195], v174 offset:18432
	ds_read_b128 v[196:199], v174 offset:19456
	ds_read_b128 v[200:203], v174 offset:20480
	ds_read_b128 v[204:207], v174 offset:21504
	ds_read_b128 v[208:211], v174 offset:22528
	ds_read_b128 v[212:215], v174 offset:23552
	global_load_lds_dwordx4 v[216:217], off
	s_add_i32 m0, s64, 0x2000
	s_add_u32 s64, s8, 0x100000
	v_lshl_add_u64 v[218:219], s[8:9], 0, v[152:153]
	s_addc_u32 s65, s9, 0
	s_add_i32 s66, s54, s46
	global_load_lds_dwordx4 v[218:219], off
	v_lshl_add_u64 v[220:221], s[64:65], 0, v[148:149]
	s_mov_b32 m0, s66
	v_lshl_add_u64 v[222:223], s[40:41], 0, v[150:151]
	global_load_lds_dwordx4 v[220:221], off
	v_lshl_add_u64 v[220:221], s[64:65], 0, v[152:153]
	s_add_i32 m0, s66, 0x2000
	s_nop 0
	global_load_lds_dwordx4 v[220:221], off
	v_lshl_add_u64 v[220:221], s[40:41], 0, v[146:147]
	s_mov_b32 m0, s13
	s_nop 0
	global_load_lds_dwordx4 v[220:221], off
	s_mov_b32 m0, s47
	s_nop 0
	global_load_lds_dwordx4 v[222:223], off
	s_waitcnt vmcnt(8)
	s_waitcnt lgkmcnt(0)
	s_barrier
; #define PG8_STAGE(bufoff, gbase, voff) do { _Pragma("unroll") for (int _i = 0; _i < 2; ++_i) \
;         __builtin_amdgcn_global_load_lds((const unsigned*)((const char*)(gbase) + (voff)[_i]), (PG8_LAS unsigned*)(lds + (bufoff) + ldsw + _i * 8192), 16, 0, 0); } while (0)
; #define PG8_LDA(dst, b, h) do { _Pragma("unroll") for (int m = 0; m < 4; ++m) _Pragma("unroll") for (int k = 0; k < 2; ++k) dst[m][k] = *(const PG8_LAS bf16x8*)(lds + PG8_SA(b, h) + aoff + m * 2048 + k * 1024); } while (0)
; #define PG8_LDB(dst, b, h) do { _Pragma("unroll") for (int n = 0; n < 2; ++n) _Pragma("unroll") for (int k = 0; k < 2; ++k) dst[n][k] = *(const PG8_LAS bf16x8*)(lds + PG8_SB(b, h) + boff + n * 2048 + k * 1024); } while (0)
; #define PG8_MMA(ai, bj, At, Bt) do { __builtin_amdgcn_s_setprio(1); _Pragma("unroll") for (int m = 0; m < 4; ++m) _Pragma("unroll") for (int n = 0; n < 2; ++n) _Pragma("unroll") for (int k = 0; k < 2; ++k) \
;         acc[ai][bj][m][n] = __builtin_amdgcn_mfma_f32_16x16x32_bf16(Bt[n][k], At[m][k], acc[ai][bj][m][n], 0, 0, 0); __builtin_amdgcn_s_setprio(0); } while (0)
; #define PG8_WAIT_V(n) asm volatile("s_waitcnt vmcnt(" #n ")" ::: "memory")
; template <class Epi, class Sched, bool ALIGN_EPI = false>
; __device__ __forceinline__ void gemm_phase(PG8_LAS unsigned char* lds, const Gemm g, const Sched& S, const Epi& E) {
;     ...
;             PG8_LDB(B0, 0, 0); PG8_LDB(B1, 0, 1); PG8_SCHED; PG8_LDA(At, 0, 0); PG8_STAGE(PG8_SA(1, 1), a1 + hstepA, voffA);
;             PG8_WAIT_V(8); PG8_WAIT_L(0); PG8_BAR; PG8_MMA(0, 0, At, B0); PG8_MMA(0, 1, At, B1); PG8_BAR; PG8_SCHED;
;             PG8_LDA(At, 0, 1); PG8_STAGE(PG8_SB(0, 0), b2, voffB); PG8_STAGE(PG8_SB(0, 1), b2 + hstepB, voffB); PG8_STAGE(PG8_SA(0, 0), a2, voffA);
;             PG8_WAIT_V(8); PG8_WAIT_L(0); PG8_BAR; PG8_MMA(1, 0, At, B0); PG8_MMA(1, 1, At, B1); PG8_BAR; PG8_SCHED;
;             PG8_LDB(B0, 1, 0); PG8_LDB(B1, 1, 1); PG8_SCHED; PG8_LDA(At, 1, 0); PG8_STAGE(PG8_SA(0, 1), a2 + hstepA, voffA);
;             PG8_WAIT_V(8); PG8_WAIT_L(0); PG8_BAR; PG8_MMA(0, 0, At, B0); PG8_MMA(0, 1, At, B1); PG8_BAR; PG8_SCHED;
;             PG8_LDA(At, 1, 1); PG8_STAGE(PG8_SB(1, 0), b3, voffB); PG8_STAGE(PG8_SB(1, 1), b3 + hstepB, voffB); PG8_STAGE(PG8_SA(1, 0), a3, voffA);
;             PG8_WAIT_V(8); PG8_WAIT_L(0); PG8_BAR; PG8_MMA(1, 0, At, B0); PG8_MMA(1, 1, At, B1); PG8_BAR; PG8_SCHED;
	s_waitcnt lgkmcnt(0)
	v_mfma_f32_16x16x32_bf16 v[78:81], v[42:45], v[184:187], v[78:81]
	v_mfma_f32_16x16x32_bf16 v[74:77], v[50:53], v[184:187], v[74:77]
	v_mfma_f32_16x16x32_bf16 v[62:65], v[42:45], v[192:195], v[62:65]
	v_mfma_f32_16x16x32_bf16 v[54:57], v[50:53], v[192:195], v[54:57]
	v_mfma_f32_16x16x32_bf16 v[30:33], v[42:45], v[200:203], v[30:33]
	v_mfma_f32_16x16x32_bf16 v[26:29], v[50:53], v[200:203], v[26:29]
	v_mfma_f32_16x16x32_bf16 v[14:17], v[42:45], v[208:211], v[14:17]
	v_mfma_f32_16x16x32_bf16 v[10:13], v[50:53], v[208:211], v[10:13]
	v_mfma_f32_16x16x32_bf16 v[78:81], v[46:49], v[188:191], v[78:81]
	v_mfma_f32_16x16x32_bf16 v[74:77], v[58:61], v[188:191], v[74:77]
	v_mfma_f32_16x16x32_bf16 v[62:65], v[46:49], v[196:199], v[62:65]
	v_mfma_f32_16x16x32_bf16 v[54:57], v[58:61], v[196:199], v[54:57]
	v_mfma_f32_16x16x32_bf16 v[30:33], v[46:49], v[204:207], v[30:33]
	v_mfma_f32_16x16x32_bf16 v[26:29], v[58:61], v[204:207], v[26:29]
	v_mfma_f32_16x16x32_bf16 v[14:17], v[46:49], v[212:215], v[14:17]
	v_mfma_f32_16x16x32_bf16 v[10:13], v[58:61], v[212:215], v[10:13]
	v_mfma_f32_16x16x32_bf16 v[38:41], v[164:167], v[192:195], v[38:41]
	v_mfma_f32_16x16x32_bf16 v[34:37], v[176:179], v[192:195], v[34:37]
	v_mfma_f32_16x16x32_bf16 v[22:25], v[164:167], v[200:203], v[22:25]
	v_mfma_f32_16x16x32_bf16 v[18:21], v[176:179], v[200:203], v[18:21]
	v_mfma_f32_16x16x32_bf16 v[6:9], v[164:167], v[208:211], v[6:9]
	v_mfma_f32_16x16x32_bf16 v[2:5], v[176:179], v[208:211], v[2:5]
	v_mfma_f32_16x16x32_bf16 v[42:45], v[164:167], v[184:187], v[70:73]
	v_mfma_f32_16x16x32_bf16 v[46:49], v[176:179], v[184:187], v[66:69]
	v_mfma_f32_16x16x32_bf16 v[38:41], v[168:171], v[196:199], v[38:41]
	v_mfma_f32_16x16x32_bf16 v[34:37], v[180:183], v[196:199], v[34:37]
	v_mfma_f32_16x16x32_bf16 v[22:25], v[168:171], v[204:207], v[22:25]
	v_mfma_f32_16x16x32_bf16 v[18:21], v[180:183], v[204:207], v[18:21]
	v_mfma_f32_16x16x32_bf16 v[6:9], v[168:171], v[212:215], v[6:9]
	v_mfma_f32_16x16x32_bf16 v[2:5], v[180:183], v[212:215], v[2:5]
	v_mfma_f32_16x16x32_bf16 v[42:45], v[168:171], v[188:191], v[42:45]
	v_mfma_f32_16x16x32_bf16 v[46:49], v[180:183], v[188:191], v[46:49]
	s_barrier
	s_add_i32 s64, 0, 0x18000
	s_add_i32 s65, 0, 0x1c000
	v_add_u32_e32 v70, s64, v1
	v_add_u32_e32 v154, s65, v1
	ds_read_b128 v[50:53], v70
	ds_read_b128 v[58:61], v70 offset:1024
	ds_read_b128 v[66:69], v70 offset:2048
	ds_read_b128 v[70:73], v70 offset:3072
	ds_read_b128 v[164:167], v154
	ds_read_b128 v[168:171], v154 offset:1024
	ds_read_b128 v[176:179], v154 offset:2048
	ds_read_b128 v[180:183], v154 offset:3072
	s_add_u32 s40, s40, 0x100000
	s_addc_u32 s41, s41, 0
	s_mov_b32 m0, s48
	v_lshl_add_u64 v[224:225], s[40:41], 0, v[146:147]
	ds_read_b128 v[184:187], v174 offset:32768
	ds_read_b128 v[188:191], v174 offset:33792
	ds_read_b128 v[192:195], v174 offset:34816
	ds_read_b128 v[196:199], v174 offset:35840
	ds_read_b128 v[200:203], v174 offset:36864
	ds_read_b128 v[204:207], v174 offset:37888
	ds_read_b128 v[208:211], v174 offset:38912
	ds_read_b128 v[212:215], v174 offset:39936
	global_load_lds_dwordx4 v[224:225], off
	v_lshl_add_u64 v[224:225], s[40:41], 0, v[150:151]
	s_mov_b32 m0, s49
	s_nop 0
	global_load_lds_dwordx4 v[224:225], off
	s_waitcnt vmcnt(8)
	s_waitcnt lgkmcnt(0)
	s_barrier
	s_waitcnt lgkmcnt(0)
	v_mfma_f32_16x16x32_bf16 v[142:145], v[50:53], v[184:187], v[142:145]
	v_mfma_f32_16x16x32_bf16 v[138:141], v[66:69], v[184:187], v[138:141]
	v_mfma_f32_16x16x32_bf16 v[126:129], v[50:53], v[192:195], v[126:129]
	v_mfma_f32_16x16x32_bf16 v[122:125], v[66:69], v[192:195], v[122:125]
	v_mfma_f32_16x16x32_bf16 v[110:113], v[50:53], v[200:203], v[110:113]
	v_mfma_f32_16x16x32_bf16 v[106:109], v[66:69], v[200:203], v[106:109]
	v_mfma_f32_16x16x32_bf16 v[94:97], v[50:53], v[208:211], v[94:97]
	v_mfma_f32_16x16x32_bf16 v[90:93], v[66:69], v[208:211], v[90:93]
	v_mfma_f32_16x16x32_bf16 v[142:145], v[58:61], v[188:191], v[142:145]
	v_mfma_f32_16x16x32_bf16 v[138:141], v[70:73], v[188:191], v[138:141]
	v_mfma_f32_16x16x32_bf16 v[126:129], v[58:61], v[196:199], v[126:129]
	v_mfma_f32_16x16x32_bf16 v[122:125], v[70:73], v[196:199], v[122:125]
	v_mfma_f32_16x16x32_bf16 v[110:113], v[58:61], v[204:207], v[110:113]
	v_mfma_f32_16x16x32_bf16 v[106:109], v[70:73], v[204:207], v[106:109]
	v_mfma_f32_16x16x32_bf16 v[94:97], v[58:61], v[212:215], v[94:97]
	v_mfma_f32_16x16x32_bf16 v[90:93], v[70:73], v[212:215], v[90:93]
	v_mfma_f32_16x16x32_bf16 v[134:137], v[164:167], v[184:187], v[134:137]
	v_mfma_f32_16x16x32_bf16 v[130:133], v[176:179], v[184:187], v[130:133]
	v_mfma_f32_16x16x32_bf16 v[118:121], v[164:167], v[192:195], v[118:121]
	v_mfma_f32_16x16x32_bf16 v[114:117], v[176:179], v[192:195], v[114:117]
	v_mfma_f32_16x16x32_bf16 v[102:105], v[164:167], v[200:203], v[102:105]
	v_mfma_f32_16x16x32_bf16 v[98:101], v[176:179], v[200:203], v[98:101]
	v_mfma_f32_16x16x32_bf16 v[86:89], v[164:167], v[208:211], v[86:89]
	v_mfma_f32_16x16x32_bf16 v[82:85], v[176:179], v[208:211], v[82:85]
	v_mfma_f32_16x16x32_bf16 v[134:137], v[168:171], v[188:191], v[134:137]
	v_mfma_f32_16x16x32_bf16 v[130:133], v[180:183], v[188:191], v[130:133]
	v_mfma_f32_16x16x32_bf16 v[118:121], v[168:171], v[196:199], v[118:121]
	v_mfma_f32_16x16x32_bf16 v[114:117], v[180:183], v[196:199], v[114:117]
	v_mfma_f32_16x16x32_bf16 v[102:105], v[168:171], v[204:207], v[102:105]
	v_mfma_f32_16x16x32_bf16 v[98:101], v[180:183], v[204:207], v[98:101]
	v_mfma_f32_16x16x32_bf16 v[86:89], v[168:171], v[212:215], v[86:89]
	v_mfma_f32_16x16x32_bf16 v[82:85], v[180:183], v[212:215], v[82:85]
	s_barrier
; #define PG8_STAGE(bufoff, gbase, voff) do { _Pragma("unroll") for (int _i = 0; _i < 2; ++_i) \
;         __builtin_amdgcn_global_load_lds((const unsigned*)((const char*)(gbase) + (voff)[_i]), (PG8_LAS unsigned*)(lds + (bufoff) + ldsw + _i * 8192), 16, 0, 0); } while (0)
; #define PG8_LDA(dst, b, h) do { _Pragma("unroll") for (int m = 0; m < 4; ++m) _Pragma("unroll") for (int k = 0; k < 2; ++k) dst[m][k] = *(const PG8_LAS bf16x8*)(lds + PG8_SA(b, h) + aoff + m * 2048 + k * 1024); } while (0)
; #define PG8_LDB(dst, b, h) do { _Pragma("unroll") for (int n = 0; n < 2; ++n) _Pragma("unroll") for (int k = 0; k < 2; ++k) dst[n][k] = *(const PG8_LAS bf16x8*)(lds + PG8_SB(b, h) + boff + n * 2048 + k * 1024); } while (0)
; #define PG8_MMA(ai, bj, At, Bt) do { __builtin_amdgcn_s_setprio(1); _Pragma("unroll") for (int m = 0; m < 4; ++m) _Pragma("unroll") for (int n = 0; n < 2; ++n) _Pragma("unroll") for (int k = 0; k < 2; ++k) \
;         acc[ai][bj][m][n] = __builtin_amdgcn_mfma_f32_16x16x32_bf16(Bt[n][k], At[m][k], acc[ai][bj][m][n], 0, 0, 0); __builtin_amdgcn_s_setprio(0); } while (0)
; #define PG8_WAIT_V(n) asm volatile("s_waitcnt vmcnt(" #n ")" ::: "memory")
; template <class Epi, class Sched, bool ALIGN_EPI = false>
; __device__ __forceinline__ void gemm_phase(PG8_LAS unsigned char* lds, const Gemm g, const Sched& S, const Epi& E) {
;     ...
;             PG8_LDB(B0, 0, 0); PG8_LDB(B1, 0, 1); PG8_SCHED; PG8_LDA(At, 0, 0); PG8_STAGE(PG8_SA(1, 1), a1 + hstepA, voffA);
;             PG8_WAIT_V(8); PG8_WAIT_L(0); PG8_BAR; PG8_MMA(0, 0, At, B0); PG8_MMA(0, 1, At, B1); PG8_BAR; PG8_SCHED;
;             PG8_LDA(At, 0, 1); PG8_STAGE(PG8_SB(0, 0), b2, voffB); PG8_STAGE(PG8_SB(0, 1), b2 + hstepB, voffB); PG8_STAGE(PG8_SA(0, 0), a2, voffA);
;             PG8_WAIT_V(8); PG8_WAIT_L(0); PG8_BAR; PG8_MMA(1, 0, At, B0); PG8_MMA(1, 1, At, B1); PG8_BAR; PG8_SCHED;
;             PG8_LDB(B0, 1, 0); PG8_LDB(B1, 1, 1); PG8_SCHED; PG8_LDA(At, 1, 0); PG8_STAGE(PG8_SA(0, 1), a2 + hstepA, voffA);
;             PG8_WAIT_V(8); PG8_WAIT_L(0); PG8_BAR; PG8_MMA(0, 0, At, B0); PG8_MMA(0, 1, At, B1); PG8_BAR; PG8_SCHED;
;             PG8_LDA(At, 1, 1); PG8_STAGE(PG8_SB(1, 0), b3, voffB); PG8_STAGE(PG8_SB(1, 1), b3 + hstepB, voffB); PG8_STAGE(PG8_SA(1, 0), a3, voffA);
;             PG8_WAIT_V(8); PG8_WAIT_L(0); PG8_BAR; PG8_MMA(1, 0, At, B0); PG8_MMA(1, 1, At, B1); PG8_BAR; PG8_SCHED;
	s_add_i32 s40, s64, s46
	v_lshl_add_u64 v[216:217], v[216:217], 0, s[24:25]
	s_mov_b32 m0, s40
	ds_read_b128 v[184:187], v174 offset:49152
	ds_read_b128 v[188:191], v174 offset:50176
	ds_read_b128 v[192:195], v174 offset:51200
	ds_read_b128 v[196:199], v174 offset:52224
	ds_read_b128 v[200:203], v174 offset:53248
	ds_read_b128 v[204:207], v174 offset:54272
	ds_read_b128 v[208:211], v174 offset:55296
	ds_read_b128 v[212:215], v174 offset:56320
	global_load_lds_dwordx4 v[216:217], off
	s_add_i32 m0, s40, 0x2000
	s_add_u32 s8, s8, 0x100080
	v_lshl_add_u64 v[216:217], v[218:219], 0, s[24:25]
	s_addc_u32 s9, s9, 0
	s_add_i32 s40, s65, s46
	global_load_lds_dwordx4 v[216:217], off
	v_lshl_add_u64 v[216:217], s[8:9], 0, v[148:149]
	s_mov_b32 m0, s40
	s_nop 0
	global_load_lds_dwordx4 v[216:217], off
	v_lshl_add_u64 v[216:217], s[8:9], 0, v[152:153]
	s_add_i32 m0, s40, 0x2000
	s_nop 0
	global_load_lds_dwordx4 v[216:217], off
	v_lshl_add_u64 v[216:217], v[220:221], 0, s[24:25]
	s_mov_b32 m0, s0
	s_nop 0
	global_load_lds_dwordx4 v[216:217], off
	v_lshl_add_u64 v[216:217], v[222:223], 0, s[24:25]
	s_mov_b32 m0, s1
	s_nop 0
	global_load_lds_dwordx4 v[216:217], off
	s_waitcnt vmcnt(8)
	s_waitcnt lgkmcnt(0)
	s_barrier
	s_waitcnt lgkmcnt(0)
	v_mfma_f32_16x16x32_bf16 v[78:81], v[50:53], v[184:187], v[78:81]
	v_mfma_f32_16x16x32_bf16 v[74:77], v[66:69], v[184:187], v[74:77]
	v_mfma_f32_16x16x32_bf16 v[62:65], v[50:53], v[192:195], v[62:65]
	v_mfma_f32_16x16x32_bf16 v[54:57], v[66:69], v[192:195], v[54:57]
	v_mfma_f32_16x16x32_bf16 v[30:33], v[50:53], v[200:203], v[30:33]
	v_mfma_f32_16x16x32_bf16 v[26:29], v[66:69], v[200:203], v[26:29]
	v_mfma_f32_16x16x32_bf16 v[14:17], v[50:53], v[208:211], v[14:17]
	v_mfma_f32_16x16x32_bf16 v[10:13], v[66:69], v[208:211], v[10:13]
	v_mfma_f32_16x16x32_bf16 v[78:81], v[58:61], v[188:191], v[78:81]
	v_mfma_f32_16x16x32_bf16 v[74:77], v[70:73], v[188:191], v[74:77]
	v_mfma_f32_16x16x32_bf16 v[62:65], v[58:61], v[196:199], v[62:65]
	v_mfma_f32_16x16x32_bf16 v[54:57], v[70:73], v[196:199], v[54:57]
	v_mfma_f32_16x16x32_bf16 v[30:33], v[58:61], v[204:207], v[30:33]
	v_mfma_f32_16x16x32_bf16 v[26:29], v[70:73], v[204:207], v[26:29]
	v_mfma_f32_16x16x32_bf16 v[14:17], v[58:61], v[212:215], v[14:17]
	v_mfma_f32_16x16x32_bf16 v[10:13], v[70:73], v[212:215], v[10:13]
	v_mfma_f32_16x16x32_bf16 v[42:45], v[164:167], v[184:187], v[42:45]
	v_mfma_f32_16x16x32_bf16 v[70:73], v[168:171], v[188:191], v[42:45]
	v_mfma_f32_16x16x32_bf16 v[42:45], v[176:179], v[184:187], v[46:49]
	v_mfma_f32_16x16x32_bf16 v[38:41], v[164:167], v[192:195], v[38:41]
	v_mfma_f32_16x16x32_bf16 v[34:37], v[176:179], v[192:195], v[34:37]
	v_mfma_f32_16x16x32_bf16 v[22:25], v[164:167], v[200:203], v[22:25]
	v_mfma_f32_16x16x32_bf16 v[18:21], v[176:179], v[200:203], v[18:21]
	v_mfma_f32_16x16x32_bf16 v[6:9], v[164:167], v[208:211], v[6:9]
	v_mfma_f32_16x16x32_bf16 v[2:5], v[176:179], v[208:211], v[2:5]
	v_mfma_f32_16x16x32_bf16 v[66:69], v[180:183], v[188:191], v[42:45]
	v_mfma_f32_16x16x32_bf16 v[38:41], v[168:171], v[196:199], v[38:41]
	v_mfma_f32_16x16x32_bf16 v[34:37], v[180:183], v[196:199], v[34:37]
	v_mfma_f32_16x16x32_bf16 v[22:25], v[168:171], v[204:207], v[22:25]
	v_mfma_f32_16x16x32_bf16 v[18:21], v[180:183], v[204:207], v[18:21]
	v_mfma_f32_16x16x32_bf16 v[6:9], v[168:171], v[212:215], v[6:9]
	v_mfma_f32_16x16x32_bf16 v[2:5], v[180:183], v[212:215], v[2:5]
	s_barrier
	s_add_i32 s63, s63, 2
	s_add_u32 s6, s6, 0x100
	s_addc_u32 s7, s7, 0
	s_add_u32 s61, s61, 0x100
	s_addc_u32 s62, s62, 0
	s_cmp_gt_u32 s63, 61
	s_cbranch_scc0 .LBB0_198
	s_and_b64 vcc, exec, s[26:27]
	s_cbranch_vccz .LBB0_201
	s_barrier

; __device__ __forceinline__ unsigned xb_ld(unsigned* p)              { return __hip_atomic_load(p, __ATOMIC_RELAXED, __HIP_MEMORY_SCOPE_AGENT); }
; __device__ __forceinline__ void xcd_barrier_complete(unsigned* bar, unsigned x, unsigned& nloc, unsigned& nx) {
;     const unsigned G = gridDim.x * gridDim.y * gridDim.z;
;     unsigned sum, cnt, mine, sp = 0u;
;     for (;;) {
;         sum = 0u; cnt = 0u; mine = 0u;
; #pragma unroll
;         for (unsigned j = 0; j < 16; ++j) { const unsigned c = xb_ld(&bar[XB_XCNT(j)]); sum += c; cnt += (c > 0u) ? 1u : 0u; mine = (j == x) ? c : mine; }
;         if (sum == G) break;
; __device__ __forceinline__ void xcd_barrier(const XcdBarrier& b) {
;     asm volatile("s_waitcnt vmcnt(0)" ::: "memory");
;     __syncthreads();
;     if (threadIdx.x == 0) {
;         unsigned* bar = b.bar;
;         __builtin_amdgcn_s_waitcnt(0);
;         unsigned nloc = b.st[0], nx = b.st[1];
;         if (nloc == 0u) { xcd_barrier_complete(bar, b.x, nloc, nx); b.st[0] = nloc; b.st[1] = nx; }
.LBB0_317:
	s_setprio 0
	s_cmp_gt_i32 s59, 3
	s_cselect_b64 s[2:3], -1, 0
	s_and_b64 s[0:1], s[10:11], s[2:3]
	s_andn2_b64 vcc, exec, s[0:1]
	s_cbranch_vccnz .LBB0_367
	s_waitcnt vmcnt(0)
	v_cmp_eq_u32_e32 vcc, 0, v0
	s_waitcnt vmcnt(0)
	s_barrier
	s_and_saveexec_b64 s[4:5], vcc
	s_cbranch_execz .LBB0_366
	v_readlane_b32 s0, v228, 5
	s_waitcnt vmcnt(0) expcnt(0) lgkmcnt(0)
	s_nop 0
	v_mov_b32_e32 v1, s0
	ds_read_b32 v3, v1
	ds_read_b32 v1, v1 offset:4
	s_waitcnt lgkmcnt(1)
	v_cmp_ne_u32_e32 vcc, 0, v3
	s_cbranch_vccnz .LBB0_334
	v_readlane_b32 s6, v228, 0
	v_readlane_b32 s7, v228, 1
	s_load_dwordx2 s[0:1], s[6:7], 0x4
	s_add_u32 s6, s56, 0x4200
	s_addc_u32 s7, s57, 0
	s_add_u32 s8, s56, 0x4400
	s_addc_u32 s9, s57, 0
	s_add_u32 s10, s56, 0x4500
	s_addc_u32 s11, s57, 0
	s_add_u32 s12, s56, 0x4600
	s_addc_u32 s13, s57, 0
	s_add_u32 s14, s56, 0x4700
	s_addc_u32 s15, s57, 0
	s_add_u32 s16, s56, 0x4800
	s_addc_u32 s17, s57, 0
	s_add_u32 s18, s56, 0x4900
	s_addc_u32 s19, s57, 0
	s_add_u32 s20, s56, 0x4a00
	s_addc_u32 s21, s57, 0
	s_add_u32 s22, s56, 0x4b00
	s_addc_u32 s23, s57, 0
	s_add_u32 s24, s56, 0x4c00
	s_addc_u32 s25, s57, 0
	s_add_u32 s26, s56, 0x4d00
	s_addc_u32 s27, s57, 0
	s_add_u32 s28, s56, 0x4e00
	s_addc_u32 s29, s57, 0
	s_add_u32 s30, s56, 0x4f00
	s_addc_u32 s31, s57, 0
	s_add_u32 s34, s56, 0x5000
	s_addc_u32 s35, s57, 0
	s_add_u32 s36, s56, 0x5100
	s_addc_u32 s37, s57, 0
	s_add_u32 s38, s56, 0x5200
	s_addc_u32 s39, s57, 0
	s_waitcnt lgkmcnt(0)
	s_mul_i32 s0, s0, s86
	s_add_u32 s40, s56, 0x5300
	s_mul_i32 s0, s0, s1
	s_addc_u32 s41, s57, 0
	s_mov_b32 s1, 1
	v_mov_b32_e32 v17, 0
	s_branch .LBB0_322

; #define PG8_STAGE(bufoff, gbase, voff) do { _Pragma("unroll") for (int _i = 0; _i < 2; ++_i) \
;         __builtin_amdgcn_global_load_lds((const unsigned*)((const char*)(gbase) + (voff)[_i]), (PG8_LAS unsigned*)(lds + (bufoff) + ldsw + _i * 8192), 16, 0, 0); } while (0)
; #define PG8_LDA(dst, b, h) do { _Pragma("unroll") for (int m = 0; m < 4; ++m) _Pragma("unroll") for (int k = 0; k < 2; ++k) dst[m][k] = *(const PG8_LAS bf16x8*)(lds + PG8_SA(b, h) + aoff + m * 2048 + k * 1024); } while (0)
; #define PG8_LDB(dst, b, h) do { _Pragma("unroll") for (int n = 0; n < 2; ++n) _Pragma("unroll") for (int k = 0; k < 2; ++k) dst[n][k] = *(const PG8_LAS bf16x8*)(lds + PG8_SB(b, h) + boff + n * 2048 + k * 1024); } while (0)
; #define PG8_MMA(ai, bj, At, Bt) do { __builtin_amdgcn_s_setprio(1); _Pragma("unroll") for (int m = 0; m < 4; ++m) _Pragma("unroll") for (int n = 0; n < 2; ++n) _Pragma("unroll") for (int k = 0; k < 2; ++k) \
;         acc[ai][bj][m][n] = __builtin_amdgcn_mfma_f32_16x16x32_bf16(Bt[n][k], At[m][k], acc[ai][bj][m][n], 0, 0, 0); __builtin_amdgcn_s_setprio(0); } while (0)
; #define PG8_WAIT_V(n) asm volatile("s_waitcnt vmcnt(" #n ")" ::: "memory")
; template <class Epi, class Sched, bool ALIGN_EPI = false>
; __device__ __forceinline__ void gemm_phase(PG8_LAS unsigned char* lds, const Gemm g, const Sched& S, const Epi& E) {
;     ...
;             PG8_LDB(B0, 0, 0); PG8_LDB(B1, 0, 1); PG8_SCHED; PG8_LDA(At, 0, 0); PG8_STAGE(PG8_SA(1, 1), a1 + hstepA, voffA);
;             PG8_WAIT_V(8); PG8_WAIT_L(0); PG8_BAR; PG8_MMA(0, 0, At, B0); PG8_MMA(0, 1, At, B1); PG8_BAR; PG8_SCHED;
;             PG8_LDA(At, 0, 1); PG8_STAGE(PG8_SB(0, 0), b2, voffB); PG8_STAGE(PG8_SB(0, 1), b2 + hstepB, voffB); PG8_STAGE(PG8_SA(0, 0), a2, voffA);
;             PG8_WAIT_V(8); PG8_WAIT_L(0); PG8_BAR; PG8_MMA(1, 0, At, B0); PG8_MMA(1, 1, At, B1); PG8_BAR; PG8_SCHED;
;             PG8_LDB(B0, 1, 0); PG8_LDB(B1, 1, 1); PG8_SCHED; PG8_LDA(At, 1, 0); PG8_STAGE(PG8_SA(0, 1), a2 + hstepA, voffA);
;             PG8_WAIT_V(8); PG8_WAIT_L(0); PG8_BAR; PG8_MMA(0, 0, At, B0); PG8_MMA(0, 1, At, B1); PG8_BAR; PG8_SCHED;
;             PG8_LDA(At, 1, 1); PG8_STAGE(PG8_SB(1, 0), b3, voffB); PG8_STAGE(PG8_SB(1, 1), b3 + hstepB, voffB); PG8_STAGE(PG8_SA(1, 0), a3, voffA);
;             PG8_WAIT_V(8); PG8_WAIT_L(0); PG8_BAR; PG8_MMA(1, 0, At, B0); PG8_MMA(1, 1, At, B1); PG8_BAR; PG8_SCHED;
.LBB0_393:
	ds_read_b128 v[148:151], v144
	ds_read_b128 v[152:155], v144 offset:1024
	ds_read_b128 v[156:159], v144 offset:2048
	ds_read_b128 v[160:163], v144 offset:3072
	ds_read_b128 v[164:167], v145
	ds_read_b128 v[168:171], v145 offset:1024
	ds_read_b128 v[172:175], v145 offset:2048
	ds_read_b128 v[176:179], v145 offset:3072
	s_add_u32 s36, s34, 0xfff00080
	s_addc_u32 s37, s35, -1
	s_cmp_eq_u32 s66, 60
	s_cselect_b32 s39, s25, s37
	s_cselect_b32 s38, s62, s36
	s_cselect_b32 s37, s23, s65
	s_cselect_b32 s36, s63, s64
	v_lshl_add_u64 v[142:143], s[34:35], 0, v[138:139]
	s_add_i32 m0, s31, 0xc000
	ds_read_b128 v[180:183], v146
	ds_read_b128 v[184:187], v146 offset:1024
	ds_read_b128 v[188:191], v146 offset:2048
	ds_read_b128 v[192:195], v146 offset:3072
	ds_read_b128 v[196:199], v146 offset:4096
	ds_read_b128 v[200:203], v146 offset:5120
	ds_read_b128 v[204:207], v146 offset:6144
	ds_read_b128 v[208:211], v146 offset:7168
	global_load_lds_dwordx4 v[142:143], off
	v_lshl_add_u64 v[142:143], s[34:35], 0, v[140:141]
	s_add_i32 m0, s31, 0xe000
	s_nop 0
	global_load_lds_dwordx4 v[142:143], off
	s_waitcnt vmcnt(8)
	s_waitcnt lgkmcnt(0)
	s_barrier
	s_waitcnt lgkmcnt(0)
	v_mfma_f32_16x16x32_bf16 v[126:129], v[148:151], v[180:183], v[126:129]
	v_mfma_f32_16x16x32_bf16 v[122:125], v[156:159], v[180:183], v[122:125]
	v_mfma_f32_16x16x32_bf16 v[118:121], v[148:151], v[188:191], v[118:121]
	v_mfma_f32_16x16x32_bf16 v[110:113], v[156:159], v[188:191], v[110:113]
	v_mfma_f32_16x16x32_bf16 v[102:105], v[148:151], v[196:199], v[102:105]
	v_mfma_f32_16x16x32_bf16 v[94:97], v[156:159], v[196:199], v[94:97]
	v_mfma_f32_16x16x32_bf16 v[86:89], v[148:151], v[204:207], v[86:89]
	v_mfma_f32_16x16x32_bf16 v[78:81], v[156:159], v[204:207], v[78:81]
	v_mfma_f32_16x16x32_bf16 v[126:129], v[152:155], v[184:187], v[126:129]
	v_mfma_f32_16x16x32_bf16 v[122:125], v[160:163], v[184:187], v[122:125]
	v_mfma_f32_16x16x32_bf16 v[118:121], v[152:155], v[192:195], v[118:121]
	v_mfma_f32_16x16x32_bf16 v[110:113], v[160:163], v[192:195], v[110:113]
	v_mfma_f32_16x16x32_bf16 v[102:105], v[152:155], v[200:203], v[102:105]
	v_mfma_f32_16x16x32_bf16 v[94:97], v[160:163], v[200:203], v[94:97]
	v_mfma_f32_16x16x32_bf16 v[86:89], v[152:155], v[208:211], v[86:89]
	v_mfma_f32_16x16x32_bf16 v[78:81], v[160:163], v[208:211], v[78:81]
	v_mfma_f32_16x16x32_bf16 v[114:117], v[164:167], v[180:183], v[114:117]
	v_mfma_f32_16x16x32_bf16 v[106:109], v[172:175], v[180:183], v[106:109]
	v_mfma_f32_16x16x32_bf16 v[98:101], v[164:167], v[188:191], v[98:101]
	v_mfma_f32_16x16x32_bf16 v[90:93], v[172:175], v[188:191], v[90:93]
	v_mfma_f32_16x16x32_bf16 v[82:85], v[164:167], v[196:199], v[82:85]
	v_mfma_f32_16x16x32_bf16 v[74:77], v[172:175], v[196:199], v[74:77]
	v_mfma_f32_16x16x32_bf16 v[70:73], v[164:167], v[204:207], v[70:73]
	v_mfma_f32_16x16x32_bf16 v[66:69], v[172:175], v[204:207], v[66:69]
	v_mfma_f32_16x16x32_bf16 v[114:117], v[168:171], v[184:187], v[114:117]
	v_mfma_f32_16x16x32_bf16 v[106:109], v[176:179], v[184:187], v[106:109]
	v_mfma_f32_16x16x32_bf16 v[98:101], v[168:171], v[192:195], v[98:101]
	v_mfma_f32_16x16x32_bf16 v[90:93], v[176:179], v[192:195], v[90:93]
	v_mfma_f32_16x16x32_bf16 v[82:85], v[168:171], v[200:203], v[82:85]
	v_mfma_f32_16x16x32_bf16 v[74:77], v[176:179], v[200:203], v[74:77]
	v_mfma_f32_16x16x32_bf16 v[70:73], v[168:171], v[208:211], v[70:73]
	v_mfma_f32_16x16x32_bf16 v[66:69], v[176:179], v[208:211], v[66:69]
	s_barrier
	s_add_i32 s67, s51, s43
	v_lshl_add_u64 v[142:143], s[36:37], 0, v[132:133]
	s_mov_b32 m0, s67
	ds_read_b128 v[180:183], v146 offset:16384
	ds_read_b128 v[184:187], v146 offset:17408
	ds_read_b128 v[188:191], v146 offset:18432
	ds_read_b128 v[192:195], v146 offset:19456
	ds_read_b128 v[196:199], v146 offset:20480
	ds_read_b128 v[200:203], v146 offset:21504
	ds_read_b128 v[204:207], v146 offset:22528
	ds_read_b128 v[208:211], v146 offset:23552
	global_load_lds_dwordx4 v[142:143], off
	s_add_i32 m0, s67, 0x2000
	s_add_u32 s68, s36, 0x100000
	v_lshl_add_u64 v[212:213], s[36:37], 0, v[136:137]
	s_addc_u32 s69, s37, 0
	s_add_i32 s67, s52, s43
	global_load_lds_dwordx4 v[212:213], off
	v_lshl_add_u64 v[214:215], s[68:69], 0, v[132:133]
	s_mov_b32 m0, s67
	v_lshl_add_u64 v[216:217], s[38:39], 0, v[134:135]
	global_load_lds_dwordx4 v[214:215], off
	v_lshl_add_u64 v[214:215], s[68:69], 0, v[136:137]
	s_add_i32 m0, s67, 0x2000
	s_nop 0
	global_load_lds_dwordx4 v[214:215], off
	v_lshl_add_u64 v[214:215], s[38:39], 0, v[130:131]
	s_mov_b32 m0, s31
	s_nop 0
	global_load_lds_dwordx4 v[214:215], off
	s_mov_b32 m0, s44
	s_nop 0
	global_load_lds_dwordx4 v[216:217], off
	s_waitcnt vmcnt(8)
	s_waitcnt lgkmcnt(0)
	s_barrier
; #define PG8_STAGE(bufoff, gbase, voff) do { _Pragma("unroll") for (int _i = 0; _i < 2; ++_i) \
;         __builtin_amdgcn_global_load_lds((const unsigned*)((const char*)(gbase) + (voff)[_i]), (PG8_LAS unsigned*)(lds + (bufoff) + ldsw + _i * 8192), 16, 0, 0); } while (0)
; #define PG8_LDA(dst, b, h) do { _Pragma("unroll") for (int m = 0; m < 4; ++m) _Pragma("unroll") for (int k = 0; k < 2; ++k) dst[m][k] = *(const PG8_LAS bf16x8*)(lds + PG8_SA(b, h) + aoff + m * 2048 + k * 1024); } while (0)
; #define PG8_LDB(dst, b, h) do { _Pragma("unroll") for (int n = 0; n < 2; ++n) _Pragma("unroll") for (int k = 0; k < 2; ++k) dst[n][k] = *(const PG8_LAS bf16x8*)(lds + PG8_SB(b, h) + boff + n * 2048 + k * 1024); } while (0)
; #define PG8_MMA(ai, bj, At, Bt) do { __builtin_amdgcn_s_setprio(1); _Pragma("unroll") for (int m = 0; m < 4; ++m) _Pragma("unroll") for (int n = 0; n < 2; ++n) _Pragma("unroll") for (int k = 0; k < 2; ++k) \
;         acc[ai][bj][m][n] = __builtin_amdgcn_mfma_f32_16x16x32_bf16(Bt[n][k], At[m][k], acc[ai][bj][m][n], 0, 0, 0); __builtin_amdgcn_s_setprio(0); } while (0)
; #define PG8_WAIT_V(n) asm volatile("s_waitcnt vmcnt(" #n ")" ::: "memory")
; template <class Epi, class Sched, bool ALIGN_EPI = false>
; __device__ __forceinline__ void gemm_phase(PG8_LAS unsigned char* lds, const Gemm g, const Sched& S, const Epi& E) {
;     ...
;             PG8_LDB(B0, 0, 0); PG8_LDB(B1, 0, 1); PG8_SCHED; PG8_LDA(At, 0, 0); PG8_STAGE(PG8_SA(1, 1), a1 + hstepA, voffA);
;             PG8_WAIT_V(8); PG8_WAIT_L(0); PG8_BAR; PG8_MMA(0, 0, At, B0); PG8_MMA(0, 1, At, B1); PG8_BAR; PG8_SCHED;
;             PG8_LDA(At, 0, 1); PG8_STAGE(PG8_SB(0, 0), b2, voffB); PG8_STAGE(PG8_SB(0, 1), b2 + hstepB, voffB); PG8_STAGE(PG8_SA(0, 0), a2, voffA);
;             PG8_WAIT_V(8); PG8_WAIT_L(0); PG8_BAR; PG8_MMA(1, 0, At, B0); PG8_MMA(1, 1, At, B1); PG8_BAR; PG8_SCHED;
;             PG8_LDB(B0, 1, 0); PG8_LDB(B1, 1, 1); PG8_SCHED; PG8_LDA(At, 1, 0); PG8_STAGE(PG8_SA(0, 1), a2 + hstepA, voffA);
;             PG8_WAIT_V(8); PG8_WAIT_L(0); PG8_BAR; PG8_MMA(0, 0, At, B0); PG8_MMA(0, 1, At, B1); PG8_BAR; PG8_SCHED;
;             PG8_LDA(At, 1, 1); PG8_STAGE(PG8_SB(1, 0), b3, voffB); PG8_STAGE(PG8_SB(1, 1), b3 + hstepB, voffB); PG8_STAGE(PG8_SA(1, 0), a3, voffA);
;             PG8_WAIT_V(8); PG8_WAIT_L(0); PG8_BAR; PG8_MMA(1, 0, At, B0); PG8_MMA(1, 1, At, B1); PG8_BAR; PG8_SCHED;
	s_waitcnt lgkmcnt(0)
	v_mfma_f32_16x16x32_bf16 v[62:65], v[148:151], v[180:183], v[62:65]
	v_mfma_f32_16x16x32_bf16 v[58:61], v[156:159], v[180:183], v[58:61]
	v_mfma_f32_16x16x32_bf16 v[54:57], v[148:151], v[188:191], v[54:57]
	v_mfma_f32_16x16x32_bf16 v[46:49], v[156:159], v[188:191], v[46:49]
	v_mfma_f32_16x16x32_bf16 v[38:41], v[148:151], v[196:199], v[38:41]
	v_mfma_f32_16x16x32_bf16 v[30:33], v[156:159], v[196:199], v[30:33]
	v_mfma_f32_16x16x32_bf16 v[22:25], v[148:151], v[204:207], v[22:25]
	v_mfma_f32_16x16x32_bf16 v[14:17], v[156:159], v[204:207], v[14:17]
	v_mfma_f32_16x16x32_bf16 v[62:65], v[152:155], v[184:187], v[62:65]
	v_mfma_f32_16x16x32_bf16 v[58:61], v[160:163], v[184:187], v[58:61]
	v_mfma_f32_16x16x32_bf16 v[54:57], v[152:155], v[192:195], v[54:57]
	v_mfma_f32_16x16x32_bf16 v[46:49], v[160:163], v[192:195], v[46:49]
	v_mfma_f32_16x16x32_bf16 v[38:41], v[152:155], v[200:203], v[38:41]
	v_mfma_f32_16x16x32_bf16 v[30:33], v[160:163], v[200:203], v[30:33]
	v_mfma_f32_16x16x32_bf16 v[22:25], v[152:155], v[208:211], v[22:25]
	v_mfma_f32_16x16x32_bf16 v[14:17], v[160:163], v[208:211], v[14:17]
	v_mfma_f32_16x16x32_bf16 v[50:53], v[164:167], v[180:183], v[50:53]
	v_mfma_f32_16x16x32_bf16 v[42:45], v[172:175], v[180:183], v[42:45]
	v_mfma_f32_16x16x32_bf16 v[34:37], v[164:167], v[188:191], v[34:37]
	v_mfma_f32_16x16x32_bf16 v[26:29], v[172:175], v[188:191], v[26:29]
	v_mfma_f32_16x16x32_bf16 v[18:21], v[164:167], v[196:199], v[18:21]
	v_mfma_f32_16x16x32_bf16 v[10:13], v[172:175], v[196:199], v[10:13]
	v_mfma_f32_16x16x32_bf16 v[6:9], v[164:167], v[204:207], v[6:9]
	v_mfma_f32_16x16x32_bf16 v[2:5], v[172:175], v[204:207], v[2:5]
	v_mfma_f32_16x16x32_bf16 v[50:53], v[168:171], v[184:187], v[50:53]
	v_mfma_f32_16x16x32_bf16 v[42:45], v[176:179], v[184:187], v[42:45]
	v_mfma_f32_16x16x32_bf16 v[34:37], v[168:171], v[192:195], v[34:37]
	v_mfma_f32_16x16x32_bf16 v[26:29], v[176:179], v[192:195], v[26:29]
	v_mfma_f32_16x16x32_bf16 v[18:21], v[168:171], v[200:203], v[18:21]
	v_mfma_f32_16x16x32_bf16 v[10:13], v[176:179], v[200:203], v[10:13]
	v_mfma_f32_16x16x32_bf16 v[6:9], v[168:171], v[208:211], v[6:9]
	v_mfma_f32_16x16x32_bf16 v[2:5], v[176:179], v[208:211], v[2:5]
	s_barrier
	s_add_i32 s67, 0, 0x18000
	v_add_u32_e32 v147, s67, v1
	s_add_i32 s68, 0, 0x1c000
	ds_read_b128 v[148:151], v147
	ds_read_b128 v[152:155], v147 offset:1024
	ds_read_b128 v[156:159], v147 offset:2048
	ds_read_b128 v[160:163], v147 offset:3072
	v_add_u32_e32 v147, s68, v1
	ds_read_b128 v[164:167], v147
	ds_read_b128 v[168:171], v147 offset:1024
	ds_read_b128 v[172:175], v147 offset:2048
	ds_read_b128 v[176:179], v147 offset:3072
	s_add_u32 s38, s38, 0x100000
	s_addc_u32 s39, s39, 0
	s_mov_b32 m0, s45
	v_lshl_add_u64 v[218:219], s[38:39], 0, v[130:131]
	ds_read_b128 v[180:183], v146 offset:32768
	ds_read_b128 v[184:187], v146 offset:33792
	ds_read_b128 v[188:191], v146 offset:34816
	ds_read_b128 v[192:195], v146 offset:35840
	ds_read_b128 v[196:199], v146 offset:36864
	ds_read_b128 v[200:203], v146 offset:37888
	ds_read_b128 v[204:207], v146 offset:38912
	ds_read_b128 v[208:211], v146 offset:39936
	global_load_lds_dwordx4 v[218:219], off
	v_lshl_add_u64 v[218:219], s[38:39], 0, v[134:135]
	s_mov_b32 m0, s46
	s_nop 0
	global_load_lds_dwordx4 v[218:219], off
	s_waitcnt vmcnt(8)
	s_waitcnt lgkmcnt(0)
	s_barrier
	s_waitcnt lgkmcnt(0)
	v_mfma_f32_16x16x32_bf16 v[126:129], v[148:151], v[180:183], v[126:129]
	v_mfma_f32_16x16x32_bf16 v[122:125], v[156:159], v[180:183], v[122:125]
	v_mfma_f32_16x16x32_bf16 v[118:121], v[148:151], v[188:191], v[118:121]
	v_mfma_f32_16x16x32_bf16 v[110:113], v[156:159], v[188:191], v[110:113]
	v_mfma_f32_16x16x32_bf16 v[102:105], v[148:151], v[196:199], v[102:105]
	v_mfma_f32_16x16x32_bf16 v[94:97], v[156:159], v[196:199], v[94:97]
	v_mfma_f32_16x16x32_bf16 v[86:89], v[148:151], v[204:207], v[86:89]
	v_mfma_f32_16x16x32_bf16 v[78:81], v[156:159], v[204:207], v[78:81]
	v_mfma_f32_16x16x32_bf16 v[126:129], v[152:155], v[184:187], v[126:129]
	v_mfma_f32_16x16x32_bf16 v[122:125], v[160:163], v[184:187], v[122:125]
	v_mfma_f32_16x16x32_bf16 v[118:121], v[152:155], v[192:195], v[118:121]
	v_mfma_f32_16x16x32_bf16 v[110:113], v[160:163], v[192:195], v[110:113]
	v_mfma_f32_16x16x32_bf16 v[102:105], v[152:155], v[200:203], v[102:105]
	v_mfma_f32_16x16x32_bf16 v[94:97], v[160:163], v[200:203], v[94:97]
	v_mfma_f32_16x16x32_bf16 v[86:89], v[152:155], v[208:211], v[86:89]
	v_mfma_f32_16x16x32_bf16 v[78:81], v[160:163], v[208:211], v[78:81]
	v_mfma_f32_16x16x32_bf16 v[114:117], v[164:167], v[180:183], v[114:117]
	v_mfma_f32_16x16x32_bf16 v[106:109], v[172:175], v[180:183], v[106:109]
	v_mfma_f32_16x16x32_bf16 v[98:101], v[164:167], v[188:191], v[98:101]
	v_mfma_f32_16x16x32_bf16 v[90:93], v[172:175], v[188:191], v[90:93]
	v_mfma_f32_16x16x32_bf16 v[82:85], v[164:167], v[196:199], v[82:85]
	v_mfma_f32_16x16x32_bf16 v[74:77], v[172:175], v[196:199], v[74:77]
	v_mfma_f32_16x16x32_bf16 v[70:73], v[164:167], v[204:207], v[70:73]
	v_mfma_f32_16x16x32_bf16 v[66:69], v[172:175], v[204:207], v[66:69]
	v_mfma_f32_16x16x32_bf16 v[114:117], v[168:171], v[184:187], v[114:117]
	v_mfma_f32_16x16x32_bf16 v[106:109], v[176:179], v[184:187], v[106:109]
	v_mfma_f32_16x16x32_bf16 v[98:101], v[168:171], v[192:195], v[98:101]
	v_mfma_f32_16x16x32_bf16 v[90:93], v[176:179], v[192:195], v[90:93]
	v_mfma_f32_16x16x32_bf16 v[82:85], v[168:171], v[200:203], v[82:85]
	v_mfma_f32_16x16x32_bf16 v[74:77], v[176:179], v[200:203], v[74:77]
	v_mfma_f32_16x16x32_bf16 v[70:73], v[168:171], v[208:211], v[70:73]
	v_mfma_f32_16x16x32_bf16 v[66:69], v[176:179], v[208:211], v[66:69]
	s_barrier
; #define PG8_STAGE(bufoff, gbase, voff) do { _Pragma("unroll") for (int _i = 0; _i < 2; ++_i) \
;         __builtin_amdgcn_global_load_lds((const unsigned*)((const char*)(gbase) + (voff)[_i]), (PG8_LAS unsigned*)(lds + (bufoff) + ldsw + _i * 8192), 16, 0, 0); } while (0)
; #define PG8_LDA(dst, b, h) do { _Pragma("unroll") for (int m = 0; m < 4; ++m) _Pragma("unroll") for (int k = 0; k < 2; ++k) dst[m][k] = *(const PG8_LAS bf16x8*)(lds + PG8_SA(b, h) + aoff + m * 2048 + k * 1024); } while (0)
; #define PG8_LDB(dst, b, h) do { _Pragma("unroll") for (int n = 0; n < 2; ++n) _Pragma("unroll") for (int k = 0; k < 2; ++k) dst[n][k] = *(const PG8_LAS bf16x8*)(lds + PG8_SB(b, h) + boff + n * 2048 + k * 1024); } while (0)
; #define PG8_MMA(ai, bj, At, Bt) do { __builtin_amdgcn_s_setprio(1); _Pragma("unroll") for (int m = 0; m < 4; ++m) _Pragma("unroll") for (int n = 0; n < 2; ++n) _Pragma("unroll") for (int k = 0; k < 2; ++k) \
;         acc[ai][bj][m][n] = __builtin_amdgcn_mfma_f32_16x16x32_bf16(Bt[n][k], At[m][k], acc[ai][bj][m][n], 0, 0, 0); __builtin_amdgcn_s_setprio(0); } while (0)
; #define PG8_WAIT_V(n) asm volatile("s_waitcnt vmcnt(" #n ")" ::: "memory")
; template <class Epi, class Sched, bool ALIGN_EPI = false>
; __device__ __forceinline__ void gemm_phase(PG8_LAS unsigned char* lds, const Gemm g, const Sched& S, const Epi& E) {
;     ...
;             PG8_LDB(B0, 0, 0); PG8_LDB(B1, 0, 1); PG8_SCHED; PG8_LDA(At, 0, 0); PG8_STAGE(PG8_SA(1, 1), a1 + hstepA, voffA);
;             PG8_WAIT_V(8); PG8_WAIT_L(0); PG8_BAR; PG8_MMA(0, 0, At, B0); PG8_MMA(0, 1, At, B1); PG8_BAR; PG8_SCHED;
;             PG8_LDA(At, 0, 1); PG8_STAGE(PG8_SB(0, 0), b2, voffB); PG8_STAGE(PG8_SB(0, 1), b2 + hstepB, voffB); PG8_STAGE(PG8_SA(0, 0), a2, voffA);
;             PG8_WAIT_V(8); PG8_WAIT_L(0); PG8_BAR; PG8_MMA(1, 0, At, B0); PG8_MMA(1, 1, At, B1); PG8_BAR; PG8_SCHED;
;             PG8_LDB(B0, 1, 0); PG8_LDB(B1, 1, 1); PG8_SCHED; PG8_LDA(At, 1, 0); PG8_STAGE(PG8_SA(0, 1), a2 + hstepA, voffA);
;             PG8_WAIT_V(8); PG8_WAIT_L(0); PG8_BAR; PG8_MMA(0, 0, At, B0); PG8_MMA(0, 1, At, B1); PG8_BAR; PG8_SCHED;
;             PG8_LDA(At, 1, 1); PG8_STAGE(PG8_SB(1, 0), b3, voffB); PG8_STAGE(PG8_SB(1, 1), b3 + hstepB, voffB); PG8_STAGE(PG8_SA(1, 0), a3, voffA);
;             PG8_WAIT_V(8); PG8_WAIT_L(0); PG8_BAR; PG8_MMA(1, 0, At, B0); PG8_MMA(1, 1, At, B1); PG8_BAR; PG8_SCHED;
	s_add_i32 s38, s67, s43
	v_lshl_add_u64 v[142:143], v[142:143], 0, s[8:9]
	s_mov_b32 m0, s38
	ds_read_b128 v[180:183], v146 offset:49152
	ds_read_b128 v[184:187], v146 offset:50176
	ds_read_b128 v[188:191], v146 offset:51200
	ds_read_b128 v[192:195], v146 offset:52224
	ds_read_b128 v[196:199], v146 offset:53248
	ds_read_b128 v[200:203], v146 offset:54272
	ds_read_b128 v[204:207], v146 offset:55296
	ds_read_b128 v[208:211], v146 offset:56320
	global_load_lds_dwordx4 v[142:143], off
	s_add_i32 m0, s38, 0x2000
	s_add_u32 s36, s36, 0x100080
	v_lshl_add_u64 v[142:143], v[212:213], 0, s[8:9]
	s_addc_u32 s37, s37, 0
	s_add_i32 s38, s68, s43
	global_load_lds_dwordx4 v[142:143], off
	v_lshl_add_u64 v[142:143], s[36:37], 0, v[132:133]
	s_mov_b32 m0, s38
	s_nop 0
	global_load_lds_dwordx4 v[142:143], off
	v_lshl_add_u64 v[142:143], s[36:37], 0, v[136:137]
	s_add_i32 m0, s38, 0x2000
	s_nop 0
	global_load_lds_dwordx4 v[142:143], off
	v_lshl_add_u64 v[142:143], v[214:215], 0, s[8:9]
	s_mov_b32 m0, s48
	s_nop 0
	global_load_lds_dwordx4 v[142:143], off
	v_lshl_add_u64 v[142:143], v[216:217], 0, s[8:9]
	s_mov_b32 m0, s49
	s_nop 0
	global_load_lds_dwordx4 v[142:143], off
	s_waitcnt vmcnt(8)
	s_waitcnt lgkmcnt(0)
	s_barrier
	s_waitcnt lgkmcnt(0)
	v_mfma_f32_16x16x32_bf16 v[62:65], v[148:151], v[180:183], v[62:65]
	v_mfma_f32_16x16x32_bf16 v[58:61], v[156:159], v[180:183], v[58:61]
	v_mfma_f32_16x16x32_bf16 v[54:57], v[148:151], v[188:191], v[54:57]
	v_mfma_f32_16x16x32_bf16 v[46:49], v[156:159], v[188:191], v[46:49]
	v_mfma_f32_16x16x32_bf16 v[38:41], v[148:151], v[196:199], v[38:41]
	v_mfma_f32_16x16x32_bf16 v[30:33], v[156:159], v[196:199], v[30:33]
	v_mfma_f32_16x16x32_bf16 v[22:25], v[148:151], v[204:207], v[22:25]
	v_mfma_f32_16x16x32_bf16 v[14:17], v[156:159], v[204:207], v[14:17]
	v_mfma_f32_16x16x32_bf16 v[62:65], v[152:155], v[184:187], v[62:65]
	v_mfma_f32_16x16x32_bf16 v[58:61], v[160:163], v[184:187], v[58:61]
	v_mfma_f32_16x16x32_bf16 v[54:57], v[152:155], v[192:195], v[54:57]
	v_mfma_f32_16x16x32_bf16 v[46:49], v[160:163], v[192:195], v[46:49]
	v_mfma_f32_16x16x32_bf16 v[38:41], v[152:155], v[200:203], v[38:41]
	v_mfma_f32_16x16x32_bf16 v[30:33], v[160:163], v[200:203], v[30:33]
	v_mfma_f32_16x16x32_bf16 v[22:25], v[152:155], v[208:211], v[22:25]
	v_mfma_f32_16x16x32_bf16 v[14:17], v[160:163], v[208:211], v[14:17]
	v_mfma_f32_16x16x32_bf16 v[50:53], v[164:167], v[180:183], v[50:53]
	v_mfma_f32_16x16x32_bf16 v[42:45], v[172:175], v[180:183], v[42:45]
	v_mfma_f32_16x16x32_bf16 v[34:37], v[164:167], v[188:191], v[34:37]
	v_mfma_f32_16x16x32_bf16 v[26:29], v[172:175], v[188:191], v[26:29]
	v_mfma_f32_16x16x32_bf16 v[18:21], v[164:167], v[196:199], v[18:21]
	v_mfma_f32_16x16x32_bf16 v[10:13], v[172:175], v[196:199], v[10:13]
	v_mfma_f32_16x16x32_bf16 v[6:9], v[164:167], v[204:207], v[6:9]
	v_mfma_f32_16x16x32_bf16 v[2:5], v[172:175], v[204:207], v[2:5]
	v_mfma_f32_16x16x32_bf16 v[50:53], v[168:171], v[184:187], v[50:53]
	v_mfma_f32_16x16x32_bf16 v[42:45], v[176:179], v[184:187], v[42:45]
	v_mfma_f32_16x16x32_bf16 v[34:37], v[168:171], v[192:195], v[34:37]
	v_mfma_f32_16x16x32_bf16 v[26:29], v[176:179], v[192:195], v[26:29]
	v_mfma_f32_16x16x32_bf16 v[18:21], v[168:171], v[200:203], v[18:21]
	v_mfma_f32_16x16x32_bf16 v[10:13], v[176:179], v[200:203], v[10:13]
	v_mfma_f32_16x16x32_bf16 v[6:9], v[168:171], v[208:211], v[6:9]
	v_mfma_f32_16x16x32_bf16 v[2:5], v[176:179], v[208:211], v[2:5]
	s_barrier
	s_add_i32 s66, s66, 2
	s_add_u32 s34, s34, 0x100
	s_addc_u32 s35, s35, 0
	s_add_u32 s64, s64, 0x100
	s_addc_u32 s65, s65, 0
	s_cmp_gt_u32 s66, 61
	s_cbranch_scc0 .LBB0_393
	s_and_b64 vcc, exec, s[10:11]
	s_cbranch_vccz .LBB0_396
	s_barrier

;     __host__ __device__ bool next(int i, Unit& u) const {
;         const long L = (long)i * G + c; if (L >= nwg) return false;
;         int wgid = (int)L; { const int q = nwg / NXCD, r = nwg % NXCD, xcd = wgid % NXCD, off = wgid / NXCD; wgid = (xcd < r ? xcd * (q + 1) : r * (q + 1) + (xcd - r) * q) + off; }
.LBB0_517:
	s_cmp_lt_i32 s58, 7
	s_cselect_b64 s[0:1], -1, 0
	s_cmp_gt_i32 s59, 6
	s_cselect_b64 s[2:3], -1, 0
	s_and_b64 s[4:5], s[0:1], s[2:3]
	s_andn2_b64 vcc, exec, s[4:5]
	s_cbranch_vccnz .LBB0_542
	v_readfirstlane_b32 s98, v0
	s_nop 3
	s_lshr_b32 s98, s98, 8
	s_cmp_eq_u32 s98, 0
	s_cbranch_scc0 .Lmy_prio1
	s_setprio 1
.Lmy_prio1:
	s_mov_b64 s[2:3], s[82:83]
	v_mov_b32_e32 v1, v0
	s_cmpk_gt_i32 s33, 0x1ff
	v_readfirstlane_b32 s17, v1
	s_cbranch_scc1 .LBB0_542
	s_ashr_i32 s0, s33, 31
	s_lshr_b32 s1, s0, 29
	s_add_i32 s1, s33, s1
	s_and_b32 s6, s1, -8
	s_sub_i32 s9, s33, s6
	s_cmp_gt_i32 s9, -1
	s_cbranch_scc0 .LBB0_521
	s_lshl_b32 s8, s9, 6
	s_cbranch_execz .LBB0_522
	s_branch .LBB0_523

; #define PG8_STAGE(bufoff, gbase, voff) do { _Pragma("unroll") for (int _i = 0; _i < 2; ++_i) \
;         __builtin_amdgcn_global_load_lds((const unsigned*)((const char*)(gbase) + (voff)[_i]), (PG8_LAS unsigned*)(lds + (bufoff) + ldsw + _i * 8192), 16, 0, 0); } while (0)
; #define PG8_LDA(dst, b, h) do { _Pragma("unroll") for (int m = 0; m < 4; ++m) _Pragma("unroll") for (int k = 0; k < 2; ++k) dst[m][k] = *(const PG8_LAS bf16x8*)(lds + PG8_SA(b, h) + aoff + m * 2048 + k * 1024); } while (0)
; #define PG8_LDB(dst, b, h) do { _Pragma("unroll") for (int n = 0; n < 2; ++n) _Pragma("unroll") for (int k = 0; k < 2; ++k) dst[n][k] = *(const PG8_LAS bf16x8*)(lds + PG8_SB(b, h) + boff + n * 2048 + k * 1024); } while (0)
; #define PG8_MMA(ai, bj, At, Bt) do { __builtin_amdgcn_s_setprio(1); _Pragma("unroll") for (int m = 0; m < 4; ++m) _Pragma("unroll") for (int n = 0; n < 2; ++n) _Pragma("unroll") for (int k = 0; k < 2; ++k) \
;         acc[ai][bj][m][n] = __builtin_amdgcn_mfma_f32_16x16x32_bf16(Bt[n][k], At[m][k], acc[ai][bj][m][n], 0, 0, 0); __builtin_amdgcn_s_setprio(0); } while (0)
; #define PG8_WAIT_V(n) asm volatile("s_waitcnt vmcnt(" #n ")" ::: "memory")
; template <class Epi, class Sched, bool ALIGN_EPI = false>
; __device__ __forceinline__ void gemm_phase(PG8_LAS unsigned char* lds, const Gemm g, const Sched& S, const Epi& E) {
;     ...
;             PG8_LDB(B0, 0, 0); PG8_LDB(B1, 0, 1); PG8_SCHED; PG8_LDA(At, 0, 0); PG8_STAGE(PG8_SA(1, 1), a1 + hstepA, voffA);
;             PG8_WAIT_V(8); PG8_WAIT_L(0); PG8_BAR; PG8_MMA(0, 0, At, B0); PG8_MMA(0, 1, At, B1); PG8_BAR; PG8_SCHED;
;             PG8_LDA(At, 0, 1); PG8_STAGE(PG8_SB(0, 0), b2, voffB); PG8_STAGE(PG8_SB(0, 1), b2 + hstepB, voffB); PG8_STAGE(PG8_SA(0, 0), a2, voffA);
;             PG8_WAIT_V(8); PG8_WAIT_L(0); PG8_BAR; PG8_MMA(1, 0, At, B0); PG8_MMA(1, 1, At, B1); PG8_BAR; PG8_SCHED;
;             PG8_LDB(B0, 1, 0); PG8_LDB(B1, 1, 1); PG8_SCHED; PG8_LDA(At, 1, 0); PG8_STAGE(PG8_SA(0, 1), a2 + hstepA, voffA);
;             PG8_WAIT_V(8); PG8_WAIT_L(0); PG8_BAR; PG8_MMA(0, 0, At, B0); PG8_MMA(0, 1, At, B1); PG8_BAR; PG8_SCHED;
;             PG8_LDA(At, 1, 1); PG8_STAGE(PG8_SB(1, 0), b3, voffB); PG8_STAGE(PG8_SB(1, 1), b3 + hstepB, voffB); PG8_STAGE(PG8_SA(1, 0), a3, voffA);
;             PG8_WAIT_V(8); PG8_WAIT_L(0); PG8_BAR; PG8_MMA(1, 0, At, B0); PG8_MMA(1, 1, At, B1); PG8_BAR; PG8_SCHED;
.LBB0_535:
	ds_read_b128 v[146:149], v152
	ds_read_b128 v[156:159], v152 offset:1024
	ds_read_b128 v[160:163], v152 offset:2048
	ds_read_b128 v[164:167], v152 offset:3072
	ds_read_b128 v[168:171], v153
	ds_read_b128 v[172:175], v153 offset:1024
	ds_read_b128 v[176:179], v153 offset:2048
	ds_read_b128 v[180:183], v153 offset:3072
	s_add_u32 s38, s36, 0xfff80080
	s_addc_u32 s39, s37, -1
	s_cmp_eq_u32 s64, 28
	s_cselect_b32 s41, s27, s39
	s_cselect_b32 s40, s60, s38
	s_cselect_b32 s39, s25, s63
	s_cselect_b32 s38, s61, s62
	v_lshl_add_u64 v[150:151], s[36:37], 0, v[138:139]
	s_add_i32 m0, s35, 0xc000
	ds_read_b128 v[184:187], v154
	ds_read_b128 v[188:191], v154 offset:1024
	ds_read_b128 v[192:195], v154 offset:2048
	ds_read_b128 v[196:199], v154 offset:3072
	ds_read_b128 v[200:203], v154 offset:4096
	ds_read_b128 v[204:207], v154 offset:5120
	ds_read_b128 v[208:211], v154 offset:6144
	ds_read_b128 v[212:215], v154 offset:7168
	global_load_lds_dwordx4 v[150:151], off
	v_lshl_add_u64 v[150:151], s[36:37], 0, v[140:141]
	s_add_i32 m0, s35, 0xe000
	s_nop 0
	global_load_lds_dwordx4 v[150:151], off
	s_waitcnt vmcnt(8)
	s_waitcnt lgkmcnt(0)
	s_barrier
	s_waitcnt lgkmcnt(0)
	v_mfma_f32_16x16x32_bf16 v[126:129], v[146:149], v[184:187], v[126:129]
	v_mfma_f32_16x16x32_bf16 v[122:125], v[160:163], v[184:187], v[122:125]
	v_mfma_f32_16x16x32_bf16 v[110:113], v[146:149], v[192:195], v[110:113]
	v_mfma_f32_16x16x32_bf16 v[106:109], v[160:163], v[192:195], v[106:109]
	v_mfma_f32_16x16x32_bf16 v[94:97], v[146:149], v[200:203], v[94:97]
	v_mfma_f32_16x16x32_bf16 v[90:93], v[160:163], v[200:203], v[90:93]
	v_mfma_f32_16x16x32_bf16 v[78:81], v[146:149], v[208:211], v[78:81]
	v_mfma_f32_16x16x32_bf16 v[74:77], v[160:163], v[208:211], v[74:77]
	v_mfma_f32_16x16x32_bf16 v[126:129], v[156:159], v[188:191], v[126:129]
	v_mfma_f32_16x16x32_bf16 v[122:125], v[164:167], v[188:191], v[122:125]
	v_mfma_f32_16x16x32_bf16 v[110:113], v[156:159], v[196:199], v[110:113]
	v_mfma_f32_16x16x32_bf16 v[106:109], v[164:167], v[196:199], v[106:109]
	v_mfma_f32_16x16x32_bf16 v[94:97], v[156:159], v[204:207], v[94:97]
	v_mfma_f32_16x16x32_bf16 v[90:93], v[164:167], v[204:207], v[90:93]
	v_mfma_f32_16x16x32_bf16 v[78:81], v[156:159], v[212:215], v[78:81]
	v_mfma_f32_16x16x32_bf16 v[74:77], v[164:167], v[212:215], v[74:77]
	v_mfma_f32_16x16x32_bf16 v[118:121], v[168:171], v[184:187], v[118:121]
	v_mfma_f32_16x16x32_bf16 v[114:117], v[176:179], v[184:187], v[114:117]
	v_mfma_f32_16x16x32_bf16 v[102:105], v[168:171], v[192:195], v[102:105]
	v_mfma_f32_16x16x32_bf16 v[98:101], v[176:179], v[192:195], v[98:101]
	v_mfma_f32_16x16x32_bf16 v[86:89], v[168:171], v[200:203], v[86:89]
	v_mfma_f32_16x16x32_bf16 v[82:85], v[176:179], v[200:203], v[82:85]
	v_mfma_f32_16x16x32_bf16 v[70:73], v[168:171], v[208:211], v[70:73]
	v_mfma_f32_16x16x32_bf16 v[66:69], v[176:179], v[208:211], v[66:69]
	v_mfma_f32_16x16x32_bf16 v[118:121], v[172:175], v[188:191], v[118:121]
	v_mfma_f32_16x16x32_bf16 v[114:117], v[180:183], v[188:191], v[114:117]
	v_mfma_f32_16x16x32_bf16 v[102:105], v[172:175], v[196:199], v[102:105]
	v_mfma_f32_16x16x32_bf16 v[98:101], v[180:183], v[196:199], v[98:101]
	v_mfma_f32_16x16x32_bf16 v[86:89], v[172:175], v[204:207], v[86:89]
	v_mfma_f32_16x16x32_bf16 v[82:85], v[180:183], v[204:207], v[82:85]
	v_mfma_f32_16x16x32_bf16 v[70:73], v[172:175], v[212:215], v[70:73]
	v_mfma_f32_16x16x32_bf16 v[66:69], v[180:183], v[212:215], v[66:69]
	s_barrier
	s_add_i32 s65, s53, s45
	v_lshl_add_u64 v[150:151], s[38:39], 0, v[132:133]
	s_mov_b32 m0, s65
	ds_read_b128 v[184:187], v154 offset:16384
	ds_read_b128 v[188:191], v154 offset:17408
	ds_read_b128 v[192:195], v154 offset:18432
	ds_read_b128 v[196:199], v154 offset:19456
	ds_read_b128 v[200:203], v154 offset:20480
	ds_read_b128 v[204:207], v154 offset:21504
	ds_read_b128 v[208:211], v154 offset:22528
	ds_read_b128 v[212:215], v154 offset:23552
	global_load_lds_dwordx4 v[150:151], off
	s_add_i32 m0, s65, 0x2000
	s_add_u32 s66, s38, 0x80000
	v_lshl_add_u64 v[216:217], s[38:39], 0, v[136:137]
	s_addc_u32 s67, s39, 0
	s_add_i32 s65, s54, s45
	global_load_lds_dwordx4 v[216:217], off
	v_lshl_add_u64 v[218:219], s[66:67], 0, v[132:133]
	s_mov_b32 m0, s65
	v_lshl_add_u64 v[220:221], s[40:41], 0, v[134:135]
	global_load_lds_dwordx4 v[218:219], off
	v_lshl_add_u64 v[218:219], s[66:67], 0, v[136:137]
	s_add_i32 m0, s65, 0x2000
	s_nop 0
	global_load_lds_dwordx4 v[218:219], off
	v_lshl_add_u64 v[218:219], s[40:41], 0, v[130:131]
	s_mov_b32 m0, s35
	s_nop 0
	global_load_lds_dwordx4 v[218:219], off
	s_mov_b32 m0, s46
	s_nop 0
	global_load_lds_dwordx4 v[220:221], off
	s_waitcnt vmcnt(8)
	s_waitcnt lgkmcnt(0)
	s_barrier
; #define PG8_STAGE(bufoff, gbase, voff) do { _Pragma("unroll") for (int _i = 0; _i < 2; ++_i) \
;         __builtin_amdgcn_global_load_lds((const unsigned*)((const char*)(gbase) + (voff)[_i]), (PG8_LAS unsigned*)(lds + (bufoff) + ldsw + _i * 8192), 16, 0, 0); } while (0)
; #define PG8_LDA(dst, b, h) do { _Pragma("unroll") for (int m = 0; m < 4; ++m) _Pragma("unroll") for (int k = 0; k < 2; ++k) dst[m][k] = *(const PG8_LAS bf16x8*)(lds + PG8_SA(b, h) + aoff + m * 2048 + k * 1024); } while (0)
; #define PG8_LDB(dst, b, h) do { _Pragma("unroll") for (int n = 0; n < 2; ++n) _Pragma("unroll") for (int k = 0; k < 2; ++k) dst[n][k] = *(const PG8_LAS bf16x8*)(lds + PG8_SB(b, h) + boff + n * 2048 + k * 1024); } while (0)
; #define PG8_MMA(ai, bj, At, Bt) do { __builtin_amdgcn_s_setprio(1); _Pragma("unroll") for (int m = 0; m < 4; ++m) _Pragma("unroll") for (int n = 0; n < 2; ++n) _Pragma("unroll") for (int k = 0; k < 2; ++k) \
;         acc[ai][bj][m][n] = __builtin_amdgcn_mfma_f32_16x16x32_bf16(Bt[n][k], At[m][k], acc[ai][bj][m][n], 0, 0, 0); __builtin_amdgcn_s_setprio(0); } while (0)
; #define PG8_WAIT_V(n) asm volatile("s_waitcnt vmcnt(" #n ")" ::: "memory")
; template <class Epi, class Sched, bool ALIGN_EPI = false>
; __device__ __forceinline__ void gemm_phase(PG8_LAS unsigned char* lds, const Gemm g, const Sched& S, const Epi& E) {
;     ...
;             PG8_LDB(B0, 0, 0); PG8_LDB(B1, 0, 1); PG8_SCHED; PG8_LDA(At, 0, 0); PG8_STAGE(PG8_SA(1, 1), a1 + hstepA, voffA);
;             PG8_WAIT_V(8); PG8_WAIT_L(0); PG8_BAR; PG8_MMA(0, 0, At, B0); PG8_MMA(0, 1, At, B1); PG8_BAR; PG8_SCHED;
;             PG8_LDA(At, 0, 1); PG8_STAGE(PG8_SB(0, 0), b2, voffB); PG8_STAGE(PG8_SB(0, 1), b2 + hstepB, voffB); PG8_STAGE(PG8_SA(0, 0), a2, voffA);
;             PG8_WAIT_V(8); PG8_WAIT_L(0); PG8_BAR; PG8_MMA(1, 0, At, B0); PG8_MMA(1, 1, At, B1); PG8_BAR; PG8_SCHED;
;             PG8_LDB(B0, 1, 0); PG8_LDB(B1, 1, 1); PG8_SCHED; PG8_LDA(At, 1, 0); PG8_STAGE(PG8_SA(0, 1), a2 + hstepA, voffA);
;             PG8_WAIT_V(8); PG8_WAIT_L(0); PG8_BAR; PG8_MMA(0, 0, At, B0); PG8_MMA(0, 1, At, B1); PG8_BAR; PG8_SCHED;
;             PG8_LDA(At, 1, 1); PG8_STAGE(PG8_SB(1, 0), b3, voffB); PG8_STAGE(PG8_SB(1, 1), b3 + hstepB, voffB); PG8_STAGE(PG8_SA(1, 0), a3, voffA);
;             PG8_WAIT_V(8); PG8_WAIT_L(0); PG8_BAR; PG8_MMA(1, 0, At, B0); PG8_MMA(1, 1, At, B1); PG8_BAR; PG8_SCHED;
	s_waitcnt lgkmcnt(0)
	v_mfma_f32_16x16x32_bf16 v[62:65], v[146:149], v[184:187], v[62:65]
	v_mfma_f32_16x16x32_bf16 v[58:61], v[160:163], v[184:187], v[58:61]
	v_mfma_f32_16x16x32_bf16 v[46:49], v[146:149], v[192:195], v[46:49]
	v_mfma_f32_16x16x32_bf16 v[42:45], v[160:163], v[192:195], v[42:45]
	v_mfma_f32_16x16x32_bf16 v[30:33], v[146:149], v[200:203], v[30:33]
	v_mfma_f32_16x16x32_bf16 v[26:29], v[160:163], v[200:203], v[26:29]
	v_mfma_f32_16x16x32_bf16 v[14:17], v[146:149], v[208:211], v[14:17]
	v_mfma_f32_16x16x32_bf16 v[10:13], v[160:163], v[208:211], v[10:13]
	v_mfma_f32_16x16x32_bf16 v[62:65], v[156:159], v[188:191], v[62:65]
	v_mfma_f32_16x16x32_bf16 v[58:61], v[164:167], v[188:191], v[58:61]
	v_mfma_f32_16x16x32_bf16 v[46:49], v[156:159], v[196:199], v[46:49]
	v_mfma_f32_16x16x32_bf16 v[42:45], v[164:167], v[196:199], v[42:45]
	v_mfma_f32_16x16x32_bf16 v[30:33], v[156:159], v[204:207], v[30:33]
	v_mfma_f32_16x16x32_bf16 v[26:29], v[164:167], v[204:207], v[26:29]
	v_mfma_f32_16x16x32_bf16 v[14:17], v[156:159], v[212:215], v[14:17]
	v_mfma_f32_16x16x32_bf16 v[10:13], v[164:167], v[212:215], v[10:13]
	v_mfma_f32_16x16x32_bf16 v[54:57], v[168:171], v[184:187], v[54:57]
	v_mfma_f32_16x16x32_bf16 v[50:53], v[176:179], v[184:187], v[50:53]
	v_mfma_f32_16x16x32_bf16 v[38:41], v[168:171], v[192:195], v[38:41]
	v_mfma_f32_16x16x32_bf16 v[34:37], v[176:179], v[192:195], v[34:37]
	v_mfma_f32_16x16x32_bf16 v[22:25], v[168:171], v[200:203], v[22:25]
	v_mfma_f32_16x16x32_bf16 v[18:21], v[176:179], v[200:203], v[18:21]
	v_mfma_f32_16x16x32_bf16 v[6:9], v[168:171], v[208:211], v[6:9]
	v_mfma_f32_16x16x32_bf16 v[2:5], v[176:179], v[208:211], v[2:5]
	v_mfma_f32_16x16x32_bf16 v[54:57], v[172:175], v[188:191], v[54:57]
	v_mfma_f32_16x16x32_bf16 v[50:53], v[180:183], v[188:191], v[50:53]
	v_mfma_f32_16x16x32_bf16 v[38:41], v[172:175], v[196:199], v[38:41]
	v_mfma_f32_16x16x32_bf16 v[34:37], v[180:183], v[196:199], v[34:37]
	v_mfma_f32_16x16x32_bf16 v[22:25], v[172:175], v[204:207], v[22:25]
	v_mfma_f32_16x16x32_bf16 v[18:21], v[180:183], v[204:207], v[18:21]
	v_mfma_f32_16x16x32_bf16 v[6:9], v[172:175], v[212:215], v[6:9]
	v_mfma_f32_16x16x32_bf16 v[2:5], v[180:183], v[212:215], v[2:5]
	s_barrier
	s_add_i32 s65, 0, 0x18000
	v_add_u32_e32 v155, s65, v1
	s_add_i32 s66, 0, 0x1c000
	ds_read_b128 v[146:149], v155
	ds_read_b128 v[156:159], v155 offset:1024
	ds_read_b128 v[160:163], v155 offset:2048
	ds_read_b128 v[164:167], v155 offset:3072
	v_add_u32_e32 v155, s66, v1
	ds_read_b128 v[168:171], v155
	ds_read_b128 v[172:175], v155 offset:1024
	ds_read_b128 v[176:179], v155 offset:2048
	ds_read_b128 v[180:183], v155 offset:3072
	s_add_u32 s40, s40, 0x80000
	s_addc_u32 s41, s41, 0
	s_mov_b32 m0, s47
	v_lshl_add_u64 v[222:223], s[40:41], 0, v[130:131]
	ds_read_b128 v[184:187], v154 offset:32768
	ds_read_b128 v[188:191], v154 offset:33792
	ds_read_b128 v[192:195], v154 offset:34816
	ds_read_b128 v[196:199], v154 offset:35840
	ds_read_b128 v[200:203], v154 offset:36864
	ds_read_b128 v[204:207], v154 offset:37888
	ds_read_b128 v[208:211], v154 offset:38912
	ds_read_b128 v[212:215], v154 offset:39936
	global_load_lds_dwordx4 v[222:223], off
	v_lshl_add_u64 v[222:223], s[40:41], 0, v[134:135]
	s_mov_b32 m0, s48
	s_nop 0
	global_load_lds_dwordx4 v[222:223], off
	s_waitcnt vmcnt(8)
	s_waitcnt lgkmcnt(0)
	s_barrier
	s_waitcnt lgkmcnt(0)
	v_mfma_f32_16x16x32_bf16 v[126:129], v[146:149], v[184:187], v[126:129]
	v_mfma_f32_16x16x32_bf16 v[122:125], v[160:163], v[184:187], v[122:125]
	v_mfma_f32_16x16x32_bf16 v[110:113], v[146:149], v[192:195], v[110:113]
	v_mfma_f32_16x16x32_bf16 v[106:109], v[160:163], v[192:195], v[106:109]
	v_mfma_f32_16x16x32_bf16 v[94:97], v[146:149], v[200:203], v[94:97]
	v_mfma_f32_16x16x32_bf16 v[90:93], v[160:163], v[200:203], v[90:93]
	v_mfma_f32_16x16x32_bf16 v[78:81], v[146:149], v[208:211], v[78:81]
	v_mfma_f32_16x16x32_bf16 v[74:77], v[160:163], v[208:211], v[74:77]
	v_mfma_f32_16x16x32_bf16 v[126:129], v[156:159], v[188:191], v[126:129]
	v_mfma_f32_16x16x32_bf16 v[122:125], v[164:167], v[188:191], v[122:125]
	v_mfma_f32_16x16x32_bf16 v[110:113], v[156:159], v[196:199], v[110:113]
	v_mfma_f32_16x16x32_bf16 v[106:109], v[164:167], v[196:199], v[106:109]
	v_mfma_f32_16x16x32_bf16 v[94:97], v[156:159], v[204:207], v[94:97]
	v_mfma_f32_16x16x32_bf16 v[90:93], v[164:167], v[204:207], v[90:93]
	v_mfma_f32_16x16x32_bf16 v[78:81], v[156:159], v[212:215], v[78:81]
	v_mfma_f32_16x16x32_bf16 v[74:77], v[164:167], v[212:215], v[74:77]
	v_mfma_f32_16x16x32_bf16 v[118:121], v[168:171], v[184:187], v[118:121]
	v_mfma_f32_16x16x32_bf16 v[114:117], v[176:179], v[184:187], v[114:117]
	v_mfma_f32_16x16x32_bf16 v[102:105], v[168:171], v[192:195], v[102:105]
	v_mfma_f32_16x16x32_bf16 v[98:101], v[176:179], v[192:195], v[98:101]
	v_mfma_f32_16x16x32_bf16 v[86:89], v[168:171], v[200:203], v[86:89]
	v_mfma_f32_16x16x32_bf16 v[82:85], v[176:179], v[200:203], v[82:85]
	v_mfma_f32_16x16x32_bf16 v[70:73], v[168:171], v[208:211], v[70:73]
	v_mfma_f32_16x16x32_bf16 v[66:69], v[176:179], v[208:211], v[66:69]
	v_mfma_f32_16x16x32_bf16 v[118:121], v[172:175], v[188:191], v[118:121]
	v_mfma_f32_16x16x32_bf16 v[114:117], v[180:183], v[188:191], v[114:117]
	v_mfma_f32_16x16x32_bf16 v[102:105], v[172:175], v[196:199], v[102:105]
	v_mfma_f32_16x16x32_bf16 v[98:101], v[180:183], v[196:199], v[98:101]
	v_mfma_f32_16x16x32_bf16 v[86:89], v[172:175], v[204:207], v[86:89]
	v_mfma_f32_16x16x32_bf16 v[82:85], v[180:183], v[204:207], v[82:85]
	v_mfma_f32_16x16x32_bf16 v[70:73], v[172:175], v[212:215], v[70:73]
	v_mfma_f32_16x16x32_bf16 v[66:69], v[180:183], v[212:215], v[66:69]
	s_barrier
; #define PG8_STAGE(bufoff, gbase, voff) do { _Pragma("unroll") for (int _i = 0; _i < 2; ++_i) \
;         __builtin_amdgcn_global_load_lds((const unsigned*)((const char*)(gbase) + (voff)[_i]), (PG8_LAS unsigned*)(lds + (bufoff) + ldsw + _i * 8192), 16, 0, 0); } while (0)
; #define PG8_LDA(dst, b, h) do { _Pragma("unroll") for (int m = 0; m < 4; ++m) _Pragma("unroll") for (int k = 0; k < 2; ++k) dst[m][k] = *(const PG8_LAS bf16x8*)(lds + PG8_SA(b, h) + aoff + m * 2048 + k * 1024); } while (0)
; #define PG8_MMA(ai, bj, At, Bt) do { __builtin_amdgcn_s_setprio(1); _Pragma("unroll") for (int m = 0; m < 4; ++m) _Pragma("unroll") for (int n = 0; n < 2; ++n) _Pragma("unroll") for (int k = 0; k < 2; ++k) \
;         acc[ai][bj][m][n] = __builtin_amdgcn_mfma_f32_16x16x32_bf16(Bt[n][k], At[m][k], acc[ai][bj][m][n], 0, 0, 0); __builtin_amdgcn_s_setprio(0); } while (0)
; #define PG8_WAIT_V(n) asm volatile("s_waitcnt vmcnt(" #n ")" ::: "memory")
; #define PG8_WAIT_L(n) asm volatile("s_waitcnt lgkmcnt(" #n ")" ::: "memory")
; #define PG8_BAR __builtin_amdgcn_s_barrier()
; #define PG8_SCHED __builtin_amdgcn_sched_barrier(0)
; template <class Epi, class Sched, bool ALIGN_EPI = false>
; __device__ __forceinline__ void gemm_phase(PG8_LAS unsigned char* lds, const Gemm g, const Sched& S, const Epi& E) {
;     ...
;             PG8_LDA(At, 1, 1); PG8_STAGE(PG8_SB(1, 0), b3, voffB); PG8_STAGE(PG8_SB(1, 1), b3 + hstepB, voffB); PG8_STAGE(PG8_SA(1, 0), a3, voffA);
;             PG8_WAIT_V(8); PG8_WAIT_L(0); PG8_BAR; PG8_MMA(1, 0, At, B0); PG8_MMA(1, 1, At, B1); PG8_BAR; PG8_SCHED;
;         }
;         if constexpr (ALIGN_EPI) { if (wr == 0) PG8_BAR; }
	s_add_i32 s40, s65, s45
	v_lshl_add_u64 v[150:151], v[150:151], 0, s[14:15]
	s_mov_b32 m0, s40
	ds_read_b128 v[184:187], v154 offset:49152
	ds_read_b128 v[188:191], v154 offset:50176
	ds_read_b128 v[192:195], v154 offset:51200
	ds_read_b128 v[196:199], v154 offset:52224
	ds_read_b128 v[200:203], v154 offset:53248
	ds_read_b128 v[204:207], v154 offset:54272
	ds_read_b128 v[208:211], v154 offset:55296
	ds_read_b128 v[212:215], v154 offset:56320
	global_load_lds_dwordx4 v[150:151], off
	s_add_i32 m0, s40, 0x2000
	s_add_u32 s38, s38, 0x80080
	v_lshl_add_u64 v[150:151], v[216:217], 0, s[14:15]
	s_addc_u32 s39, s39, 0
	s_add_i32 s40, s66, s45
	global_load_lds_dwordx4 v[150:151], off
	v_lshl_add_u64 v[150:151], s[38:39], 0, v[132:133]
	s_mov_b32 m0, s40
	s_nop 0
	global_load_lds_dwordx4 v[150:151], off
	v_lshl_add_u64 v[150:151], s[38:39], 0, v[136:137]
	s_add_i32 m0, s40, 0x2000
	s_nop 0
	global_load_lds_dwordx4 v[150:151], off
	v_lshl_add_u64 v[150:151], v[218:219], 0, s[14:15]
	s_mov_b32 m0, s50
	s_nop 0
	global_load_lds_dwordx4 v[150:151], off
	v_lshl_add_u64 v[150:151], v[220:221], 0, s[14:15]
	s_mov_b32 m0, s51
	s_nop 0
	global_load_lds_dwordx4 v[150:151], off
	s_waitcnt vmcnt(8)
	s_waitcnt lgkmcnt(0)
	s_barrier
	s_waitcnt lgkmcnt(0)
	v_mfma_f32_16x16x32_bf16 v[62:65], v[146:149], v[184:187], v[62:65]
	v_mfma_f32_16x16x32_bf16 v[58:61], v[160:163], v[184:187], v[58:61]
	v_mfma_f32_16x16x32_bf16 v[46:49], v[146:149], v[192:195], v[46:49]
	v_mfma_f32_16x16x32_bf16 v[42:45], v[160:163], v[192:195], v[42:45]
	v_mfma_f32_16x16x32_bf16 v[30:33], v[146:149], v[200:203], v[30:33]
	v_mfma_f32_16x16x32_bf16 v[26:29], v[160:163], v[200:203], v[26:29]
	v_mfma_f32_16x16x32_bf16 v[14:17], v[146:149], v[208:211], v[14:17]
	v_mfma_f32_16x16x32_bf16 v[10:13], v[160:163], v[208:211], v[10:13]
	v_mfma_f32_16x16x32_bf16 v[62:65], v[156:159], v[188:191], v[62:65]
	v_mfma_f32_16x16x32_bf16 v[58:61], v[164:167], v[188:191], v[58:61]
	v_mfma_f32_16x16x32_bf16 v[46:49], v[156:159], v[196:199], v[46:49]
	v_mfma_f32_16x16x32_bf16 v[42:45], v[164:167], v[196:199], v[42:45]
	v_mfma_f32_16x16x32_bf16 v[30:33], v[156:159], v[204:207], v[30:33]
	v_mfma_f32_16x16x32_bf16 v[26:29], v[164:167], v[204:207], v[26:29]
	v_mfma_f32_16x16x32_bf16 v[14:17], v[156:159], v[212:215], v[14:17]
	v_mfma_f32_16x16x32_bf16 v[10:13], v[164:167], v[212:215], v[10:13]
	v_mfma_f32_16x16x32_bf16 v[54:57], v[168:171], v[184:187], v[54:57]
	v_mfma_f32_16x16x32_bf16 v[50:53], v[176:179], v[184:187], v[50:53]
	v_mfma_f32_16x16x32_bf16 v[38:41], v[168:171], v[192:195], v[38:41]
	v_mfma_f32_16x16x32_bf16 v[34:37], v[176:179], v[192:195], v[34:37]
	v_mfma_f32_16x16x32_bf16 v[22:25], v[168:171], v[200:203], v[22:25]
	v_mfma_f32_16x16x32_bf16 v[18:21], v[176:179], v[200:203], v[18:21]
	v_mfma_f32_16x16x32_bf16 v[6:9], v[168:171], v[208:211], v[6:9]
	v_mfma_f32_16x16x32_bf16 v[2:5], v[176:179], v[208:211], v[2:5]
	v_mfma_f32_16x16x32_bf16 v[54:57], v[172:175], v[188:191], v[54:57]
	v_mfma_f32_16x16x32_bf16 v[50:53], v[180:183], v[188:191], v[50:53]
	v_mfma_f32_16x16x32_bf16 v[38:41], v[172:175], v[196:199], v[38:41]
	v_mfma_f32_16x16x32_bf16 v[34:37], v[180:183], v[196:199], v[34:37]
	v_mfma_f32_16x16x32_bf16 v[22:25], v[172:175], v[204:207], v[22:25]
	v_mfma_f32_16x16x32_bf16 v[18:21], v[180:183], v[204:207], v[18:21]
	v_mfma_f32_16x16x32_bf16 v[6:9], v[172:175], v[212:215], v[6:9]
	v_mfma_f32_16x16x32_bf16 v[2:5], v[180:183], v[212:215], v[2:5]
	s_barrier
	s_add_i32 s64, s64, 2
	s_add_u32 s36, s36, 0x100
	s_addc_u32 s37, s37, 0
	s_add_u32 s62, s62, 0x100
	s_addc_u32 s63, s63, 0
	s_cmp_gt_u32 s64, 29
	s_cbranch_scc0 .LBB0_535
	s_and_b64 vcc, exec, s[16:17]
	s_cbranch_vccz .LBB0_538
	s_barrier

; __device__ __forceinline__ unsigned xb_ld(unsigned* p)              { return __hip_atomic_load(p, __ATOMIC_RELAXED, __HIP_MEMORY_SCOPE_AGENT); }
; __device__ __forceinline__ void xcd_barrier_complete(unsigned* bar, unsigned x, unsigned& nloc, unsigned& nx) {
;     const unsigned G = gridDim.x * gridDim.y * gridDim.z;
;     unsigned sum, cnt, mine, sp = 0u;
;     for (;;) {
;         sum = 0u; cnt = 0u; mine = 0u;
; #pragma unroll
;         for (unsigned j = 0; j < 16; ++j) { const unsigned c = xb_ld(&bar[XB_XCNT(j)]); sum += c; cnt += (c > 0u) ? 1u : 0u; mine = (j == x) ? c : mine; }
;         if (sum == G) break;
; __device__ __forceinline__ void xcd_barrier(const XcdBarrier& b) {
;     asm volatile("s_waitcnt vmcnt(0)" ::: "memory");
;     __syncthreads();
;     if (threadIdx.x == 0) {
;         unsigned* bar = b.bar;
;         __builtin_amdgcn_s_waitcnt(0);
;         unsigned nloc = b.st[0], nx = b.st[1];
;         if (nloc == 0u) { xcd_barrier_complete(bar, b.x, nloc, nx); b.st[0] = nloc; b.st[1] = nx; }
.LBB0_542:
	s_setprio 0
	s_cmp_gt_i32 s59, 7
	s_cselect_b64 s[2:3], -1, 0
	s_and_b64 s[0:1], s[4:5], s[2:3]
	s_andn2_b64 vcc, exec, s[0:1]
	s_cbranch_vccnz .LBB0_592
	s_waitcnt vmcnt(0)
	v_cmp_eq_u32_e32 vcc, 0, v0
	s_waitcnt vmcnt(0)
	s_barrier
	s_and_saveexec_b64 s[4:5], vcc
	s_cbranch_execz .LBB0_591
	v_readlane_b32 s0, v228, 5
	s_waitcnt vmcnt(0) expcnt(0) lgkmcnt(0)
	s_nop 0
	v_mov_b32_e32 v1, s0
	ds_read_b32 v3, v1
	ds_read_b32 v1, v1 offset:4
	s_waitcnt lgkmcnt(1)
	v_cmp_ne_u32_e32 vcc, 0, v3
	s_cbranch_vccnz .LBB0_559
	v_readlane_b32 s6, v228, 0
	v_readlane_b32 s7, v228, 1
	s_load_dwordx2 s[0:1], s[6:7], 0x4
	s_add_u32 s6, s56, 0x4200
	s_addc_u32 s7, s57, 0
	s_add_u32 s8, s56, 0x4400
	s_addc_u32 s9, s57, 0
	s_add_u32 s10, s56, 0x4500
	s_addc_u32 s11, s57, 0
	s_add_u32 s12, s56, 0x4600
	s_addc_u32 s13, s57, 0
	s_add_u32 s14, s56, 0x4700
	s_addc_u32 s15, s57, 0
	s_add_u32 s16, s56, 0x4800
	s_addc_u32 s17, s57, 0
	s_add_u32 s18, s56, 0x4900
	s_addc_u32 s19, s57, 0
	s_add_u32 s20, s56, 0x4a00
	s_addc_u32 s21, s57, 0
	s_add_u32 s22, s56, 0x4b00
	s_addc_u32 s23, s57, 0
	s_add_u32 s24, s56, 0x4c00
	s_addc_u32 s25, s57, 0
	s_add_u32 s26, s56, 0x4d00
	s_addc_u32 s27, s57, 0
	s_add_u32 s28, s56, 0x4e00
	s_addc_u32 s29, s57, 0
	s_add_u32 s30, s56, 0x4f00
	s_addc_u32 s31, s57, 0
	s_add_u32 s34, s56, 0x5000
	s_addc_u32 s35, s57, 0
	s_add_u32 s36, s56, 0x5100
	s_addc_u32 s37, s57, 0
	s_add_u32 s38, s56, 0x5200
	s_addc_u32 s39, s57, 0
	s_waitcnt lgkmcnt(0)
	s_mul_i32 s0, s0, s86
	s_add_u32 s40, s56, 0x5300
	s_mul_i32 s0, s0, s1
	s_addc_u32 s41, s57, 0
	s_mov_b32 s1, 1
	v_mov_b32_e32 v17, 0
	s_branch .LBB0_547

; #define PG8_STAGE(bufoff, gbase, voff) do { _Pragma("unroll") for (int _i = 0; _i < 2; ++_i) \
;         __builtin_amdgcn_global_load_lds((const unsigned*)((const char*)(gbase) + (voff)[_i]), (PG8_LAS unsigned*)(lds + (bufoff) + ldsw + _i * 8192), 16, 0, 0); } while (0)
; #define PG8_BAR __builtin_amdgcn_s_barrier()
; template <class Epi, class Sched, bool ALIGN_EPI = false>
; __device__ __forceinline__ void gemm_phase(PG8_LAS unsigned char* lds, const Gemm g, const Sched& S, const Epi& E) {
;     int tid_ = threadIdx.x; asm volatile("" : "+v"(tid_));
;     const int tid = tid_, wid = __builtin_amdgcn_readfirstlane(tid >> 6), lane = tid & 63, wr = wid >> 2, wc = wid & 3, fr = lane & 15, fq = lane >> 4;
;     const int K = g.K, nt = K / BK;
;     unsigned voffA[2], voffB[2];
; #pragma unroll
;     for (int i = 0; i < 2; ++i) { int R, C; stage_rc(tid * 16 + i * 8192, R, C); const int Rb = Epi::PERM ? ((R & ~31) + perm32(R & 31)) : R;
;         voffA[i] = (unsigned)(R * g.lda + C) * 2u; voffB[i] = (unsigned)(Rb * g.ldb + C) * 2u; }
;     const size_t kstep = (size_t)(BK * 2);
;     const size_t hstepA = (size_t)HALF * g.lda * 2, hstepB = (size_t)HALF * g.ldb * 2;
;     const size_t tstepA = 2 * hstepA, tstepB = 2 * hstepB;
;     const unsigned ldsw = (unsigned)wid * 1024u;
;     const int aoff = lds_byte(wr * 64 + fr, fq * 8), boff = lds_byte(wc * 32 + fr, fq * 8);
;     ...
;     Unit cur, nxt; int ui = 0;
;     if (!S.next(0, cur)) return;
;     f32x4 acc[2][2][4][2];
; #pragma unroll
;     for (int a = 0; a < 2; ++a)
; #pragma unroll
;         for (int b = 0; b < 2; ++b)
; #pragma unroll
;             for (int m = 0; m < 4; ++m)
; #pragma unroll
;                 for (int n = 0; n < 2; ++n) acc[a][b][m][n] = (f32x4){0.f, 0.f, 0.f, 0.f};
;     bf16x8 At[4][2], B0[2][2], B1[2][2];
;     const char* cA = (const char*)g.A + (size_t)cur.pm * tstepA; const char* cB = (const char*)g.Bt + (size_t)cur.pn * tstepB;
;     S.a_ready(cur);
;     PG8_STAGE(PG8_SB(0, 0), cB, voffB); PG8_STAGE(PG8_SB(0, 1), cB + hstepB, voffB); PG8_STAGE(PG8_SA(0, 0), cA, voffA); PG8_STAGE(PG8_SA(0, 1), cA + hstepA, voffA);
;     if (wr == 1) PG8_BAR;
.LBB0_646:
	s_cmp_lt_i32 s58, 9
	s_cselect_b64 s[0:1], -1, 0
	s_and_b64 s[10:11], s[0:1], s[2:3]
	s_andn2_b64 vcc, exec, s[10:11]
	s_cbranch_vccnz .LBB0_675
	v_readfirstlane_b32 s98, v0
	s_nop 3
	s_lshr_b32 s98, s98, 8
	s_cmp_eq_u32 s98, 0
	s_cbranch_scc0 .Lmy_prio2
	s_setprio 1
.Lmy_prio2:
	s_mov_b64 s[2:3], s[82:83]
	v_mov_b32_e32 v1, v0
	s_cmpk_gt_i32 s33, 0xdff
	s_nop 0
	v_readfirstlane_b32 s35, v1
	s_cbranch_scc1 .LBB0_675
	v_lshlrev_b32_e32 v2, 4, v1
	v_add_u32_e32 v3, 0x2000, v2
	v_ashrrev_i32_e32 v4, 31, v3
	v_lshrrev_b32_e32 v4, 22, v4
	v_add_u32_e32 v4, v3, v4
	v_ashrrev_i32_e32 v10, 10, v4
	v_mul_i32_i24_e32 v4, 0x400, v10
	v_sub_u32_e32 v3, v3, v4
	v_lshrrev_b32_e32 v4, 4, v3
	v_bitop3_b32 v3, v4, v3, 32 bitop3:0x6c
	v_ashrrev_i32_e32 v4, 31, v3
	v_lshrrev_b32_e32 v4, 26, v4
	v_add_u32_e32 v4, v3, v4
	v_lshlrev_b32_e32 v5, 3, v10
	v_ashrrev_i32_e32 v11, 6, v4
	v_and_b32_e32 v5, -16, v5
	v_add_u32_e32 v5, v11, v5
	v_and_b32_e32 v6, 3, v11
	s_mov_b32 s4, 0x7ffe0
	v_lshrrev_b32_e32 v7, 2, v5
	v_lshlrev_b32_e32 v8, 1, v5
	v_and_b32_e32 v4, 0xc0, v4
	v_and_or_b32 v6, v5, s4, v6
	v_and_b32_e32 v7, 4, v7
	v_and_b32_e32 v8, 24, v8
	v_sub_u32_e32 v3, v3, v4
	v_mov_b32_e32 v4, 1
	v_or3_b32 v6, v6, v7, v8
	v_lshlrev_b32_e32 v7, 5, v10
	v_ashrrev_i16_sdwa v3, v4, sext(v3) dst_sel:DWORD dst_unused:UNUSED_PAD src0_sel:DWORD src1_sel:BYTE_0
	v_and_b32_e32 v7, 32, v7
	v_bfe_i32 v12, v3, 0, 16
	v_add_lshl_u32 v3, v7, v12, 1
	v_lshl_add_u32 v146, v6, 13, v3
	v_lshl_add_u32 v148, v5, 13, v3
	v_bfe_i32 v3, v1, 27, 1
	v_lshrrev_b32_e32 v3, 22, v3
	v_add_u32_e32 v3, v2, v3
	v_and_b32_e32 v3, 0xfffffc00, v3
	v_sub_u32_e32 v2, v2, v3
	v_lshrrev_b32_e32 v3, 4, v2
	v_ashrrev_i32_e32 v5, 31, v1
	v_bitop3_b32 v2, v3, v2, 32 bitop3:0x6c
	v_lshrrev_b32_e32 v5, 26, v5
	v_ashrrev_i32_e32 v3, 31, v2
	v_add_u32_e32 v5, v1, v5
	s_add_u32 s0, s56, 0x41200000
	v_lshrrev_b32_e32 v3, 26, v3
	v_ashrrev_i32_e32 v14, 6, v5
	s_addc_u32 s1, s57, 0
	v_add_u32_e32 v3, v2, v3
	v_lshlrev_b32_e32 v5, 3, v14
	s_add_u32 s52, s56, 0xf200000
	v_ashrrev_i32_e32 v13, 6, v3
	v_and_b32_e32 v5, -16, v5
	s_addc_u32 s53, s57, 0
	v_add_u32_e32 v5, v13, v5
	v_and_b32_e32 v6, 3, v13
	s_ashr_i32 s55, s33, 31
	v_and_or_b32 v6, v5, s4, v6
	s_lshr_b32 s4, s55, 29
	s_add_i32 s4, s33, s4
	s_ashr_i32 s30, s35, 6
	s_ashr_i32 s5, s4, 3
	s_and_b32 s4, s4, -8
	s_ashr_i32 s31, s35, 8
	s_lshl_b32 s54, s30, 10
	s_sub_i32 s4, s33, s4
	s_cmp_lt_i32 s4, 0
	s_movk_i32 s60, 0x1c1
	s_cselect_b32 s6, s60, 0x1c0
	s_mul_i32 s4, s4, s6
	s_add_i32 s4, s4, s5
	s_mul_hi_i32 s5, s4, 0x92492493
	s_add_i32 s5, s5, s4
	s_lshr_b32 s6, s5, 31
	s_ashr_i32 s5, s5, 9
	s_add_i32 s5, s5, s6
	s_lshl_b32 s6, s5, 3
	s_mulk_i32 s5, 0x380
	s_sub_i32 s4, s4, s5
	s_sext_i32_i16 s5, s4
	s_bfe_u32 s5, s5, 0x3001c
	s_add_i32 s5, s4, s5
	s_sext_i32_i16 s7, s5
	s_and_b32 s5, s5, 0xfff8
	s_sub_i32 s4, s4, s5
	s_sext_i32_i16 s4, s4
	v_lshrrev_b32_e32 v7, 2, v5
	v_lshlrev_b32_e32 v8, 1, v5
	v_and_b32_e32 v3, 0xc0, v3
	s_lshr_b32 s34, s7, 3
	s_add_i32 s8, s6, s4
	v_and_b32_e32 v7, 4, v7
	v_and_b32_e32 v8, 24, v8
	v_sub_u32_e32 v2, v2, v3
	s_ashr_i32 s9, s8, 31
	s_bfe_i64 s[6:7], s[34:35], 0x100000
	v_or3_b32 v6, v6, v7, v8
	v_lshlrev_b32_e32 v7, 5, v14
	v_ashrrev_i16_sdwa v2, v4, sext(v2) dst_sel:DWORD dst_unused:UNUSED_PAD src0_sel:DWORD src1_sel:BYTE_0
	s_lshl_b64 s[4:5], s[8:9], 21
	s_lshl_b64 s[6:7], s[6:7], 21
	v_and_b32_e32 v7, 32, v7
	v_bfe_i32 v15, v2, 0, 16
	s_add_u32 s6, s52, s6
	v_add_lshl_u32 v2, v7, v15, 1
	s_addc_u32 s7, s53, s7
	s_add_i32 s61, s54, 0
	v_lshl_add_u32 v150, v6, 13, v2
	s_add_i32 m0, s61, 0x10000
	v_lshl_add_u32 v152, v5, 13, v2
	global_load_lds_dwordx4 v150, s[6:7]
	s_add_i32 m0, s61, 0x12000
	s_add_u32 s12, s6, 0x100000
	global_load_lds_dwordx4 v146, s[6:7]
	s_addc_u32 s13, s7, 0
	s_add_i32 m0, s61, 0x14000
	v_mov_b32_e32 v155, 0
	global_load_lds_dwordx4 v150, s[12:13]
	s_add_i32 m0, s61, 0x16000
	s_add_u32 s4, s0, s4
	s_addc_u32 s5, s1, s5
	s_add_i32 s62, s61, 0x2000
	global_load_lds_dwordx4 v146, s[12:13]
	s_mov_b32 m0, s61
	s_add_u32 s12, s4, 0x100000
	global_load_lds_dwordx4 v152, s[4:5]
	s_mov_b32 m0, s62
	s_addc_u32 s13, s5, 0
	s_add_i32 s63, s61, 0x4000
	global_load_lds_dwordx4 v148, s[4:5]
	s_mov_b32 m0, s63
	s_add_i32 s64, s61, 0x6000
	global_load_lds_dwordx4 v152, s[12:13]
	s_mov_b32 m0, s64
	v_mov_b32_e32 v151, v155
	global_load_lds_dwordx4 v148, s[12:13]
	s_load_dwordx4 s[12:15], s[2:3], 0xd0
	v_mov_b32_e32 v147, v155
	v_mov_b32_e32 v153, v155
	v_mov_b32_e32 v149, v155
	s_cmp_eq_u32 s31, 1
	s_mov_b32 s65, 0
	v_lshl_add_u64 v[8:9], s[6:7], 0, v[150:151]
	v_lshl_add_u64 v[6:7], s[6:7], 0, v[146:147]
	v_lshl_add_u64 v[2:3], s[4:5], 0, v[152:153]
	s_cselect_b64 s[16:17], -1, 0
	s_cmp_lg_u32 s31, 1
	v_lshl_add_u64 v[4:5], s[4:5], 0, v[148:149]
	s_cbranch_scc1 .LBB0_650
	s_barrier

; #define PG8_STAGE(bufoff, gbase, voff) do { _Pragma("unroll") for (int _i = 0; _i < 2; ++_i) \
;         __builtin_amdgcn_global_load_lds((const unsigned*)((const char*)(gbase) + (voff)[_i]), (PG8_LAS unsigned*)(lds + (bufoff) + ldsw + _i * 8192), 16, 0, 0); } while (0)
; #define PG8_LDA(dst, b, h) do { _Pragma("unroll") for (int m = 0; m < 4; ++m) _Pragma("unroll") for (int k = 0; k < 2; ++k) dst[m][k] = *(const PG8_LAS bf16x8*)(lds + PG8_SA(b, h) + aoff + m * 2048 + k * 1024); } while (0)
; #define PG8_LDB(dst, b, h) do { _Pragma("unroll") for (int n = 0; n < 2; ++n) _Pragma("unroll") for (int k = 0; k < 2; ++k) dst[n][k] = *(const PG8_LAS bf16x8*)(lds + PG8_SB(b, h) + boff + n * 2048 + k * 1024); } while (0)
; #define PG8_MMA(ai, bj, At, Bt) do { __builtin_amdgcn_s_setprio(1); _Pragma("unroll") for (int m = 0; m < 4; ++m) _Pragma("unroll") for (int n = 0; n < 2; ++n) _Pragma("unroll") for (int k = 0; k < 2; ++k) \
;         acc[ai][bj][m][n] = __builtin_amdgcn_mfma_f32_16x16x32_bf16(Bt[n][k], At[m][k], acc[ai][bj][m][n], 0, 0, 0); __builtin_amdgcn_s_setprio(0); } while (0)
; #define PG8_WAIT_V(n) asm volatile("s_waitcnt vmcnt(" #n ")" ::: "memory")
; #define PG8_WAIT_L(n) asm volatile("s_waitcnt lgkmcnt(" #n ")" ::: "memory")
; #define PG8_BAR __builtin_amdgcn_s_barrier()
; template <class Epi, class Sched, bool ALIGN_EPI = false>
; __device__ __forceinline__ void gemm_phase(PG8_LAS unsigned char* lds, const Gemm g, const Sched& S, const Epi& E) {
;     ...
;         for (int t = 0; t < nt; t += 2) {
;             const bool last = (t == nt - 2);
;             const char* a1 = cA + (size_t)(t + 1) * kstep;
;             const char* a2 = last ? nA : cA + (size_t)(t + 2) * kstep; const char* b2 = last ? nB : cB + (size_t)(t + 2) * kstep;
;             const char* a3 = a2 + kstep; const char* b3 = b2 + kstep;
;             if (last && has_next) S.a_ready(nxt);
;             PG8_LDB(B0, 0, 0); PG8_LDB(B1, 0, 1); PG8_SCHED; PG8_LDA(At, 0, 0); PG8_STAGE(PG8_SA(1, 1), a1 + hstepA, voffA);
;             PG8_WAIT_V(8); PG8_WAIT_L(0); PG8_BAR; PG8_MMA(0, 0, At, B0); PG8_MMA(0, 1, At, B1); PG8_BAR; PG8_SCHED;
;             PG8_LDA(At, 0, 1); PG8_STAGE(PG8_SB(0, 0), b2, voffB); PG8_STAGE(PG8_SB(0, 1), b2 + hstepB, voffB); PG8_STAGE(PG8_SA(0, 0), a2, voffA);
;             PG8_WAIT_V(8); PG8_WAIT_L(0); PG8_BAR; PG8_MMA(1, 0, At, B0); PG8_MMA(1, 1, At, B1); PG8_BAR; PG8_SCHED;
.LBB0_656:
	ds_read_b128 v[130:133], v176
	ds_read_b128 v[134:137], v176 offset:1024
	ds_read_b128 v[138:141], v176 offset:2048
	ds_read_b128 v[142:145], v176 offset:3072
	ds_read_b128 v[164:167], v177
	ds_read_b128 v[168:171], v177 offset:1024
	ds_read_b128 v[172:175], v177 offset:2048
	ds_read_b128 v[180:183], v177 offset:3072
	s_add_u32 s6, s4, 0xfff00080
	s_addc_u32 s7, s5, -1
	s_cmp_eq_u32 s76, 60
	s_cselect_b32 s49, s43, s7
	s_cselect_b32 s48, s50, s6
	s_cselect_b32 s7, s41, s75
	s_cselect_b32 s6, s51, s74
	s_add_i32 m0, s61, 0xc000
	ds_read_b128 v[184:187], v178
	ds_read_b128 v[188:191], v178 offset:1024
	ds_read_b128 v[192:195], v178 offset:2048
	ds_read_b128 v[196:199], v178 offset:3072
	ds_read_b128 v[200:203], v178 offset:4096
	ds_read_b128 v[204:207], v178 offset:5120
	ds_read_b128 v[208:211], v178 offset:6144
	ds_read_b128 v[212:215], v178 offset:7168
	global_load_lds_dwordx4 v156, s[4:5]
	s_add_i32 m0, s61, 0xe000
	s_nop 0
	global_load_lds_dwordx4 v158, s[4:5]
	s_waitcnt vmcnt(8)
	s_waitcnt lgkmcnt(0)
	s_barrier
	s_waitcnt lgkmcnt(0)
	v_mfma_f32_16x16x32_bf16 v[90:93], v[130:133], v[184:187], v[90:93]
	v_mfma_f32_16x16x32_bf16 v[86:89], v[138:141], v[184:187], v[86:89]
	v_mfma_f32_16x16x32_bf16 v[126:129], v[130:133], v[192:195], v[126:129]
	v_mfma_f32_16x16x32_bf16 v[106:109], v[138:141], v[192:195], v[106:109]
	v_mfma_f32_16x16x32_bf16 v[122:125], v[130:133], v[200:203], v[122:125]
	v_mfma_f32_16x16x32_bf16 v[102:105], v[138:141], v[200:203], v[102:105]
	v_mfma_f32_16x16x32_bf16 v[70:73], v[130:133], v[208:211], v[70:73]
	v_mfma_f32_16x16x32_bf16 v[66:69], v[138:141], v[208:211], v[66:69]
	v_mfma_f32_16x16x32_bf16 v[90:93], v[134:137], v[188:191], v[90:93]
	v_mfma_f32_16x16x32_bf16 v[86:89], v[142:145], v[188:191], v[86:89]
	v_mfma_f32_16x16x32_bf16 v[126:129], v[134:137], v[196:199], v[126:129]
	v_mfma_f32_16x16x32_bf16 v[106:109], v[142:145], v[196:199], v[106:109]
	v_mfma_f32_16x16x32_bf16 v[122:125], v[134:137], v[204:207], v[122:125]
	v_mfma_f32_16x16x32_bf16 v[102:105], v[142:145], v[204:207], v[102:105]
	v_mfma_f32_16x16x32_bf16 v[70:73], v[134:137], v[212:215], v[70:73]
	v_mfma_f32_16x16x32_bf16 v[66:69], v[142:145], v[212:215], v[66:69]
	v_mfma_f32_16x16x32_bf16 v[78:81], v[164:167], v[184:187], v[78:81]
	v_mfma_f32_16x16x32_bf16 v[74:77], v[172:175], v[184:187], v[74:77]
	v_mfma_f32_16x16x32_bf16 v[118:121], v[164:167], v[192:195], v[118:121]
	v_mfma_f32_16x16x32_bf16 v[98:101], v[172:175], v[192:195], v[98:101]
	v_mfma_f32_16x16x32_bf16 v[114:117], v[164:167], v[200:203], v[114:117]
	v_mfma_f32_16x16x32_bf16 v[94:97], v[172:175], v[200:203], v[94:97]
	v_mfma_f32_16x16x32_bf16 v[110:113], v[164:167], v[208:211], v[110:113]
	v_mfma_f32_16x16x32_bf16 v[82:85], v[172:175], v[208:211], v[82:85]
	v_mfma_f32_16x16x32_bf16 v[78:81], v[168:171], v[188:191], v[78:81]
	v_mfma_f32_16x16x32_bf16 v[74:77], v[180:183], v[188:191], v[74:77]
	v_mfma_f32_16x16x32_bf16 v[118:121], v[168:171], v[196:199], v[118:121]
	v_mfma_f32_16x16x32_bf16 v[98:101], v[180:183], v[196:199], v[98:101]
	v_mfma_f32_16x16x32_bf16 v[114:117], v[168:171], v[204:207], v[114:117]
	v_mfma_f32_16x16x32_bf16 v[94:97], v[180:183], v[204:207], v[94:97]
	v_mfma_f32_16x16x32_bf16 v[110:113], v[168:171], v[212:215], v[110:113]
	v_mfma_f32_16x16x32_bf16 v[82:85], v[180:183], v[212:215], v[82:85]
	s_barrier
	s_add_i32 s77, s70, s54
	s_add_u32 s98, s6, s30
	s_addc_u32 s99, s7, s31
	s_mov_b32 m0, s77
	ds_read_b128 v[184:187], v178 offset:16384
	ds_read_b128 v[188:191], v178 offset:17408
	ds_read_b128 v[192:195], v178 offset:18432
	ds_read_b128 v[196:199], v178 offset:19456
	ds_read_b128 v[200:203], v178 offset:20480
	ds_read_b128 v[204:207], v178 offset:21504
	ds_read_b128 v[208:211], v178 offset:22528
	ds_read_b128 v[212:215], v178 offset:23552
	global_load_lds_dwordx4 v150, s[6:7]
	s_add_i32 m0, s77, 0x2000
	s_add_u32 s78, s6, 0x100000
	s_addc_u32 s79, s7, 0
	s_add_i32 s77, s71, s54
	global_load_lds_dwordx4 v146, s[6:7]
	s_mov_b32 m0, s77
	s_nop 0
	global_load_lds_dwordx4 v150, s[78:79]
	s_add_i32 m0, s77, 0x2000
	s_nop 0
	global_load_lds_dwordx4 v146, s[78:79]
	s_add_u32 s100, s48, s30
	s_addc_u32 s101, s49, s31
	s_mov_b32 m0, s61
	s_nop 0
	global_load_lds_dwordx4 v152, s[48:49]
	s_mov_b32 m0, s62
	s_nop 0
	global_load_lds_dwordx4 v148, s[48:49]
	s_waitcnt vmcnt(8)
	s_waitcnt lgkmcnt(0)
	s_barrier
	s_waitcnt lgkmcnt(0)
	v_mfma_f32_16x16x32_bf16 v[26:29], v[130:133], v[184:187], v[26:29]
	v_mfma_f32_16x16x32_bf16 v[22:25], v[138:141], v[184:187], v[22:25]
	v_mfma_f32_16x16x32_bf16 v[62:65], v[130:133], v[192:195], v[62:65]
	v_mfma_f32_16x16x32_bf16 v[42:45], v[138:141], v[192:195], v[42:45]
	v_mfma_f32_16x16x32_bf16 v[58:61], v[130:133], v[200:203], v[58:61]
	v_mfma_f32_16x16x32_bf16 v[38:41], v[138:141], v[200:203], v[38:41]
	v_mfma_f32_16x16x32_bf16 v[6:9], v[130:133], v[208:211], v[6:9]
	v_mfma_f32_16x16x32_bf16 v[2:5], v[138:141], v[208:211], v[2:5]
	v_mfma_f32_16x16x32_bf16 v[26:29], v[134:137], v[188:191], v[26:29]
	v_mfma_f32_16x16x32_bf16 v[22:25], v[142:145], v[188:191], v[22:25]
	v_mfma_f32_16x16x32_bf16 v[62:65], v[134:137], v[196:199], v[62:65]
	v_mfma_f32_16x16x32_bf16 v[42:45], v[142:145], v[196:199], v[42:45]
	v_mfma_f32_16x16x32_bf16 v[58:61], v[134:137], v[204:207], v[58:61]
	v_mfma_f32_16x16x32_bf16 v[38:41], v[142:145], v[204:207], v[38:41]
	v_mfma_f32_16x16x32_bf16 v[6:9], v[134:137], v[212:215], v[6:9]
	v_mfma_f32_16x16x32_bf16 v[2:5], v[142:145], v[212:215], v[2:5]
	v_mfma_f32_16x16x32_bf16 v[14:17], v[164:167], v[184:187], v[14:17]
	v_mfma_f32_16x16x32_bf16 v[10:13], v[172:175], v[184:187], v[10:13]
	v_mfma_f32_16x16x32_bf16 v[54:57], v[164:167], v[192:195], v[54:57]
	v_mfma_f32_16x16x32_bf16 v[34:37], v[172:175], v[192:195], v[34:37]
	v_mfma_f32_16x16x32_bf16 v[50:53], v[164:167], v[200:203], v[50:53]
	v_mfma_f32_16x16x32_bf16 v[30:33], v[172:175], v[200:203], v[30:33]
	v_mfma_f32_16x16x32_bf16 v[46:49], v[164:167], v[208:211], v[46:49]
	v_mfma_f32_16x16x32_bf16 v[18:21], v[172:175], v[208:211], v[18:21]
	v_mfma_f32_16x16x32_bf16 v[14:17], v[168:171], v[188:191], v[14:17]
	v_mfma_f32_16x16x32_bf16 v[10:13], v[180:183], v[188:191], v[10:13]
	v_mfma_f32_16x16x32_bf16 v[54:57], v[168:171], v[196:199], v[54:57]
	v_mfma_f32_16x16x32_bf16 v[34:37], v[180:183], v[196:199], v[34:37]
	v_mfma_f32_16x16x32_bf16 v[50:53], v[168:171], v[204:207], v[50:53]
	v_mfma_f32_16x16x32_bf16 v[30:33], v[180:183], v[204:207], v[30:33]
	v_mfma_f32_16x16x32_bf16 v[46:49], v[168:171], v[212:215], v[46:49]
	v_mfma_f32_16x16x32_bf16 v[18:21], v[180:183], v[212:215], v[18:21]
	s_barrier
; #define PG8_STAGE(bufoff, gbase, voff) do { _Pragma("unroll") for (int _i = 0; _i < 2; ++_i) \
;         __builtin_amdgcn_global_load_lds((const unsigned*)((const char*)(gbase) + (voff)[_i]), (PG8_LAS unsigned*)(lds + (bufoff) + ldsw + _i * 8192), 16, 0, 0); } while (0)
; #define PG8_LDA(dst, b, h) do { _Pragma("unroll") for (int m = 0; m < 4; ++m) _Pragma("unroll") for (int k = 0; k < 2; ++k) dst[m][k] = *(const PG8_LAS bf16x8*)(lds + PG8_SA(b, h) + aoff + m * 2048 + k * 1024); } while (0)
; #define PG8_LDB(dst, b, h) do { _Pragma("unroll") for (int n = 0; n < 2; ++n) _Pragma("unroll") for (int k = 0; k < 2; ++k) dst[n][k] = *(const PG8_LAS bf16x8*)(lds + PG8_SB(b, h) + boff + n * 2048 + k * 1024); } while (0)
; #define PG8_MMA(ai, bj, At, Bt) do { __builtin_amdgcn_s_setprio(1); _Pragma("unroll") for (int m = 0; m < 4; ++m) _Pragma("unroll") for (int n = 0; n < 2; ++n) _Pragma("unroll") for (int k = 0; k < 2; ++k) \
;         acc[ai][bj][m][n] = __builtin_amdgcn_mfma_f32_16x16x32_bf16(Bt[n][k], At[m][k], acc[ai][bj][m][n], 0, 0, 0); __builtin_amdgcn_s_setprio(0); } while (0)
; #define PG8_WAIT_V(n) asm volatile("s_waitcnt vmcnt(" #n ")" ::: "memory")
; #define PG8_WAIT_L(n) asm volatile("s_waitcnt lgkmcnt(" #n ")" ::: "memory")
; #define PG8_BAR __builtin_amdgcn_s_barrier()
; #define PG8_SCHED __builtin_amdgcn_sched_barrier(0)
; template <class Epi, class Sched, bool ALIGN_EPI = false>
; __device__ __forceinline__ void gemm_phase(PG8_LAS unsigned char* lds, const Gemm g, const Sched& S, const Epi& E) {
;     ...
;             PG8_LDB(B0, 1, 0); PG8_LDB(B1, 1, 1); PG8_SCHED; PG8_LDA(At, 1, 0); PG8_STAGE(PG8_SA(0, 1), a2 + hstepA, voffA);
;             PG8_WAIT_V(8); PG8_WAIT_L(0); PG8_BAR; PG8_MMA(0, 0, At, B0); PG8_MMA(0, 1, At, B1); PG8_BAR; PG8_SCHED;
;             PG8_LDA(At, 1, 1); PG8_STAGE(PG8_SB(1, 0), b3, voffB); PG8_STAGE(PG8_SB(1, 1), b3 + hstepB, voffB); PG8_STAGE(PG8_SA(1, 0), a3, voffA);
;             PG8_WAIT_V(8); PG8_WAIT_L(0); PG8_BAR; PG8_MMA(1, 0, At, B0); PG8_MMA(1, 1, At, B1); PG8_BAR; PG8_SCHED;
;         }
;         if constexpr (ALIGN_EPI) { if (wr == 0) PG8_BAR; }
	s_add_i32 s77, 0, 0x18000
	s_add_i32 s78, 0, 0x1c000
	v_add_u32_e32 v142, s77, v1
	v_add_u32_e32 v154, s78, v1
	ds_read_b128 v[130:133], v142
	ds_read_b128 v[134:137], v142 offset:1024
	ds_read_b128 v[138:141], v142 offset:2048
	ds_read_b128 v[142:145], v142 offset:3072
	ds_read_b128 v[164:167], v154
	ds_read_b128 v[168:171], v154 offset:1024
	ds_read_b128 v[172:175], v154 offset:2048
	ds_read_b128 v[180:183], v154 offset:3072
	s_add_u32 s48, s48, 0x100000
	s_addc_u32 s49, s49, 0
	s_mov_b32 m0, s63
	ds_read_b128 v[184:187], v178 offset:32768
	ds_read_b128 v[188:191], v178 offset:33792
	ds_read_b128 v[192:195], v178 offset:34816
	ds_read_b128 v[196:199], v178 offset:35840
	ds_read_b128 v[200:203], v178 offset:36864
	ds_read_b128 v[204:207], v178 offset:37888
	ds_read_b128 v[208:211], v178 offset:38912
	ds_read_b128 v[212:215], v178 offset:39936
	global_load_lds_dwordx4 v152, s[48:49]
	s_mov_b32 m0, s64
	s_nop 0
	global_load_lds_dwordx4 v148, s[48:49]
	s_waitcnt vmcnt(8)
	s_waitcnt lgkmcnt(0)
	s_barrier
	s_waitcnt lgkmcnt(0)
	v_mfma_f32_16x16x32_bf16 v[90:93], v[130:133], v[184:187], v[90:93]
	v_mfma_f32_16x16x32_bf16 v[86:89], v[138:141], v[184:187], v[86:89]
	v_mfma_f32_16x16x32_bf16 v[126:129], v[130:133], v[192:195], v[126:129]
	v_mfma_f32_16x16x32_bf16 v[106:109], v[138:141], v[192:195], v[106:109]
	v_mfma_f32_16x16x32_bf16 v[122:125], v[130:133], v[200:203], v[122:125]
	v_mfma_f32_16x16x32_bf16 v[102:105], v[138:141], v[200:203], v[102:105]
	v_mfma_f32_16x16x32_bf16 v[70:73], v[130:133], v[208:211], v[70:73]
	v_mfma_f32_16x16x32_bf16 v[66:69], v[138:141], v[208:211], v[66:69]
	v_mfma_f32_16x16x32_bf16 v[90:93], v[134:137], v[188:191], v[90:93]
	v_mfma_f32_16x16x32_bf16 v[86:89], v[142:145], v[188:191], v[86:89]
	v_mfma_f32_16x16x32_bf16 v[126:129], v[134:137], v[196:199], v[126:129]
	v_mfma_f32_16x16x32_bf16 v[106:109], v[142:145], v[196:199], v[106:109]
	v_mfma_f32_16x16x32_bf16 v[122:125], v[134:137], v[204:207], v[122:125]
	v_mfma_f32_16x16x32_bf16 v[102:105], v[142:145], v[204:207], v[102:105]
	v_mfma_f32_16x16x32_bf16 v[70:73], v[134:137], v[212:215], v[70:73]
	v_mfma_f32_16x16x32_bf16 v[66:69], v[142:145], v[212:215], v[66:69]
	v_mfma_f32_16x16x32_bf16 v[78:81], v[164:167], v[184:187], v[78:81]
	v_mfma_f32_16x16x32_bf16 v[74:77], v[172:175], v[184:187], v[74:77]
	v_mfma_f32_16x16x32_bf16 v[118:121], v[164:167], v[192:195], v[118:121]
	v_mfma_f32_16x16x32_bf16 v[98:101], v[172:175], v[192:195], v[98:101]
	v_mfma_f32_16x16x32_bf16 v[114:117], v[164:167], v[200:203], v[114:117]
	v_mfma_f32_16x16x32_bf16 v[94:97], v[172:175], v[200:203], v[94:97]
	v_mfma_f32_16x16x32_bf16 v[110:113], v[164:167], v[208:211], v[110:113]
	v_mfma_f32_16x16x32_bf16 v[82:85], v[172:175], v[208:211], v[82:85]
	v_mfma_f32_16x16x32_bf16 v[78:81], v[168:171], v[188:191], v[78:81]
	v_mfma_f32_16x16x32_bf16 v[74:77], v[180:183], v[188:191], v[74:77]
	v_mfma_f32_16x16x32_bf16 v[118:121], v[168:171], v[196:199], v[118:121]
	v_mfma_f32_16x16x32_bf16 v[98:101], v[180:183], v[196:199], v[98:101]
	v_mfma_f32_16x16x32_bf16 v[114:117], v[168:171], v[204:207], v[114:117]
	v_mfma_f32_16x16x32_bf16 v[94:97], v[180:183], v[204:207], v[94:97]
	v_mfma_f32_16x16x32_bf16 v[110:113], v[168:171], v[212:215], v[110:113]
	v_mfma_f32_16x16x32_bf16 v[82:85], v[180:183], v[212:215], v[82:85]
	s_barrier
	s_add_i32 s48, s77, s54
	s_mov_b32 m0, s48
	ds_read_b128 v[184:187], v178 offset:49152
	ds_read_b128 v[188:191], v178 offset:50176
	ds_read_b128 v[192:195], v178 offset:51200
	ds_read_b128 v[196:199], v178 offset:52224
	ds_read_b128 v[200:203], v178 offset:53248
	ds_read_b128 v[204:207], v178 offset:54272
	ds_read_b128 v[208:211], v178 offset:55296
	ds_read_b128 v[212:215], v178 offset:56320
	global_load_lds_dwordx4 v150, s[98:99]
	s_add_i32 m0, s48, 0x2000
	s_add_u32 s6, s6, 0x100080
	s_addc_u32 s7, s7, 0
	s_add_i32 s48, s78, s54
	global_load_lds_dwordx4 v146, s[98:99]
	s_mov_b32 m0, s48
	s_nop 0
	global_load_lds_dwordx4 v150, s[6:7]
	s_add_i32 m0, s48, 0x2000
	s_nop 0
	global_load_lds_dwordx4 v146, s[6:7]
	s_mov_b32 m0, s67
	s_nop 0
	global_load_lds_dwordx4 v152, s[100:101]
	s_mov_b32 m0, s68
	s_nop 0
	global_load_lds_dwordx4 v148, s[100:101]
	s_waitcnt vmcnt(8)
	s_waitcnt lgkmcnt(0)
	s_barrier
	s_waitcnt lgkmcnt(0)
	v_mfma_f32_16x16x32_bf16 v[26:29], v[130:133], v[184:187], v[26:29]
	v_mfma_f32_16x16x32_bf16 v[22:25], v[138:141], v[184:187], v[22:25]
	v_mfma_f32_16x16x32_bf16 v[62:65], v[130:133], v[192:195], v[62:65]
	v_mfma_f32_16x16x32_bf16 v[42:45], v[138:141], v[192:195], v[42:45]
	v_mfma_f32_16x16x32_bf16 v[58:61], v[130:133], v[200:203], v[58:61]
	v_mfma_f32_16x16x32_bf16 v[38:41], v[138:141], v[200:203], v[38:41]
	v_mfma_f32_16x16x32_bf16 v[6:9], v[130:133], v[208:211], v[6:9]
	v_mfma_f32_16x16x32_bf16 v[2:5], v[138:141], v[208:211], v[2:5]
	v_mfma_f32_16x16x32_bf16 v[26:29], v[134:137], v[188:191], v[26:29]
	v_mfma_f32_16x16x32_bf16 v[22:25], v[142:145], v[188:191], v[22:25]
	v_mfma_f32_16x16x32_bf16 v[62:65], v[134:137], v[196:199], v[62:65]
	v_mfma_f32_16x16x32_bf16 v[42:45], v[142:145], v[196:199], v[42:45]
	v_mfma_f32_16x16x32_bf16 v[58:61], v[134:137], v[204:207], v[58:61]
	v_mfma_f32_16x16x32_bf16 v[38:41], v[142:145], v[204:207], v[38:41]
	v_mfma_f32_16x16x32_bf16 v[6:9], v[134:137], v[212:215], v[6:9]
	v_mfma_f32_16x16x32_bf16 v[2:5], v[142:145], v[212:215], v[2:5]
	v_mfma_f32_16x16x32_bf16 v[14:17], v[164:167], v[184:187], v[14:17]
	v_mfma_f32_16x16x32_bf16 v[10:13], v[172:175], v[184:187], v[10:13]
	v_mfma_f32_16x16x32_bf16 v[54:57], v[164:167], v[192:195], v[54:57]
	v_mfma_f32_16x16x32_bf16 v[34:37], v[172:175], v[192:195], v[34:37]
	v_mfma_f32_16x16x32_bf16 v[50:53], v[164:167], v[200:203], v[50:53]
	v_mfma_f32_16x16x32_bf16 v[30:33], v[172:175], v[200:203], v[30:33]
	v_mfma_f32_16x16x32_bf16 v[46:49], v[164:167], v[208:211], v[46:49]
	v_mfma_f32_16x16x32_bf16 v[18:21], v[172:175], v[208:211], v[18:21]
	v_mfma_f32_16x16x32_bf16 v[14:17], v[168:171], v[188:191], v[14:17]
	v_mfma_f32_16x16x32_bf16 v[10:13], v[180:183], v[188:191], v[10:13]
	v_mfma_f32_16x16x32_bf16 v[54:57], v[168:171], v[196:199], v[54:57]
	v_mfma_f32_16x16x32_bf16 v[34:37], v[180:183], v[196:199], v[34:37]
	v_mfma_f32_16x16x32_bf16 v[50:53], v[168:171], v[204:207], v[50:53]
	v_mfma_f32_16x16x32_bf16 v[30:33], v[180:183], v[204:207], v[30:33]
	v_mfma_f32_16x16x32_bf16 v[46:49], v[168:171], v[212:215], v[46:49]
	v_mfma_f32_16x16x32_bf16 v[18:21], v[180:183], v[212:215], v[18:21]
	s_barrier
	s_add_i32 s76, s76, 2
	s_add_u32 s4, s4, 0x100
	s_addc_u32 s5, s5, 0
	s_add_u32 s74, s74, 0x100
	s_addc_u32 s75, s75, 0
	s_cmp_gt_u32 s76, 61
	s_cbranch_scc0 .LBB0_656
	s_and_b64 vcc, exec, s[34:35]
	s_cbranch_vccz .LBB0_659
	s_barrier

; __device__ __forceinline__ unsigned xb_ld(unsigned* p)              { return __hip_atomic_load(p, __ATOMIC_RELAXED, __HIP_MEMORY_SCOPE_AGENT); }
; __device__ __forceinline__ void xcd_barrier_complete(unsigned* bar, unsigned x, unsigned& nloc, unsigned& nx) {
;     const unsigned G = gridDim.x * gridDim.y * gridDim.z;
;     unsigned sum, cnt, mine, sp = 0u;
;     for (;;) {
;         sum = 0u; cnt = 0u; mine = 0u;
; #pragma unroll
;         for (unsigned j = 0; j < 16; ++j) { const unsigned c = xb_ld(&bar[XB_XCNT(j)]); sum += c; cnt += (c > 0u) ? 1u : 0u; mine = (j == x) ? c : mine; }
;         if (sum == G) break;
; __device__ __forceinline__ void xcd_barrier(const XcdBarrier& b) {
;     asm volatile("s_waitcnt vmcnt(0)" ::: "memory");
;     __syncthreads();
;     if (threadIdx.x == 0) {
;         unsigned* bar = b.bar;
;         __builtin_amdgcn_s_waitcnt(0);
;         unsigned nloc = b.st[0], nx = b.st[1];
;         if (nloc == 0u) { xcd_barrier_complete(bar, b.x, nloc, nx); b.st[0] = nloc; b.st[1] = nx; }
.LBB0_675:
	s_setprio 0
	s_cmp_gt_i32 s59, 9
	s_cselect_b64 s[2:3], -1, 0
	s_and_b64 s[0:1], s[10:11], s[2:3]
	s_andn2_b64 vcc, exec, s[0:1]
	s_cbranch_vccnz .LBB0_725
	s_waitcnt vmcnt(0)
	v_cmp_eq_u32_e32 vcc, 0, v0
	s_waitcnt vmcnt(0)
	s_barrier
	s_and_saveexec_b64 s[4:5], vcc
	s_cbranch_execz .LBB0_724
	v_readlane_b32 s0, v228, 5
	s_waitcnt vmcnt(0) expcnt(0) lgkmcnt(0)
	s_nop 0
	v_mov_b32_e32 v1, s0
	ds_read_b32 v3, v1
	ds_read_b32 v1, v1 offset:4
	s_waitcnt lgkmcnt(1)
	v_cmp_ne_u32_e32 vcc, 0, v3
	s_cbranch_vccnz .LBB0_692
	v_readlane_b32 s6, v228, 0
	v_readlane_b32 s7, v228, 1
	s_load_dwordx2 s[0:1], s[6:7], 0x4
	s_add_u32 s6, s56, 0x4200
	s_addc_u32 s7, s57, 0
	s_add_u32 s8, s56, 0x4400
	s_addc_u32 s9, s57, 0
	s_add_u32 s10, s56, 0x4500
	s_addc_u32 s11, s57, 0
	s_add_u32 s12, s56, 0x4600
	s_addc_u32 s13, s57, 0
	s_add_u32 s14, s56, 0x4700
	s_addc_u32 s15, s57, 0
	s_add_u32 s16, s56, 0x4800
	s_addc_u32 s17, s57, 0
	s_add_u32 s18, s56, 0x4900
	s_addc_u32 s19, s57, 0
	s_add_u32 s20, s56, 0x4a00
	s_addc_u32 s21, s57, 0
	s_add_u32 s22, s56, 0x4b00
	s_addc_u32 s23, s57, 0
	s_add_u32 s24, s56, 0x4c00
	s_addc_u32 s25, s57, 0
	s_add_u32 s26, s56, 0x4d00
	s_addc_u32 s27, s57, 0
	s_add_u32 s28, s56, 0x4e00
	s_addc_u32 s29, s57, 0
	s_add_u32 s30, s56, 0x4f00
	s_addc_u32 s31, s57, 0
	s_add_u32 s34, s56, 0x5000
	s_addc_u32 s35, s57, 0
	s_add_u32 s36, s56, 0x5100
	s_addc_u32 s37, s57, 0
	s_add_u32 s38, s56, 0x5200
	s_addc_u32 s39, s57, 0
	s_waitcnt lgkmcnt(0)
	s_mul_i32 s0, s0, s86
	s_add_u32 s40, s56, 0x5300
	s_mul_i32 s0, s0, s1
	s_addc_u32 s41, s57, 0
	s_mov_b32 s1, 1
	v_mov_b32_e32 v17, 0
	s_branch .LBB0_680

;     __host__ __device__ bool next(int i, Unit& u) const {
;         const long L = (long)i * G + c; if (L >= nwg) return false;
;         int wgid = (int)L; { const int q = nwg / NXCD, r = nwg % NXCD, xcd = wgid % NXCD, off = wgid / NXCD; wgid = (xcd < r ? xcd * (q + 1) : r * (q + 1) + (xcd - r) * q) + off; }
;         const int nig = WGM * nN, gid = wgid / nig, fm = gid * WGM, gsz = (nM - fm) < WGM ? (nM - fm) : WGM;
;         u.pm = fm + ((wgid % nig) % gsz); u.pn = (wgid % nig) / gsz; return true;
.LBB0_790:
	s_cmp_lt_i32 s58, 11
	s_cselect_b64 s[0:1], -1, 0
	s_and_b64 s[6:7], s[0:1], s[2:3]
	s_andn2_b64 vcc, exec, s[6:7]
	s_cbranch_vccnz .LBB0_819
	v_readfirstlane_b32 s98, v0
	s_nop 3
	s_lshr_b32 s98, s98, 8
	s_cmp_eq_u32 s98, 0
	s_cbranch_scc0 .Lmy_prio3
	s_setprio 1
.Lmy_prio3:
	v_mov_b32_e32 v1, v0
	s_cmpk_gt_i32 s33, 0x1ff
	v_readfirstlane_b32 s4, v1
	s_cbranch_scc1 .LBB0_819
	s_ashr_i32 s0, s33, 31
	s_lshr_b32 s1, s0, 29
	s_add_i32 s1, s33, s1
	s_and_b32 s2, s1, -8
	s_sub_i32 s8, s33, s2
	s_cmp_gt_i32 s8, -1
	s_cbranch_scc0 .LBB0_794
	s_lshl_b32 s5, s8, 6
	s_cbranch_execz .LBB0_795
	s_branch .LBB0_796

; #define PG8_STAGE(bufoff, gbase, voff) do { _Pragma("unroll") for (int _i = 0; _i < 2; ++_i) \
;         __builtin_amdgcn_global_load_lds((const unsigned*)((const char*)(gbase) + (voff)[_i]), (PG8_LAS unsigned*)(lds + (bufoff) + ldsw + _i * 8192), 16, 0, 0); } while (0)
; #define PG8_LDA(dst, b, h) do { _Pragma("unroll") for (int m = 0; m < 4; ++m) _Pragma("unroll") for (int k = 0; k < 2; ++k) dst[m][k] = *(const PG8_LAS bf16x8*)(lds + PG8_SA(b, h) + aoff + m * 2048 + k * 1024); } while (0)
; #define PG8_LDB(dst, b, h) do { _Pragma("unroll") for (int n = 0; n < 2; ++n) _Pragma("unroll") for (int k = 0; k < 2; ++k) dst[n][k] = *(const PG8_LAS bf16x8*)(lds + PG8_SB(b, h) + boff + n * 2048 + k * 1024); } while (0)
; #define PG8_MMA(ai, bj, At, Bt) do { __builtin_amdgcn_s_setprio(1); _Pragma("unroll") for (int m = 0; m < 4; ++m) _Pragma("unroll") for (int n = 0; n < 2; ++n) _Pragma("unroll") for (int k = 0; k < 2; ++k) \
;         acc[ai][bj][m][n] = __builtin_amdgcn_mfma_f32_16x16x32_bf16(Bt[n][k], At[m][k], acc[ai][bj][m][n], 0, 0, 0); __builtin_amdgcn_s_setprio(0); } while (0)
; #define PG8_WAIT_V(n) asm volatile("s_waitcnt vmcnt(" #n ")" ::: "memory")
; #define PG8_WAIT_L(n) asm volatile("s_waitcnt lgkmcnt(" #n ")" ::: "memory")
; #define PG8_BAR __builtin_amdgcn_s_barrier()
; template <class Epi, class Sched, bool ALIGN_EPI = false>
; __device__ __forceinline__ void gemm_phase(PG8_LAS unsigned char* lds, const Gemm g, const Sched& S, const Epi& E) {
;     ...
;         for (int t = 0; t < nt; t += 2) {
;             const bool last = (t == nt - 2);
;             const char* a1 = cA + (size_t)(t + 1) * kstep;
;             const char* a2 = last ? nA : cA + (size_t)(t + 2) * kstep; const char* b2 = last ? nB : cB + (size_t)(t + 2) * kstep;
;             const char* a3 = a2 + kstep; const char* b3 = b2 + kstep;
;             if (last && has_next) S.a_ready(nxt);
;             PG8_LDB(B0, 0, 0); PG8_LDB(B1, 0, 1); PG8_SCHED; PG8_LDA(At, 0, 0); PG8_STAGE(PG8_SA(1, 1), a1 + hstepA, voffA);
;             PG8_WAIT_V(8); PG8_WAIT_L(0); PG8_BAR; PG8_MMA(0, 0, At, B0); PG8_MMA(0, 1, At, B1); PG8_BAR; PG8_SCHED;
;             PG8_LDA(At, 0, 1); PG8_STAGE(PG8_SB(0, 0), b2, voffB); PG8_STAGE(PG8_SB(0, 1), b2 + hstepB, voffB); PG8_STAGE(PG8_SA(0, 0), a2, voffA);
;             PG8_WAIT_V(8); PG8_WAIT_L(0); PG8_BAR; PG8_MMA(1, 0, At, B0); PG8_MMA(1, 1, At, B1); PG8_BAR; PG8_SCHED;
.LBB0_812:
	ds_read_b128 v[146:149], v152
	ds_read_b128 v[156:159], v152 offset:1024
	ds_read_b128 v[160:163], v152 offset:2048
	ds_read_b128 v[164:167], v152 offset:3072
	ds_read_b128 v[168:171], v153
	ds_read_b128 v[172:175], v153 offset:1024
	ds_read_b128 v[176:179], v153 offset:2048
	ds_read_b128 v[180:183], v153 offset:3072
	s_add_u32 s28, s26, 0x100
	s_addc_u32 s29, s27, 0
	s_cmpk_eq_i32 s64, 0xdc
	s_cselect_b32 s35, s5, s29
	s_cselect_b32 s34, s4, s28
	s_cselect_b32 s31, s25, s63
	s_cselect_b32 s30, s24, s62
	v_lshl_add_u64 v[150:151], s[26:27], 0, v[138:139]
	s_add_i32 m0, s40, 0xc000
	ds_read_b128 v[184:187], v154
	ds_read_b128 v[188:191], v154 offset:1024
	ds_read_b128 v[192:195], v154 offset:2048
	ds_read_b128 v[196:199], v154 offset:3072
	ds_read_b128 v[200:203], v154 offset:4096
	ds_read_b128 v[204:207], v154 offset:5120
	ds_read_b128 v[208:211], v154 offset:6144
	ds_read_b128 v[212:215], v154 offset:7168
	global_load_lds_dwordx4 v[150:151], off
	v_lshl_add_u64 v[150:151], s[26:27], 0, v[140:141]
	s_add_i32 m0, s40, 0xe000
	s_nop 0
	global_load_lds_dwordx4 v[150:151], off
	s_waitcnt vmcnt(8)
	s_waitcnt lgkmcnt(0)
	s_barrier
	s_waitcnt lgkmcnt(0)
	v_mfma_f32_16x16x32_bf16 v[126:129], v[146:149], v[184:187], v[126:129]
	v_mfma_f32_16x16x32_bf16 v[122:125], v[160:163], v[184:187], v[122:125]
	v_mfma_f32_16x16x32_bf16 v[114:117], v[146:149], v[192:195], v[114:117]
	v_mfma_f32_16x16x32_bf16 v[106:109], v[160:163], v[192:195], v[106:109]
	v_mfma_f32_16x16x32_bf16 v[98:101], v[146:149], v[200:203], v[98:101]
	v_mfma_f32_16x16x32_bf16 v[90:93], v[160:163], v[200:203], v[90:93]
	v_mfma_f32_16x16x32_bf16 v[82:85], v[146:149], v[208:211], v[82:85]
	v_mfma_f32_16x16x32_bf16 v[74:77], v[160:163], v[208:211], v[74:77]
	v_mfma_f32_16x16x32_bf16 v[126:129], v[156:159], v[188:191], v[126:129]
	v_mfma_f32_16x16x32_bf16 v[122:125], v[164:167], v[188:191], v[122:125]
	v_mfma_f32_16x16x32_bf16 v[114:117], v[156:159], v[196:199], v[114:117]
	v_mfma_f32_16x16x32_bf16 v[106:109], v[164:167], v[196:199], v[106:109]
	v_mfma_f32_16x16x32_bf16 v[98:101], v[156:159], v[204:207], v[98:101]
	v_mfma_f32_16x16x32_bf16 v[90:93], v[164:167], v[204:207], v[90:93]
	v_mfma_f32_16x16x32_bf16 v[82:85], v[156:159], v[212:215], v[82:85]
	v_mfma_f32_16x16x32_bf16 v[74:77], v[164:167], v[212:215], v[74:77]
	v_mfma_f32_16x16x32_bf16 v[118:121], v[168:171], v[184:187], v[118:121]
	v_mfma_f32_16x16x32_bf16 v[110:113], v[176:179], v[184:187], v[110:113]
	v_mfma_f32_16x16x32_bf16 v[102:105], v[168:171], v[192:195], v[102:105]
	v_mfma_f32_16x16x32_bf16 v[94:97], v[176:179], v[192:195], v[94:97]
	v_mfma_f32_16x16x32_bf16 v[86:89], v[168:171], v[200:203], v[86:89]
	v_mfma_f32_16x16x32_bf16 v[78:81], v[176:179], v[200:203], v[78:81]
	v_mfma_f32_16x16x32_bf16 v[70:73], v[168:171], v[208:211], v[70:73]
	v_mfma_f32_16x16x32_bf16 v[66:69], v[176:179], v[208:211], v[66:69]
	v_mfma_f32_16x16x32_bf16 v[118:121], v[172:175], v[188:191], v[118:121]
	v_mfma_f32_16x16x32_bf16 v[110:113], v[180:183], v[188:191], v[110:113]
	v_mfma_f32_16x16x32_bf16 v[102:105], v[172:175], v[196:199], v[102:105]
	v_mfma_f32_16x16x32_bf16 v[94:97], v[180:183], v[196:199], v[94:97]
	v_mfma_f32_16x16x32_bf16 v[86:89], v[172:175], v[204:207], v[86:89]
	v_mfma_f32_16x16x32_bf16 v[78:81], v[180:183], v[204:207], v[78:81]
	v_mfma_f32_16x16x32_bf16 v[70:73], v[172:175], v[212:215], v[70:73]
	v_mfma_f32_16x16x32_bf16 v[66:69], v[180:183], v[212:215], v[66:69]
	s_barrier
	s_add_i32 s26, s48, s39
	v_lshl_add_u64 v[150:151], s[30:31], 0, v[132:133]
	s_mov_b32 m0, s26
	ds_read_b128 v[184:187], v154 offset:16384
	ds_read_b128 v[188:191], v154 offset:17408
	ds_read_b128 v[192:195], v154 offset:18432
	ds_read_b128 v[196:199], v154 offset:19456
	ds_read_b128 v[200:203], v154 offset:20480
	ds_read_b128 v[204:207], v154 offset:21504
	ds_read_b128 v[208:211], v154 offset:22528
	ds_read_b128 v[212:215], v154 offset:23552
	global_load_lds_dwordx4 v[150:151], off
	s_add_i32 m0, s26, 0x2000
	s_add_u32 s26, s30, 0x380000
	v_lshl_add_u64 v[216:217], s[30:31], 0, v[136:137]
	s_addc_u32 s27, s31, 0
	s_add_i32 s65, s49, s39
	global_load_lds_dwordx4 v[216:217], off
	v_lshl_add_u64 v[218:219], s[26:27], 0, v[132:133]
	s_mov_b32 m0, s65
	v_lshl_add_u64 v[220:221], s[34:35], 0, v[134:135]
	global_load_lds_dwordx4 v[218:219], off
	v_lshl_add_u64 v[218:219], s[26:27], 0, v[136:137]
	s_add_i32 m0, s65, 0x2000
	s_nop 0
	global_load_lds_dwordx4 v[218:219], off
	v_lshl_add_u64 v[218:219], s[34:35], 0, v[130:131]
	s_mov_b32 m0, s40
	s_nop 0
	global_load_lds_dwordx4 v[218:219], off
	s_mov_b32 m0, s41
	s_nop 0
	global_load_lds_dwordx4 v[220:221], off
	s_waitcnt vmcnt(8)
	s_waitcnt lgkmcnt(0)
	s_barrier
; #define PG8_STAGE(bufoff, gbase, voff) do { _Pragma("unroll") for (int _i = 0; _i < 2; ++_i) \
;         __builtin_amdgcn_global_load_lds((const unsigned*)((const char*)(gbase) + (voff)[_i]), (PG8_LAS unsigned*)(lds + (bufoff) + ldsw + _i * 8192), 16, 0, 0); } while (0)
; #define PG8_LDA(dst, b, h) do { _Pragma("unroll") for (int m = 0; m < 4; ++m) _Pragma("unroll") for (int k = 0; k < 2; ++k) dst[m][k] = *(const PG8_LAS bf16x8*)(lds + PG8_SA(b, h) + aoff + m * 2048 + k * 1024); } while (0)
; #define PG8_LDB(dst, b, h) do { _Pragma("unroll") for (int n = 0; n < 2; ++n) _Pragma("unroll") for (int k = 0; k < 2; ++k) dst[n][k] = *(const PG8_LAS bf16x8*)(lds + PG8_SB(b, h) + boff + n * 2048 + k * 1024); } while (0)
; #define PG8_MMA(ai, bj, At, Bt) do { __builtin_amdgcn_s_setprio(1); _Pragma("unroll") for (int m = 0; m < 4; ++m) _Pragma("unroll") for (int n = 0; n < 2; ++n) _Pragma("unroll") for (int k = 0; k < 2; ++k) \
;         acc[ai][bj][m][n] = __builtin_amdgcn_mfma_f32_16x16x32_bf16(Bt[n][k], At[m][k], acc[ai][bj][m][n], 0, 0, 0); __builtin_amdgcn_s_setprio(0); } while (0)
; #define PG8_WAIT_V(n) asm volatile("s_waitcnt vmcnt(" #n ")" ::: "memory")
; #define PG8_WAIT_L(n) asm volatile("s_waitcnt lgkmcnt(" #n ")" ::: "memory")
; #define PG8_BAR __builtin_amdgcn_s_barrier()
; #define PG8_SCHED __builtin_amdgcn_sched_barrier(0)
; template <class Epi, class Sched, bool ALIGN_EPI = false>
; __device__ __forceinline__ void gemm_phase(PG8_LAS unsigned char* lds, const Gemm g, const Sched& S, const Epi& E) {
;     ...
;             PG8_WAIT_V(8); PG8_WAIT_L(0); PG8_BAR; PG8_MMA(1, 0, At, B0); PG8_MMA(1, 1, At, B1); PG8_BAR; PG8_SCHED;
;             PG8_LDB(B0, 1, 0); PG8_LDB(B1, 1, 1); PG8_SCHED; PG8_LDA(At, 1, 0); PG8_STAGE(PG8_SA(0, 1), a2 + hstepA, voffA);
;             PG8_WAIT_V(8); PG8_WAIT_L(0); PG8_BAR; PG8_MMA(0, 0, At, B0); PG8_MMA(0, 1, At, B1); PG8_BAR; PG8_SCHED;
	s_waitcnt lgkmcnt(0)
	v_mfma_f32_16x16x32_bf16 v[62:65], v[146:149], v[184:187], v[62:65]
	v_mfma_f32_16x16x32_bf16 v[58:61], v[160:163], v[184:187], v[58:61]
	v_mfma_f32_16x16x32_bf16 v[50:53], v[146:149], v[192:195], v[50:53]
	v_mfma_f32_16x16x32_bf16 v[42:45], v[160:163], v[192:195], v[42:45]
	v_mfma_f32_16x16x32_bf16 v[34:37], v[146:149], v[200:203], v[34:37]
	v_mfma_f32_16x16x32_bf16 v[26:29], v[160:163], v[200:203], v[26:29]
	v_mfma_f32_16x16x32_bf16 v[18:21], v[146:149], v[208:211], v[18:21]
	v_mfma_f32_16x16x32_bf16 v[10:13], v[160:163], v[208:211], v[10:13]
	v_mfma_f32_16x16x32_bf16 v[62:65], v[156:159], v[188:191], v[62:65]
	v_mfma_f32_16x16x32_bf16 v[58:61], v[164:167], v[188:191], v[58:61]
	v_mfma_f32_16x16x32_bf16 v[50:53], v[156:159], v[196:199], v[50:53]
	v_mfma_f32_16x16x32_bf16 v[42:45], v[164:167], v[196:199], v[42:45]
	v_mfma_f32_16x16x32_bf16 v[34:37], v[156:159], v[204:207], v[34:37]
	v_mfma_f32_16x16x32_bf16 v[26:29], v[164:167], v[204:207], v[26:29]
	v_mfma_f32_16x16x32_bf16 v[18:21], v[156:159], v[212:215], v[18:21]
	v_mfma_f32_16x16x32_bf16 v[10:13], v[164:167], v[212:215], v[10:13]
	v_mfma_f32_16x16x32_bf16 v[54:57], v[168:171], v[184:187], v[54:57]
	v_mfma_f32_16x16x32_bf16 v[46:49], v[176:179], v[184:187], v[46:49]
	v_mfma_f32_16x16x32_bf16 v[38:41], v[168:171], v[192:195], v[38:41]
	v_mfma_f32_16x16x32_bf16 v[30:33], v[176:179], v[192:195], v[30:33]
	v_mfma_f32_16x16x32_bf16 v[22:25], v[168:171], v[200:203], v[22:25]
	v_mfma_f32_16x16x32_bf16 v[14:17], v[176:179], v[200:203], v[14:17]
	v_mfma_f32_16x16x32_bf16 v[6:9], v[168:171], v[208:211], v[6:9]
	v_mfma_f32_16x16x32_bf16 v[2:5], v[176:179], v[208:211], v[2:5]
	v_mfma_f32_16x16x32_bf16 v[54:57], v[172:175], v[188:191], v[54:57]
	v_mfma_f32_16x16x32_bf16 v[46:49], v[180:183], v[188:191], v[46:49]
	v_mfma_f32_16x16x32_bf16 v[38:41], v[172:175], v[196:199], v[38:41]
	v_mfma_f32_16x16x32_bf16 v[30:33], v[180:183], v[196:199], v[30:33]
	v_mfma_f32_16x16x32_bf16 v[22:25], v[172:175], v[204:207], v[22:25]
	v_mfma_f32_16x16x32_bf16 v[14:17], v[180:183], v[204:207], v[14:17]
	v_mfma_f32_16x16x32_bf16 v[6:9], v[172:175], v[212:215], v[6:9]
	v_mfma_f32_16x16x32_bf16 v[2:5], v[180:183], v[212:215], v[2:5]
	s_barrier
	s_add_i32 s65, 0, 0x18000
	v_add_u32_e32 v155, s65, v1
	s_add_i32 s66, 0, 0x1c000
	ds_read_b128 v[146:149], v155
	ds_read_b128 v[156:159], v155 offset:1024
	ds_read_b128 v[160:163], v155 offset:2048
	ds_read_b128 v[164:167], v155 offset:3072
	v_add_u32_e32 v155, s66, v1
	ds_read_b128 v[168:171], v155
	ds_read_b128 v[172:175], v155 offset:1024
	ds_read_b128 v[176:179], v155 offset:2048
	ds_read_b128 v[180:183], v155 offset:3072
	s_add_u32 s26, s34, 0x380000
	s_addc_u32 s27, s35, 0
	s_mov_b32 m0, s42
	v_lshl_add_u64 v[222:223], s[26:27], 0, v[130:131]
	ds_read_b128 v[184:187], v154 offset:32768
	ds_read_b128 v[188:191], v154 offset:33792
	ds_read_b128 v[192:195], v154 offset:34816
	ds_read_b128 v[196:199], v154 offset:35840
	ds_read_b128 v[200:203], v154 offset:36864
	ds_read_b128 v[204:207], v154 offset:37888
	ds_read_b128 v[208:211], v154 offset:38912
	ds_read_b128 v[212:215], v154 offset:39936
	global_load_lds_dwordx4 v[222:223], off
	v_lshl_add_u64 v[222:223], s[26:27], 0, v[134:135]
	s_mov_b32 m0, s43
	s_nop 0
	global_load_lds_dwordx4 v[222:223], off
	s_waitcnt vmcnt(8)
	s_waitcnt lgkmcnt(0)
	s_barrier
	s_waitcnt lgkmcnt(0)
	v_mfma_f32_16x16x32_bf16 v[126:129], v[146:149], v[184:187], v[126:129]
	v_mfma_f32_16x16x32_bf16 v[122:125], v[160:163], v[184:187], v[122:125]
	v_mfma_f32_16x16x32_bf16 v[114:117], v[146:149], v[192:195], v[114:117]
	v_mfma_f32_16x16x32_bf16 v[106:109], v[160:163], v[192:195], v[106:109]
	v_mfma_f32_16x16x32_bf16 v[98:101], v[146:149], v[200:203], v[98:101]
	v_mfma_f32_16x16x32_bf16 v[90:93], v[160:163], v[200:203], v[90:93]
	v_mfma_f32_16x16x32_bf16 v[82:85], v[146:149], v[208:211], v[82:85]
	v_mfma_f32_16x16x32_bf16 v[74:77], v[160:163], v[208:211], v[74:77]
	v_mfma_f32_16x16x32_bf16 v[126:129], v[156:159], v[188:191], v[126:129]
	v_mfma_f32_16x16x32_bf16 v[122:125], v[164:167], v[188:191], v[122:125]
	v_mfma_f32_16x16x32_bf16 v[114:117], v[156:159], v[196:199], v[114:117]
	v_mfma_f32_16x16x32_bf16 v[106:109], v[164:167], v[196:199], v[106:109]
	v_mfma_f32_16x16x32_bf16 v[98:101], v[156:159], v[204:207], v[98:101]
	v_mfma_f32_16x16x32_bf16 v[90:93], v[164:167], v[204:207], v[90:93]
	v_mfma_f32_16x16x32_bf16 v[82:85], v[156:159], v[212:215], v[82:85]
	v_mfma_f32_16x16x32_bf16 v[74:77], v[164:167], v[212:215], v[74:77]
	v_mfma_f32_16x16x32_bf16 v[118:121], v[168:171], v[184:187], v[118:121]
	v_mfma_f32_16x16x32_bf16 v[110:113], v[176:179], v[184:187], v[110:113]
	v_mfma_f32_16x16x32_bf16 v[102:105], v[168:171], v[192:195], v[102:105]
	v_mfma_f32_16x16x32_bf16 v[94:97], v[176:179], v[192:195], v[94:97]
	v_mfma_f32_16x16x32_bf16 v[86:89], v[168:171], v[200:203], v[86:89]
	v_mfma_f32_16x16x32_bf16 v[78:81], v[176:179], v[200:203], v[78:81]
	v_mfma_f32_16x16x32_bf16 v[70:73], v[168:171], v[208:211], v[70:73]
	v_mfma_f32_16x16x32_bf16 v[66:69], v[176:179], v[208:211], v[66:69]
	v_mfma_f32_16x16x32_bf16 v[118:121], v[172:175], v[188:191], v[118:121]
	v_mfma_f32_16x16x32_bf16 v[110:113], v[180:183], v[188:191], v[110:113]
	v_mfma_f32_16x16x32_bf16 v[102:105], v[172:175], v[196:199], v[102:105]
	v_mfma_f32_16x16x32_bf16 v[94:97], v[180:183], v[196:199], v[94:97]
	v_mfma_f32_16x16x32_bf16 v[86:89], v[172:175], v[204:207], v[86:89]
	v_mfma_f32_16x16x32_bf16 v[78:81], v[180:183], v[204:207], v[78:81]
	v_mfma_f32_16x16x32_bf16 v[70:73], v[172:175], v[212:215], v[70:73]
	v_mfma_f32_16x16x32_bf16 v[66:69], v[180:183], v[212:215], v[66:69]
	s_barrier
; #define PG8_STAGE(bufoff, gbase, voff) do { _Pragma("unroll") for (int _i = 0; _i < 2; ++_i) \
;         __builtin_amdgcn_global_load_lds((const unsigned*)((const char*)(gbase) + (voff)[_i]), (PG8_LAS unsigned*)(lds + (bufoff) + ldsw + _i * 8192), 16, 0, 0); } while (0)
; #define PG8_LDA(dst, b, h) do { _Pragma("unroll") for (int m = 0; m < 4; ++m) _Pragma("unroll") for (int k = 0; k < 2; ++k) dst[m][k] = *(const PG8_LAS bf16x8*)(lds + PG8_SA(b, h) + aoff + m * 2048 + k * 1024); } while (0)
; #define PG8_MMA(ai, bj, At, Bt) do { __builtin_amdgcn_s_setprio(1); _Pragma("unroll") for (int m = 0; m < 4; ++m) _Pragma("unroll") for (int n = 0; n < 2; ++n) _Pragma("unroll") for (int k = 0; k < 2; ++k) \
;         acc[ai][bj][m][n] = __builtin_amdgcn_mfma_f32_16x16x32_bf16(Bt[n][k], At[m][k], acc[ai][bj][m][n], 0, 0, 0); __builtin_amdgcn_s_setprio(0); } while (0)
; #define PG8_WAIT_V(n) asm volatile("s_waitcnt vmcnt(" #n ")" ::: "memory")
; #define PG8_WAIT_L(n) asm volatile("s_waitcnt lgkmcnt(" #n ")" ::: "memory")
; #define PG8_BAR __builtin_amdgcn_s_barrier()
; #define PG8_SCHED __builtin_amdgcn_sched_barrier(0)
; template <class Epi, class Sched, bool ALIGN_EPI = false>
; __device__ __forceinline__ void gemm_phase(PG8_LAS unsigned char* lds, const Gemm g, const Sched& S, const Epi& E) {
;     ...
;             PG8_LDA(At, 1, 1); PG8_STAGE(PG8_SB(1, 0), b3, voffB); PG8_STAGE(PG8_SB(1, 1), b3 + hstepB, voffB); PG8_STAGE(PG8_SA(1, 0), a3, voffA);
;             PG8_WAIT_V(8); PG8_WAIT_L(0); PG8_BAR; PG8_MMA(1, 0, At, B0); PG8_MMA(1, 1, At, B1); PG8_BAR; PG8_SCHED;
;         }
;         if constexpr (ALIGN_EPI) { if (wr == 0) PG8_BAR; }
	s_add_i32 s26, s65, s39
	v_lshl_add_u64 v[150:151], v[150:151], 0, s[12:13]
	s_mov_b32 m0, s26
	ds_read_b128 v[184:187], v154 offset:49152
	ds_read_b128 v[188:191], v154 offset:50176
	ds_read_b128 v[192:195], v154 offset:51200
	ds_read_b128 v[196:199], v154 offset:52224
	ds_read_b128 v[200:203], v154 offset:53248
	ds_read_b128 v[204:207], v154 offset:54272
	ds_read_b128 v[208:211], v154 offset:55296
	ds_read_b128 v[212:215], v154 offset:56320
	global_load_lds_dwordx4 v[150:151], off
	s_add_i32 m0, s26, 0x2000
	s_add_u32 s26, s30, 0x380080
	v_lshl_add_u64 v[150:151], v[216:217], 0, s[12:13]
	s_addc_u32 s27, s31, 0
	s_add_i32 s30, s66, s39
	global_load_lds_dwordx4 v[150:151], off
	v_lshl_add_u64 v[150:151], s[26:27], 0, v[132:133]
	s_mov_b32 m0, s30
	s_nop 0
	global_load_lds_dwordx4 v[150:151], off
	v_lshl_add_u64 v[150:151], s[26:27], 0, v[136:137]
	s_add_i32 m0, s30, 0x2000
	s_nop 0
	global_load_lds_dwordx4 v[150:151], off
	v_lshl_add_u64 v[150:151], v[218:219], 0, s[12:13]
	s_mov_b32 m0, s45
	s_nop 0
	global_load_lds_dwordx4 v[150:151], off
	v_lshl_add_u64 v[150:151], v[220:221], 0, s[12:13]
	s_mov_b32 m0, s46
	s_nop 0
	global_load_lds_dwordx4 v[150:151], off
	s_waitcnt vmcnt(8)
	s_waitcnt lgkmcnt(0)
	s_barrier
	s_waitcnt lgkmcnt(0)
	v_mfma_f32_16x16x32_bf16 v[62:65], v[146:149], v[184:187], v[62:65]
	v_mfma_f32_16x16x32_bf16 v[58:61], v[160:163], v[184:187], v[58:61]
	v_mfma_f32_16x16x32_bf16 v[50:53], v[146:149], v[192:195], v[50:53]
	v_mfma_f32_16x16x32_bf16 v[42:45], v[160:163], v[192:195], v[42:45]
	v_mfma_f32_16x16x32_bf16 v[34:37], v[146:149], v[200:203], v[34:37]
	v_mfma_f32_16x16x32_bf16 v[26:29], v[160:163], v[200:203], v[26:29]
	v_mfma_f32_16x16x32_bf16 v[18:21], v[146:149], v[208:211], v[18:21]
	v_mfma_f32_16x16x32_bf16 v[10:13], v[160:163], v[208:211], v[10:13]
	v_mfma_f32_16x16x32_bf16 v[62:65], v[156:159], v[188:191], v[62:65]
	v_mfma_f32_16x16x32_bf16 v[58:61], v[164:167], v[188:191], v[58:61]
	v_mfma_f32_16x16x32_bf16 v[50:53], v[156:159], v[196:199], v[50:53]
	v_mfma_f32_16x16x32_bf16 v[42:45], v[164:167], v[196:199], v[42:45]
	v_mfma_f32_16x16x32_bf16 v[34:37], v[156:159], v[204:207], v[34:37]
	v_mfma_f32_16x16x32_bf16 v[26:29], v[164:167], v[204:207], v[26:29]
	v_mfma_f32_16x16x32_bf16 v[18:21], v[156:159], v[212:215], v[18:21]
	v_mfma_f32_16x16x32_bf16 v[10:13], v[164:167], v[212:215], v[10:13]
	v_mfma_f32_16x16x32_bf16 v[54:57], v[168:171], v[184:187], v[54:57]
	v_mfma_f32_16x16x32_bf16 v[46:49], v[176:179], v[184:187], v[46:49]
	v_mfma_f32_16x16x32_bf16 v[38:41], v[168:171], v[192:195], v[38:41]
	v_mfma_f32_16x16x32_bf16 v[30:33], v[176:179], v[192:195], v[30:33]
	v_mfma_f32_16x16x32_bf16 v[22:25], v[168:171], v[200:203], v[22:25]
	v_mfma_f32_16x16x32_bf16 v[14:17], v[176:179], v[200:203], v[14:17]
	v_mfma_f32_16x16x32_bf16 v[6:9], v[168:171], v[208:211], v[6:9]
	v_mfma_f32_16x16x32_bf16 v[2:5], v[176:179], v[208:211], v[2:5]
	v_mfma_f32_16x16x32_bf16 v[54:57], v[172:175], v[188:191], v[54:57]
	v_mfma_f32_16x16x32_bf16 v[46:49], v[180:183], v[188:191], v[46:49]
	v_mfma_f32_16x16x32_bf16 v[38:41], v[172:175], v[196:199], v[38:41]
	v_mfma_f32_16x16x32_bf16 v[30:33], v[180:183], v[196:199], v[30:33]
	v_mfma_f32_16x16x32_bf16 v[22:25], v[172:175], v[204:207], v[22:25]
	v_mfma_f32_16x16x32_bf16 v[14:17], v[180:183], v[204:207], v[14:17]
	v_mfma_f32_16x16x32_bf16 v[6:9], v[172:175], v[212:215], v[6:9]
	v_mfma_f32_16x16x32_bf16 v[2:5], v[180:183], v[212:215], v[2:5]
	s_barrier
	s_add_i32 s64, s64, 2
	s_add_u32 s62, s62, 0x100
	s_addc_u32 s63, s63, 0
	s_cmpk_gt_u32 s64, 0xdd
	s_mov_b64 s[26:27], s[28:29]
	s_cbranch_scc0 .LBB0_812
	s_and_b64 vcc, exec, s[14:15]
	s_cbranch_vccz .LBB0_815
	s_barrier

; __device__ __forceinline__ unsigned xb_ld(unsigned* p)              { return __hip_atomic_load(p, __ATOMIC_RELAXED, __HIP_MEMORY_SCOPE_AGENT); }
; __device__ __forceinline__ void xcd_barrier_complete(unsigned* bar, unsigned x, unsigned& nloc, unsigned& nx) {
;     const unsigned G = gridDim.x * gridDim.y * gridDim.z;
;     unsigned sum, cnt, mine, sp = 0u;
;     for (;;) {
;         sum = 0u; cnt = 0u; mine = 0u;
; #pragma unroll
;         for (unsigned j = 0; j < 16; ++j) { const unsigned c = xb_ld(&bar[XB_XCNT(j)]); sum += c; cnt += (c > 0u) ? 1u : 0u; mine = (j == x) ? c : mine; }
;         if (sum == G) break;
; __device__ __forceinline__ void xcd_barrier(const XcdBarrier& b) {
;     asm volatile("s_waitcnt vmcnt(0)" ::: "memory");
;     __syncthreads();
;     if (threadIdx.x == 0) {
;         unsigned* bar = b.bar;
;         __builtin_amdgcn_s_waitcnt(0);
;         unsigned nloc = b.st[0], nx = b.st[1];
;         if (nloc == 0u) { xcd_barrier_complete(bar, b.x, nloc, nx); b.st[0] = nloc; b.st[1] = nx; }
.LBB0_819:
	s_setprio 0
	s_cmp_gt_i32 s59, 11
	s_cselect_b64 s[2:3], -1, 0
	s_and_b64 s[0:1], s[6:7], s[2:3]
	s_andn2_b64 vcc, exec, s[0:1]
	s_cbranch_vccnz .LBB0_869
	s_waitcnt vmcnt(0)
	v_cmp_eq_u32_e32 vcc, 0, v0
	s_waitcnt vmcnt(0)
	s_barrier
	s_and_saveexec_b64 s[4:5], vcc
	s_cbranch_execz .LBB0_868
	v_readlane_b32 s0, v228, 5
	s_waitcnt vmcnt(0) expcnt(0) lgkmcnt(0)
	s_nop 0
	v_mov_b32_e32 v1, s0
	ds_read_b32 v3, v1
	ds_read_b32 v1, v1 offset:4
	s_waitcnt lgkmcnt(1)
	v_cmp_ne_u32_e32 vcc, 0, v3
	s_cbranch_vccnz .LBB0_836
	v_readlane_b32 s6, v228, 0
	v_readlane_b32 s7, v228, 1
	s_load_dwordx2 s[0:1], s[6:7], 0x4
	s_add_u32 s6, s56, 0x4200
	s_addc_u32 s7, s57, 0
	s_add_u32 s8, s56, 0x4400
	s_addc_u32 s9, s57, 0
	s_add_u32 s10, s56, 0x4500
	s_addc_u32 s11, s57, 0
	s_add_u32 s12, s56, 0x4600
	s_addc_u32 s13, s57, 0
	s_add_u32 s14, s56, 0x4700
	s_addc_u32 s15, s57, 0
	s_add_u32 s16, s56, 0x4800
	s_addc_u32 s17, s57, 0
	s_add_u32 s18, s56, 0x4900
	s_addc_u32 s19, s57, 0
	s_add_u32 s20, s56, 0x4a00
	s_addc_u32 s21, s57, 0
	s_add_u32 s22, s56, 0x4b00
	s_addc_u32 s23, s57, 0
	s_add_u32 s24, s56, 0x4c00
	s_addc_u32 s25, s57, 0
	s_add_u32 s26, s56, 0x4d00
	s_addc_u32 s27, s57, 0
	s_add_u32 s28, s56, 0x4e00
	s_addc_u32 s29, s57, 0
	s_add_u32 s30, s56, 0x4f00
	s_addc_u32 s31, s57, 0
	s_add_u32 s34, s56, 0x5000
	s_addc_u32 s35, s57, 0
	s_add_u32 s36, s56, 0x5100
	s_addc_u32 s37, s57, 0
	s_add_u32 s38, s56, 0x5200
	s_addc_u32 s39, s57, 0
	s_waitcnt lgkmcnt(0)
	s_mul_i32 s0, s0, s86
	s_add_u32 s40, s56, 0x5300
	s_mul_i32 s0, s0, s1
	s_addc_u32 s41, s57, 0
	s_mov_b32 s1, 1
	v_mov_b32_e32 v17, 0
	s_branch .LBB0_824

; #define PG8_STAGE(bufoff, gbase, voff) do { _Pragma("unroll") for (int _i = 0; _i < 2; ++_i) \
;         __builtin_amdgcn_global_load_lds((const unsigned*)((const char*)(gbase) + (voff)[_i]), (PG8_LAS unsigned*)(lds + (bufoff) + ldsw + _i * 8192), 16, 0, 0); } while (0)
; #define PG8_BAR __builtin_amdgcn_s_barrier()
; template <class Epi, class Sched, bool ALIGN_EPI = false>
; __device__ __forceinline__ void gemm_phase(PG8_LAS unsigned char* lds, const Gemm g, const Sched& S, const Epi& E) {
;     int tid_ = threadIdx.x; asm volatile("" : "+v"(tid_));
;     const int tid = tid_, wid = __builtin_amdgcn_readfirstlane(tid >> 6), lane = tid & 63, wr = wid >> 2, wc = wid & 3, fr = lane & 15, fq = lane >> 4;
;     const int K = g.K, nt = K / BK;
;     unsigned voffA[2], voffB[2];
; #pragma unroll
;     for (int i = 0; i < 2; ++i) { int R, C; stage_rc(tid * 16 + i * 8192, R, C); const int Rb = Epi::PERM ? ((R & ~31) + perm32(R & 31)) : R;
;         voffA[i] = (unsigned)(R * g.lda + C) * 2u; voffB[i] = (unsigned)(Rb * g.ldb + C) * 2u; }
;     const size_t kstep = (size_t)(BK * 2);
;     const size_t hstepA = (size_t)HALF * g.lda * 2, hstepB = (size_t)HALF * g.ldb * 2;
;     const size_t tstepA = 2 * hstepA, tstepB = 2 * hstepB;
;     const unsigned ldsw = (unsigned)wid * 1024u;
;     const int aoff = lds_byte(wr * 64 + fr, fq * 8), boff = lds_byte(wc * 32 + fr, fq * 8);
;     ...
;     Unit cur, nxt; int ui = 0;
;     if (!S.next(0, cur)) return;
;     f32x4 acc[2][2][4][2];
; #pragma unroll
;     for (int a = 0; a < 2; ++a)
; #pragma unroll
;         for (int b = 0; b < 2; ++b)
; #pragma unroll
;             for (int m = 0; m < 4; ++m)
; #pragma unroll
;                 for (int n = 0; n < 2; ++n) acc[a][b][m][n] = (f32x4){0.f, 0.f, 0.f, 0.f};
;     bf16x8 At[4][2], B0[2][2], B1[2][2];
;     const char* cA = (const char*)g.A + (size_t)cur.pm * tstepA; const char* cB = (const char*)g.Bt + (size_t)cur.pn * tstepB;
;     S.a_ready(cur);
;     PG8_STAGE(PG8_SB(0, 0), cB, voffB); PG8_STAGE(PG8_SB(0, 1), cB + hstepB, voffB); PG8_STAGE(PG8_SA(0, 0), cA, voffA); PG8_STAGE(PG8_SA(0, 1), cA + hstepA, voffA);
;     if (wr == 1) PG8_BAR;
.LBB0_923:
	s_cmp_lt_i32 s58, 13
	s_cselect_b64 s[0:1], -1, 0
	s_and_b64 s[4:5], s[0:1], s[2:3]
	s_andn2_b64 vcc, exec, s[4:5]
	s_cbranch_vccnz .LBB0_951
	v_readfirstlane_b32 s98, v0
	s_nop 3
	s_lshr_b32 s98, s98, 8
	s_cmp_eq_u32 s98, 0
	s_cbranch_scc0 .Lmy_prio4
	s_setprio 1
.Lmy_prio4:
	v_mov_b32_e32 v1, v0
	s_cmpk_gt_i32 s33, 0x57f
	v_readfirstlane_b32 s3, v1
	s_cbranch_scc1 .LBB0_940
	v_lshlrev_b32_e32 v2, 4, v1
	v_add_u32_e32 v3, 0x2000, v2
	v_ashrrev_i32_e32 v4, 31, v3
	v_lshrrev_b32_e32 v4, 22, v4
	v_add_u32_e32 v4, v3, v4
	v_ashrrev_i32_e32 v10, 10, v4
	v_mul_i32_i24_e32 v4, 0x400, v10
	v_sub_u32_e32 v3, v3, v4
	v_lshrrev_b32_e32 v4, 4, v3
	v_bitop3_b32 v3, v4, v3, 32 bitop3:0x6c
	v_ashrrev_i32_e32 v4, 31, v3
	v_lshrrev_b32_e32 v4, 26, v4
	v_add_u32_e32 v4, v3, v4
	v_lshlrev_b32_e32 v5, 3, v10
	v_ashrrev_i32_e32 v11, 6, v4
	v_and_b32_e32 v5, -16, v5
	v_add_u32_e32 v5, v11, v5
	v_and_b32_e32 v6, 3, v11
	s_mov_b32 s2, 0x7ffe0
	v_lshrrev_b32_e32 v7, 2, v5
	v_lshlrev_b32_e32 v8, 1, v5
	v_and_b32_e32 v4, 0xc0, v4
	v_and_or_b32 v6, v5, s2, v6
	v_and_b32_e32 v7, 4, v7
	v_and_b32_e32 v8, 24, v8
	v_sub_u32_e32 v3, v3, v4
	v_mov_b32_e32 v4, 1
	v_or3_b32 v6, v6, v7, v8
	v_lshlrev_b32_e32 v7, 5, v10
	v_ashrrev_i16_sdwa v3, v4, sext(v3) dst_sel:DWORD dst_unused:UNUSED_PAD src0_sel:DWORD src1_sel:BYTE_0
	v_and_b32_e32 v7, 32, v7
	v_bfe_i32 v12, v3, 0, 16
	v_add_lshl_u32 v3, v7, v12, 1
	v_lshl_add_u32 v130, v6, 13, v3
	v_lshl_add_u32 v132, v5, 13, v3
	v_bfe_i32 v3, v1, 27, 1
	v_lshrrev_b32_e32 v3, 22, v3
	v_add_u32_e32 v3, v2, v3
	v_and_b32_e32 v3, 0xfffffc00, v3
	v_sub_u32_e32 v2, v2, v3
	v_lshrrev_b32_e32 v3, 4, v2
	v_ashrrev_i32_e32 v5, 31, v1
	v_bitop3_b32 v2, v3, v2, 32 bitop3:0x6c
	v_lshrrev_b32_e32 v5, 26, v5
	v_ashrrev_i32_e32 v3, 31, v2
	v_add_u32_e32 v5, v1, v5
	s_add_u32 s0, s56, 0x41200000
	v_lshrrev_b32_e32 v3, 26, v3
	v_ashrrev_i32_e32 v14, 6, v5
	s_addc_u32 s1, s57, 0
	v_add_u32_e32 v3, v2, v3
	v_lshlrev_b32_e32 v5, 3, v14
	s_add_u32 s30, s56, 0x7200000
	v_ashrrev_i32_e32 v13, 6, v3
	v_and_b32_e32 v5, -16, v5
	s_addc_u32 s31, s57, 0
	v_add_u32_e32 v5, v13, v5
	v_and_b32_e32 v6, 3, v13
	s_ashr_i32 s35, s33, 31
	v_and_or_b32 v6, v5, s2, v6
	s_lshr_b32 s2, s35, 29
	s_add_i32 s2, s33, s2
	s_ashr_i32 s10, s3, 6
	s_ashr_i32 s6, s2, 3
	s_and_b32 s2, s2, -8
	s_ashr_i32 s11, s3, 8
	s_lshl_b32 s34, s10, 10
	s_sub_i32 s2, s33, s2
	s_cmp_lt_i32 s2, 0
	s_movk_i32 s36, 0xb1
	s_cselect_b32 s7, s36, 0xb0
	s_mul_i32 s2, s2, s7
	s_add_i32 s2, s2, s6
	s_mul_hi_i32 s6, s2, 0x2e8ba2e9
	s_lshr_b32 s7, s6, 31
	s_ashr_i32 s6, s6, 6
	s_add_i32 s6, s6, s7
	s_lshl_b32 s7, s6, 3
	s_mulk_i32 s6, 0x160
	s_sub_i32 s6, s2, s6
	s_sext_i32_i16 s2, s6
	s_bfe_u32 s2, s2, 0x3001c
	s_add_i32 s8, s6, s2
	s_sext_i32_i16 s2, s8
	s_and_b32 s8, s8, 0xfff8
	s_sub_i32 s6, s6, s8
	s_sext_i32_i16 s6, s6
	v_lshrrev_b32_e32 v7, 2, v5
	v_lshlrev_b32_e32 v8, 1, v5
	v_and_b32_e32 v3, 0xc0, v3
	s_lshr_b32 s2, s2, 3
	s_add_i32 s22, s7, s6
	v_and_b32_e32 v7, 4, v7
	v_and_b32_e32 v8, 24, v8
	v_sub_u32_e32 v2, v2, v3
	s_ashr_i32 s23, s22, 31
	s_bfe_i64 s[8:9], s[2:3], 0x100000
	v_or3_b32 v6, v6, v7, v8
	v_lshlrev_b32_e32 v7, 5, v14
	v_ashrrev_i16_sdwa v2, v4, sext(v2) dst_sel:DWORD dst_unused:UNUSED_PAD src0_sel:DWORD src1_sel:BYTE_0
	s_lshl_b64 s[6:7], s[22:23], 21
	s_lshl_b64 s[8:9], s[8:9], 21
	v_and_b32_e32 v7, 32, v7
	v_bfe_i32 v15, v2, 0, 16
	s_add_u32 s26, s30, s8
	v_add_lshl_u32 v2, v7, v15, 1
	s_addc_u32 s27, s31, s9
	s_add_i32 s23, s34, 0
	v_lshl_add_u32 v134, v6, 13, v2
	s_add_i32 m0, s23, 0x10000
	v_lshl_add_u32 v136, v5, 13, v2
	global_load_lds_dwordx4 v134, s[26:27]
	s_add_i32 m0, s23, 0x12000
	s_add_u32 s8, s26, 0x100000
	global_load_lds_dwordx4 v130, s[26:27]
	s_addc_u32 s9, s27, 0
	s_add_i32 m0, s23, 0x14000
	v_mov_b32_e32 v135, 0
	global_load_lds_dwordx4 v134, s[8:9]
	s_add_i32 m0, s23, 0x16000
	s_add_u32 s24, s0, s6
	s_addc_u32 s25, s1, s7
	s_add_i32 s37, s23, 0x2000
	global_load_lds_dwordx4 v130, s[8:9]
	s_mov_b32 m0, s23
	s_add_u32 s6, s24, 0x100000
	global_load_lds_dwordx4 v136, s[24:25]
	s_mov_b32 m0, s37
	s_addc_u32 s7, s25, 0
	s_add_i32 s38, s23, 0x4000
	global_load_lds_dwordx4 v132, s[24:25]
	s_mov_b32 m0, s38
	s_add_i32 s39, s23, 0x6000
	global_load_lds_dwordx4 v136, s[6:7]
	s_mov_b32 m0, s39
	v_mov_b32_e32 v131, v135
	global_load_lds_dwordx4 v132, s[6:7]
	v_mov_b32_e32 v137, v135
	v_mov_b32_e32 v133, v135
	s_cmp_eq_u32 s11, 1
	s_mov_b32 s40, 0
	v_lshl_add_u64 v[8:9], s[26:27], 0, v[134:135]
	v_lshl_add_u64 v[6:7], s[26:27], 0, v[130:131]
	v_lshl_add_u64 v[2:3], s[24:25], 0, v[136:137]
	s_cselect_b64 s[6:7], -1, 0
	s_cmp_lg_u32 s11, 1
	v_lshl_add_u64 v[4:5], s[24:25], 0, v[132:133]
	s_cbranch_scc1 .LBB0_927
	s_barrier

; #define PG8_STAGE(bufoff, gbase, voff) do { _Pragma("unroll") for (int _i = 0; _i < 2; ++_i) \
;         __builtin_amdgcn_global_load_lds((const unsigned*)((const char*)(gbase) + (voff)[_i]), (PG8_LAS unsigned*)(lds + (bufoff) + ldsw + _i * 8192), 16, 0, 0); } while (0)
; #define PG8_LDA(dst, b, h) do { _Pragma("unroll") for (int m = 0; m < 4; ++m) _Pragma("unroll") for (int k = 0; k < 2; ++k) dst[m][k] = *(const PG8_LAS bf16x8*)(lds + PG8_SA(b, h) + aoff + m * 2048 + k * 1024); } while (0)
; #define PG8_LDB(dst, b, h) do { _Pragma("unroll") for (int n = 0; n < 2; ++n) _Pragma("unroll") for (int k = 0; k < 2; ++k) dst[n][k] = *(const PG8_LAS bf16x8*)(lds + PG8_SB(b, h) + boff + n * 2048 + k * 1024); } while (0)
; #define PG8_MMA(ai, bj, At, Bt) do { __builtin_amdgcn_s_setprio(1); _Pragma("unroll") for (int m = 0; m < 4; ++m) _Pragma("unroll") for (int n = 0; n < 2; ++n) _Pragma("unroll") for (int k = 0; k < 2; ++k) \
;         acc[ai][bj][m][n] = __builtin_amdgcn_mfma_f32_16x16x32_bf16(Bt[n][k], At[m][k], acc[ai][bj][m][n], 0, 0, 0); __builtin_amdgcn_s_setprio(0); } while (0)
; #define PG8_WAIT_V(n) asm volatile("s_waitcnt vmcnt(" #n ")" ::: "memory")
; #define PG8_WAIT_L(n) asm volatile("s_waitcnt lgkmcnt(" #n ")" ::: "memory")
; #define PG8_BAR __builtin_amdgcn_s_barrier()
; template <class Epi, class Sched, bool ALIGN_EPI = false>
; __device__ __forceinline__ void gemm_phase(PG8_LAS unsigned char* lds, const Gemm g, const Sched& S, const Epi& E) {
;     ...
;         for (int t = 0; t < nt; t += 2) {
;             const bool last = (t == nt - 2);
;             const char* a1 = cA + (size_t)(t + 1) * kstep;
;             const char* a2 = last ? nA : cA + (size_t)(t + 2) * kstep; const char* b2 = last ? nB : cB + (size_t)(t + 2) * kstep;
;             const char* a3 = a2 + kstep; const char* b3 = b2 + kstep;
;             if (last && has_next) S.a_ready(nxt);
;             PG8_LDB(B0, 0, 0); PG8_LDB(B1, 0, 1); PG8_SCHED; PG8_LDA(At, 0, 0); PG8_STAGE(PG8_SA(1, 1), a1 + hstepA, voffA);
;             PG8_WAIT_V(8); PG8_WAIT_L(0); PG8_BAR; PG8_MMA(0, 0, At, B0); PG8_MMA(0, 1, At, B1); PG8_BAR; PG8_SCHED;
;             PG8_LDA(At, 0, 1); PG8_STAGE(PG8_SB(0, 0), b2, voffB); PG8_STAGE(PG8_SB(0, 1), b2 + hstepB, voffB); PG8_STAGE(PG8_SA(0, 0), a2, voffA);
;             PG8_WAIT_V(8); PG8_WAIT_L(0); PG8_BAR; PG8_MMA(1, 0, At, B0); PG8_MMA(1, 1, At, B1); PG8_BAR; PG8_SCHED;
.LBB0_933:
	ds_read_b128 v[146:149], v150
	ds_read_b128 v[154:157], v150 offset:1024
	ds_read_b128 v[158:161], v150 offset:2048
	ds_read_b128 v[162:165], v150 offset:3072
	ds_read_b128 v[166:169], v151
	ds_read_b128 v[170:173], v151 offset:1024
	ds_read_b128 v[174:177], v151 offset:2048
	ds_read_b128 v[178:181], v151 offset:3072
	s_add_u32 s26, s24, 0xfff00080
	s_addc_u32 s27, s25, -1
	s_cmp_eq_u32 s52, 60
	s_cselect_b32 s29, s17, s27
	s_cselect_b32 s28, s48, s26
	s_cselect_b32 s27, s15, s51
	s_cselect_b32 s26, s49, s50
	v_lshl_add_u64 v[214:215], s[24:25], 0, v[138:139]
	s_add_i32 m0, s23, 0xc000
	ds_read_b128 v[182:185], v152
	ds_read_b128 v[186:189], v152 offset:1024
	ds_read_b128 v[190:193], v152 offset:2048
	ds_read_b128 v[194:197], v152 offset:3072
	ds_read_b128 v[198:201], v152 offset:4096
	ds_read_b128 v[202:205], v152 offset:5120
	ds_read_b128 v[206:209], v152 offset:6144
	ds_read_b128 v[210:213], v152 offset:7168
	global_load_lds_dwordx4 v[214:215], off
	v_lshl_add_u64 v[214:215], s[24:25], 0, v[140:141]
	s_add_i32 m0, s23, 0xe000
	s_nop 0
	global_load_lds_dwordx4 v[214:215], off
	s_waitcnt vmcnt(8)
	s_waitcnt lgkmcnt(0)
	s_barrier
	s_waitcnt lgkmcnt(0)
	v_mfma_f32_16x16x32_bf16 v[126:129], v[146:149], v[182:185], v[126:129]
	v_mfma_f32_16x16x32_bf16 v[122:125], v[158:161], v[182:185], v[122:125]
	v_mfma_f32_16x16x32_bf16 v[118:121], v[146:149], v[190:193], v[118:121]
	v_mfma_f32_16x16x32_bf16 v[110:113], v[158:161], v[190:193], v[110:113]
	v_mfma_f32_16x16x32_bf16 v[102:105], v[146:149], v[198:201], v[102:105]
	v_mfma_f32_16x16x32_bf16 v[94:97], v[158:161], v[198:201], v[94:97]
	v_mfma_f32_16x16x32_bf16 v[86:89], v[146:149], v[206:209], v[86:89]
	v_mfma_f32_16x16x32_bf16 v[78:81], v[158:161], v[206:209], v[78:81]
	v_mfma_f32_16x16x32_bf16 v[126:129], v[154:157], v[186:189], v[126:129]
	v_mfma_f32_16x16x32_bf16 v[122:125], v[162:165], v[186:189], v[122:125]
	v_mfma_f32_16x16x32_bf16 v[118:121], v[154:157], v[194:197], v[118:121]
	v_mfma_f32_16x16x32_bf16 v[110:113], v[162:165], v[194:197], v[110:113]
	v_mfma_f32_16x16x32_bf16 v[102:105], v[154:157], v[202:205], v[102:105]
	v_mfma_f32_16x16x32_bf16 v[94:97], v[162:165], v[202:205], v[94:97]
	v_mfma_f32_16x16x32_bf16 v[86:89], v[154:157], v[210:213], v[86:89]
	v_mfma_f32_16x16x32_bf16 v[78:81], v[162:165], v[210:213], v[78:81]
	v_mfma_f32_16x16x32_bf16 v[114:117], v[166:169], v[182:185], v[114:117]
	v_mfma_f32_16x16x32_bf16 v[106:109], v[174:177], v[182:185], v[106:109]
	v_mfma_f32_16x16x32_bf16 v[98:101], v[166:169], v[190:193], v[98:101]
	v_mfma_f32_16x16x32_bf16 v[90:93], v[174:177], v[190:193], v[90:93]
	v_mfma_f32_16x16x32_bf16 v[82:85], v[166:169], v[198:201], v[82:85]
	v_mfma_f32_16x16x32_bf16 v[74:77], v[174:177], v[198:201], v[74:77]
	v_mfma_f32_16x16x32_bf16 v[70:73], v[166:169], v[206:209], v[70:73]
	v_mfma_f32_16x16x32_bf16 v[66:69], v[174:177], v[206:209], v[66:69]
	v_mfma_f32_16x16x32_bf16 v[114:117], v[170:173], v[186:189], v[114:117]
	v_mfma_f32_16x16x32_bf16 v[106:109], v[178:181], v[186:189], v[106:109]
	v_mfma_f32_16x16x32_bf16 v[98:101], v[170:173], v[194:197], v[98:101]
	v_mfma_f32_16x16x32_bf16 v[90:93], v[178:181], v[194:197], v[90:93]
	v_mfma_f32_16x16x32_bf16 v[82:85], v[170:173], v[202:205], v[82:85]
	v_mfma_f32_16x16x32_bf16 v[74:77], v[178:181], v[202:205], v[74:77]
	v_mfma_f32_16x16x32_bf16 v[70:73], v[170:173], v[210:213], v[70:73]
	v_mfma_f32_16x16x32_bf16 v[66:69], v[178:181], v[210:213], v[66:69]
	s_barrier
	s_add_i32 s53, s44, s34
	v_lshl_add_u64 v[214:215], s[26:27], 0, v[134:135]
	s_mov_b32 m0, s53
	ds_read_b128 v[182:185], v152 offset:16384
	ds_read_b128 v[186:189], v152 offset:17408
	ds_read_b128 v[190:193], v152 offset:18432
	ds_read_b128 v[194:197], v152 offset:19456
	ds_read_b128 v[198:201], v152 offset:20480
	ds_read_b128 v[202:205], v152 offset:21504
	ds_read_b128 v[206:209], v152 offset:22528
	ds_read_b128 v[210:213], v152 offset:23552
	global_load_lds_dwordx4 v[214:215], off
	s_add_i32 m0, s53, 0x2000
	s_add_u32 s54, s26, 0x100000
	v_lshl_add_u64 v[216:217], s[26:27], 0, v[130:131]
	s_addc_u32 s55, s27, 0
	s_add_i32 s53, s45, s34
	global_load_lds_dwordx4 v[216:217], off
	v_lshl_add_u64 v[218:219], s[54:55], 0, v[134:135]
	s_mov_b32 m0, s53
	v_lshl_add_u64 v[220:221], s[28:29], 0, v[132:133]
	global_load_lds_dwordx4 v[218:219], off
	v_lshl_add_u64 v[218:219], s[54:55], 0, v[130:131]
	s_add_i32 m0, s53, 0x2000
	s_nop 0
	global_load_lds_dwordx4 v[218:219], off
	v_lshl_add_u64 v[218:219], s[28:29], 0, v[136:137]
	s_mov_b32 m0, s23
	s_nop 0
	global_load_lds_dwordx4 v[218:219], off
	s_mov_b32 m0, s37
	s_nop 0
	global_load_lds_dwordx4 v[220:221], off
	s_waitcnt vmcnt(8)
	s_waitcnt lgkmcnt(0)
	s_barrier
; #define PG8_STAGE(bufoff, gbase, voff) do { _Pragma("unroll") for (int _i = 0; _i < 2; ++_i) \
;         __builtin_amdgcn_global_load_lds((const unsigned*)((const char*)(gbase) + (voff)[_i]), (PG8_LAS unsigned*)(lds + (bufoff) + ldsw + _i * 8192), 16, 0, 0); } while (0)
; #define PG8_LDA(dst, b, h) do { _Pragma("unroll") for (int m = 0; m < 4; ++m) _Pragma("unroll") for (int k = 0; k < 2; ++k) dst[m][k] = *(const PG8_LAS bf16x8*)(lds + PG8_SA(b, h) + aoff + m * 2048 + k * 1024); } while (0)
; #define PG8_LDB(dst, b, h) do { _Pragma("unroll") for (int n = 0; n < 2; ++n) _Pragma("unroll") for (int k = 0; k < 2; ++k) dst[n][k] = *(const PG8_LAS bf16x8*)(lds + PG8_SB(b, h) + boff + n * 2048 + k * 1024); } while (0)
; #define PG8_MMA(ai, bj, At, Bt) do { __builtin_amdgcn_s_setprio(1); _Pragma("unroll") for (int m = 0; m < 4; ++m) _Pragma("unroll") for (int n = 0; n < 2; ++n) _Pragma("unroll") for (int k = 0; k < 2; ++k) \
;         acc[ai][bj][m][n] = __builtin_amdgcn_mfma_f32_16x16x32_bf16(Bt[n][k], At[m][k], acc[ai][bj][m][n], 0, 0, 0); __builtin_amdgcn_s_setprio(0); } while (0)
; #define PG8_WAIT_V(n) asm volatile("s_waitcnt vmcnt(" #n ")" ::: "memory")
; #define PG8_WAIT_L(n) asm volatile("s_waitcnt lgkmcnt(" #n ")" ::: "memory")
; #define PG8_BAR __builtin_amdgcn_s_barrier()
; #define PG8_SCHED __builtin_amdgcn_sched_barrier(0)
; template <class Epi, class Sched, bool ALIGN_EPI = false>
; __device__ __forceinline__ void gemm_phase(PG8_LAS unsigned char* lds, const Gemm g, const Sched& S, const Epi& E) {
;     ...
;             PG8_WAIT_V(8); PG8_WAIT_L(0); PG8_BAR; PG8_MMA(1, 0, At, B0); PG8_MMA(1, 1, At, B1); PG8_BAR; PG8_SCHED;
;             PG8_LDB(B0, 1, 0); PG8_LDB(B1, 1, 1); PG8_SCHED; PG8_LDA(At, 1, 0); PG8_STAGE(PG8_SA(0, 1), a2 + hstepA, voffA);
;             PG8_WAIT_V(8); PG8_WAIT_L(0); PG8_BAR; PG8_MMA(0, 0, At, B0); PG8_MMA(0, 1, At, B1); PG8_BAR; PG8_SCHED;
	s_waitcnt lgkmcnt(0)
	v_mfma_f32_16x16x32_bf16 v[62:65], v[146:149], v[182:185], v[62:65]
	v_mfma_f32_16x16x32_bf16 v[58:61], v[158:161], v[182:185], v[58:61]
	v_mfma_f32_16x16x32_bf16 v[54:57], v[146:149], v[190:193], v[54:57]
	v_mfma_f32_16x16x32_bf16 v[46:49], v[158:161], v[190:193], v[46:49]
	v_mfma_f32_16x16x32_bf16 v[38:41], v[146:149], v[198:201], v[38:41]
	v_mfma_f32_16x16x32_bf16 v[30:33], v[158:161], v[198:201], v[30:33]
	v_mfma_f32_16x16x32_bf16 v[22:25], v[146:149], v[206:209], v[22:25]
	v_mfma_f32_16x16x32_bf16 v[14:17], v[158:161], v[206:209], v[14:17]
	v_mfma_f32_16x16x32_bf16 v[62:65], v[154:157], v[186:189], v[62:65]
	v_mfma_f32_16x16x32_bf16 v[58:61], v[162:165], v[186:189], v[58:61]
	v_mfma_f32_16x16x32_bf16 v[54:57], v[154:157], v[194:197], v[54:57]
	v_mfma_f32_16x16x32_bf16 v[46:49], v[162:165], v[194:197], v[46:49]
	v_mfma_f32_16x16x32_bf16 v[38:41], v[154:157], v[202:205], v[38:41]
	v_mfma_f32_16x16x32_bf16 v[30:33], v[162:165], v[202:205], v[30:33]
	v_mfma_f32_16x16x32_bf16 v[22:25], v[154:157], v[210:213], v[22:25]
	v_mfma_f32_16x16x32_bf16 v[14:17], v[162:165], v[210:213], v[14:17]
	v_mfma_f32_16x16x32_bf16 v[50:53], v[166:169], v[182:185], v[50:53]
	v_mfma_f32_16x16x32_bf16 v[42:45], v[174:177], v[182:185], v[42:45]
	v_mfma_f32_16x16x32_bf16 v[34:37], v[166:169], v[190:193], v[34:37]
	v_mfma_f32_16x16x32_bf16 v[26:29], v[174:177], v[190:193], v[26:29]
	v_mfma_f32_16x16x32_bf16 v[18:21], v[166:169], v[198:201], v[18:21]
	v_mfma_f32_16x16x32_bf16 v[10:13], v[174:177], v[198:201], v[10:13]
	v_mfma_f32_16x16x32_bf16 v[6:9], v[166:169], v[206:209], v[6:9]
	v_mfma_f32_16x16x32_bf16 v[2:5], v[174:177], v[206:209], v[2:5]
	v_mfma_f32_16x16x32_bf16 v[50:53], v[170:173], v[186:189], v[50:53]
	v_mfma_f32_16x16x32_bf16 v[42:45], v[178:181], v[186:189], v[42:45]
	v_mfma_f32_16x16x32_bf16 v[34:37], v[170:173], v[194:197], v[34:37]
	v_mfma_f32_16x16x32_bf16 v[26:29], v[178:181], v[194:197], v[26:29]
	v_mfma_f32_16x16x32_bf16 v[18:21], v[170:173], v[202:205], v[18:21]
	v_mfma_f32_16x16x32_bf16 v[10:13], v[178:181], v[202:205], v[10:13]
	v_mfma_f32_16x16x32_bf16 v[6:9], v[170:173], v[210:213], v[6:9]
	v_mfma_f32_16x16x32_bf16 v[2:5], v[178:181], v[210:213], v[2:5]
	s_barrier
	s_add_i32 s53, 0, 0x18000
	v_add_u32_e32 v153, s53, v1
	s_add_i32 s54, 0, 0x1c000
	ds_read_b128 v[146:149], v153
	ds_read_b128 v[154:157], v153 offset:1024
	ds_read_b128 v[158:161], v153 offset:2048
	ds_read_b128 v[162:165], v153 offset:3072
	v_add_u32_e32 v153, s54, v1
	ds_read_b128 v[166:169], v153
	ds_read_b128 v[170:173], v153 offset:1024
	ds_read_b128 v[174:177], v153 offset:2048
	ds_read_b128 v[178:181], v153 offset:3072
	s_add_u32 s28, s28, 0x100000
	s_addc_u32 s29, s29, 0
	s_mov_b32 m0, s38
	v_lshl_add_u64 v[222:223], s[28:29], 0, v[136:137]
	ds_read_b128 v[182:185], v152 offset:32768
	ds_read_b128 v[186:189], v152 offset:33792
	ds_read_b128 v[190:193], v152 offset:34816
	ds_read_b128 v[194:197], v152 offset:35840
	ds_read_b128 v[198:201], v152 offset:36864
	ds_read_b128 v[202:205], v152 offset:37888
	ds_read_b128 v[206:209], v152 offset:38912
	ds_read_b128 v[210:213], v152 offset:39936
	global_load_lds_dwordx4 v[222:223], off
	v_lshl_add_u64 v[222:223], s[28:29], 0, v[132:133]
	s_mov_b32 m0, s39
	s_nop 0
	global_load_lds_dwordx4 v[222:223], off
	s_waitcnt vmcnt(8)
	s_waitcnt lgkmcnt(0)
	s_barrier
	s_waitcnt lgkmcnt(0)
	v_mfma_f32_16x16x32_bf16 v[126:129], v[146:149], v[182:185], v[126:129]
	v_mfma_f32_16x16x32_bf16 v[122:125], v[158:161], v[182:185], v[122:125]
	v_mfma_f32_16x16x32_bf16 v[118:121], v[146:149], v[190:193], v[118:121]
	v_mfma_f32_16x16x32_bf16 v[110:113], v[158:161], v[190:193], v[110:113]
	v_mfma_f32_16x16x32_bf16 v[102:105], v[146:149], v[198:201], v[102:105]
	v_mfma_f32_16x16x32_bf16 v[94:97], v[158:161], v[198:201], v[94:97]
	v_mfma_f32_16x16x32_bf16 v[86:89], v[146:149], v[206:209], v[86:89]
	v_mfma_f32_16x16x32_bf16 v[78:81], v[158:161], v[206:209], v[78:81]
	v_mfma_f32_16x16x32_bf16 v[126:129], v[154:157], v[186:189], v[126:129]
	v_mfma_f32_16x16x32_bf16 v[122:125], v[162:165], v[186:189], v[122:125]
	v_mfma_f32_16x16x32_bf16 v[118:121], v[154:157], v[194:197], v[118:121]
	v_mfma_f32_16x16x32_bf16 v[110:113], v[162:165], v[194:197], v[110:113]
	v_mfma_f32_16x16x32_bf16 v[102:105], v[154:157], v[202:205], v[102:105]
	v_mfma_f32_16x16x32_bf16 v[94:97], v[162:165], v[202:205], v[94:97]
	v_mfma_f32_16x16x32_bf16 v[86:89], v[154:157], v[210:213], v[86:89]
	v_mfma_f32_16x16x32_bf16 v[78:81], v[162:165], v[210:213], v[78:81]
	v_mfma_f32_16x16x32_bf16 v[114:117], v[166:169], v[182:185], v[114:117]
	v_mfma_f32_16x16x32_bf16 v[106:109], v[174:177], v[182:185], v[106:109]
	v_mfma_f32_16x16x32_bf16 v[98:101], v[166:169], v[190:193], v[98:101]
	v_mfma_f32_16x16x32_bf16 v[90:93], v[174:177], v[190:193], v[90:93]
	v_mfma_f32_16x16x32_bf16 v[82:85], v[166:169], v[198:201], v[82:85]
	v_mfma_f32_16x16x32_bf16 v[74:77], v[174:177], v[198:201], v[74:77]
	v_mfma_f32_16x16x32_bf16 v[70:73], v[166:169], v[206:209], v[70:73]
	v_mfma_f32_16x16x32_bf16 v[66:69], v[174:177], v[206:209], v[66:69]
	v_mfma_f32_16x16x32_bf16 v[114:117], v[170:173], v[186:189], v[114:117]
	v_mfma_f32_16x16x32_bf16 v[106:109], v[178:181], v[186:189], v[106:109]
	v_mfma_f32_16x16x32_bf16 v[98:101], v[170:173], v[194:197], v[98:101]
	v_mfma_f32_16x16x32_bf16 v[90:93], v[178:181], v[194:197], v[90:93]
	v_mfma_f32_16x16x32_bf16 v[82:85], v[170:173], v[202:205], v[82:85]
	v_mfma_f32_16x16x32_bf16 v[74:77], v[178:181], v[202:205], v[74:77]
	v_mfma_f32_16x16x32_bf16 v[70:73], v[170:173], v[210:213], v[70:73]
	v_mfma_f32_16x16x32_bf16 v[66:69], v[178:181], v[210:213], v[66:69]
	s_barrier
; #define PG8_STAGE(bufoff, gbase, voff) do { _Pragma("unroll") for (int _i = 0; _i < 2; ++_i) \
;         __builtin_amdgcn_global_load_lds((const unsigned*)((const char*)(gbase) + (voff)[_i]), (PG8_LAS unsigned*)(lds + (bufoff) + ldsw + _i * 8192), 16, 0, 0); } while (0)
; #define PG8_LDA(dst, b, h) do { _Pragma("unroll") for (int m = 0; m < 4; ++m) _Pragma("unroll") for (int k = 0; k < 2; ++k) dst[m][k] = *(const PG8_LAS bf16x8*)(lds + PG8_SA(b, h) + aoff + m * 2048 + k * 1024); } while (0)
; #define PG8_MMA(ai, bj, At, Bt) do { __builtin_amdgcn_s_setprio(1); _Pragma("unroll") for (int m = 0; m < 4; ++m) _Pragma("unroll") for (int n = 0; n < 2; ++n) _Pragma("unroll") for (int k = 0; k < 2; ++k) \
;         acc[ai][bj][m][n] = __builtin_amdgcn_mfma_f32_16x16x32_bf16(Bt[n][k], At[m][k], acc[ai][bj][m][n], 0, 0, 0); __builtin_amdgcn_s_setprio(0); } while (0)
; #define PG8_WAIT_V(n) asm volatile("s_waitcnt vmcnt(" #n ")" ::: "memory")
; #define PG8_WAIT_L(n) asm volatile("s_waitcnt lgkmcnt(" #n ")" ::: "memory")
; #define PG8_BAR __builtin_amdgcn_s_barrier()
; #define PG8_SCHED __builtin_amdgcn_sched_barrier(0)
; template <class Epi, class Sched, bool ALIGN_EPI = false>
; __device__ __forceinline__ void gemm_phase(PG8_LAS unsigned char* lds, const Gemm g, const Sched& S, const Epi& E) {
;     ...
;             PG8_LDA(At, 1, 1); PG8_STAGE(PG8_SB(1, 0), b3, voffB); PG8_STAGE(PG8_SB(1, 1), b3 + hstepB, voffB); PG8_STAGE(PG8_SA(1, 0), a3, voffA);
;             PG8_WAIT_V(8); PG8_WAIT_L(0); PG8_BAR; PG8_MMA(1, 0, At, B0); PG8_MMA(1, 1, At, B1); PG8_BAR; PG8_SCHED;
;         }
;         if constexpr (ALIGN_EPI) { if (wr == 0) PG8_BAR; }
	s_add_i32 s28, s53, s34
	v_lshl_add_u64 v[214:215], v[214:215], 0, s[10:11]
	s_mov_b32 m0, s28
	ds_read_b128 v[182:185], v152 offset:49152
	ds_read_b128 v[186:189], v152 offset:50176
	ds_read_b128 v[190:193], v152 offset:51200
	ds_read_b128 v[194:197], v152 offset:52224
	ds_read_b128 v[198:201], v152 offset:53248
	ds_read_b128 v[202:205], v152 offset:54272
	ds_read_b128 v[206:209], v152 offset:55296
	ds_read_b128 v[210:213], v152 offset:56320
	global_load_lds_dwordx4 v[214:215], off
	s_add_i32 m0, s28, 0x2000
	s_add_u32 s26, s26, 0x100080
	v_lshl_add_u64 v[214:215], v[216:217], 0, s[10:11]
	s_addc_u32 s27, s27, 0
	s_add_i32 s28, s54, s34
	global_load_lds_dwordx4 v[214:215], off
	v_lshl_add_u64 v[214:215], s[26:27], 0, v[134:135]
	s_mov_b32 m0, s28
	s_nop 0
	global_load_lds_dwordx4 v[214:215], off
	v_lshl_add_u64 v[214:215], s[26:27], 0, v[130:131]
	s_add_i32 m0, s28, 0x2000
	s_nop 0
	global_load_lds_dwordx4 v[214:215], off
	v_lshl_add_u64 v[214:215], v[218:219], 0, s[10:11]
	s_mov_b32 m0, s41
	s_nop 0
	global_load_lds_dwordx4 v[214:215], off
	v_lshl_add_u64 v[214:215], v[220:221], 0, s[10:11]
	s_mov_b32 m0, s42
	s_nop 0
	global_load_lds_dwordx4 v[214:215], off
	s_waitcnt vmcnt(8)
	s_waitcnt lgkmcnt(0)
	s_barrier
	s_waitcnt lgkmcnt(0)
	v_mfma_f32_16x16x32_bf16 v[62:65], v[146:149], v[182:185], v[62:65]
	v_mfma_f32_16x16x32_bf16 v[58:61], v[158:161], v[182:185], v[58:61]
	v_mfma_f32_16x16x32_bf16 v[54:57], v[146:149], v[190:193], v[54:57]
	v_mfma_f32_16x16x32_bf16 v[46:49], v[158:161], v[190:193], v[46:49]
	v_mfma_f32_16x16x32_bf16 v[38:41], v[146:149], v[198:201], v[38:41]
	v_mfma_f32_16x16x32_bf16 v[30:33], v[158:161], v[198:201], v[30:33]
	v_mfma_f32_16x16x32_bf16 v[22:25], v[146:149], v[206:209], v[22:25]
	v_mfma_f32_16x16x32_bf16 v[14:17], v[158:161], v[206:209], v[14:17]
	v_mfma_f32_16x16x32_bf16 v[62:65], v[154:157], v[186:189], v[62:65]
	v_mfma_f32_16x16x32_bf16 v[58:61], v[162:165], v[186:189], v[58:61]
	v_mfma_f32_16x16x32_bf16 v[54:57], v[154:157], v[194:197], v[54:57]
	v_mfma_f32_16x16x32_bf16 v[46:49], v[162:165], v[194:197], v[46:49]
	v_mfma_f32_16x16x32_bf16 v[38:41], v[154:157], v[202:205], v[38:41]
	v_mfma_f32_16x16x32_bf16 v[30:33], v[162:165], v[202:205], v[30:33]
	v_mfma_f32_16x16x32_bf16 v[22:25], v[154:157], v[210:213], v[22:25]
	v_mfma_f32_16x16x32_bf16 v[14:17], v[162:165], v[210:213], v[14:17]
	v_mfma_f32_16x16x32_bf16 v[50:53], v[166:169], v[182:185], v[50:53]
	v_mfma_f32_16x16x32_bf16 v[42:45], v[174:177], v[182:185], v[42:45]
	v_mfma_f32_16x16x32_bf16 v[34:37], v[166:169], v[190:193], v[34:37]
	v_mfma_f32_16x16x32_bf16 v[26:29], v[174:177], v[190:193], v[26:29]
	v_mfma_f32_16x16x32_bf16 v[18:21], v[166:169], v[198:201], v[18:21]
	v_mfma_f32_16x16x32_bf16 v[10:13], v[174:177], v[198:201], v[10:13]
	v_mfma_f32_16x16x32_bf16 v[6:9], v[166:169], v[206:209], v[6:9]
	v_mfma_f32_16x16x32_bf16 v[2:5], v[174:177], v[206:209], v[2:5]
	v_mfma_f32_16x16x32_bf16 v[50:53], v[170:173], v[186:189], v[50:53]
	v_mfma_f32_16x16x32_bf16 v[42:45], v[178:181], v[186:189], v[42:45]
	v_mfma_f32_16x16x32_bf16 v[34:37], v[170:173], v[194:197], v[34:37]
	v_mfma_f32_16x16x32_bf16 v[26:29], v[178:181], v[194:197], v[26:29]
	v_mfma_f32_16x16x32_bf16 v[18:21], v[170:173], v[202:205], v[18:21]
	v_mfma_f32_16x16x32_bf16 v[10:13], v[178:181], v[202:205], v[10:13]
	v_mfma_f32_16x16x32_bf16 v[6:9], v[170:173], v[210:213], v[6:9]
	v_mfma_f32_16x16x32_bf16 v[2:5], v[178:181], v[210:213], v[2:5]
	s_barrier
	s_add_i32 s52, s52, 2
	s_add_u32 s24, s24, 0x100
	s_addc_u32 s25, s25, 0
	s_add_u32 s50, s50, 0x100
	s_addc_u32 s51, s51, 0
	s_cmp_gt_u32 s52, 61
	s_cbranch_scc0 .LBB0_933
	s_and_b64 vcc, exec, s[12:13]
	s_cbranch_vccz .LBB0_936
	s_barrier

; __device__ __forceinline__ unsigned xb_ld(unsigned* p)              { return __hip_atomic_load(p, __ATOMIC_RELAXED, __HIP_MEMORY_SCOPE_AGENT); }
; __device__ __forceinline__ void xcd_barrier_complete(unsigned* bar, unsigned x, unsigned& nloc, unsigned& nx) {
;     const unsigned G = gridDim.x * gridDim.y * gridDim.z;
;     unsigned sum, cnt, mine, sp = 0u;
;     for (;;) {
;         sum = 0u; cnt = 0u; mine = 0u;
; #pragma unroll
;         for (unsigned j = 0; j < 16; ++j) { const unsigned c = xb_ld(&bar[XB_XCNT(j)]); sum += c; cnt += (c > 0u) ? 1u : 0u; mine = (j == x) ? c : mine; }
;         if (sum == G) break;
; __device__ __forceinline__ void xcd_barrier(const XcdBarrier& b) {
;     asm volatile("s_waitcnt vmcnt(0)" ::: "memory");
;     __syncthreads();
;     if (threadIdx.x == 0) {
;         unsigned* bar = b.bar;
;         __builtin_amdgcn_s_waitcnt(0);
;         unsigned nloc = b.st[0], nx = b.st[1];
;         if (nloc == 0u) { xcd_barrier_complete(bar, b.x, nloc, nx); b.st[0] = nloc; b.st[1] = nx; }
.LBB0_951:
	s_setprio 0
	s_cmp_gt_i32 s59, 13
	s_cselect_b64 s[2:3], -1, 0
	s_and_b64 s[0:1], s[4:5], s[2:3]
	s_andn2_b64 vcc, exec, s[0:1]
	s_cbranch_vccnz .LBB0_1001
	s_waitcnt vmcnt(0)
	v_cmp_eq_u32_e32 vcc, 0, v0
	s_waitcnt vmcnt(0)
	s_barrier
	s_and_saveexec_b64 s[4:5], vcc
	s_cbranch_execz .LBB0_1000
	v_readlane_b32 s0, v228, 5
	s_waitcnt vmcnt(0) expcnt(0) lgkmcnt(0)
	s_nop 0
	v_mov_b32_e32 v1, s0
	ds_read_b32 v3, v1
	ds_read_b32 v1, v1 offset:4
	s_waitcnt lgkmcnt(1)
	v_cmp_ne_u32_e32 vcc, 0, v3
	s_cbranch_vccnz .LBB0_968
	v_readlane_b32 s6, v228, 0
	v_readlane_b32 s7, v228, 1
	s_load_dwordx2 s[0:1], s[6:7], 0x4
	s_add_u32 s6, s56, 0x4200
	s_addc_u32 s7, s57, 0
	s_add_u32 s8, s56, 0x4400
	s_addc_u32 s9, s57, 0
	s_add_u32 s10, s56, 0x4500
	s_addc_u32 s11, s57, 0
	s_add_u32 s12, s56, 0x4600
	s_addc_u32 s13, s57, 0
	s_add_u32 s14, s56, 0x4700
	s_addc_u32 s15, s57, 0
	s_add_u32 s16, s56, 0x4800
	s_addc_u32 s17, s57, 0
	s_add_u32 s18, s56, 0x4900
	s_addc_u32 s19, s57, 0
	s_add_u32 s20, s56, 0x4a00
	s_addc_u32 s21, s57, 0
	s_add_u32 s22, s56, 0x4b00
	s_addc_u32 s23, s57, 0
	s_add_u32 s24, s56, 0x4c00
	s_addc_u32 s25, s57, 0
	s_add_u32 s26, s56, 0x4d00
	s_addc_u32 s27, s57, 0
	s_add_u32 s28, s56, 0x4e00
	s_addc_u32 s29, s57, 0
	s_add_u32 s30, s56, 0x4f00
	s_addc_u32 s31, s57, 0
	s_add_u32 s34, s56, 0x5000
	s_addc_u32 s35, s57, 0
	s_add_u32 s36, s56, 0x5100
	s_addc_u32 s37, s57, 0
	s_add_u32 s38, s56, 0x5200
	s_addc_u32 s39, s57, 0
	s_waitcnt lgkmcnt(0)
	s_mul_i32 s0, s0, s86
	s_add_u32 s40, s56, 0x5300
	s_mul_i32 s0, s0, s1
	s_addc_u32 s41, s57, 0
	s_mov_b32 s1, 1
	v_mov_b32_e32 v17, 0
	s_branch .LBB0_956

; #define PG8_STAGE(bufoff, gbase, voff) do { _Pragma("unroll") for (int _i = 0; _i < 2; ++_i) \
;         __builtin_amdgcn_global_load_lds((const unsigned*)((const char*)(gbase) + (voff)[_i]), (PG8_LAS unsigned*)(lds + (bufoff) + ldsw + _i * 8192), 16, 0, 0); } while (0)
; #define PG8_BAR __builtin_amdgcn_s_barrier()
; template <class Epi, class Sched, bool ALIGN_EPI = false>
; __device__ __forceinline__ void gemm_phase(PG8_LAS unsigned char* lds, const Gemm g, const Sched& S, const Epi& E) {
;     int tid_ = threadIdx.x; asm volatile("" : "+v"(tid_));
;     const int tid = tid_, wid = __builtin_amdgcn_readfirstlane(tid >> 6), lane = tid & 63, wr = wid >> 2, wc = wid & 3, fr = lane & 15, fq = lane >> 4;
;     const int K = g.K, nt = K / BK;
;     unsigned voffA[2], voffB[2];
; #pragma unroll
;     for (int i = 0; i < 2; ++i) { int R, C; stage_rc(tid * 16 + i * 8192, R, C); const int Rb = Epi::PERM ? ((R & ~31) + perm32(R & 31)) : R;
;         voffA[i] = (unsigned)(R * g.lda + C) * 2u; voffB[i] = (unsigned)(Rb * g.ldb + C) * 2u; }
;     const size_t kstep = (size_t)(BK * 2);
;     const size_t hstepA = (size_t)HALF * g.lda * 2, hstepB = (size_t)HALF * g.ldb * 2;
;     const size_t tstepA = 2 * hstepA, tstepB = 2 * hstepB;
;     const unsigned ldsw = (unsigned)wid * 1024u;
;     const int aoff = lds_byte(wr * 64 + fr, fq * 8), boff = lds_byte(wc * 32 + fr, fq * 8);
;     ...
;     Unit cur, nxt; int ui = 0;
;     if (!S.next(0, cur)) return;
;     f32x4 acc[2][2][4][2];
; #pragma unroll
;     for (int a = 0; a < 2; ++a)
; #pragma unroll
;         for (int b = 0; b < 2; ++b)
; #pragma unroll
;             for (int m = 0; m < 4; ++m)
; #pragma unroll
;                 for (int n = 0; n < 2; ++n) acc[a][b][m][n] = (f32x4){0.f, 0.f, 0.f, 0.f};
;     bf16x8 At[4][2], B0[2][2], B1[2][2];
;     const char* cA = (const char*)g.A + (size_t)cur.pm * tstepA; const char* cB = (const char*)g.Bt + (size_t)cur.pn * tstepB;
;     S.a_ready(cur);
;     PG8_STAGE(PG8_SB(0, 0), cB, voffB); PG8_STAGE(PG8_SB(0, 1), cB + hstepB, voffB); PG8_STAGE(PG8_SA(0, 0), cA, voffA); PG8_STAGE(PG8_SA(0, 1), cA + hstepA, voffA);
;     if (wr == 1) PG8_BAR;
.LBB0_1152:
	s_cmp_lt_i32 s58, 15
	s_cselect_b64 s[0:1], -1, 0
	s_and_b64 s[8:9], s[0:1], s[2:3]
	s_andn2_b64 vcc, exec, s[8:9]
	s_cbranch_vccnz .LBB0_1218
	v_readfirstlane_b32 s98, v0
	s_nop 3
	s_lshr_b32 s98, s98, 8
	s_cmp_eq_u32 s98, 0
	s_cbranch_scc0 .Lmy_prio5
	s_setprio 1
.Lmy_prio5:
	s_ashr_i32 s51, s33, 31
	s_lshr_b32 s0, s51, 29
	s_add_i32 s0, s33, s0
	s_ashr_i32 s52, s0, 3
	s_and_b32 s0, s0, -8
	s_ashr_i32 s50, s86, 31
	s_sub_i32 s53, s33, s0
	s_cmp_lt_i32 s53, 0
	s_mov_b64 s[18:19], s[82:83]
	s_movk_i32 s2, 0x100
	v_mov_b32_e32 v1, v0
	s_cselect_b64 s[10:11], -1, 0
	s_cmpk_gt_i32 s33, 0x2ff
	s_movk_i32 s30, 0x100
	s_nop 0
	v_readfirstlane_b32 s5, v1
	s_cbranch_scc1 .LBB0_1172
	v_lshlrev_b32_e32 v2, 4, v1
	v_add_u32_e32 v3, 0x2000, v2
	v_ashrrev_i32_e32 v4, 31, v3
	v_lshrrev_b32_e32 v4, 22, v4
	v_add_u32_e32 v4, v3, v4
	v_ashrrev_i32_e32 v14, 10, v4
	v_mul_i32_i24_e32 v4, 0x400, v14
	v_sub_u32_e32 v3, v3, v4
	v_lshrrev_b32_e32 v4, 4, v3
	v_bitop3_b32 v3, v4, v3, 32 bitop3:0x6c
	v_ashrrev_i32_e32 v4, 31, v3
	v_lshrrev_b32_e32 v4, 26, v4
	v_add_u32_e32 v4, v3, v4
	v_lshlrev_b32_e32 v5, 3, v14
	v_ashrrev_i32_e32 v15, 6, v4
	v_and_b32_e32 v5, -16, v5
	v_add_u32_e32 v5, v15, v5
	v_and_b32_e32 v6, 3, v15
	s_mov_b32 s4, 0x7fffffe0
	v_lshrrev_b32_e32 v7, 2, v5
	v_lshlrev_b32_e32 v8, 1, v5
	v_and_b32_e32 v4, 0xc0, v4
	v_and_or_b32 v6, v5, s4, v6
	v_and_b32_e32 v7, 4, v7
	v_and_b32_e32 v8, 24, v8
	v_sub_u32_e32 v3, v3, v4
	v_mov_b32_e32 v4, 1
	v_or3_b32 v6, v6, v7, v8
	v_lshlrev_b32_e32 v7, 5, v14
	v_ashrrev_i16_sdwa v3, v4, sext(v3) dst_sel:DWORD dst_unused:UNUSED_PAD src0_sel:DWORD src1_sel:BYTE_0
	v_and_b32_e32 v7, 32, v7
	v_bfe_i32 v16, v3, 0, 16
	v_mul_lo_u32 v6, v6, s2
	v_add_u32_e32 v3, v7, v16
	v_lshlrev_b32_e32 v5, 11, v5
	v_add_lshl_u32 v138, v6, v3, 1
	v_lshl_add_u32 v140, v3, 1, v5
	v_bfe_i32 v3, v1, 27, 1
	v_lshrrev_b32_e32 v3, 22, v3
	v_add_u32_e32 v3, v2, v3
	v_and_b32_e32 v3, 0xfffffc00, v3
	v_sub_u32_e32 v2, v2, v3
	v_lshrrev_b32_e32 v3, 4, v2
	v_ashrrev_i32_e32 v5, 31, v1
	s_add_u32 s0, s56, 0xb7900000
	v_bitop3_b32 v2, v3, v2, 32 bitop3:0x6c
	v_lshrrev_b32_e32 v5, 26, v5
	s_addc_u32 s1, s57, 0
	v_ashrrev_i32_e32 v3, 31, v2
	v_add_u32_e32 v5, v1, v5
	s_add_u32 s31, s56, 0xca00000
	v_lshrrev_b32_e32 v3, 26, v3
	v_ashrrev_i32_e32 v18, 6, v5
	s_addc_u32 s44, s57, 0
	s_ashr_i32 s6, s5, 6
	s_ashr_i32 s3, s2, 31
	v_add_u32_e32 v3, v2, v3
	v_lshlrev_b32_e32 v5, 3, v18
	s_ashr_i32 s7, s5, 8
	s_waitcnt lgkmcnt(0)
	s_lshl_b64 s[12:13], s[2:3], 8
	s_lshl_b64 s[14:15], s[2:3], 9
	s_lshl_b32 s45, s6, 10
	v_ashrrev_i32_e32 v17, 6, v3
	v_and_b32_e32 v5, -16, v5
	v_add_u32_e32 v5, v17, v5
	v_and_b32_e32 v6, 3, v17
	s_movk_i32 s46, 0x61
	s_and_b64 s[16:17], s[10:11], exec
	v_and_or_b32 v6, v5, s4, v6
	s_cselect_b32 s4, s46, 0x60
	s_mul_i32 s4, s53, s4
	s_add_i32 s4, s4, s52
	s_mul_hi_i32 s16, s4, 0x2aaaaaab
	s_lshr_b32 s17, s16, 31
	s_ashr_i32 s16, s16, 5
	s_add_i32 s16, s16, s17
	s_lshl_b32 s17, s16, 3
	s_mulk_i32 s16, 0xc0
	s_sub_i32 s16, s4, s16
	s_sext_i32_i16 s4, s16
	s_bfe_u32 s4, s4, 0x3001c
	s_add_i32 s20, s16, s4
	s_sext_i32_i16 s22, s20
	s_lshr_b32 s4, s22, 3
	s_and_b32 s20, s20, 0xfff8
	s_sub_i32 s16, s16, s20
	s_bfe_i64 s[20:21], s[4:5], 0x100000
	s_ashr_i32 s22, s22, 3
	s_sext_i32_i16 s16, s16
	s_mul_hi_u32 s20, s14, s22
	s_mul_i32 s21, s14, s21
	v_lshrrev_b32_e32 v7, 2, v5
	v_lshlrev_b32_e32 v8, 1, v5
	v_and_b32_e32 v3, 0xc0, v3
	s_add_i32 s38, s17, s16
	s_add_i32 s23, s20, s21
	s_lshr_b64 s[20:21], s[2:3], 23
	v_and_b32_e32 v7, 4, v7
	v_and_b32_e32 v8, 24, v8
	v_sub_u32_e32 v2, v2, v3
	s_ashr_i32 s39, s38, 31
	s_mul_i32 s20, s20, s22
	v_or3_b32 v6, v6, v7, v8
	v_lshlrev_b32_e32 v7, 5, v18
	v_ashrrev_i16_sdwa v2, v4, sext(v2) dst_sel:DWORD dst_unused:UNUSED_PAD src0_sel:DWORD src1_sel:BYTE_0
	s_lshl_b64 s[16:17], s[38:39], 19
	s_add_i32 s23, s23, s20
	s_mul_i32 s20, s14, s22
	v_and_b32_e32 v7, 32, v7
	v_bfe_i32 v19, v2, 0, 16
	s_add_u32 s40, s31, s20
	v_mul_lo_u32 v6, v6, s2
	v_add_u32_e32 v2, v7, v19
	s_addc_u32 s41, s44, s23
	s_add_i32 s39, s45, 0
	v_add_lshl_u32 v142, v6, v2, 1
	s_add_i32 m0, s39, 0x10000
	v_lshlrev_b32_e32 v3, 11, v5
	global_load_lds_dwordx4 v142, s[40:41]
	s_add_i32 m0, s39, 0x12000
	s_add_u32 s22, s40, s12
	global_load_lds_dwordx4 v138, s[40:41]
	s_addc_u32 s23, s41, s13
	s_add_i32 m0, s39, 0x14000
	v_lshl_add_u32 v144, v2, 1, v3
	global_load_lds_dwordx4 v142, s[22:23]
	s_add_i32 m0, s39, 0x16000
	s_add_u32 s42, s0, s16
	s_addc_u32 s43, s1, s17
	s_add_i32 s47, s39, 0x2000
	global_load_lds_dwordx4 v138, s[22:23]
	s_mov_b32 m0, s39
	s_add_u32 s16, s42, 0x40000
	global_load_lds_dwordx4 v144, s[42:43]
	s_mov_b32 m0, s47
	s_addc_u32 s17, s43, 0
	s_add_i32 s48, s39, 0x4000
	global_load_lds_dwordx4 v140, s[42:43]
	s_mov_b32 m0, s48
	s_add_i32 s49, s39, 0x6000
	global_load_lds_dwordx4 v144, s[16:17]
	s_mov_b32 m0, s49
	v_mov_b32_e32 v143, 0
	global_load_lds_dwordx4 v140, s[16:17]
	s_load_dwordx2 s[16:17], s[18:19], 0x58
	s_load_dwordx2 s[20:21], s[18:19], 0x68
	v_mov_b32_e32 v139, v143
	v_mov_b32_e32 v145, v143
	v_mov_b32_e32 v141, v143
	s_cmp_eq_u32 s7, 1
	v_lshl_add_u64 v[10:11], s[40:41], 0, v[142:143]
	v_lshl_add_u64 v[6:7], s[40:41], 0, v[138:139]
	v_lshl_add_u64 v[4:5], s[22:23], 0, v[142:143]
	v_lshl_add_u64 v[2:3], s[22:23], 0, v[138:139]
	v_lshl_add_u64 v[8:9], s[42:43], 0, v[144:145]
	s_cselect_b64 s[22:23], -1, 0
	s_cmp_lg_u32 s7, 1
	v_lshl_add_u64 v[12:13], s[42:43], 0, v[140:141]
	s_cbranch_scc1 .LBB0_1156
	s_barrier

; #define PG8_STAGE(bufoff, gbase, voff) do { _Pragma("unroll") for (int _i = 0; _i < 2; ++_i) \
;         __builtin_amdgcn_global_load_lds((const unsigned*)((const char*)(gbase) + (voff)[_i]), (PG8_LAS unsigned*)(lds + (bufoff) + ldsw + _i * 8192), 16, 0, 0); } while (0)
; #define PG8_LDA(dst, b, h) do { _Pragma("unroll") for (int m = 0; m < 4; ++m) _Pragma("unroll") for (int k = 0; k < 2; ++k) dst[m][k] = *(const PG8_LAS bf16x8*)(lds + PG8_SA(b, h) + aoff + m * 2048 + k * 1024); } while (0)
; #define PG8_LDB(dst, b, h) do { _Pragma("unroll") for (int n = 0; n < 2; ++n) _Pragma("unroll") for (int k = 0; k < 2; ++k) dst[n][k] = *(const PG8_LAS bf16x8*)(lds + PG8_SB(b, h) + boff + n * 2048 + k * 1024); } while (0)
; #define PG8_MMA(ai, bj, At, Bt) do { __builtin_amdgcn_s_setprio(1); _Pragma("unroll") for (int m = 0; m < 4; ++m) _Pragma("unroll") for (int n = 0; n < 2; ++n) _Pragma("unroll") for (int k = 0; k < 2; ++k) \
;         acc[ai][bj][m][n] = __builtin_amdgcn_mfma_f32_16x16x32_bf16(Bt[n][k], At[m][k], acc[ai][bj][m][n], 0, 0, 0); __builtin_amdgcn_s_setprio(0); } while (0)
; #define PG8_WAIT_V(n) asm volatile("s_waitcnt vmcnt(" #n ")" ::: "memory")
; #define PG8_WAIT_L(n) asm volatile("s_waitcnt lgkmcnt(" #n ")" ::: "memory")
; #define PG8_BAR __builtin_amdgcn_s_barrier()
; template <class Epi, class Sched, bool ALIGN_EPI = false>
; __device__ __forceinline__ void gemm_phase(PG8_LAS unsigned char* lds, const Gemm g, const Sched& S, const Epi& E) {
;     ...
;         for (int t = 0; t < nt; t += 2) {
;             const bool last = (t == nt - 2);
;             const char* a1 = cA + (size_t)(t + 1) * kstep;
;             const char* a2 = last ? nA : cA + (size_t)(t + 2) * kstep; const char* b2 = last ? nB : cB + (size_t)(t + 2) * kstep;
;             const char* a3 = a2 + kstep; const char* b3 = b2 + kstep;
;             if (last && has_next) S.a_ready(nxt);
;             PG8_LDB(B0, 0, 0); PG8_LDB(B1, 0, 1); PG8_SCHED; PG8_LDA(At, 0, 0); PG8_STAGE(PG8_SA(1, 1), a1 + hstepA, voffA);
;             PG8_WAIT_V(8); PG8_WAIT_L(0); PG8_BAR; PG8_MMA(0, 0, At, B0); PG8_MMA(0, 1, At, B1); PG8_BAR; PG8_SCHED;
;             PG8_LDA(At, 0, 1); PG8_STAGE(PG8_SB(0, 0), b2, voffB); PG8_STAGE(PG8_SB(0, 1), b2 + hstepB, voffB); PG8_STAGE(PG8_SA(0, 0), a2, voffA);
;             PG8_WAIT_V(8); PG8_WAIT_L(0); PG8_BAR; PG8_MMA(1, 0, At, B0); PG8_MMA(1, 1, At, B1); PG8_BAR; PG8_SCHED;
.LBB0_1165:
	ds_read_b128 v[130:133], v160
	ds_read_b128 v[134:137], v160 offset:1024
	ds_read_b128 v[154:157], v160 offset:2048
	ds_read_b128 v[164:167], v160 offset:3072
	ds_read_b128 v[168:171], v161
	ds_read_b128 v[172:175], v161 offset:1024
	ds_read_b128 v[176:179], v161 offset:2048
	ds_read_b128 v[180:183], v161 offset:3072
	s_add_i32 s70, s40, 2
	s_add_u32 s71, s6, 0xfffc0080
	s_addc_u32 s41, s7, -1
	s_cmp_eq_u32 s62, s40
	s_cselect_b32 s40, s69, s71
	s_cselect_b32 s41, s29, s41
	s_cselect_b32 s73, s35, s43
	s_cselect_b32 s72, s34, s42
	v_lshl_add_u64 v[158:159], s[6:7], 0, v[146:147]
	s_add_i32 m0, s39, 0xc000
	ds_read_b128 v[184:187], v162
	ds_read_b128 v[188:191], v162 offset:1024
	ds_read_b128 v[192:195], v162 offset:2048
	ds_read_b128 v[196:199], v162 offset:3072
	ds_read_b128 v[200:203], v162 offset:4096
	ds_read_b128 v[204:207], v162 offset:5120
	ds_read_b128 v[208:211], v162 offset:6144
	ds_read_b128 v[212:215], v162 offset:7168
	global_load_lds_dwordx4 v[158:159], off
	v_lshl_add_u64 v[158:159], s[6:7], 0, v[148:149]
	s_add_i32 m0, s39, 0xe000
	s_nop 0
	global_load_lds_dwordx4 v[158:159], off
	s_waitcnt vmcnt(8)
	s_waitcnt lgkmcnt(0)
	s_barrier
	s_waitcnt lgkmcnt(0)
	v_mfma_f32_16x16x32_bf16 v[122:125], v[130:133], v[184:187], v[122:125]
	v_mfma_f32_16x16x32_bf16 v[126:129], v[154:157], v[184:187], v[126:129]
	v_mfma_f32_16x16x32_bf16 v[118:121], v[130:133], v[192:195], v[118:121]
	v_mfma_f32_16x16x32_bf16 v[114:117], v[154:157], v[192:195], v[114:117]
	v_mfma_f32_16x16x32_bf16 v[110:113], v[130:133], v[200:203], v[110:113]
	v_mfma_f32_16x16x32_bf16 v[106:109], v[154:157], v[200:203], v[106:109]
	v_mfma_f32_16x16x32_bf16 v[102:105], v[130:133], v[208:211], v[102:105]
	v_mfma_f32_16x16x32_bf16 v[98:101], v[154:157], v[208:211], v[98:101]
	v_mfma_f32_16x16x32_bf16 v[122:125], v[134:137], v[188:191], v[122:125]
	v_mfma_f32_16x16x32_bf16 v[126:129], v[164:167], v[188:191], v[126:129]
	v_mfma_f32_16x16x32_bf16 v[118:121], v[134:137], v[196:199], v[118:121]
	v_mfma_f32_16x16x32_bf16 v[114:117], v[164:167], v[196:199], v[114:117]
	v_mfma_f32_16x16x32_bf16 v[110:113], v[134:137], v[204:207], v[110:113]
	v_mfma_f32_16x16x32_bf16 v[106:109], v[164:167], v[204:207], v[106:109]
	v_mfma_f32_16x16x32_bf16 v[102:105], v[134:137], v[212:215], v[102:105]
	v_mfma_f32_16x16x32_bf16 v[98:101], v[164:167], v[212:215], v[98:101]
	v_mfma_f32_16x16x32_bf16 v[62:65], v[168:171], v[184:187], v[62:65]
	v_mfma_f32_16x16x32_bf16 v[58:61], v[176:179], v[184:187], v[58:61]
	v_mfma_f32_16x16x32_bf16 v[54:57], v[168:171], v[192:195], v[54:57]
	v_mfma_f32_16x16x32_bf16 v[50:53], v[176:179], v[192:195], v[50:53]
	v_mfma_f32_16x16x32_bf16 v[46:49], v[168:171], v[200:203], v[46:49]
	v_mfma_f32_16x16x32_bf16 v[42:45], v[176:179], v[200:203], v[42:45]
	v_mfma_f32_16x16x32_bf16 v[38:41], v[168:171], v[208:211], v[38:41]
	v_mfma_f32_16x16x32_bf16 v[34:37], v[176:179], v[208:211], v[34:37]
	v_mfma_f32_16x16x32_bf16 v[62:65], v[172:175], v[188:191], v[62:65]
	v_mfma_f32_16x16x32_bf16 v[58:61], v[180:183], v[188:191], v[58:61]
	v_mfma_f32_16x16x32_bf16 v[54:57], v[172:175], v[196:199], v[54:57]
	v_mfma_f32_16x16x32_bf16 v[50:53], v[180:183], v[196:199], v[50:53]
	v_mfma_f32_16x16x32_bf16 v[46:49], v[172:175], v[204:207], v[46:49]
	v_mfma_f32_16x16x32_bf16 v[42:45], v[180:183], v[204:207], v[42:45]
	v_mfma_f32_16x16x32_bf16 v[38:41], v[172:175], v[212:215], v[38:41]
	v_mfma_f32_16x16x32_bf16 v[34:37], v[180:183], v[212:215], v[34:37]
	s_barrier
	s_add_i32 s71, s63, s45
	v_lshl_add_u64 v[158:159], s[72:73], 0, v[142:143]
	s_mov_b32 m0, s71
	ds_read_b128 v[184:187], v162 offset:16384
	ds_read_b128 v[188:191], v162 offset:17408
	ds_read_b128 v[192:195], v162 offset:18432
	ds_read_b128 v[196:199], v162 offset:19456
	ds_read_b128 v[200:203], v162 offset:20480
	ds_read_b128 v[204:207], v162 offset:21504
	ds_read_b128 v[208:211], v162 offset:22528
	ds_read_b128 v[212:215], v162 offset:23552
	global_load_lds_dwordx4 v[158:159], off
	s_add_i32 m0, s71, 0x2000
	v_lshl_add_u64 v[216:217], s[72:73], 0, v[138:139]
	s_add_u32 s72, s72, s12
	s_addc_u32 s73, s73, s13
	s_add_i32 s71, s64, s45
	global_load_lds_dwordx4 v[216:217], off
	v_lshl_add_u64 v[218:219], s[72:73], 0, v[142:143]
	s_mov_b32 m0, s71
	v_lshl_add_u64 v[220:221], s[72:73], 0, v[138:139]
	global_load_lds_dwordx4 v[218:219], off
	s_add_i32 m0, s71, 0x2000
	v_lshl_add_u64 v[222:223], s[40:41], 0, v[144:145]
	global_load_lds_dwordx4 v[220:221], off
	s_mov_b32 m0, s39
	v_lshl_add_u64 v[224:225], s[40:41], 0, v[140:141]
	global_load_lds_dwordx4 v[222:223], off
	s_mov_b32 m0, s47
	s_nop 0
	global_load_lds_dwordx4 v[224:225], off
	s_waitcnt vmcnt(8)
	s_waitcnt lgkmcnt(0)
	s_barrier
; #define PG8_STAGE(bufoff, gbase, voff) do { _Pragma("unroll") for (int _i = 0; _i < 2; ++_i) \
;         __builtin_amdgcn_global_load_lds((const unsigned*)((const char*)(gbase) + (voff)[_i]), (PG8_LAS unsigned*)(lds + (bufoff) + ldsw + _i * 8192), 16, 0, 0); } while (0)
; #define PG8_LDA(dst, b, h) do { _Pragma("unroll") for (int m = 0; m < 4; ++m) _Pragma("unroll") for (int k = 0; k < 2; ++k) dst[m][k] = *(const PG8_LAS bf16x8*)(lds + PG8_SA(b, h) + aoff + m * 2048 + k * 1024); } while (0)
; #define PG8_LDB(dst, b, h) do { _Pragma("unroll") for (int n = 0; n < 2; ++n) _Pragma("unroll") for (int k = 0; k < 2; ++k) dst[n][k] = *(const PG8_LAS bf16x8*)(lds + PG8_SB(b, h) + boff + n * 2048 + k * 1024); } while (0)
; #define PG8_MMA(ai, bj, At, Bt) do { __builtin_amdgcn_s_setprio(1); _Pragma("unroll") for (int m = 0; m < 4; ++m) _Pragma("unroll") for (int n = 0; n < 2; ++n) _Pragma("unroll") for (int k = 0; k < 2; ++k) \
;         acc[ai][bj][m][n] = __builtin_amdgcn_mfma_f32_16x16x32_bf16(Bt[n][k], At[m][k], acc[ai][bj][m][n], 0, 0, 0); __builtin_amdgcn_s_setprio(0); } while (0)
; #define PG8_WAIT_V(n) asm volatile("s_waitcnt vmcnt(" #n ")" ::: "memory")
; #define PG8_WAIT_L(n) asm volatile("s_waitcnt lgkmcnt(" #n ")" ::: "memory")
; #define PG8_BAR __builtin_amdgcn_s_barrier()
; #define PG8_SCHED __builtin_amdgcn_sched_barrier(0)
; template <class Epi, class Sched, bool ALIGN_EPI = false>
; __device__ __forceinline__ void gemm_phase(PG8_LAS unsigned char* lds, const Gemm g, const Sched& S, const Epi& E) {
;     ...
;             PG8_WAIT_V(8); PG8_WAIT_L(0); PG8_BAR; PG8_MMA(1, 0, At, B0); PG8_MMA(1, 1, At, B1); PG8_BAR; PG8_SCHED;
;             PG8_LDB(B0, 1, 0); PG8_LDB(B1, 1, 1); PG8_SCHED; PG8_LDA(At, 1, 0); PG8_STAGE(PG8_SA(0, 1), a2 + hstepA, voffA);
;             PG8_WAIT_V(8); PG8_WAIT_L(0); PG8_BAR; PG8_MMA(0, 0, At, B0); PG8_MMA(0, 1, At, B1); PG8_BAR; PG8_SCHED;
	s_waitcnt lgkmcnt(0)
	v_mfma_f32_16x16x32_bf16 v[94:97], v[130:133], v[184:187], v[94:97]
	v_mfma_f32_16x16x32_bf16 v[90:93], v[154:157], v[184:187], v[90:93]
	v_mfma_f32_16x16x32_bf16 v[86:89], v[130:133], v[192:195], v[86:89]
	v_mfma_f32_16x16x32_bf16 v[82:85], v[154:157], v[192:195], v[82:85]
	v_mfma_f32_16x16x32_bf16 v[78:81], v[130:133], v[200:203], v[78:81]
	v_mfma_f32_16x16x32_bf16 v[74:77], v[154:157], v[200:203], v[74:77]
	v_mfma_f32_16x16x32_bf16 v[70:73], v[130:133], v[208:211], v[70:73]
	v_mfma_f32_16x16x32_bf16 v[66:69], v[154:157], v[208:211], v[66:69]
	v_mfma_f32_16x16x32_bf16 v[94:97], v[134:137], v[188:191], v[94:97]
	v_mfma_f32_16x16x32_bf16 v[90:93], v[164:167], v[188:191], v[90:93]
	v_mfma_f32_16x16x32_bf16 v[86:89], v[134:137], v[196:199], v[86:89]
	v_mfma_f32_16x16x32_bf16 v[82:85], v[164:167], v[196:199], v[82:85]
	v_mfma_f32_16x16x32_bf16 v[78:81], v[134:137], v[204:207], v[78:81]
	v_mfma_f32_16x16x32_bf16 v[74:77], v[164:167], v[204:207], v[74:77]
	v_mfma_f32_16x16x32_bf16 v[70:73], v[134:137], v[212:215], v[70:73]
	v_mfma_f32_16x16x32_bf16 v[66:69], v[164:167], v[212:215], v[66:69]
	v_mfma_f32_16x16x32_bf16 v[30:33], v[168:171], v[184:187], v[30:33]
	v_mfma_f32_16x16x32_bf16 v[26:29], v[176:179], v[184:187], v[26:29]
	v_mfma_f32_16x16x32_bf16 v[22:25], v[168:171], v[192:195], v[22:25]
	v_mfma_f32_16x16x32_bf16 v[18:21], v[176:179], v[192:195], v[18:21]
	v_mfma_f32_16x16x32_bf16 v[14:17], v[168:171], v[200:203], v[14:17]
	v_mfma_f32_16x16x32_bf16 v[10:13], v[176:179], v[200:203], v[10:13]
	v_mfma_f32_16x16x32_bf16 v[6:9], v[168:171], v[208:211], v[6:9]
	v_mfma_f32_16x16x32_bf16 v[2:5], v[176:179], v[208:211], v[2:5]
	v_mfma_f32_16x16x32_bf16 v[30:33], v[172:175], v[188:191], v[30:33]
	v_mfma_f32_16x16x32_bf16 v[26:29], v[180:183], v[188:191], v[26:29]
	v_mfma_f32_16x16x32_bf16 v[22:25], v[172:175], v[196:199], v[22:25]
	v_mfma_f32_16x16x32_bf16 v[18:21], v[180:183], v[196:199], v[18:21]
	v_mfma_f32_16x16x32_bf16 v[14:17], v[172:175], v[204:207], v[14:17]
	v_mfma_f32_16x16x32_bf16 v[10:13], v[180:183], v[204:207], v[10:13]
	v_mfma_f32_16x16x32_bf16 v[6:9], v[172:175], v[212:215], v[6:9]
	v_mfma_f32_16x16x32_bf16 v[2:5], v[180:183], v[212:215], v[2:5]
	s_barrier
	s_add_i32 s71, 0, 0x18000
	s_add_i32 s72, 0, 0x1c000
	v_add_u32_e32 v164, s71, v1
	v_add_u32_e32 v180, s72, v1
	ds_read_b128 v[130:133], v164
	ds_read_b128 v[134:137], v164 offset:1024
	ds_read_b128 v[154:157], v164 offset:2048
	ds_read_b128 v[164:167], v164 offset:3072
	ds_read_b128 v[168:171], v180
	ds_read_b128 v[172:175], v180 offset:1024
	ds_read_b128 v[176:179], v180 offset:2048
	ds_read_b128 v[180:183], v180 offset:3072
	s_add_u32 s40, s40, 0x40000
	s_addc_u32 s41, s41, 0
	s_mov_b32 m0, s48
	v_lshl_add_u64 v[226:227], s[40:41], 0, v[144:145]
	ds_read_b128 v[184:187], v162 offset:32768
	ds_read_b128 v[188:191], v162 offset:33792
	ds_read_b128 v[192:195], v162 offset:34816
	ds_read_b128 v[196:199], v162 offset:35840
	ds_read_b128 v[200:203], v162 offset:36864
	ds_read_b128 v[204:207], v162 offset:37888
	ds_read_b128 v[208:211], v162 offset:38912
	ds_read_b128 v[212:215], v162 offset:39936
	global_load_lds_dwordx4 v[226:227], off
	v_lshl_add_u64 v[226:227], s[40:41], 0, v[140:141]
	s_mov_b32 m0, s49
	s_nop 0
	global_load_lds_dwordx4 v[226:227], off
	s_waitcnt vmcnt(8)
	s_waitcnt lgkmcnt(0)
	s_barrier
	s_waitcnt lgkmcnt(0)
	v_mfma_f32_16x16x32_bf16 v[122:125], v[130:133], v[184:187], v[122:125]
	v_mfma_f32_16x16x32_bf16 v[126:129], v[154:157], v[184:187], v[126:129]
	v_mfma_f32_16x16x32_bf16 v[118:121], v[130:133], v[192:195], v[118:121]
	v_mfma_f32_16x16x32_bf16 v[114:117], v[154:157], v[192:195], v[114:117]
	v_mfma_f32_16x16x32_bf16 v[110:113], v[130:133], v[200:203], v[110:113]
	v_mfma_f32_16x16x32_bf16 v[106:109], v[154:157], v[200:203], v[106:109]
	v_mfma_f32_16x16x32_bf16 v[102:105], v[130:133], v[208:211], v[102:105]
	v_mfma_f32_16x16x32_bf16 v[98:101], v[154:157], v[208:211], v[98:101]
	v_mfma_f32_16x16x32_bf16 v[122:125], v[134:137], v[188:191], v[122:125]
	v_mfma_f32_16x16x32_bf16 v[126:129], v[164:167], v[188:191], v[126:129]
	v_mfma_f32_16x16x32_bf16 v[118:121], v[134:137], v[196:199], v[118:121]
	v_mfma_f32_16x16x32_bf16 v[114:117], v[164:167], v[196:199], v[114:117]
	v_mfma_f32_16x16x32_bf16 v[110:113], v[134:137], v[204:207], v[110:113]
	v_mfma_f32_16x16x32_bf16 v[106:109], v[164:167], v[204:207], v[106:109]
	v_mfma_f32_16x16x32_bf16 v[102:105], v[134:137], v[212:215], v[102:105]
	v_mfma_f32_16x16x32_bf16 v[98:101], v[164:167], v[212:215], v[98:101]
	v_mfma_f32_16x16x32_bf16 v[62:65], v[168:171], v[184:187], v[62:65]
	v_mfma_f32_16x16x32_bf16 v[58:61], v[176:179], v[184:187], v[58:61]
	v_mfma_f32_16x16x32_bf16 v[54:57], v[168:171], v[192:195], v[54:57]
	v_mfma_f32_16x16x32_bf16 v[50:53], v[176:179], v[192:195], v[50:53]
	v_mfma_f32_16x16x32_bf16 v[46:49], v[168:171], v[200:203], v[46:49]
	v_mfma_f32_16x16x32_bf16 v[42:45], v[176:179], v[200:203], v[42:45]
	v_mfma_f32_16x16x32_bf16 v[38:41], v[168:171], v[208:211], v[38:41]
	v_mfma_f32_16x16x32_bf16 v[34:37], v[176:179], v[208:211], v[34:37]
	v_mfma_f32_16x16x32_bf16 v[62:65], v[172:175], v[188:191], v[62:65]
	v_mfma_f32_16x16x32_bf16 v[58:61], v[180:183], v[188:191], v[58:61]
	v_mfma_f32_16x16x32_bf16 v[54:57], v[172:175], v[196:199], v[54:57]
	v_mfma_f32_16x16x32_bf16 v[50:53], v[180:183], v[196:199], v[50:53]
	v_mfma_f32_16x16x32_bf16 v[46:49], v[172:175], v[204:207], v[46:49]
	v_mfma_f32_16x16x32_bf16 v[42:45], v[180:183], v[204:207], v[42:45]
	v_mfma_f32_16x16x32_bf16 v[38:41], v[172:175], v[212:215], v[38:41]
	v_mfma_f32_16x16x32_bf16 v[34:37], v[180:183], v[212:215], v[34:37]
	s_barrier
; #define PG8_STAGE(bufoff, gbase, voff) do { _Pragma("unroll") for (int _i = 0; _i < 2; ++_i) \
;         __builtin_amdgcn_global_load_lds((const unsigned*)((const char*)(gbase) + (voff)[_i]), (PG8_LAS unsigned*)(lds + (bufoff) + ldsw + _i * 8192), 16, 0, 0); } while (0)
; #define PG8_LDA(dst, b, h) do { _Pragma("unroll") for (int m = 0; m < 4; ++m) _Pragma("unroll") for (int k = 0; k < 2; ++k) dst[m][k] = *(const PG8_LAS bf16x8*)(lds + PG8_SA(b, h) + aoff + m * 2048 + k * 1024); } while (0)
; #define PG8_MMA(ai, bj, At, Bt) do { __builtin_amdgcn_s_setprio(1); _Pragma("unroll") for (int m = 0; m < 4; ++m) _Pragma("unroll") for (int n = 0; n < 2; ++n) _Pragma("unroll") for (int k = 0; k < 2; ++k) \
;         acc[ai][bj][m][n] = __builtin_amdgcn_mfma_f32_16x16x32_bf16(Bt[n][k], At[m][k], acc[ai][bj][m][n], 0, 0, 0); __builtin_amdgcn_s_setprio(0); } while (0)
; #define PG8_WAIT_V(n) asm volatile("s_waitcnt vmcnt(" #n ")" ::: "memory")
; #define PG8_WAIT_L(n) asm volatile("s_waitcnt lgkmcnt(" #n ")" ::: "memory")
; #define PG8_BAR __builtin_amdgcn_s_barrier()
; #define PG8_SCHED __builtin_amdgcn_sched_barrier(0)
; template <class Epi, class Sched, bool ALIGN_EPI = false>
; __device__ __forceinline__ void gemm_phase(PG8_LAS unsigned char* lds, const Gemm g, const Sched& S, const Epi& E) {
;     ...
;             PG8_LDA(At, 1, 1); PG8_STAGE(PG8_SB(1, 0), b3, voffB); PG8_STAGE(PG8_SB(1, 1), b3 + hstepB, voffB); PG8_STAGE(PG8_SA(1, 0), a3, voffA);
;             PG8_WAIT_V(8); PG8_WAIT_L(0); PG8_BAR; PG8_MMA(1, 0, At, B0); PG8_MMA(1, 1, At, B1); PG8_BAR; PG8_SCHED;
;         }
	s_add_i32 s40, s71, s45
	v_lshl_add_u64 v[158:159], v[158:159], 0, s[24:25]
	s_mov_b32 m0, s40
	ds_read_b128 v[184:187], v162 offset:49152
	ds_read_b128 v[188:191], v162 offset:50176
	ds_read_b128 v[192:195], v162 offset:51200
	ds_read_b128 v[196:199], v162 offset:52224
	ds_read_b128 v[200:203], v162 offset:53248
	ds_read_b128 v[204:207], v162 offset:54272
	ds_read_b128 v[208:211], v162 offset:55296
	ds_read_b128 v[212:215], v162 offset:56320
	global_load_lds_dwordx4 v[158:159], off
	v_lshl_add_u64 v[158:159], v[216:217], 0, s[24:25]
	s_add_i32 m0, s40, 0x2000
	s_add_i32 s40, s72, s45
	global_load_lds_dwordx4 v[158:159], off
	v_lshl_add_u64 v[158:159], v[218:219], 0, s[24:25]
	s_mov_b32 m0, s40
	s_nop 0
	global_load_lds_dwordx4 v[158:159], off
	v_lshl_add_u64 v[158:159], v[220:221], 0, s[24:25]
	s_add_i32 m0, s40, 0x2000
	s_nop 0
	global_load_lds_dwordx4 v[158:159], off
	v_lshl_add_u64 v[158:159], v[222:223], 0, s[24:25]
	s_mov_b32 m0, s54
	s_nop 0
	global_load_lds_dwordx4 v[158:159], off
	v_lshl_add_u64 v[158:159], v[224:225], 0, s[24:25]
	s_mov_b32 m0, s55
	s_nop 0
	global_load_lds_dwordx4 v[158:159], off
	s_waitcnt vmcnt(8)
	s_waitcnt lgkmcnt(0)
	s_barrier
	s_waitcnt lgkmcnt(0)
	v_mfma_f32_16x16x32_bf16 v[94:97], v[130:133], v[184:187], v[94:97]
	v_mfma_f32_16x16x32_bf16 v[90:93], v[154:157], v[184:187], v[90:93]
	v_mfma_f32_16x16x32_bf16 v[86:89], v[130:133], v[192:195], v[86:89]
	v_mfma_f32_16x16x32_bf16 v[82:85], v[154:157], v[192:195], v[82:85]
	v_mfma_f32_16x16x32_bf16 v[78:81], v[130:133], v[200:203], v[78:81]
	v_mfma_f32_16x16x32_bf16 v[74:77], v[154:157], v[200:203], v[74:77]
	v_mfma_f32_16x16x32_bf16 v[70:73], v[130:133], v[208:211], v[70:73]
	v_mfma_f32_16x16x32_bf16 v[66:69], v[154:157], v[208:211], v[66:69]
	v_mfma_f32_16x16x32_bf16 v[94:97], v[134:137], v[188:191], v[94:97]
	v_mfma_f32_16x16x32_bf16 v[90:93], v[164:167], v[188:191], v[90:93]
	v_mfma_f32_16x16x32_bf16 v[86:89], v[134:137], v[196:199], v[86:89]
	v_mfma_f32_16x16x32_bf16 v[82:85], v[164:167], v[196:199], v[82:85]
	v_mfma_f32_16x16x32_bf16 v[78:81], v[134:137], v[204:207], v[78:81]
	v_mfma_f32_16x16x32_bf16 v[74:77], v[164:167], v[204:207], v[74:77]
	v_mfma_f32_16x16x32_bf16 v[70:73], v[134:137], v[212:215], v[70:73]
	v_mfma_f32_16x16x32_bf16 v[66:69], v[164:167], v[212:215], v[66:69]
	v_mfma_f32_16x16x32_bf16 v[30:33], v[168:171], v[184:187], v[30:33]
	v_mfma_f32_16x16x32_bf16 v[26:29], v[176:179], v[184:187], v[26:29]
	v_mfma_f32_16x16x32_bf16 v[22:25], v[168:171], v[192:195], v[22:25]
	v_mfma_f32_16x16x32_bf16 v[18:21], v[176:179], v[192:195], v[18:21]
	v_mfma_f32_16x16x32_bf16 v[14:17], v[168:171], v[200:203], v[14:17]
	v_mfma_f32_16x16x32_bf16 v[10:13], v[176:179], v[200:203], v[10:13]
	v_mfma_f32_16x16x32_bf16 v[6:9], v[168:171], v[208:211], v[6:9]
	v_mfma_f32_16x16x32_bf16 v[2:5], v[176:179], v[208:211], v[2:5]
	v_mfma_f32_16x16x32_bf16 v[30:33], v[172:175], v[188:191], v[30:33]
	v_mfma_f32_16x16x32_bf16 v[26:29], v[180:183], v[188:191], v[26:29]
	v_mfma_f32_16x16x32_bf16 v[22:25], v[172:175], v[196:199], v[22:25]
	v_mfma_f32_16x16x32_bf16 v[18:21], v[180:183], v[196:199], v[18:21]
	v_mfma_f32_16x16x32_bf16 v[14:17], v[172:175], v[204:207], v[14:17]
	v_mfma_f32_16x16x32_bf16 v[10:13], v[180:183], v[204:207], v[10:13]
	v_mfma_f32_16x16x32_bf16 v[6:9], v[172:175], v[212:215], v[6:9]
	v_mfma_f32_16x16x32_bf16 v[2:5], v[180:183], v[212:215], v[2:5]
	s_barrier
	s_add_u32 s6, s6, 0x100
	s_addc_u32 s7, s7, 0
	s_add_u32 s42, s42, 0x100
	s_addc_u32 s43, s43, 0
	s_cmp_ge_i32 s70, s60
	s_mov_b32 s40, s70
	s_cbranch_scc0 .LBB0_1165

; #define PG8_STAGE(bufoff, gbase, voff) do { _Pragma("unroll") for (int _i = 0; _i < 2; ++_i) \
;         __builtin_amdgcn_global_load_lds((const unsigned*)((const char*)(gbase) + (voff)[_i]), (PG8_LAS unsigned*)(lds + (bufoff) + ldsw + _i * 8192), 16, 0, 0); } while (0)
; #define PG8_LDA(dst, b, h) do { _Pragma("unroll") for (int m = 0; m < 4; ++m) _Pragma("unroll") for (int k = 0; k < 2; ++k) dst[m][k] = *(const PG8_LAS bf16x8*)(lds + PG8_SA(b, h) + aoff + m * 2048 + k * 1024); } while (0)
; #define PG8_LDB(dst, b, h) do { _Pragma("unroll") for (int n = 0; n < 2; ++n) _Pragma("unroll") for (int k = 0; k < 2; ++k) dst[n][k] = *(const PG8_LAS bf16x8*)(lds + PG8_SB(b, h) + boff + n * 2048 + k * 1024); } while (0)
; #define PG8_MMA(ai, bj, At, Bt) do { __builtin_amdgcn_s_setprio(1); _Pragma("unroll") for (int m = 0; m < 4; ++m) _Pragma("unroll") for (int n = 0; n < 2; ++n) _Pragma("unroll") for (int k = 0; k < 2; ++k) \
;         acc[ai][bj][m][n] = __builtin_amdgcn_mfma_f32_16x16x32_bf16(Bt[n][k], At[m][k], acc[ai][bj][m][n], 0, 0, 0); __builtin_amdgcn_s_setprio(0); } while (0)
; #define PG8_WAIT_V(n) asm volatile("s_waitcnt vmcnt(" #n ")" ::: "memory")
; #define PG8_WAIT_L(n) asm volatile("s_waitcnt lgkmcnt(" #n ")" ::: "memory")
; #define PG8_BAR __builtin_amdgcn_s_barrier()
; template <class Epi, class Sched, bool ALIGN_EPI = false>
; __device__ __forceinline__ void gemm_phase(PG8_LAS unsigned char* lds, const Gemm g, const Sched& S, const Epi& E) {
;     ...
;         for (int t = 0; t < nt; t += 2) {
;             const bool last = (t == nt - 2);
;             const char* a1 = cA + (size_t)(t + 1) * kstep;
;             const char* a2 = last ? nA : cA + (size_t)(t + 2) * kstep; const char* b2 = last ? nB : cB + (size_t)(t + 2) * kstep;
;             const char* a3 = a2 + kstep; const char* b3 = b2 + kstep;
;             if (last && has_next) S.a_ready(nxt);
;             PG8_LDB(B0, 0, 0); PG8_LDB(B1, 0, 1); PG8_SCHED; PG8_LDA(At, 0, 0); PG8_STAGE(PG8_SA(1, 1), a1 + hstepA, voffA);
;             PG8_WAIT_V(8); PG8_WAIT_L(0); PG8_BAR; PG8_MMA(0, 0, At, B0); PG8_MMA(0, 1, At, B1); PG8_BAR; PG8_SCHED;
;             PG8_LDA(At, 0, 1); PG8_STAGE(PG8_SB(0, 0), b2, voffB); PG8_STAGE(PG8_SB(0, 1), b2 + hstepB, voffB); PG8_STAGE(PG8_SA(0, 0), a2, voffA);
;             PG8_WAIT_V(8); PG8_WAIT_L(0); PG8_BAR; PG8_MMA(1, 0, At, B0); PG8_MMA(1, 1, At, B1); PG8_BAR; PG8_SCHED;
.LBB0_1184:
	ds_read_b128 v[122:125], v190
	ds_read_b128 v[126:129], v190 offset:1024
	ds_read_b128 v[130:133], v190 offset:2048
	ds_read_b128 v[134:137], v190 offset:3072
	ds_read_b128 v[146:149], v191
	ds_read_b128 v[150:153], v191 offset:1024
	ds_read_b128 v[172:175], v191 offset:2048
	ds_read_b128 v[176:179], v191 offset:3072
	s_add_i32 s49, s46, 2
	s_add_u32 s64, s4, 0xfffc0080
	s_addc_u32 s47, s5, -1
	s_cmp_eq_u32 s75, s46
	s_cselect_b32 s46, s7, s64
	s_cselect_b32 s47, s1, s47
	s_cselect_b32 s65, s43, s48
	s_cselect_b32 s64, s42, s41
	v_lshl_add_u64 v[154:155], s[4:5], 0, v[164:165]
	s_add_i32 m0, s63, 0xc000
	ds_read_b128 v[180:183], v192
	ds_read_b128 v[184:187], v192 offset:1024
	ds_read_b128 v[194:197], v192 offset:2048
	ds_read_b128 v[198:201], v192 offset:3072
	ds_read_b128 v[202:205], v192 offset:4096
	ds_read_b128 v[206:209], v192 offset:5120
	ds_read_b128 v[210:213], v192 offset:6144
	ds_read_b128 v[214:217], v192 offset:7168
	global_load_lds_dwordx4 v[154:155], off
	v_lshl_add_u64 v[154:155], s[4:5], 0, v[166:167]
	s_add_i32 m0, s63, 0xe000
	s_nop 0
	global_load_lds_dwordx4 v[154:155], off
	s_waitcnt vmcnt(8)
	s_waitcnt lgkmcnt(0)
	s_barrier
	s_waitcnt lgkmcnt(0)
	v_mfma_f32_16x16x32_bf16 v[142:145], v[122:125], v[180:183], v[142:145]
	v_mfma_f32_16x16x32_bf16 v[138:141], v[130:133], v[180:183], v[138:141]
	v_mfma_f32_16x16x32_bf16 v[118:121], v[122:125], v[194:197], v[118:121]
	v_mfma_f32_16x16x32_bf16 v[114:117], v[130:133], v[194:197], v[114:117]
	v_mfma_f32_16x16x32_bf16 v[110:113], v[122:125], v[202:205], v[110:113]
	v_mfma_f32_16x16x32_bf16 v[106:109], v[130:133], v[202:205], v[106:109]
	v_mfma_f32_16x16x32_bf16 v[102:105], v[122:125], v[210:213], v[102:105]
	v_mfma_f32_16x16x32_bf16 v[98:101], v[130:133], v[210:213], v[98:101]
	v_mfma_f32_16x16x32_bf16 v[142:145], v[126:129], v[184:187], v[142:145]
	v_mfma_f32_16x16x32_bf16 v[138:141], v[134:137], v[184:187], v[138:141]
	v_mfma_f32_16x16x32_bf16 v[118:121], v[126:129], v[198:201], v[118:121]
	v_mfma_f32_16x16x32_bf16 v[114:117], v[134:137], v[198:201], v[114:117]
	v_mfma_f32_16x16x32_bf16 v[110:113], v[126:129], v[206:209], v[110:113]
	v_mfma_f32_16x16x32_bf16 v[106:109], v[134:137], v[206:209], v[106:109]
	v_mfma_f32_16x16x32_bf16 v[102:105], v[126:129], v[214:217], v[102:105]
	v_mfma_f32_16x16x32_bf16 v[98:101], v[134:137], v[214:217], v[98:101]
	v_mfma_f32_16x16x32_bf16 v[62:65], v[146:149], v[180:183], v[62:65]
	v_mfma_f32_16x16x32_bf16 v[58:61], v[172:175], v[180:183], v[58:61]
	v_mfma_f32_16x16x32_bf16 v[54:57], v[146:149], v[194:197], v[54:57]
	v_mfma_f32_16x16x32_bf16 v[50:53], v[172:175], v[194:197], v[50:53]
	v_mfma_f32_16x16x32_bf16 v[46:49], v[146:149], v[202:205], v[46:49]
	v_mfma_f32_16x16x32_bf16 v[42:45], v[172:175], v[202:205], v[42:45]
	v_mfma_f32_16x16x32_bf16 v[38:41], v[146:149], v[210:213], v[38:41]
	v_mfma_f32_16x16x32_bf16 v[34:37], v[172:175], v[210:213], v[34:37]
	v_mfma_f32_16x16x32_bf16 v[62:65], v[150:153], v[184:187], v[62:65]
	v_mfma_f32_16x16x32_bf16 v[58:61], v[176:179], v[184:187], v[58:61]
	v_mfma_f32_16x16x32_bf16 v[54:57], v[150:153], v[198:201], v[54:57]
	v_mfma_f32_16x16x32_bf16 v[50:53], v[176:179], v[198:201], v[50:53]
	v_mfma_f32_16x16x32_bf16 v[46:49], v[150:153], v[206:209], v[46:49]
	v_mfma_f32_16x16x32_bf16 v[42:45], v[176:179], v[206:209], v[42:45]
	v_mfma_f32_16x16x32_bf16 v[38:41], v[150:153], v[214:217], v[38:41]
	v_mfma_f32_16x16x32_bf16 v[34:37], v[176:179], v[214:217], v[34:37]
	s_barrier
	s_add_i32 s66, s76, s54
	v_lshl_add_u64 v[154:155], s[64:65], 0, v[160:161]
	s_mov_b32 m0, s66
	ds_read_b128 v[180:183], v192 offset:16384
	ds_read_b128 v[184:187], v192 offset:17408
	ds_read_b128 v[194:197], v192 offset:18432
	ds_read_b128 v[198:201], v192 offset:19456
	ds_read_b128 v[202:205], v192 offset:20480
	ds_read_b128 v[206:209], v192 offset:21504
	ds_read_b128 v[210:213], v192 offset:22528
	ds_read_b128 v[214:217], v192 offset:23552
	global_load_lds_dwordx4 v[154:155], off
	s_add_i32 m0, s66, 0x2000
	v_lshl_add_u64 v[188:189], s[64:65], 0, v[156:157]
	s_add_u32 s64, s64, s14
	s_addc_u32 s65, s65, s15
	s_add_i32 s66, s77, s54
	global_load_lds_dwordx4 v[188:189], off
	v_lshl_add_u64 v[218:219], s[64:65], 0, v[160:161]
	s_mov_b32 m0, s66
	v_lshl_add_u64 v[220:221], s[64:65], 0, v[156:157]
	global_load_lds_dwordx4 v[218:219], off
	s_add_i32 m0, s66, 0x2000
	v_lshl_add_u64 v[222:223], s[46:47], 0, v[162:163]
	global_load_lds_dwordx4 v[220:221], off
	s_mov_b32 m0, s63
	v_lshl_add_u64 v[224:225], s[46:47], 0, v[158:159]
	global_load_lds_dwordx4 v[222:223], off
	s_mov_b32 m0, s68
	s_nop 0
	global_load_lds_dwordx4 v[224:225], off
	s_waitcnt vmcnt(8)
	s_waitcnt lgkmcnt(0)
	s_barrier
; #define PG8_STAGE(bufoff, gbase, voff) do { _Pragma("unroll") for (int _i = 0; _i < 2; ++_i) \
;         __builtin_amdgcn_global_load_lds((const unsigned*)((const char*)(gbase) + (voff)[_i]), (PG8_LAS unsigned*)(lds + (bufoff) + ldsw + _i * 8192), 16, 0, 0); } while (0)
; #define PG8_LDA(dst, b, h) do { _Pragma("unroll") for (int m = 0; m < 4; ++m) _Pragma("unroll") for (int k = 0; k < 2; ++k) dst[m][k] = *(const PG8_LAS bf16x8*)(lds + PG8_SA(b, h) + aoff + m * 2048 + k * 1024); } while (0)
; #define PG8_LDB(dst, b, h) do { _Pragma("unroll") for (int n = 0; n < 2; ++n) _Pragma("unroll") for (int k = 0; k < 2; ++k) dst[n][k] = *(const PG8_LAS bf16x8*)(lds + PG8_SB(b, h) + boff + n * 2048 + k * 1024); } while (0)
; #define PG8_MMA(ai, bj, At, Bt) do { __builtin_amdgcn_s_setprio(1); _Pragma("unroll") for (int m = 0; m < 4; ++m) _Pragma("unroll") for (int n = 0; n < 2; ++n) _Pragma("unroll") for (int k = 0; k < 2; ++k) \
;         acc[ai][bj][m][n] = __builtin_amdgcn_mfma_f32_16x16x32_bf16(Bt[n][k], At[m][k], acc[ai][bj][m][n], 0, 0, 0); __builtin_amdgcn_s_setprio(0); } while (0)
; #define PG8_WAIT_V(n) asm volatile("s_waitcnt vmcnt(" #n ")" ::: "memory")
; #define PG8_WAIT_L(n) asm volatile("s_waitcnt lgkmcnt(" #n ")" ::: "memory")
; #define PG8_BAR __builtin_amdgcn_s_barrier()
; #define PG8_SCHED __builtin_amdgcn_sched_barrier(0)
; template <class Epi, class Sched, bool ALIGN_EPI = false>
; __device__ __forceinline__ void gemm_phase(PG8_LAS unsigned char* lds, const Gemm g, const Sched& S, const Epi& E) {
;     ...
;             PG8_WAIT_V(8); PG8_WAIT_L(0); PG8_BAR; PG8_MMA(1, 0, At, B0); PG8_MMA(1, 1, At, B1); PG8_BAR; PG8_SCHED;
;             PG8_LDB(B0, 1, 0); PG8_LDB(B1, 1, 1); PG8_SCHED; PG8_LDA(At, 1, 0); PG8_STAGE(PG8_SA(0, 1), a2 + hstepA, voffA);
;             PG8_WAIT_V(8); PG8_WAIT_L(0); PG8_BAR; PG8_MMA(0, 0, At, B0); PG8_MMA(0, 1, At, B1); PG8_BAR; PG8_SCHED;
	s_waitcnt lgkmcnt(0)
	v_mfma_f32_16x16x32_bf16 v[94:97], v[122:125], v[180:183], v[94:97]
	v_mfma_f32_16x16x32_bf16 v[90:93], v[130:133], v[180:183], v[90:93]
	v_mfma_f32_16x16x32_bf16 v[86:89], v[122:125], v[194:197], v[86:89]
	v_mfma_f32_16x16x32_bf16 v[82:85], v[130:133], v[194:197], v[82:85]
	v_mfma_f32_16x16x32_bf16 v[78:81], v[122:125], v[202:205], v[78:81]
	v_mfma_f32_16x16x32_bf16 v[74:77], v[130:133], v[202:205], v[74:77]
	v_mfma_f32_16x16x32_bf16 v[70:73], v[122:125], v[210:213], v[70:73]
	v_mfma_f32_16x16x32_bf16 v[66:69], v[130:133], v[210:213], v[66:69]
	v_mfma_f32_16x16x32_bf16 v[94:97], v[126:129], v[184:187], v[94:97]
	v_mfma_f32_16x16x32_bf16 v[90:93], v[134:137], v[184:187], v[90:93]
	v_mfma_f32_16x16x32_bf16 v[86:89], v[126:129], v[198:201], v[86:89]
	v_mfma_f32_16x16x32_bf16 v[82:85], v[134:137], v[198:201], v[82:85]
	v_mfma_f32_16x16x32_bf16 v[78:81], v[126:129], v[206:209], v[78:81]
	v_mfma_f32_16x16x32_bf16 v[74:77], v[134:137], v[206:209], v[74:77]
	v_mfma_f32_16x16x32_bf16 v[70:73], v[126:129], v[214:217], v[70:73]
	v_mfma_f32_16x16x32_bf16 v[66:69], v[134:137], v[214:217], v[66:69]
	v_mfma_f32_16x16x32_bf16 v[30:33], v[146:149], v[180:183], v[30:33]
	v_mfma_f32_16x16x32_bf16 v[26:29], v[172:175], v[180:183], v[26:29]
	v_mfma_f32_16x16x32_bf16 v[22:25], v[146:149], v[194:197], v[22:25]
	v_mfma_f32_16x16x32_bf16 v[18:21], v[172:175], v[194:197], v[18:21]
	v_mfma_f32_16x16x32_bf16 v[14:17], v[146:149], v[202:205], v[14:17]
	v_mfma_f32_16x16x32_bf16 v[10:13], v[172:175], v[202:205], v[10:13]
	v_mfma_f32_16x16x32_bf16 v[6:9], v[146:149], v[210:213], v[6:9]
	v_mfma_f32_16x16x32_bf16 v[2:5], v[172:175], v[210:213], v[2:5]
	v_mfma_f32_16x16x32_bf16 v[30:33], v[150:153], v[184:187], v[30:33]
	v_mfma_f32_16x16x32_bf16 v[26:29], v[176:179], v[184:187], v[26:29]
	v_mfma_f32_16x16x32_bf16 v[22:25], v[150:153], v[198:201], v[22:25]
	v_mfma_f32_16x16x32_bf16 v[18:21], v[176:179], v[198:201], v[18:21]
	v_mfma_f32_16x16x32_bf16 v[14:17], v[150:153], v[206:209], v[14:17]
	v_mfma_f32_16x16x32_bf16 v[10:13], v[176:179], v[206:209], v[10:13]
	v_mfma_f32_16x16x32_bf16 v[6:9], v[150:153], v[214:217], v[6:9]
	v_mfma_f32_16x16x32_bf16 v[2:5], v[176:179], v[214:217], v[2:5]
	s_barrier
	s_add_i32 s64, 0, 0x18000
	s_add_i32 s65, 0, 0x1c000
	v_add_u32_e32 v134, s64, v1
	v_add_u32_e32 v176, s65, v1
	ds_read_b128 v[122:125], v134
	ds_read_b128 v[126:129], v134 offset:1024
	ds_read_b128 v[130:133], v134 offset:2048
	ds_read_b128 v[134:137], v134 offset:3072
	ds_read_b128 v[146:149], v176
	ds_read_b128 v[150:153], v176 offset:1024
	ds_read_b128 v[172:175], v176 offset:2048
	ds_read_b128 v[176:179], v176 offset:3072
	s_add_u32 s46, s46, 0x40000
	s_addc_u32 s47, s47, 0
	s_mov_b32 m0, s69
	v_lshl_add_u64 v[226:227], s[46:47], 0, v[162:163]
	ds_read_b128 v[180:183], v192 offset:32768
	ds_read_b128 v[184:187], v192 offset:33792
	ds_read_b128 v[194:197], v192 offset:34816
	ds_read_b128 v[198:201], v192 offset:35840
	ds_read_b128 v[202:205], v192 offset:36864
	ds_read_b128 v[206:209], v192 offset:37888
	ds_read_b128 v[210:213], v192 offset:38912
	ds_read_b128 v[214:217], v192 offset:39936
	global_load_lds_dwordx4 v[226:227], off
	v_lshl_add_u64 v[226:227], s[46:47], 0, v[158:159]
	s_mov_b32 m0, s70
	s_nop 0
	global_load_lds_dwordx4 v[226:227], off
	s_waitcnt vmcnt(8)
	s_waitcnt lgkmcnt(0)
	s_barrier
	s_waitcnt lgkmcnt(0)
	v_mfma_f32_16x16x32_bf16 v[142:145], v[122:125], v[180:183], v[142:145]
	v_mfma_f32_16x16x32_bf16 v[138:141], v[130:133], v[180:183], v[138:141]
	v_mfma_f32_16x16x32_bf16 v[118:121], v[122:125], v[194:197], v[118:121]
	v_mfma_f32_16x16x32_bf16 v[114:117], v[130:133], v[194:197], v[114:117]
	v_mfma_f32_16x16x32_bf16 v[110:113], v[122:125], v[202:205], v[110:113]
	v_mfma_f32_16x16x32_bf16 v[106:109], v[130:133], v[202:205], v[106:109]
	v_mfma_f32_16x16x32_bf16 v[102:105], v[122:125], v[210:213], v[102:105]
	v_mfma_f32_16x16x32_bf16 v[98:101], v[130:133], v[210:213], v[98:101]
	v_mfma_f32_16x16x32_bf16 v[142:145], v[126:129], v[184:187], v[142:145]
	v_mfma_f32_16x16x32_bf16 v[138:141], v[134:137], v[184:187], v[138:141]
	v_mfma_f32_16x16x32_bf16 v[118:121], v[126:129], v[198:201], v[118:121]
	v_mfma_f32_16x16x32_bf16 v[114:117], v[134:137], v[198:201], v[114:117]
	v_mfma_f32_16x16x32_bf16 v[110:113], v[126:129], v[206:209], v[110:113]
	v_mfma_f32_16x16x32_bf16 v[106:109], v[134:137], v[206:209], v[106:109]
	v_mfma_f32_16x16x32_bf16 v[102:105], v[126:129], v[214:217], v[102:105]
	v_mfma_f32_16x16x32_bf16 v[98:101], v[134:137], v[214:217], v[98:101]
	v_mfma_f32_16x16x32_bf16 v[62:65], v[146:149], v[180:183], v[62:65]
	v_mfma_f32_16x16x32_bf16 v[58:61], v[172:175], v[180:183], v[58:61]
	v_mfma_f32_16x16x32_bf16 v[54:57], v[146:149], v[194:197], v[54:57]
	v_mfma_f32_16x16x32_bf16 v[50:53], v[172:175], v[194:197], v[50:53]
	v_mfma_f32_16x16x32_bf16 v[46:49], v[146:149], v[202:205], v[46:49]
	v_mfma_f32_16x16x32_bf16 v[42:45], v[172:175], v[202:205], v[42:45]
	v_mfma_f32_16x16x32_bf16 v[38:41], v[146:149], v[210:213], v[38:41]
	v_mfma_f32_16x16x32_bf16 v[34:37], v[172:175], v[210:213], v[34:37]
	v_mfma_f32_16x16x32_bf16 v[62:65], v[150:153], v[184:187], v[62:65]
	v_mfma_f32_16x16x32_bf16 v[58:61], v[176:179], v[184:187], v[58:61]
	v_mfma_f32_16x16x32_bf16 v[54:57], v[150:153], v[198:201], v[54:57]
	v_mfma_f32_16x16x32_bf16 v[50:53], v[176:179], v[198:201], v[50:53]
	v_mfma_f32_16x16x32_bf16 v[46:49], v[150:153], v[206:209], v[46:49]
	v_mfma_f32_16x16x32_bf16 v[42:45], v[176:179], v[206:209], v[42:45]
	v_mfma_f32_16x16x32_bf16 v[38:41], v[150:153], v[214:217], v[38:41]
	v_mfma_f32_16x16x32_bf16 v[34:37], v[176:179], v[214:217], v[34:37]
	s_barrier
; #define PG8_STAGE(bufoff, gbase, voff) do { _Pragma("unroll") for (int _i = 0; _i < 2; ++_i) \
;         __builtin_amdgcn_global_load_lds((const unsigned*)((const char*)(gbase) + (voff)[_i]), (PG8_LAS unsigned*)(lds + (bufoff) + ldsw + _i * 8192), 16, 0, 0); } while (0)
; #define PG8_LDA(dst, b, h) do { _Pragma("unroll") for (int m = 0; m < 4; ++m) _Pragma("unroll") for (int k = 0; k < 2; ++k) dst[m][k] = *(const PG8_LAS bf16x8*)(lds + PG8_SA(b, h) + aoff + m * 2048 + k * 1024); } while (0)
; #define PG8_MMA(ai, bj, At, Bt) do { __builtin_amdgcn_s_setprio(1); _Pragma("unroll") for (int m = 0; m < 4; ++m) _Pragma("unroll") for (int n = 0; n < 2; ++n) _Pragma("unroll") for (int k = 0; k < 2; ++k) \
;         acc[ai][bj][m][n] = __builtin_amdgcn_mfma_f32_16x16x32_bf16(Bt[n][k], At[m][k], acc[ai][bj][m][n], 0, 0, 0); __builtin_amdgcn_s_setprio(0); } while (0)
; #define PG8_WAIT_V(n) asm volatile("s_waitcnt vmcnt(" #n ")" ::: "memory")
; #define PG8_WAIT_L(n) asm volatile("s_waitcnt lgkmcnt(" #n ")" ::: "memory")
; #define PG8_BAR __builtin_amdgcn_s_barrier()
; #define PG8_SCHED __builtin_amdgcn_sched_barrier(0)
; template <class Epi, class Sched, bool ALIGN_EPI = false>
; __device__ __forceinline__ void gemm_phase(PG8_LAS unsigned char* lds, const Gemm g, const Sched& S, const Epi& E) {
;     ...
;             PG8_LDA(At, 1, 1); PG8_STAGE(PG8_SB(1, 0), b3, voffB); PG8_STAGE(PG8_SB(1, 1), b3 + hstepB, voffB); PG8_STAGE(PG8_SA(1, 0), a3, voffA);
;             PG8_WAIT_V(8); PG8_WAIT_L(0); PG8_BAR; PG8_MMA(1, 0, At, B0); PG8_MMA(1, 1, At, B1); PG8_BAR; PG8_SCHED;
;         }
	s_add_i32 s46, s64, s54
	v_lshl_add_u64 v[154:155], v[154:155], 0, s[28:29]
	s_mov_b32 m0, s46
	ds_read_b128 v[180:183], v192 offset:49152
	ds_read_b128 v[184:187], v192 offset:50176
	ds_read_b128 v[194:197], v192 offset:51200
	ds_read_b128 v[198:201], v192 offset:52224
	ds_read_b128 v[202:205], v192 offset:53248
	ds_read_b128 v[206:209], v192 offset:54272
	ds_read_b128 v[210:213], v192 offset:55296
	ds_read_b128 v[214:217], v192 offset:56320
	global_load_lds_dwordx4 v[154:155], off
	v_lshl_add_u64 v[154:155], v[188:189], 0, s[28:29]
	s_add_i32 m0, s46, 0x2000
	s_add_i32 s46, s65, s54
	global_load_lds_dwordx4 v[154:155], off
	v_lshl_add_u64 v[154:155], v[218:219], 0, s[28:29]
	s_mov_b32 m0, s46
	s_nop 0
	global_load_lds_dwordx4 v[154:155], off
	v_lshl_add_u64 v[154:155], v[220:221], 0, s[28:29]
	s_add_i32 m0, s46, 0x2000
	s_nop 0
	global_load_lds_dwordx4 v[154:155], off
	v_lshl_add_u64 v[154:155], v[222:223], 0, s[28:29]
	s_mov_b32 m0, s73
	s_nop 0
	global_load_lds_dwordx4 v[154:155], off
	v_lshl_add_u64 v[154:155], v[224:225], 0, s[28:29]
	s_mov_b32 m0, s74
	s_nop 0
	global_load_lds_dwordx4 v[154:155], off
	s_waitcnt vmcnt(8)
	s_waitcnt lgkmcnt(0)
	s_barrier
	s_waitcnt lgkmcnt(0)
	v_mfma_f32_16x16x32_bf16 v[94:97], v[122:125], v[180:183], v[94:97]
	v_mfma_f32_16x16x32_bf16 v[90:93], v[130:133], v[180:183], v[90:93]
	v_mfma_f32_16x16x32_bf16 v[86:89], v[122:125], v[194:197], v[86:89]
	v_mfma_f32_16x16x32_bf16 v[82:85], v[130:133], v[194:197], v[82:85]
	v_mfma_f32_16x16x32_bf16 v[78:81], v[122:125], v[202:205], v[78:81]
	v_mfma_f32_16x16x32_bf16 v[74:77], v[130:133], v[202:205], v[74:77]
	v_mfma_f32_16x16x32_bf16 v[70:73], v[122:125], v[210:213], v[70:73]
	v_mfma_f32_16x16x32_bf16 v[66:69], v[130:133], v[210:213], v[66:69]
	v_mfma_f32_16x16x32_bf16 v[94:97], v[126:129], v[184:187], v[94:97]
	v_mfma_f32_16x16x32_bf16 v[90:93], v[134:137], v[184:187], v[90:93]
	v_mfma_f32_16x16x32_bf16 v[86:89], v[126:129], v[198:201], v[86:89]
	v_mfma_f32_16x16x32_bf16 v[82:85], v[134:137], v[198:201], v[82:85]
	v_mfma_f32_16x16x32_bf16 v[78:81], v[126:129], v[206:209], v[78:81]
	v_mfma_f32_16x16x32_bf16 v[74:77], v[134:137], v[206:209], v[74:77]
	v_mfma_f32_16x16x32_bf16 v[70:73], v[126:129], v[214:217], v[70:73]
	v_mfma_f32_16x16x32_bf16 v[66:69], v[134:137], v[214:217], v[66:69]
	v_mfma_f32_16x16x32_bf16 v[30:33], v[146:149], v[180:183], v[30:33]
	v_mfma_f32_16x16x32_bf16 v[26:29], v[172:175], v[180:183], v[26:29]
	v_mfma_f32_16x16x32_bf16 v[22:25], v[146:149], v[194:197], v[22:25]
	v_mfma_f32_16x16x32_bf16 v[18:21], v[172:175], v[194:197], v[18:21]
	v_mfma_f32_16x16x32_bf16 v[14:17], v[146:149], v[202:205], v[14:17]
	v_mfma_f32_16x16x32_bf16 v[10:13], v[172:175], v[202:205], v[10:13]
	v_mfma_f32_16x16x32_bf16 v[6:9], v[146:149], v[210:213], v[6:9]
	v_mfma_f32_16x16x32_bf16 v[2:5], v[172:175], v[210:213], v[2:5]
	v_mfma_f32_16x16x32_bf16 v[30:33], v[150:153], v[184:187], v[30:33]
	v_mfma_f32_16x16x32_bf16 v[26:29], v[176:179], v[184:187], v[26:29]
	v_mfma_f32_16x16x32_bf16 v[22:25], v[150:153], v[198:201], v[22:25]
	v_mfma_f32_16x16x32_bf16 v[18:21], v[176:179], v[198:201], v[18:21]
	v_mfma_f32_16x16x32_bf16 v[14:17], v[150:153], v[206:209], v[14:17]
	v_mfma_f32_16x16x32_bf16 v[10:13], v[176:179], v[206:209], v[10:13]
	v_mfma_f32_16x16x32_bf16 v[6:9], v[150:153], v[214:217], v[6:9]
	v_mfma_f32_16x16x32_bf16 v[2:5], v[176:179], v[214:217], v[2:5]
	s_barrier
	s_add_u32 s4, s4, 0x100
	s_addc_u32 s5, s5, 0
	s_add_u32 s41, s41, 0x100
	s_addc_u32 s48, s48, 0
	s_cmp_ge_i32 s49, s72
	s_mov_b32 s46, s49
	s_cbranch_scc0 .LBB0_1184

; #define PG8_STAGE(bufoff, gbase, voff) do { _Pragma("unroll") for (int _i = 0; _i < 2; ++_i) \
;         __builtin_amdgcn_global_load_lds((const unsigned*)((const char*)(gbase) + (voff)[_i]), (PG8_LAS unsigned*)(lds + (bufoff) + ldsw + _i * 8192), 16, 0, 0); } while (0)
; #define PG8_LDA(dst, b, h) do { _Pragma("unroll") for (int m = 0; m < 4; ++m) _Pragma("unroll") for (int k = 0; k < 2; ++k) dst[m][k] = *(const PG8_LAS bf16x8*)(lds + PG8_SA(b, h) + aoff + m * 2048 + k * 1024); } while (0)
; #define PG8_LDB(dst, b, h) do { _Pragma("unroll") for (int n = 0; n < 2; ++n) _Pragma("unroll") for (int k = 0; k < 2; ++k) dst[n][k] = *(const PG8_LAS bf16x8*)(lds + PG8_SB(b, h) + boff + n * 2048 + k * 1024); } while (0)
; #define PG8_MMA(ai, bj, At, Bt) do { __builtin_amdgcn_s_setprio(1); _Pragma("unroll") for (int m = 0; m < 4; ++m) _Pragma("unroll") for (int n = 0; n < 2; ++n) _Pragma("unroll") for (int k = 0; k < 2; ++k) \
;         acc[ai][bj][m][n] = __builtin_amdgcn_mfma_f32_16x16x32_bf16(Bt[n][k], At[m][k], acc[ai][bj][m][n], 0, 0, 0); __builtin_amdgcn_s_setprio(0); } while (0)
; #define PG8_WAIT_V(n) asm volatile("s_waitcnt vmcnt(" #n ")" ::: "memory")
; #define PG8_WAIT_L(n) asm volatile("s_waitcnt lgkmcnt(" #n ")" ::: "memory")
; #define PG8_BAR __builtin_amdgcn_s_barrier()
; template <class Epi, class Sched, bool ALIGN_EPI = false>
; __device__ __forceinline__ void gemm_phase(PG8_LAS unsigned char* lds, const Gemm g, const Sched& S, const Epi& E) {
;     ...
;         for (int t = 0; t < nt; t += 2) {
;             const bool last = (t == nt - 2);
;             const char* a1 = cA + (size_t)(t + 1) * kstep;
;             const char* a2 = last ? nA : cA + (size_t)(t + 2) * kstep; const char* b2 = last ? nB : cB + (size_t)(t + 2) * kstep;
;             const char* a3 = a2 + kstep; const char* b3 = b2 + kstep;
;             if (last && has_next) S.a_ready(nxt);
;             PG8_LDB(B0, 0, 0); PG8_LDB(B1, 0, 1); PG8_SCHED; PG8_LDA(At, 0, 0); PG8_STAGE(PG8_SA(1, 1), a1 + hstepA, voffA);
;             PG8_WAIT_V(8); PG8_WAIT_L(0); PG8_BAR; PG8_MMA(0, 0, At, B0); PG8_MMA(0, 1, At, B1); PG8_BAR; PG8_SCHED;
;             PG8_LDA(At, 0, 1); PG8_STAGE(PG8_SB(0, 0), b2, voffB); PG8_STAGE(PG8_SB(0, 1), b2 + hstepB, voffB); PG8_STAGE(PG8_SA(0, 0), a2, voffA);
;             PG8_WAIT_V(8); PG8_WAIT_L(0); PG8_BAR; PG8_MMA(1, 0, At, B0); PG8_MMA(1, 1, At, B1); PG8_BAR; PG8_SCHED;
.LBB0_1211:
	ds_read_b128 v[150:153], v146
	ds_read_b128 v[154:157], v146 offset:1024
	ds_read_b128 v[158:161], v146 offset:2048
	ds_read_b128 v[162:165], v146 offset:3072
	ds_read_b128 v[166:169], v147
	ds_read_b128 v[170:173], v147 offset:1024
	ds_read_b128 v[174:177], v147 offset:2048
	ds_read_b128 v[178:181], v147 offset:3072
	s_add_i32 s55, s30, 2
	s_add_u32 s60, s6, 0xfffc0080
	s_addc_u32 s31, s7, -1
	s_cmp_eq_u32 s46, s30
	s_cselect_b32 s30, s54, s60
	s_cselect_b32 s31, s25, s31
	s_cselect_b32 s61, s27, s35
	s_cselect_b32 s60, s26, s34
	v_lshl_add_u64 v[214:215], s[6:7], 0, v[138:139]
	s_add_i32 m0, s23, 0xc000
	ds_read_b128 v[182:185], v148
	ds_read_b128 v[186:189], v148 offset:1024
	ds_read_b128 v[190:193], v148 offset:2048
	ds_read_b128 v[194:197], v148 offset:3072
	ds_read_b128 v[198:201], v148 offset:4096
	ds_read_b128 v[202:205], v148 offset:5120
	ds_read_b128 v[206:209], v148 offset:6144
	ds_read_b128 v[210:213], v148 offset:7168
	global_load_lds_dwordx4 v[214:215], off
	v_lshl_add_u64 v[214:215], s[6:7], 0, v[140:141]
	s_add_i32 m0, s23, 0xe000
	s_nop 0
	global_load_lds_dwordx4 v[214:215], off
	s_waitcnt vmcnt(8)
	s_waitcnt lgkmcnt(0)
	s_barrier
	s_waitcnt lgkmcnt(0)
	v_mfma_f32_16x16x32_bf16 v[126:129], v[150:153], v[182:185], v[126:129]
	v_mfma_f32_16x16x32_bf16 v[122:125], v[158:161], v[182:185], v[122:125]
	v_mfma_f32_16x16x32_bf16 v[118:121], v[150:153], v[190:193], v[118:121]
	v_mfma_f32_16x16x32_bf16 v[114:117], v[158:161], v[190:193], v[114:117]
	v_mfma_f32_16x16x32_bf16 v[110:113], v[150:153], v[198:201], v[110:113]
	v_mfma_f32_16x16x32_bf16 v[106:109], v[158:161], v[198:201], v[106:109]
	v_mfma_f32_16x16x32_bf16 v[102:105], v[150:153], v[206:209], v[102:105]
	v_mfma_f32_16x16x32_bf16 v[98:101], v[158:161], v[206:209], v[98:101]
	v_mfma_f32_16x16x32_bf16 v[126:129], v[154:157], v[186:189], v[126:129]
	v_mfma_f32_16x16x32_bf16 v[122:125], v[162:165], v[186:189], v[122:125]
	v_mfma_f32_16x16x32_bf16 v[118:121], v[154:157], v[194:197], v[118:121]
	v_mfma_f32_16x16x32_bf16 v[114:117], v[162:165], v[194:197], v[114:117]
	v_mfma_f32_16x16x32_bf16 v[110:113], v[154:157], v[202:205], v[110:113]
	v_mfma_f32_16x16x32_bf16 v[106:109], v[162:165], v[202:205], v[106:109]
	v_mfma_f32_16x16x32_bf16 v[102:105], v[154:157], v[210:213], v[102:105]
	v_mfma_f32_16x16x32_bf16 v[98:101], v[162:165], v[210:213], v[98:101]
	v_mfma_f32_16x16x32_bf16 v[62:65], v[166:169], v[182:185], v[62:65]
	v_mfma_f32_16x16x32_bf16 v[58:61], v[174:177], v[182:185], v[58:61]
	v_mfma_f32_16x16x32_bf16 v[54:57], v[166:169], v[190:193], v[54:57]
	v_mfma_f32_16x16x32_bf16 v[50:53], v[174:177], v[190:193], v[50:53]
	v_mfma_f32_16x16x32_bf16 v[46:49], v[166:169], v[198:201], v[46:49]
	v_mfma_f32_16x16x32_bf16 v[42:45], v[174:177], v[198:201], v[42:45]
	v_mfma_f32_16x16x32_bf16 v[38:41], v[166:169], v[206:209], v[38:41]
	v_mfma_f32_16x16x32_bf16 v[34:37], v[174:177], v[206:209], v[34:37]
	v_mfma_f32_16x16x32_bf16 v[62:65], v[170:173], v[186:189], v[62:65]
	v_mfma_f32_16x16x32_bf16 v[58:61], v[178:181], v[186:189], v[58:61]
	v_mfma_f32_16x16x32_bf16 v[54:57], v[170:173], v[194:197], v[54:57]
	v_mfma_f32_16x16x32_bf16 v[50:53], v[178:181], v[194:197], v[50:53]
	v_mfma_f32_16x16x32_bf16 v[46:49], v[170:173], v[202:205], v[46:49]
	v_mfma_f32_16x16x32_bf16 v[42:45], v[178:181], v[202:205], v[42:45]
	v_mfma_f32_16x16x32_bf16 v[38:41], v[170:173], v[210:213], v[38:41]
	v_mfma_f32_16x16x32_bf16 v[34:37], v[178:181], v[210:213], v[34:37]
	s_barrier
	s_add_i32 s62, s47, s0
	v_lshl_add_u64 v[214:215], s[60:61], 0, v[134:135]
	s_mov_b32 m0, s62
	ds_read_b128 v[182:185], v148 offset:16384
	ds_read_b128 v[186:189], v148 offset:17408
	ds_read_b128 v[190:193], v148 offset:18432
	ds_read_b128 v[194:197], v148 offset:19456
	ds_read_b128 v[198:201], v148 offset:20480
	ds_read_b128 v[202:205], v148 offset:21504
	ds_read_b128 v[206:209], v148 offset:22528
	ds_read_b128 v[210:213], v148 offset:23552
	global_load_lds_dwordx4 v[214:215], off
	s_add_i32 m0, s62, 0x2000
	v_lshl_add_u64 v[216:217], s[60:61], 0, v[130:131]
	s_add_u32 s60, s60, s12
	s_addc_u32 s61, s61, s13
	s_add_i32 s62, s48, s0
	global_load_lds_dwordx4 v[216:217], off
	v_lshl_add_u64 v[218:219], s[60:61], 0, v[134:135]
	s_mov_b32 m0, s62
	v_lshl_add_u64 v[220:221], s[60:61], 0, v[130:131]
	global_load_lds_dwordx4 v[218:219], off
	s_add_i32 m0, s62, 0x2000
	v_lshl_add_u64 v[222:223], s[30:31], 0, v[136:137]
	global_load_lds_dwordx4 v[220:221], off
	s_mov_b32 m0, s23
	v_lshl_add_u64 v[224:225], s[30:31], 0, v[132:133]
	global_load_lds_dwordx4 v[222:223], off
	s_mov_b32 m0, s39
	s_nop 0
	global_load_lds_dwordx4 v[224:225], off
	s_waitcnt vmcnt(8)
	s_waitcnt lgkmcnt(0)
	s_barrier
; #define PG8_STAGE(bufoff, gbase, voff) do { _Pragma("unroll") for (int _i = 0; _i < 2; ++_i) \
;         __builtin_amdgcn_global_load_lds((const unsigned*)((const char*)(gbase) + (voff)[_i]), (PG8_LAS unsigned*)(lds + (bufoff) + ldsw + _i * 8192), 16, 0, 0); } while (0)
; #define PG8_LDA(dst, b, h) do { _Pragma("unroll") for (int m = 0; m < 4; ++m) _Pragma("unroll") for (int k = 0; k < 2; ++k) dst[m][k] = *(const PG8_LAS bf16x8*)(lds + PG8_SA(b, h) + aoff + m * 2048 + k * 1024); } while (0)
; #define PG8_LDB(dst, b, h) do { _Pragma("unroll") for (int n = 0; n < 2; ++n) _Pragma("unroll") for (int k = 0; k < 2; ++k) dst[n][k] = *(const PG8_LAS bf16x8*)(lds + PG8_SB(b, h) + boff + n * 2048 + k * 1024); } while (0)
; #define PG8_MMA(ai, bj, At, Bt) do { __builtin_amdgcn_s_setprio(1); _Pragma("unroll") for (int m = 0; m < 4; ++m) _Pragma("unroll") for (int n = 0; n < 2; ++n) _Pragma("unroll") for (int k = 0; k < 2; ++k) \
;         acc[ai][bj][m][n] = __builtin_amdgcn_mfma_f32_16x16x32_bf16(Bt[n][k], At[m][k], acc[ai][bj][m][n], 0, 0, 0); __builtin_amdgcn_s_setprio(0); } while (0)
; #define PG8_WAIT_V(n) asm volatile("s_waitcnt vmcnt(" #n ")" ::: "memory")
; #define PG8_WAIT_L(n) asm volatile("s_waitcnt lgkmcnt(" #n ")" ::: "memory")
; #define PG8_BAR __builtin_amdgcn_s_barrier()
; #define PG8_SCHED __builtin_amdgcn_sched_barrier(0)
; template <class Epi, class Sched, bool ALIGN_EPI = false>
; __device__ __forceinline__ void gemm_phase(PG8_LAS unsigned char* lds, const Gemm g, const Sched& S, const Epi& E) {
;     ...
;             PG8_WAIT_V(8); PG8_WAIT_L(0); PG8_BAR; PG8_MMA(1, 0, At, B0); PG8_MMA(1, 1, At, B1); PG8_BAR; PG8_SCHED;
;             PG8_LDB(B0, 1, 0); PG8_LDB(B1, 1, 1); PG8_SCHED; PG8_LDA(At, 1, 0); PG8_STAGE(PG8_SA(0, 1), a2 + hstepA, voffA);
;             PG8_WAIT_V(8); PG8_WAIT_L(0); PG8_BAR; PG8_MMA(0, 0, At, B0); PG8_MMA(0, 1, At, B1); PG8_BAR; PG8_SCHED;
	s_waitcnt lgkmcnt(0)
	v_mfma_f32_16x16x32_bf16 v[94:97], v[150:153], v[182:185], v[94:97]
	v_mfma_f32_16x16x32_bf16 v[90:93], v[158:161], v[182:185], v[90:93]
	v_mfma_f32_16x16x32_bf16 v[86:89], v[150:153], v[190:193], v[86:89]
	v_mfma_f32_16x16x32_bf16 v[82:85], v[158:161], v[190:193], v[82:85]
	v_mfma_f32_16x16x32_bf16 v[78:81], v[150:153], v[198:201], v[78:81]
	v_mfma_f32_16x16x32_bf16 v[74:77], v[158:161], v[198:201], v[74:77]
	v_mfma_f32_16x16x32_bf16 v[70:73], v[150:153], v[206:209], v[70:73]
	v_mfma_f32_16x16x32_bf16 v[66:69], v[158:161], v[206:209], v[66:69]
	v_mfma_f32_16x16x32_bf16 v[94:97], v[154:157], v[186:189], v[94:97]
	v_mfma_f32_16x16x32_bf16 v[90:93], v[162:165], v[186:189], v[90:93]
	v_mfma_f32_16x16x32_bf16 v[86:89], v[154:157], v[194:197], v[86:89]
	v_mfma_f32_16x16x32_bf16 v[82:85], v[162:165], v[194:197], v[82:85]
	v_mfma_f32_16x16x32_bf16 v[78:81], v[154:157], v[202:205], v[78:81]
	v_mfma_f32_16x16x32_bf16 v[74:77], v[162:165], v[202:205], v[74:77]
	v_mfma_f32_16x16x32_bf16 v[70:73], v[154:157], v[210:213], v[70:73]
	v_mfma_f32_16x16x32_bf16 v[66:69], v[162:165], v[210:213], v[66:69]
	v_mfma_f32_16x16x32_bf16 v[30:33], v[166:169], v[182:185], v[30:33]
	v_mfma_f32_16x16x32_bf16 v[26:29], v[174:177], v[182:185], v[26:29]
	v_mfma_f32_16x16x32_bf16 v[22:25], v[166:169], v[190:193], v[22:25]
	v_mfma_f32_16x16x32_bf16 v[18:21], v[174:177], v[190:193], v[18:21]
	v_mfma_f32_16x16x32_bf16 v[14:17], v[166:169], v[198:201], v[14:17]
	v_mfma_f32_16x16x32_bf16 v[10:13], v[174:177], v[198:201], v[10:13]
	v_mfma_f32_16x16x32_bf16 v[6:9], v[166:169], v[206:209], v[6:9]
	v_mfma_f32_16x16x32_bf16 v[2:5], v[174:177], v[206:209], v[2:5]
	v_mfma_f32_16x16x32_bf16 v[30:33], v[170:173], v[186:189], v[30:33]
	v_mfma_f32_16x16x32_bf16 v[26:29], v[178:181], v[186:189], v[26:29]
	v_mfma_f32_16x16x32_bf16 v[22:25], v[170:173], v[194:197], v[22:25]
	v_mfma_f32_16x16x32_bf16 v[18:21], v[178:181], v[194:197], v[18:21]
	v_mfma_f32_16x16x32_bf16 v[14:17], v[170:173], v[202:205], v[14:17]
	v_mfma_f32_16x16x32_bf16 v[10:13], v[178:181], v[202:205], v[10:13]
	v_mfma_f32_16x16x32_bf16 v[6:9], v[170:173], v[210:213], v[6:9]
	v_mfma_f32_16x16x32_bf16 v[2:5], v[178:181], v[210:213], v[2:5]
	s_barrier
	s_add_i32 s60, 0, 0x18000
	v_add_u32_e32 v149, s60, v1
	s_add_i32 s61, 0, 0x1c000
	ds_read_b128 v[150:153], v149
	ds_read_b128 v[154:157], v149 offset:1024
	ds_read_b128 v[158:161], v149 offset:2048
	ds_read_b128 v[162:165], v149 offset:3072
	v_add_u32_e32 v149, s61, v1
	ds_read_b128 v[166:169], v149
	ds_read_b128 v[170:173], v149 offset:1024
	ds_read_b128 v[174:177], v149 offset:2048
	ds_read_b128 v[178:181], v149 offset:3072
	s_add_u32 s30, s30, 0x40000
	s_addc_u32 s31, s31, 0
	s_mov_b32 m0, s40
	v_lshl_add_u64 v[226:227], s[30:31], 0, v[136:137]
	ds_read_b128 v[182:185], v148 offset:32768
	ds_read_b128 v[186:189], v148 offset:33792
	ds_read_b128 v[190:193], v148 offset:34816
	ds_read_b128 v[194:197], v148 offset:35840
	ds_read_b128 v[198:201], v148 offset:36864
	ds_read_b128 v[202:205], v148 offset:37888
	ds_read_b128 v[206:209], v148 offset:38912
	ds_read_b128 v[210:213], v148 offset:39936
	global_load_lds_dwordx4 v[226:227], off
	v_lshl_add_u64 v[226:227], s[30:31], 0, v[132:133]
	s_mov_b32 m0, s41
	s_nop 0
	global_load_lds_dwordx4 v[226:227], off
	s_waitcnt vmcnt(8)
	s_waitcnt lgkmcnt(0)
	s_barrier
	s_waitcnt lgkmcnt(0)
	v_mfma_f32_16x16x32_bf16 v[126:129], v[150:153], v[182:185], v[126:129]
	v_mfma_f32_16x16x32_bf16 v[122:125], v[158:161], v[182:185], v[122:125]
	v_mfma_f32_16x16x32_bf16 v[118:121], v[150:153], v[190:193], v[118:121]
	v_mfma_f32_16x16x32_bf16 v[114:117], v[158:161], v[190:193], v[114:117]
	v_mfma_f32_16x16x32_bf16 v[110:113], v[150:153], v[198:201], v[110:113]
	v_mfma_f32_16x16x32_bf16 v[106:109], v[158:161], v[198:201], v[106:109]
	v_mfma_f32_16x16x32_bf16 v[102:105], v[150:153], v[206:209], v[102:105]
	v_mfma_f32_16x16x32_bf16 v[98:101], v[158:161], v[206:209], v[98:101]
	v_mfma_f32_16x16x32_bf16 v[126:129], v[154:157], v[186:189], v[126:129]
	v_mfma_f32_16x16x32_bf16 v[122:125], v[162:165], v[186:189], v[122:125]
	v_mfma_f32_16x16x32_bf16 v[118:121], v[154:157], v[194:197], v[118:121]
	v_mfma_f32_16x16x32_bf16 v[114:117], v[162:165], v[194:197], v[114:117]
	v_mfma_f32_16x16x32_bf16 v[110:113], v[154:157], v[202:205], v[110:113]
	v_mfma_f32_16x16x32_bf16 v[106:109], v[162:165], v[202:205], v[106:109]
	v_mfma_f32_16x16x32_bf16 v[102:105], v[154:157], v[210:213], v[102:105]
	v_mfma_f32_16x16x32_bf16 v[98:101], v[162:165], v[210:213], v[98:101]
	v_mfma_f32_16x16x32_bf16 v[62:65], v[166:169], v[182:185], v[62:65]
	v_mfma_f32_16x16x32_bf16 v[58:61], v[174:177], v[182:185], v[58:61]
	v_mfma_f32_16x16x32_bf16 v[54:57], v[166:169], v[190:193], v[54:57]
	v_mfma_f32_16x16x32_bf16 v[50:53], v[174:177], v[190:193], v[50:53]
	v_mfma_f32_16x16x32_bf16 v[46:49], v[166:169], v[198:201], v[46:49]
	v_mfma_f32_16x16x32_bf16 v[42:45], v[174:177], v[198:201], v[42:45]
	v_mfma_f32_16x16x32_bf16 v[38:41], v[166:169], v[206:209], v[38:41]
	v_mfma_f32_16x16x32_bf16 v[34:37], v[174:177], v[206:209], v[34:37]
	v_mfma_f32_16x16x32_bf16 v[62:65], v[170:173], v[186:189], v[62:65]
	v_mfma_f32_16x16x32_bf16 v[58:61], v[178:181], v[186:189], v[58:61]
	v_mfma_f32_16x16x32_bf16 v[54:57], v[170:173], v[194:197], v[54:57]
	v_mfma_f32_16x16x32_bf16 v[50:53], v[178:181], v[194:197], v[50:53]
	v_mfma_f32_16x16x32_bf16 v[46:49], v[170:173], v[202:205], v[46:49]
	v_mfma_f32_16x16x32_bf16 v[42:45], v[178:181], v[202:205], v[42:45]
	v_mfma_f32_16x16x32_bf16 v[38:41], v[170:173], v[210:213], v[38:41]
	v_mfma_f32_16x16x32_bf16 v[34:37], v[178:181], v[210:213], v[34:37]
	s_barrier
; #define PG8_STAGE(bufoff, gbase, voff) do { _Pragma("unroll") for (int _i = 0; _i < 2; ++_i) \
;         __builtin_amdgcn_global_load_lds((const unsigned*)((const char*)(gbase) + (voff)[_i]), (PG8_LAS unsigned*)(lds + (bufoff) + ldsw + _i * 8192), 16, 0, 0); } while (0)
; #define PG8_LDA(dst, b, h) do { _Pragma("unroll") for (int m = 0; m < 4; ++m) _Pragma("unroll") for (int k = 0; k < 2; ++k) dst[m][k] = *(const PG8_LAS bf16x8*)(lds + PG8_SA(b, h) + aoff + m * 2048 + k * 1024); } while (0)
; #define PG8_MMA(ai, bj, At, Bt) do { __builtin_amdgcn_s_setprio(1); _Pragma("unroll") for (int m = 0; m < 4; ++m) _Pragma("unroll") for (int n = 0; n < 2; ++n) _Pragma("unroll") for (int k = 0; k < 2; ++k) \
;         acc[ai][bj][m][n] = __builtin_amdgcn_mfma_f32_16x16x32_bf16(Bt[n][k], At[m][k], acc[ai][bj][m][n], 0, 0, 0); __builtin_amdgcn_s_setprio(0); } while (0)
; #define PG8_WAIT_V(n) asm volatile("s_waitcnt vmcnt(" #n ")" ::: "memory")
; #define PG8_WAIT_L(n) asm volatile("s_waitcnt lgkmcnt(" #n ")" ::: "memory")
; #define PG8_BAR __builtin_amdgcn_s_barrier()
; #define PG8_SCHED __builtin_amdgcn_sched_barrier(0)
; template <class Epi, class Sched, bool ALIGN_EPI = false>
; __device__ __forceinline__ void gemm_phase(PG8_LAS unsigned char* lds, const Gemm g, const Sched& S, const Epi& E) {
;     ...
;             PG8_LDA(At, 1, 1); PG8_STAGE(PG8_SB(1, 0), b3, voffB); PG8_STAGE(PG8_SB(1, 1), b3 + hstepB, voffB); PG8_STAGE(PG8_SA(1, 0), a3, voffA);
;             PG8_WAIT_V(8); PG8_WAIT_L(0); PG8_BAR; PG8_MMA(1, 0, At, B0); PG8_MMA(1, 1, At, B1); PG8_BAR; PG8_SCHED;
;         }
	s_add_i32 s30, s60, s0
	v_lshl_add_u64 v[214:215], v[214:215], 0, s[18:19]
	s_mov_b32 m0, s30
	ds_read_b128 v[182:185], v148 offset:49152
	ds_read_b128 v[186:189], v148 offset:50176
	ds_read_b128 v[190:193], v148 offset:51200
	ds_read_b128 v[194:197], v148 offset:52224
	ds_read_b128 v[198:201], v148 offset:53248
	ds_read_b128 v[202:205], v148 offset:54272
	ds_read_b128 v[206:209], v148 offset:55296
	ds_read_b128 v[210:213], v148 offset:56320
	global_load_lds_dwordx4 v[214:215], off
	v_lshl_add_u64 v[214:215], v[216:217], 0, s[18:19]
	s_add_i32 m0, s30, 0x2000
	s_add_i32 s30, s61, s0
	global_load_lds_dwordx4 v[214:215], off
	v_lshl_add_u64 v[214:215], v[218:219], 0, s[18:19]
	s_mov_b32 m0, s30
	s_nop 0
	global_load_lds_dwordx4 v[214:215], off
	v_lshl_add_u64 v[214:215], v[220:221], 0, s[18:19]
	s_add_i32 m0, s30, 0x2000
	s_nop 0
	global_load_lds_dwordx4 v[214:215], off
	v_lshl_add_u64 v[214:215], v[222:223], 0, s[18:19]
	s_mov_b32 m0, s44
	s_nop 0
	global_load_lds_dwordx4 v[214:215], off
	v_lshl_add_u64 v[214:215], v[224:225], 0, s[18:19]
	s_mov_b32 m0, s45
	s_nop 0
	global_load_lds_dwordx4 v[214:215], off
	s_waitcnt vmcnt(8)
	s_waitcnt lgkmcnt(0)
	s_barrier
	s_waitcnt lgkmcnt(0)
	v_mfma_f32_16x16x32_bf16 v[94:97], v[150:153], v[182:185], v[94:97]
	v_mfma_f32_16x16x32_bf16 v[90:93], v[158:161], v[182:185], v[90:93]
	v_mfma_f32_16x16x32_bf16 v[86:89], v[150:153], v[190:193], v[86:89]
	v_mfma_f32_16x16x32_bf16 v[82:85], v[158:161], v[190:193], v[82:85]
	v_mfma_f32_16x16x32_bf16 v[78:81], v[150:153], v[198:201], v[78:81]
	v_mfma_f32_16x16x32_bf16 v[74:77], v[158:161], v[198:201], v[74:77]
	v_mfma_f32_16x16x32_bf16 v[70:73], v[150:153], v[206:209], v[70:73]
	v_mfma_f32_16x16x32_bf16 v[66:69], v[158:161], v[206:209], v[66:69]
	v_mfma_f32_16x16x32_bf16 v[94:97], v[154:157], v[186:189], v[94:97]
	v_mfma_f32_16x16x32_bf16 v[90:93], v[162:165], v[186:189], v[90:93]
	v_mfma_f32_16x16x32_bf16 v[86:89], v[154:157], v[194:197], v[86:89]
	v_mfma_f32_16x16x32_bf16 v[82:85], v[162:165], v[194:197], v[82:85]
	v_mfma_f32_16x16x32_bf16 v[78:81], v[154:157], v[202:205], v[78:81]
	v_mfma_f32_16x16x32_bf16 v[74:77], v[162:165], v[202:205], v[74:77]
	v_mfma_f32_16x16x32_bf16 v[70:73], v[154:157], v[210:213], v[70:73]
	v_mfma_f32_16x16x32_bf16 v[66:69], v[162:165], v[210:213], v[66:69]
	v_mfma_f32_16x16x32_bf16 v[30:33], v[166:169], v[182:185], v[30:33]
	v_mfma_f32_16x16x32_bf16 v[26:29], v[174:177], v[182:185], v[26:29]
	v_mfma_f32_16x16x32_bf16 v[22:25], v[166:169], v[190:193], v[22:25]
	v_mfma_f32_16x16x32_bf16 v[18:21], v[174:177], v[190:193], v[18:21]
	v_mfma_f32_16x16x32_bf16 v[14:17], v[166:169], v[198:201], v[14:17]
	v_mfma_f32_16x16x32_bf16 v[10:13], v[174:177], v[198:201], v[10:13]
	v_mfma_f32_16x16x32_bf16 v[6:9], v[166:169], v[206:209], v[6:9]
	v_mfma_f32_16x16x32_bf16 v[2:5], v[174:177], v[206:209], v[2:5]
	v_mfma_f32_16x16x32_bf16 v[30:33], v[170:173], v[186:189], v[30:33]
	v_mfma_f32_16x16x32_bf16 v[26:29], v[178:181], v[186:189], v[26:29]
	v_mfma_f32_16x16x32_bf16 v[22:25], v[170:173], v[194:197], v[22:25]
	v_mfma_f32_16x16x32_bf16 v[18:21], v[178:181], v[194:197], v[18:21]
	v_mfma_f32_16x16x32_bf16 v[14:17], v[170:173], v[202:205], v[14:17]
	v_mfma_f32_16x16x32_bf16 v[10:13], v[178:181], v[202:205], v[10:13]
	v_mfma_f32_16x16x32_bf16 v[6:9], v[170:173], v[210:213], v[6:9]
	v_mfma_f32_16x16x32_bf16 v[2:5], v[178:181], v[210:213], v[2:5]
	s_barrier
	s_add_u32 s6, s6, 0x100
	s_addc_u32 s7, s7, 0
	s_add_u32 s34, s34, 0x100
	s_addc_u32 s35, s35, 0
	s_cmp_ge_i32 s55, s43
	s_mov_b32 s30, s55
	s_cbranch_scc0 .LBB0_1211

; __device__ __forceinline__ unsigned xb_ld(unsigned* p)              { return __hip_atomic_load(p, __ATOMIC_RELAXED, __HIP_MEMORY_SCOPE_AGENT); }
; __device__ __forceinline__ void xcd_barrier_complete(unsigned* bar, unsigned x, unsigned& nloc, unsigned& nx) {
;     const unsigned G = gridDim.x * gridDim.y * gridDim.z;
;     unsigned sum, cnt, mine, sp = 0u;
;     for (;;) {
;         sum = 0u; cnt = 0u; mine = 0u;
; #pragma unroll
;         for (unsigned j = 0; j < 16; ++j) { const unsigned c = xb_ld(&bar[XB_XCNT(j)]); sum += c; cnt += (c > 0u) ? 1u : 0u; mine = (j == x) ? c : mine; }
;         if (sum == G) break;
; __device__ __forceinline__ void xcd_barrier(const XcdBarrier& b) {
;     asm volatile("s_waitcnt vmcnt(0)" ::: "memory");
;     __syncthreads();
;     if (threadIdx.x == 0) {
;         unsigned* bar = b.bar;
;         __builtin_amdgcn_s_waitcnt(0);
;         unsigned nloc = b.st[0], nx = b.st[1];
;         if (nloc == 0u) { xcd_barrier_complete(bar, b.x, nloc, nx); b.st[0] = nloc; b.st[1] = nx; }
.LBB0_1218:
	s_setprio 0
	s_cmp_gt_i32 s59, 15
	s_cselect_b64 s[2:3], -1, 0
	s_and_b64 s[0:1], s[8:9], s[2:3]
	s_andn2_b64 vcc, exec, s[0:1]
	s_cbranch_vccnz .LBB0_1268
	s_waitcnt vmcnt(0)
	v_cmp_eq_u32_e32 vcc, 0, v0
	s_waitcnt vmcnt(0) lgkmcnt(0)
	s_barrier
	s_and_saveexec_b64 s[4:5], vcc
	s_cbranch_execz .LBB0_1267
	v_readlane_b32 s0, v228, 5
	s_waitcnt vmcnt(0) expcnt(0) lgkmcnt(0)
	s_nop 0
	v_mov_b32_e32 v1, s0
	ds_read_b32 v3, v1
	ds_read_b32 v1, v1 offset:4
	s_waitcnt lgkmcnt(1)
	v_cmp_ne_u32_e32 vcc, 0, v3
	s_cbranch_vccnz .LBB0_1235
	v_readlane_b32 s6, v228, 0
	v_readlane_b32 s7, v228, 1
	s_load_dwordx2 s[0:1], s[6:7], 0x4
	s_add_u32 s6, s56, 0x4200
	s_addc_u32 s7, s57, 0
	s_add_u32 s8, s56, 0x4400
	s_addc_u32 s9, s57, 0
	s_add_u32 s10, s56, 0x4500
	s_addc_u32 s11, s57, 0
	s_add_u32 s12, s56, 0x4600
	s_addc_u32 s13, s57, 0
	s_add_u32 s14, s56, 0x4700
	s_addc_u32 s15, s57, 0
	s_add_u32 s16, s56, 0x4800
	s_addc_u32 s17, s57, 0
	s_add_u32 s18, s56, 0x4900
	s_addc_u32 s19, s57, 0
	s_add_u32 s20, s56, 0x4a00
	s_addc_u32 s21, s57, 0
	s_add_u32 s22, s56, 0x4b00
	s_addc_u32 s23, s57, 0
	s_add_u32 s24, s56, 0x4c00
	s_addc_u32 s25, s57, 0
	s_add_u32 s26, s56, 0x4d00
	s_addc_u32 s27, s57, 0
	s_add_u32 s28, s56, 0x4e00
	s_addc_u32 s29, s57, 0
	s_add_u32 s30, s56, 0x4f00
	s_addc_u32 s31, s57, 0
	s_add_u32 s34, s56, 0x5000
	s_addc_u32 s35, s57, 0
	s_add_u32 s36, s56, 0x5100
	s_addc_u32 s37, s57, 0
	s_add_u32 s38, s56, 0x5200
	s_addc_u32 s39, s57, 0
	s_waitcnt lgkmcnt(0)
	s_mul_i32 s0, s0, s86
	s_add_u32 s40, s56, 0x5300
	s_mul_i32 s0, s0, s1
	s_addc_u32 s41, s57, 0
	s_mov_b32 s1, 1
	v_mov_b32_e32 v17, 0
	s_branch .LBB0_1223

;     __host__ __device__ bool next(int i, Unit& u) const {
;         const long L = (long)i * G + c; if (L >= nwg) return false;
;         int wgid = (int)L; { const int q = nwg / NXCD, r = nwg % NXCD, xcd = wgid % NXCD, off = wgid / NXCD; wgid = (xcd < r ? xcd * (q + 1) : r * (q + 1) + (xcd - r) * q) + off; }
;         const int nig = WGM * nN, gid = wgid / nig, fm = gid * WGM, gsz = (nM - fm) < WGM ? (nM - fm) : WGM;
;         u.pm = fm + ((wgid % nig) % gsz); u.pn = (wgid % nig) / gsz; return true;
.LBB0_1405:
	s_cmp_lt_i32 s58, 19
	s_cselect_b64 s[0:1], -1, 0
	s_and_b64 s[4:5], s[0:1], s[4:5]
	s_andn2_b64 vcc, exec, s[4:5]
	s_cbranch_vccnz .LBB0_1430
	v_readfirstlane_b32 s98, v0
	s_nop 3
	s_lshr_b32 s98, s98, 8
	s_cmp_eq_u32 s98, 0
	s_cbranch_scc0 .Lmy_prio6
	s_setprio 1
.Lmy_prio6:
	v_mov_b32_e32 v1, v0
	s_cmpk_gt_i32 s33, 0x1ff
	v_readfirstlane_b32 s14, v1
	s_cbranch_scc1 .LBB0_1430
	s_ashr_i32 s0, s33, 31
	s_lshr_b32 s1, s0, 29
	s_add_i32 s1, s33, s1
	s_and_b32 s2, s1, -8
	s_sub_i32 s7, s33, s2
	s_cmp_gt_i32 s7, -1
	s_cbranch_scc0 .LBB0_1409
	s_lshl_b32 s6, s7, 6
	s_cbranch_execz .LBB0_1410
	s_branch .LBB0_1411

; #define PG8_STAGE(bufoff, gbase, voff) do { _Pragma("unroll") for (int _i = 0; _i < 2; ++_i) \
;         __builtin_amdgcn_global_load_lds((const unsigned*)((const char*)(gbase) + (voff)[_i]), (PG8_LAS unsigned*)(lds + (bufoff) + ldsw + _i * 8192), 16, 0, 0); } while (0)
; #define PG8_LDA(dst, b, h) do { _Pragma("unroll") for (int m = 0; m < 4; ++m) _Pragma("unroll") for (int k = 0; k < 2; ++k) dst[m][k] = *(const PG8_LAS bf16x8*)(lds + PG8_SA(b, h) + aoff + m * 2048 + k * 1024); } while (0)
; #define PG8_LDB(dst, b, h) do { _Pragma("unroll") for (int n = 0; n < 2; ++n) _Pragma("unroll") for (int k = 0; k < 2; ++k) dst[n][k] = *(const PG8_LAS bf16x8*)(lds + PG8_SB(b, h) + boff + n * 2048 + k * 1024); } while (0)
; #define PG8_MMA(ai, bj, At, Bt) do { __builtin_amdgcn_s_setprio(1); _Pragma("unroll") for (int m = 0; m < 4; ++m) _Pragma("unroll") for (int n = 0; n < 2; ++n) _Pragma("unroll") for (int k = 0; k < 2; ++k) \
;         acc[ai][bj][m][n] = __builtin_amdgcn_mfma_f32_16x16x32_bf16(Bt[n][k], At[m][k], acc[ai][bj][m][n], 0, 0, 0); __builtin_amdgcn_s_setprio(0); } while (0)
; #define PG8_WAIT_V(n) asm volatile("s_waitcnt vmcnt(" #n ")" ::: "memory")
; #define PG8_WAIT_L(n) asm volatile("s_waitcnt lgkmcnt(" #n ")" ::: "memory")
; #define PG8_BAR __builtin_amdgcn_s_barrier()
; template <class Epi, class Sched, bool ALIGN_EPI = false>
; __device__ __forceinline__ void gemm_phase(PG8_LAS unsigned char* lds, const Gemm g, const Sched& S, const Epi& E) {
;     ...
;         for (int t = 0; t < nt; t += 2) {
;             const bool last = (t == nt - 2);
;             const char* a1 = cA + (size_t)(t + 1) * kstep;
;             const char* a2 = last ? nA : cA + (size_t)(t + 2) * kstep; const char* b2 = last ? nB : cB + (size_t)(t + 2) * kstep;
;             const char* a3 = a2 + kstep; const char* b3 = b2 + kstep;
;             if (last && has_next) S.a_ready(nxt);
;             PG8_LDB(B0, 0, 0); PG8_LDB(B1, 0, 1); PG8_SCHED; PG8_LDA(At, 0, 0); PG8_STAGE(PG8_SA(1, 1), a1 + hstepA, voffA);
;             PG8_WAIT_V(8); PG8_WAIT_L(0); PG8_BAR; PG8_MMA(0, 0, At, B0); PG8_MMA(0, 1, At, B1); PG8_BAR; PG8_SCHED;
;             PG8_LDA(At, 0, 1); PG8_STAGE(PG8_SB(0, 0), b2, voffB); PG8_STAGE(PG8_SB(0, 1), b2 + hstepB, voffB); PG8_STAGE(PG8_SA(0, 0), a2, voffA);
;             PG8_WAIT_V(8); PG8_WAIT_L(0); PG8_BAR; PG8_MMA(1, 0, At, B0); PG8_MMA(1, 1, At, B1); PG8_BAR; PG8_SCHED;
.LBB0_1423:
	ds_read_b128 v[146:149], v152
	ds_read_b128 v[156:159], v152 offset:1024
	ds_read_b128 v[160:163], v152 offset:2048
	ds_read_b128 v[164:167], v152 offset:3072
	ds_read_b128 v[168:171], v153
	ds_read_b128 v[172:175], v153 offset:1024
	ds_read_b128 v[176:179], v153 offset:2048
	ds_read_b128 v[180:183], v153 offset:3072
	s_add_u32 s36, s34, 0xfff00080
	s_addc_u32 s37, s35, -1
	s_cmp_eq_u32 s66, 60
	s_cselect_b32 s39, s25, s37
	s_cselect_b32 s38, s62, s36
	s_cselect_b32 s37, s23, s65
	s_cselect_b32 s36, s63, s64
	v_lshl_add_u64 v[150:151], s[34:35], 0, v[138:139]
	s_add_i32 m0, s31, 0xc000
	ds_read_b128 v[184:187], v154
	ds_read_b128 v[188:191], v154 offset:1024
	ds_read_b128 v[192:195], v154 offset:2048
	ds_read_b128 v[196:199], v154 offset:3072
	ds_read_b128 v[200:203], v154 offset:4096
	ds_read_b128 v[204:207], v154 offset:5120
	ds_read_b128 v[208:211], v154 offset:6144
	ds_read_b128 v[212:215], v154 offset:7168
	global_load_lds_dwordx4 v[150:151], off
	v_lshl_add_u64 v[150:151], s[34:35], 0, v[140:141]
	s_add_i32 m0, s31, 0xe000
	s_nop 0
	global_load_lds_dwordx4 v[150:151], off
	s_waitcnt vmcnt(8)
	s_waitcnt lgkmcnt(0)
	s_barrier
	s_waitcnt lgkmcnt(0)
	v_mfma_f32_16x16x32_bf16 v[126:129], v[146:149], v[184:187], v[126:129]
	v_mfma_f32_16x16x32_bf16 v[122:125], v[160:163], v[184:187], v[122:125]
	v_mfma_f32_16x16x32_bf16 v[114:117], v[146:149], v[192:195], v[114:117]
	v_mfma_f32_16x16x32_bf16 v[106:109], v[160:163], v[192:195], v[106:109]
	v_mfma_f32_16x16x32_bf16 v[98:101], v[146:149], v[200:203], v[98:101]
	v_mfma_f32_16x16x32_bf16 v[90:93], v[160:163], v[200:203], v[90:93]
	v_mfma_f32_16x16x32_bf16 v[82:85], v[146:149], v[208:211], v[82:85]
	v_mfma_f32_16x16x32_bf16 v[74:77], v[160:163], v[208:211], v[74:77]
	v_mfma_f32_16x16x32_bf16 v[126:129], v[156:159], v[188:191], v[126:129]
	v_mfma_f32_16x16x32_bf16 v[122:125], v[164:167], v[188:191], v[122:125]
	v_mfma_f32_16x16x32_bf16 v[114:117], v[156:159], v[196:199], v[114:117]
	v_mfma_f32_16x16x32_bf16 v[106:109], v[164:167], v[196:199], v[106:109]
	v_mfma_f32_16x16x32_bf16 v[98:101], v[156:159], v[204:207], v[98:101]
	v_mfma_f32_16x16x32_bf16 v[90:93], v[164:167], v[204:207], v[90:93]
	v_mfma_f32_16x16x32_bf16 v[82:85], v[156:159], v[212:215], v[82:85]
	v_mfma_f32_16x16x32_bf16 v[74:77], v[164:167], v[212:215], v[74:77]
	v_mfma_f32_16x16x32_bf16 v[118:121], v[168:171], v[184:187], v[118:121]
	v_mfma_f32_16x16x32_bf16 v[110:113], v[176:179], v[184:187], v[110:113]
	v_mfma_f32_16x16x32_bf16 v[102:105], v[168:171], v[192:195], v[102:105]
	v_mfma_f32_16x16x32_bf16 v[94:97], v[176:179], v[192:195], v[94:97]
	v_mfma_f32_16x16x32_bf16 v[86:89], v[168:171], v[200:203], v[86:89]
	v_mfma_f32_16x16x32_bf16 v[78:81], v[176:179], v[200:203], v[78:81]
	v_mfma_f32_16x16x32_bf16 v[70:73], v[168:171], v[208:211], v[70:73]
	v_mfma_f32_16x16x32_bf16 v[66:69], v[176:179], v[208:211], v[66:69]
	v_mfma_f32_16x16x32_bf16 v[118:121], v[172:175], v[188:191], v[118:121]
	v_mfma_f32_16x16x32_bf16 v[110:113], v[180:183], v[188:191], v[110:113]
	v_mfma_f32_16x16x32_bf16 v[102:105], v[172:175], v[196:199], v[102:105]
	v_mfma_f32_16x16x32_bf16 v[94:97], v[180:183], v[196:199], v[94:97]
	v_mfma_f32_16x16x32_bf16 v[86:89], v[172:175], v[204:207], v[86:89]
	v_mfma_f32_16x16x32_bf16 v[78:81], v[180:183], v[204:207], v[78:81]
	v_mfma_f32_16x16x32_bf16 v[70:73], v[172:175], v[212:215], v[70:73]
	v_mfma_f32_16x16x32_bf16 v[66:69], v[180:183], v[212:215], v[66:69]
	s_barrier
	s_add_i32 s67, s51, s43
	v_lshl_add_u64 v[150:151], s[36:37], 0, v[132:133]
	s_mov_b32 m0, s67
	ds_read_b128 v[184:187], v154 offset:16384
	ds_read_b128 v[188:191], v154 offset:17408
	ds_read_b128 v[192:195], v154 offset:18432
	ds_read_b128 v[196:199], v154 offset:19456
	ds_read_b128 v[200:203], v154 offset:20480
	ds_read_b128 v[204:207], v154 offset:21504
	ds_read_b128 v[208:211], v154 offset:22528
	ds_read_b128 v[212:215], v154 offset:23552
	global_load_lds_dwordx4 v[150:151], off
	s_add_i32 m0, s67, 0x2000
	s_add_u32 s68, s36, 0x100000
	v_lshl_add_u64 v[216:217], s[36:37], 0, v[136:137]
	s_addc_u32 s69, s37, 0
	s_add_i32 s67, s52, s43
	global_load_lds_dwordx4 v[216:217], off
	v_lshl_add_u64 v[218:219], s[68:69], 0, v[132:133]
	s_mov_b32 m0, s67
	v_lshl_add_u64 v[220:221], s[38:39], 0, v[134:135]
	global_load_lds_dwordx4 v[218:219], off
	v_lshl_add_u64 v[218:219], s[68:69], 0, v[136:137]
	s_add_i32 m0, s67, 0x2000
	s_nop 0
	global_load_lds_dwordx4 v[218:219], off
	v_lshl_add_u64 v[218:219], s[38:39], 0, v[130:131]
	s_mov_b32 m0, s31
	s_nop 0
	global_load_lds_dwordx4 v[218:219], off
	s_mov_b32 m0, s44
	s_nop 0
	global_load_lds_dwordx4 v[220:221], off
	s_waitcnt vmcnt(8)
	s_waitcnt lgkmcnt(0)
	s_barrier
; #define PG8_STAGE(bufoff, gbase, voff) do { _Pragma("unroll") for (int _i = 0; _i < 2; ++_i) \
;         __builtin_amdgcn_global_load_lds((const unsigned*)((const char*)(gbase) + (voff)[_i]), (PG8_LAS unsigned*)(lds + (bufoff) + ldsw + _i * 8192), 16, 0, 0); } while (0)
; #define PG8_LDA(dst, b, h) do { _Pragma("unroll") for (int m = 0; m < 4; ++m) _Pragma("unroll") for (int k = 0; k < 2; ++k) dst[m][k] = *(const PG8_LAS bf16x8*)(lds + PG8_SA(b, h) + aoff + m * 2048 + k * 1024); } while (0)
; #define PG8_LDB(dst, b, h) do { _Pragma("unroll") for (int n = 0; n < 2; ++n) _Pragma("unroll") for (int k = 0; k < 2; ++k) dst[n][k] = *(const PG8_LAS bf16x8*)(lds + PG8_SB(b, h) + boff + n * 2048 + k * 1024); } while (0)
; #define PG8_MMA(ai, bj, At, Bt) do { __builtin_amdgcn_s_setprio(1); _Pragma("unroll") for (int m = 0; m < 4; ++m) _Pragma("unroll") for (int n = 0; n < 2; ++n) _Pragma("unroll") for (int k = 0; k < 2; ++k) \
;         acc[ai][bj][m][n] = __builtin_amdgcn_mfma_f32_16x16x32_bf16(Bt[n][k], At[m][k], acc[ai][bj][m][n], 0, 0, 0); __builtin_amdgcn_s_setprio(0); } while (0)
; #define PG8_WAIT_V(n) asm volatile("s_waitcnt vmcnt(" #n ")" ::: "memory")
; #define PG8_WAIT_L(n) asm volatile("s_waitcnt lgkmcnt(" #n ")" ::: "memory")
; #define PG8_BAR __builtin_amdgcn_s_barrier()
; #define PG8_SCHED __builtin_amdgcn_sched_barrier(0)
; template <class Epi, class Sched, bool ALIGN_EPI = false>
; __device__ __forceinline__ void gemm_phase(PG8_LAS unsigned char* lds, const Gemm g, const Sched& S, const Epi& E) {
;     ...
;             PG8_WAIT_V(8); PG8_WAIT_L(0); PG8_BAR; PG8_MMA(1, 0, At, B0); PG8_MMA(1, 1, At, B1); PG8_BAR; PG8_SCHED;
;             PG8_LDB(B0, 1, 0); PG8_LDB(B1, 1, 1); PG8_SCHED; PG8_LDA(At, 1, 0); PG8_STAGE(PG8_SA(0, 1), a2 + hstepA, voffA);
;             PG8_WAIT_V(8); PG8_WAIT_L(0); PG8_BAR; PG8_MMA(0, 0, At, B0); PG8_MMA(0, 1, At, B1); PG8_BAR; PG8_SCHED;
	s_waitcnt lgkmcnt(0)
	v_mfma_f32_16x16x32_bf16 v[62:65], v[146:149], v[184:187], v[62:65]
	v_mfma_f32_16x16x32_bf16 v[58:61], v[160:163], v[184:187], v[58:61]
	v_mfma_f32_16x16x32_bf16 v[50:53], v[146:149], v[192:195], v[50:53]
	v_mfma_f32_16x16x32_bf16 v[42:45], v[160:163], v[192:195], v[42:45]
	v_mfma_f32_16x16x32_bf16 v[34:37], v[146:149], v[200:203], v[34:37]
	v_mfma_f32_16x16x32_bf16 v[26:29], v[160:163], v[200:203], v[26:29]
	v_mfma_f32_16x16x32_bf16 v[18:21], v[146:149], v[208:211], v[18:21]
	v_mfma_f32_16x16x32_bf16 v[10:13], v[160:163], v[208:211], v[10:13]
	v_mfma_f32_16x16x32_bf16 v[62:65], v[156:159], v[188:191], v[62:65]
	v_mfma_f32_16x16x32_bf16 v[58:61], v[164:167], v[188:191], v[58:61]
	v_mfma_f32_16x16x32_bf16 v[50:53], v[156:159], v[196:199], v[50:53]
	v_mfma_f32_16x16x32_bf16 v[42:45], v[164:167], v[196:199], v[42:45]
	v_mfma_f32_16x16x32_bf16 v[34:37], v[156:159], v[204:207], v[34:37]
	v_mfma_f32_16x16x32_bf16 v[26:29], v[164:167], v[204:207], v[26:29]
	v_mfma_f32_16x16x32_bf16 v[18:21], v[156:159], v[212:215], v[18:21]
	v_mfma_f32_16x16x32_bf16 v[10:13], v[164:167], v[212:215], v[10:13]
	v_mfma_f32_16x16x32_bf16 v[54:57], v[168:171], v[184:187], v[54:57]
	v_mfma_f32_16x16x32_bf16 v[46:49], v[176:179], v[184:187], v[46:49]
	v_mfma_f32_16x16x32_bf16 v[38:41], v[168:171], v[192:195], v[38:41]
	v_mfma_f32_16x16x32_bf16 v[30:33], v[176:179], v[192:195], v[30:33]
	v_mfma_f32_16x16x32_bf16 v[22:25], v[168:171], v[200:203], v[22:25]
	v_mfma_f32_16x16x32_bf16 v[14:17], v[176:179], v[200:203], v[14:17]
	v_mfma_f32_16x16x32_bf16 v[6:9], v[168:171], v[208:211], v[6:9]
	v_mfma_f32_16x16x32_bf16 v[2:5], v[176:179], v[208:211], v[2:5]
	v_mfma_f32_16x16x32_bf16 v[54:57], v[172:175], v[188:191], v[54:57]
	v_mfma_f32_16x16x32_bf16 v[46:49], v[180:183], v[188:191], v[46:49]
	v_mfma_f32_16x16x32_bf16 v[38:41], v[172:175], v[196:199], v[38:41]
	v_mfma_f32_16x16x32_bf16 v[30:33], v[180:183], v[196:199], v[30:33]
	v_mfma_f32_16x16x32_bf16 v[22:25], v[172:175], v[204:207], v[22:25]
	v_mfma_f32_16x16x32_bf16 v[14:17], v[180:183], v[204:207], v[14:17]
	v_mfma_f32_16x16x32_bf16 v[6:9], v[172:175], v[212:215], v[6:9]
	v_mfma_f32_16x16x32_bf16 v[2:5], v[180:183], v[212:215], v[2:5]
	s_barrier
	s_add_i32 s67, 0, 0x18000
	v_add_u32_e32 v155, s67, v1
	s_add_i32 s68, 0, 0x1c000
	ds_read_b128 v[146:149], v155
	ds_read_b128 v[156:159], v155 offset:1024
	ds_read_b128 v[160:163], v155 offset:2048
	ds_read_b128 v[164:167], v155 offset:3072
	v_add_u32_e32 v155, s68, v1
	ds_read_b128 v[168:171], v155
	ds_read_b128 v[172:175], v155 offset:1024
	ds_read_b128 v[176:179], v155 offset:2048
	ds_read_b128 v[180:183], v155 offset:3072
	s_add_u32 s38, s38, 0x100000
	s_addc_u32 s39, s39, 0
	s_mov_b32 m0, s45
	v_lshl_add_u64 v[222:223], s[38:39], 0, v[130:131]
	ds_read_b128 v[184:187], v154 offset:32768
	ds_read_b128 v[188:191], v154 offset:33792
	ds_read_b128 v[192:195], v154 offset:34816
	ds_read_b128 v[196:199], v154 offset:35840
	ds_read_b128 v[200:203], v154 offset:36864
	ds_read_b128 v[204:207], v154 offset:37888
	ds_read_b128 v[208:211], v154 offset:38912
	ds_read_b128 v[212:215], v154 offset:39936
	global_load_lds_dwordx4 v[222:223], off
	v_lshl_add_u64 v[222:223], s[38:39], 0, v[134:135]
	s_mov_b32 m0, s46
	s_nop 0
	global_load_lds_dwordx4 v[222:223], off
	s_waitcnt vmcnt(8)
	s_waitcnt lgkmcnt(0)
	s_barrier
	s_waitcnt lgkmcnt(0)
	v_mfma_f32_16x16x32_bf16 v[126:129], v[146:149], v[184:187], v[126:129]
	v_mfma_f32_16x16x32_bf16 v[122:125], v[160:163], v[184:187], v[122:125]
	v_mfma_f32_16x16x32_bf16 v[114:117], v[146:149], v[192:195], v[114:117]
	v_mfma_f32_16x16x32_bf16 v[106:109], v[160:163], v[192:195], v[106:109]
	v_mfma_f32_16x16x32_bf16 v[98:101], v[146:149], v[200:203], v[98:101]
	v_mfma_f32_16x16x32_bf16 v[90:93], v[160:163], v[200:203], v[90:93]
	v_mfma_f32_16x16x32_bf16 v[82:85], v[146:149], v[208:211], v[82:85]
	v_mfma_f32_16x16x32_bf16 v[74:77], v[160:163], v[208:211], v[74:77]
	v_mfma_f32_16x16x32_bf16 v[126:129], v[156:159], v[188:191], v[126:129]
	v_mfma_f32_16x16x32_bf16 v[122:125], v[164:167], v[188:191], v[122:125]
	v_mfma_f32_16x16x32_bf16 v[114:117], v[156:159], v[196:199], v[114:117]
	v_mfma_f32_16x16x32_bf16 v[106:109], v[164:167], v[196:199], v[106:109]
	v_mfma_f32_16x16x32_bf16 v[98:101], v[156:159], v[204:207], v[98:101]
	v_mfma_f32_16x16x32_bf16 v[90:93], v[164:167], v[204:207], v[90:93]
	v_mfma_f32_16x16x32_bf16 v[82:85], v[156:159], v[212:215], v[82:85]
	v_mfma_f32_16x16x32_bf16 v[74:77], v[164:167], v[212:215], v[74:77]
	v_mfma_f32_16x16x32_bf16 v[118:121], v[168:171], v[184:187], v[118:121]
	v_mfma_f32_16x16x32_bf16 v[110:113], v[176:179], v[184:187], v[110:113]
	v_mfma_f32_16x16x32_bf16 v[102:105], v[168:171], v[192:195], v[102:105]
	v_mfma_f32_16x16x32_bf16 v[94:97], v[176:179], v[192:195], v[94:97]
	v_mfma_f32_16x16x32_bf16 v[86:89], v[168:171], v[200:203], v[86:89]
	v_mfma_f32_16x16x32_bf16 v[78:81], v[176:179], v[200:203], v[78:81]
	v_mfma_f32_16x16x32_bf16 v[70:73], v[168:171], v[208:211], v[70:73]
	v_mfma_f32_16x16x32_bf16 v[66:69], v[176:179], v[208:211], v[66:69]
	v_mfma_f32_16x16x32_bf16 v[118:121], v[172:175], v[188:191], v[118:121]
	v_mfma_f32_16x16x32_bf16 v[110:113], v[180:183], v[188:191], v[110:113]
	v_mfma_f32_16x16x32_bf16 v[102:105], v[172:175], v[196:199], v[102:105]
	v_mfma_f32_16x16x32_bf16 v[94:97], v[180:183], v[196:199], v[94:97]
	v_mfma_f32_16x16x32_bf16 v[86:89], v[172:175], v[204:207], v[86:89]
	v_mfma_f32_16x16x32_bf16 v[78:81], v[180:183], v[204:207], v[78:81]
	v_mfma_f32_16x16x32_bf16 v[70:73], v[172:175], v[212:215], v[70:73]
	v_mfma_f32_16x16x32_bf16 v[66:69], v[180:183], v[212:215], v[66:69]
	s_barrier
; #define PG8_STAGE(bufoff, gbase, voff) do { _Pragma("unroll") for (int _i = 0; _i < 2; ++_i) \
;         __builtin_amdgcn_global_load_lds((const unsigned*)((const char*)(gbase) + (voff)[_i]), (PG8_LAS unsigned*)(lds + (bufoff) + ldsw + _i * 8192), 16, 0, 0); } while (0)
; #define PG8_LDA(dst, b, h) do { _Pragma("unroll") for (int m = 0; m < 4; ++m) _Pragma("unroll") for (int k = 0; k < 2; ++k) dst[m][k] = *(const PG8_LAS bf16x8*)(lds + PG8_SA(b, h) + aoff + m * 2048 + k * 1024); } while (0)
; #define PG8_MMA(ai, bj, At, Bt) do { __builtin_amdgcn_s_setprio(1); _Pragma("unroll") for (int m = 0; m < 4; ++m) _Pragma("unroll") for (int n = 0; n < 2; ++n) _Pragma("unroll") for (int k = 0; k < 2; ++k) \
;         acc[ai][bj][m][n] = __builtin_amdgcn_mfma_f32_16x16x32_bf16(Bt[n][k], At[m][k], acc[ai][bj][m][n], 0, 0, 0); __builtin_amdgcn_s_setprio(0); } while (0)
; #define PG8_WAIT_V(n) asm volatile("s_waitcnt vmcnt(" #n ")" ::: "memory")
; #define PG8_WAIT_L(n) asm volatile("s_waitcnt lgkmcnt(" #n ")" ::: "memory")
; #define PG8_BAR __builtin_amdgcn_s_barrier()
; #define PG8_SCHED __builtin_amdgcn_sched_barrier(0)
; template <class Epi, class Sched, bool ALIGN_EPI = false>
; __device__ __forceinline__ void gemm_phase(PG8_LAS unsigned char* lds, const Gemm g, const Sched& S, const Epi& E) {
;     ...
;             PG8_LDA(At, 1, 1); PG8_STAGE(PG8_SB(1, 0), b3, voffB); PG8_STAGE(PG8_SB(1, 1), b3 + hstepB, voffB); PG8_STAGE(PG8_SA(1, 0), a3, voffA);
;             PG8_WAIT_V(8); PG8_WAIT_L(0); PG8_BAR; PG8_MMA(1, 0, At, B0); PG8_MMA(1, 1, At, B1); PG8_BAR; PG8_SCHED;
;         }
;         if constexpr (ALIGN_EPI) { if (wr == 0) PG8_BAR; }
	s_add_i32 s38, s67, s43
	v_lshl_add_u64 v[150:151], v[150:151], 0, s[12:13]
	s_mov_b32 m0, s38
	ds_read_b128 v[184:187], v154 offset:49152
	ds_read_b128 v[188:191], v154 offset:50176
	ds_read_b128 v[192:195], v154 offset:51200
	ds_read_b128 v[196:199], v154 offset:52224
	ds_read_b128 v[200:203], v154 offset:53248
	ds_read_b128 v[204:207], v154 offset:54272
	ds_read_b128 v[208:211], v154 offset:55296
	ds_read_b128 v[212:215], v154 offset:56320
	global_load_lds_dwordx4 v[150:151], off
	s_add_i32 m0, s38, 0x2000
	s_add_u32 s36, s36, 0x100080
	v_lshl_add_u64 v[150:151], v[216:217], 0, s[12:13]
	s_addc_u32 s37, s37, 0
	s_add_i32 s38, s68, s43
	global_load_lds_dwordx4 v[150:151], off
	v_lshl_add_u64 v[150:151], s[36:37], 0, v[132:133]
	s_mov_b32 m0, s38
	s_nop 0
	global_load_lds_dwordx4 v[150:151], off
	v_lshl_add_u64 v[150:151], s[36:37], 0, v[136:137]
	s_add_i32 m0, s38, 0x2000
	s_nop 0
	global_load_lds_dwordx4 v[150:151], off
	v_lshl_add_u64 v[150:151], v[218:219], 0, s[12:13]
	s_mov_b32 m0, s48
	s_nop 0
	global_load_lds_dwordx4 v[150:151], off
	v_lshl_add_u64 v[150:151], v[220:221], 0, s[12:13]
	s_mov_b32 m0, s49
	s_nop 0
	global_load_lds_dwordx4 v[150:151], off
	s_waitcnt vmcnt(8)
	s_waitcnt lgkmcnt(0)
	s_barrier
	s_waitcnt lgkmcnt(0)
	v_mfma_f32_16x16x32_bf16 v[62:65], v[146:149], v[184:187], v[62:65]
	v_mfma_f32_16x16x32_bf16 v[58:61], v[160:163], v[184:187], v[58:61]
	v_mfma_f32_16x16x32_bf16 v[50:53], v[146:149], v[192:195], v[50:53]
	v_mfma_f32_16x16x32_bf16 v[42:45], v[160:163], v[192:195], v[42:45]
	v_mfma_f32_16x16x32_bf16 v[34:37], v[146:149], v[200:203], v[34:37]
	v_mfma_f32_16x16x32_bf16 v[26:29], v[160:163], v[200:203], v[26:29]
	v_mfma_f32_16x16x32_bf16 v[18:21], v[146:149], v[208:211], v[18:21]
	v_mfma_f32_16x16x32_bf16 v[10:13], v[160:163], v[208:211], v[10:13]
	v_mfma_f32_16x16x32_bf16 v[62:65], v[156:159], v[188:191], v[62:65]
	v_mfma_f32_16x16x32_bf16 v[58:61], v[164:167], v[188:191], v[58:61]
	v_mfma_f32_16x16x32_bf16 v[50:53], v[156:159], v[196:199], v[50:53]
	v_mfma_f32_16x16x32_bf16 v[42:45], v[164:167], v[196:199], v[42:45]
	v_mfma_f32_16x16x32_bf16 v[34:37], v[156:159], v[204:207], v[34:37]
	v_mfma_f32_16x16x32_bf16 v[26:29], v[164:167], v[204:207], v[26:29]
	v_mfma_f32_16x16x32_bf16 v[18:21], v[156:159], v[212:215], v[18:21]
	v_mfma_f32_16x16x32_bf16 v[10:13], v[164:167], v[212:215], v[10:13]
	v_mfma_f32_16x16x32_bf16 v[54:57], v[168:171], v[184:187], v[54:57]
	v_mfma_f32_16x16x32_bf16 v[46:49], v[176:179], v[184:187], v[46:49]
	v_mfma_f32_16x16x32_bf16 v[38:41], v[168:171], v[192:195], v[38:41]
	v_mfma_f32_16x16x32_bf16 v[30:33], v[176:179], v[192:195], v[30:33]
	v_mfma_f32_16x16x32_bf16 v[22:25], v[168:171], v[200:203], v[22:25]
	v_mfma_f32_16x16x32_bf16 v[14:17], v[176:179], v[200:203], v[14:17]
	v_mfma_f32_16x16x32_bf16 v[6:9], v[168:171], v[208:211], v[6:9]
	v_mfma_f32_16x16x32_bf16 v[2:5], v[176:179], v[208:211], v[2:5]
	v_mfma_f32_16x16x32_bf16 v[54:57], v[172:175], v[188:191], v[54:57]
	v_mfma_f32_16x16x32_bf16 v[46:49], v[180:183], v[188:191], v[46:49]
	v_mfma_f32_16x16x32_bf16 v[38:41], v[172:175], v[196:199], v[38:41]
	v_mfma_f32_16x16x32_bf16 v[30:33], v[180:183], v[196:199], v[30:33]
	v_mfma_f32_16x16x32_bf16 v[22:25], v[172:175], v[204:207], v[22:25]
	v_mfma_f32_16x16x32_bf16 v[14:17], v[180:183], v[204:207], v[14:17]
	v_mfma_f32_16x16x32_bf16 v[6:9], v[172:175], v[212:215], v[6:9]
	v_mfma_f32_16x16x32_bf16 v[2:5], v[180:183], v[212:215], v[2:5]
	s_barrier
	s_add_i32 s66, s66, 2
	s_add_u32 s34, s34, 0x100
	s_addc_u32 s35, s35, 0
	s_add_u32 s64, s64, 0x100
	s_addc_u32 s65, s65, 0
	s_cmp_gt_u32 s66, 61
	s_cbranch_scc0 .LBB0_1423
	s_and_b64 vcc, exec, s[14:15]
	s_cbranch_vccz .LBB0_1426
	s_barrier

; __device__ __forceinline__ unsigned xb_ld(unsigned* p)              { return __hip_atomic_load(p, __ATOMIC_RELAXED, __HIP_MEMORY_SCOPE_AGENT); }
; __device__ __forceinline__ void xcd_barrier_complete(unsigned* bar, unsigned x, unsigned& nloc, unsigned& nx) {
;     const unsigned G = gridDim.x * gridDim.y * gridDim.z;
;     unsigned sum, cnt, mine, sp = 0u;
;     for (;;) {
;         sum = 0u; cnt = 0u; mine = 0u;
; #pragma unroll
;         for (unsigned j = 0; j < 16; ++j) { const unsigned c = xb_ld(&bar[XB_XCNT(j)]); sum += c; cnt += (c > 0u) ? 1u : 0u; mine = (j == x) ? c : mine; }
; __device__ __forceinline__ void xcd_barrier(const XcdBarrier& b) {
;     asm volatile("s_waitcnt vmcnt(0)" ::: "memory");
;     __syncthreads();
;     if (threadIdx.x == 0) {
;         unsigned* bar = b.bar;
;         __builtin_amdgcn_s_waitcnt(0);
;         unsigned nloc = b.st[0], nx = b.st[1];
;         if (nloc == 0u) { xcd_barrier_complete(bar, b.x, nloc, nx); b.st[0] = nloc; b.st[1] = nx; }
.LBB0_1430:
	s_setprio 0
	s_cmp_gt_i32 s59, 19
	s_cselect_b64 s[2:3], -1, 0
	s_and_b64 s[0:1], s[4:5], s[2:3]
	s_andn2_b64 vcc, exec, s[0:1]
	s_cbranch_vccnz .LBB0_1480
	s_waitcnt vmcnt(0)
	v_cmp_eq_u32_e32 vcc, 0, v0
	s_waitcnt vmcnt(0) lgkmcnt(0)
	s_barrier
	s_and_saveexec_b64 s[4:5], vcc
	s_cbranch_execz .LBB0_1479
	v_readlane_b32 s0, v228, 5
	s_waitcnt vmcnt(0) expcnt(0) lgkmcnt(0)
	s_nop 0
	v_mov_b32_e32 v1, s0
	ds_read_b32 v3, v1
	ds_read_b32 v1, v1 offset:4
	s_waitcnt lgkmcnt(1)
	v_cmp_ne_u32_e32 vcc, 0, v3
	s_cbranch_vccnz .LBB0_1447
	v_readlane_b32 s6, v228, 0
	v_readlane_b32 s7, v228, 1
	s_load_dwordx2 s[0:1], s[6:7], 0x4
	s_add_u32 s6, s56, 0x4200
	s_addc_u32 s7, s57, 0
	s_add_u32 s8, s56, 0x4400
	s_addc_u32 s9, s57, 0
	s_add_u32 s10, s56, 0x4500
	s_addc_u32 s11, s57, 0
	s_add_u32 s12, s56, 0x4600
	s_addc_u32 s13, s57, 0
	s_add_u32 s14, s56, 0x4700
	s_addc_u32 s15, s57, 0
	s_add_u32 s16, s56, 0x4800
	s_addc_u32 s17, s57, 0
	s_add_u32 s18, s56, 0x4900
	s_addc_u32 s19, s57, 0
	s_add_u32 s20, s56, 0x4a00
	s_addc_u32 s21, s57, 0
	s_add_u32 s22, s56, 0x4b00
	s_addc_u32 s23, s57, 0
	s_add_u32 s24, s56, 0x4c00
	s_addc_u32 s25, s57, 0
	s_add_u32 s26, s56, 0x4d00
	s_addc_u32 s27, s57, 0
	s_add_u32 s28, s56, 0x4e00
	s_addc_u32 s29, s57, 0
	s_add_u32 s30, s56, 0x4f00
	s_addc_u32 s31, s57, 0
	s_add_u32 s34, s56, 0x5000
	s_addc_u32 s35, s57, 0
	s_add_u32 s36, s56, 0x5100
	s_addc_u32 s37, s57, 0
	s_add_u32 s38, s56, 0x5200
	s_addc_u32 s39, s57, 0
	s_waitcnt lgkmcnt(0)
	s_mul_i32 s0, s0, s86
	s_add_u32 s40, s56, 0x5300
	s_mul_i32 s0, s0, s1
	s_addc_u32 s41, s57, 0
	s_mov_b32 s1, 1
	v_mov_b32_e32 v17, 0
	s_branch .LBB0_1435

; #define PG8_STAGE(bufoff, gbase, voff) do { _Pragma("unroll") for (int _i = 0; _i < 2; ++_i) \
;         __builtin_amdgcn_global_load_lds((const unsigned*)((const char*)(gbase) + (voff)[_i]), (PG8_LAS unsigned*)(lds + (bufoff) + ldsw + _i * 8192), 16, 0, 0); } while (0)
; #define PG8_BAR __builtin_amdgcn_s_barrier()
; template <class Epi, class Sched, bool ALIGN_EPI = false>
; __device__ __forceinline__ void gemm_phase(PG8_LAS unsigned char* lds, const Gemm g, const Sched& S, const Epi& E) {
;     int tid_ = threadIdx.x; asm volatile("" : "+v"(tid_));
;     const int tid = tid_, wid = __builtin_amdgcn_readfirstlane(tid >> 6), lane = tid & 63, wr = wid >> 2, wc = wid & 3, fr = lane & 15, fq = lane >> 4;
;     const int K = g.K, nt = K / BK;
;     unsigned voffA[2], voffB[2];
; #pragma unroll
;     for (int i = 0; i < 2; ++i) { int R, C; stage_rc(tid * 16 + i * 8192, R, C); const int Rb = Epi::PERM ? ((R & ~31) + perm32(R & 31)) : R;
;         voffA[i] = (unsigned)(R * g.lda + C) * 2u; voffB[i] = (unsigned)(Rb * g.ldb + C) * 2u; }
;     const size_t kstep = (size_t)(BK * 2);
;     const size_t hstepA = (size_t)HALF * g.lda * 2, hstepB = (size_t)HALF * g.ldb * 2;
;     const size_t tstepA = 2 * hstepA, tstepB = 2 * hstepB;
;     const unsigned ldsw = (unsigned)wid * 1024u;
;     const int aoff = lds_byte(wr * 64 + fr, fq * 8), boff = lds_byte(wc * 32 + fr, fq * 8);
;     ...
;     Unit cur, nxt; int ui = 0;
;     if (!S.next(0, cur)) return;
;     f32x4 acc[2][2][4][2];
; #pragma unroll
;     for (int a = 0; a < 2; ++a)
; #pragma unroll
;         for (int b = 0; b < 2; ++b)
; #pragma unroll
;             for (int m = 0; m < 4; ++m)
; #pragma unroll
;                 for (int n = 0; n < 2; ++n) acc[a][b][m][n] = (f32x4){0.f, 0.f, 0.f, 0.f};
;     bf16x8 At[4][2], B0[2][2], B1[2][2];
;     const char* cA = (const char*)g.A + (size_t)cur.pm * tstepA; const char* cB = (const char*)g.Bt + (size_t)cur.pn * tstepB;
;     S.a_ready(cur);
;     PG8_STAGE(PG8_SB(0, 0), cB, voffB); PG8_STAGE(PG8_SB(0, 1), cB + hstepB, voffB); PG8_STAGE(PG8_SA(0, 0), cA, voffA); PG8_STAGE(PG8_SA(0, 1), cA + hstepA, voffA);
;     if (wr == 1) PG8_BAR;
; __global__ void __launch_bounds__(NTHREADS, 2) mk_fwd(Args args) {
;     ...
;     if (IN(20)) { KARG_DECL(); for (int rep_ = 0; rep_ < REP_UP; ++rep_) GEMM_CONVACT(WSB(WS_H), WSB(WS_WUP) + WUP_L, INF(26) + 3 * DFF, INF(27) + DFF); }
.LBB0_1534:
	s_cmp_lt_i32 s58, 21
	s_cselect_b64 s[0:1], -1, 0
	s_and_b64 s[10:11], s[0:1], s[2:3]
	s_andn2_b64 vcc, exec, s[10:11]
	s_cbranch_vccnz .LBB0_1563
	v_readfirstlane_b32 s98, v0
	s_nop 3
	s_lshr_b32 s98, s98, 8
	s_cmp_eq_u32 s98, 0
	s_cbranch_scc0 .Lmy_prio7
	s_setprio 1
.Lmy_prio7:
	s_mov_b64 s[2:3], s[82:83]
	v_mov_b32_e32 v1, v0
	s_cmpk_gt_i32 s33, 0xdff
	s_nop 0
	v_readfirstlane_b32 s35, v1
	s_cbranch_scc1 .LBB0_1563
	v_lshlrev_b32_e32 v2, 4, v1
	v_add_u32_e32 v3, 0x2000, v2
	v_ashrrev_i32_e32 v4, 31, v3
	v_lshrrev_b32_e32 v4, 22, v4
	v_add_u32_e32 v4, v3, v4
	v_ashrrev_i32_e32 v10, 10, v4
	v_mul_i32_i24_e32 v4, 0x400, v10
	v_sub_u32_e32 v3, v3, v4
	v_lshrrev_b32_e32 v4, 4, v3
	v_bitop3_b32 v3, v4, v3, 32 bitop3:0x6c
	v_ashrrev_i32_e32 v4, 31, v3
	v_lshrrev_b32_e32 v4, 26, v4
	v_add_u32_e32 v4, v3, v4
	v_lshlrev_b32_e32 v5, 3, v10
	v_ashrrev_i32_e32 v11, 6, v4
	v_and_b32_e32 v5, -16, v5
	v_add_u32_e32 v5, v11, v5
	v_and_b32_e32 v6, 3, v11
	s_mov_b32 s4, 0x7ffe0
	v_lshrrev_b32_e32 v7, 2, v5
	v_lshlrev_b32_e32 v8, 1, v5
	v_and_b32_e32 v4, 0xc0, v4
	v_and_or_b32 v6, v5, s4, v6
	v_and_b32_e32 v7, 4, v7
	v_and_b32_e32 v8, 24, v8
	v_sub_u32_e32 v3, v3, v4
	v_mov_b32_e32 v4, 1
	v_or3_b32 v6, v6, v7, v8
	v_lshlrev_b32_e32 v7, 5, v10
	v_ashrrev_i16_sdwa v3, v4, sext(v3) dst_sel:DWORD dst_unused:UNUSED_PAD src0_sel:DWORD src1_sel:BYTE_0
	v_and_b32_e32 v7, 32, v7
	v_bfe_i32 v12, v3, 0, 16
	v_add_lshl_u32 v3, v7, v12, 1
	v_lshl_add_u32 v146, v6, 13, v3
	v_lshl_add_u32 v148, v5, 13, v3
	v_bfe_i32 v3, v1, 27, 1
	v_lshrrev_b32_e32 v3, 22, v3
	v_add_u32_e32 v3, v2, v3
	v_and_b32_e32 v3, 0xfffffc00, v3
	v_sub_u32_e32 v2, v2, v3
	v_lshrrev_b32_e32 v3, 4, v2
	v_ashrrev_i32_e32 v5, 31, v1
	v_bitop3_b32 v2, v3, v2, 32 bitop3:0x6c
	v_lshrrev_b32_e32 v5, 26, v5
	v_ashrrev_i32_e32 v3, 31, v2
	v_add_u32_e32 v5, v1, v5
	s_add_u32 s0, s56, 0x41200000
	v_lshrrev_b32_e32 v3, 26, v3
	v_ashrrev_i32_e32 v14, 6, v5
	s_addc_u32 s1, s57, 0
	v_add_u32_e32 v3, v2, v3
	v_lshlrev_b32_e32 v5, 3, v14
	s_add_u32 s52, s56, 0x1d200000
	v_ashrrev_i32_e32 v13, 6, v3
	v_and_b32_e32 v5, -16, v5
	s_addc_u32 s53, s57, 0
	v_add_u32_e32 v5, v13, v5
	v_and_b32_e32 v6, 3, v13
	s_ashr_i32 s55, s33, 31
	v_and_or_b32 v6, v5, s4, v6
	s_lshr_b32 s4, s55, 29
	s_add_i32 s4, s33, s4
	s_ashr_i32 s30, s35, 6
	s_ashr_i32 s5, s4, 3
	s_and_b32 s4, s4, -8
	s_ashr_i32 s31, s35, 8
	s_lshl_b32 s54, s30, 10
	s_sub_i32 s4, s33, s4
	s_cmp_lt_i32 s4, 0
	s_movk_i32 s60, 0x1c1
	s_cselect_b32 s6, s60, 0x1c0
	s_mul_i32 s4, s4, s6
	s_add_i32 s4, s4, s5
	s_mul_hi_i32 s5, s4, 0x92492493
	s_add_i32 s5, s5, s4
	s_lshr_b32 s6, s5, 31
	s_ashr_i32 s5, s5, 9
	s_add_i32 s5, s5, s6
	s_lshl_b32 s6, s5, 3
	s_mulk_i32 s5, 0x380
	s_sub_i32 s4, s4, s5
	s_sext_i32_i16 s5, s4
	s_bfe_u32 s5, s5, 0x3001c
	s_add_i32 s5, s4, s5
	s_sext_i32_i16 s7, s5
	s_and_b32 s5, s5, 0xfff8
	s_sub_i32 s4, s4, s5
	s_sext_i32_i16 s4, s4
	v_lshrrev_b32_e32 v7, 2, v5
	v_lshlrev_b32_e32 v8, 1, v5
	v_and_b32_e32 v3, 0xc0, v3
	s_lshr_b32 s34, s7, 3
	s_add_i32 s8, s6, s4
	v_and_b32_e32 v7, 4, v7
	v_and_b32_e32 v8, 24, v8
	v_sub_u32_e32 v2, v2, v3
	s_ashr_i32 s9, s8, 31
	s_bfe_i64 s[6:7], s[34:35], 0x100000
	v_or3_b32 v6, v6, v7, v8
	v_lshlrev_b32_e32 v7, 5, v14
	v_ashrrev_i16_sdwa v2, v4, sext(v2) dst_sel:DWORD dst_unused:UNUSED_PAD src0_sel:DWORD src1_sel:BYTE_0
	s_lshl_b64 s[4:5], s[8:9], 21
	s_lshl_b64 s[6:7], s[6:7], 21
	v_and_b32_e32 v7, 32, v7
	v_bfe_i32 v15, v2, 0, 16
	s_add_u32 s48, s52, s6
	v_add_lshl_u32 v2, v7, v15, 1
	s_addc_u32 s49, s53, s7
	s_add_i32 s61, s54, 0
	v_lshl_add_u32 v150, v6, 13, v2
	s_add_i32 m0, s61, 0x10000
	v_lshl_add_u32 v152, v5, 13, v2
	global_load_lds_dwordx4 v150, s[48:49]
	s_add_i32 m0, s61, 0x12000
	s_add_u32 s6, s48, 0x100000
	global_load_lds_dwordx4 v146, s[48:49]
	s_addc_u32 s7, s49, 0
	s_add_i32 m0, s61, 0x14000
	v_mov_b32_e32 v155, 0
	global_load_lds_dwordx4 v150, s[6:7]
	s_add_i32 m0, s61, 0x16000
	s_add_u32 s50, s0, s4
	s_addc_u32 s51, s1, s5
	s_add_i32 s62, s61, 0x2000
	global_load_lds_dwordx4 v146, s[6:7]
	s_mov_b32 m0, s61
	s_add_u32 s4, s50, 0x100000
	global_load_lds_dwordx4 v152, s[50:51]
	s_mov_b32 m0, s62
	s_addc_u32 s5, s51, 0
	s_add_i32 s63, s61, 0x4000
	global_load_lds_dwordx4 v148, s[50:51]
	s_mov_b32 m0, s63
	s_add_i32 s64, s61, 0x6000
	global_load_lds_dwordx4 v152, s[4:5]
	s_mov_b32 m0, s64
	v_mov_b32_e32 v151, v155
	global_load_lds_dwordx4 v148, s[4:5]
	s_load_dwordx4 s[4:7], s[2:3], 0xd0
	v_mov_b32_e32 v147, v155
	v_mov_b32_e32 v153, v155
	v_mov_b32_e32 v149, v155
	s_cmp_eq_u32 s31, 1
	s_mov_b32 s65, 0
	v_lshl_add_u64 v[8:9], s[48:49], 0, v[150:151]
	v_lshl_add_u64 v[6:7], s[48:49], 0, v[146:147]
	v_lshl_add_u64 v[2:3], s[50:51], 0, v[152:153]
	s_waitcnt lgkmcnt(0)
	s_cselect_b64 s[12:13], -1, 0
	s_cmp_lg_u32 s31, 1
	v_lshl_add_u64 v[4:5], s[50:51], 0, v[148:149]
	s_cbranch_scc1 .LBB0_1538
	s_barrier

; #define PG8_STAGE(bufoff, gbase, voff) do { _Pragma("unroll") for (int _i = 0; _i < 2; ++_i) \
;         __builtin_amdgcn_global_load_lds((const unsigned*)((const char*)(gbase) + (voff)[_i]), (PG8_LAS unsigned*)(lds + (bufoff) + ldsw + _i * 8192), 16, 0, 0); } while (0)
; #define PG8_LDA(dst, b, h) do { _Pragma("unroll") for (int m = 0; m < 4; ++m) _Pragma("unroll") for (int k = 0; k < 2; ++k) dst[m][k] = *(const PG8_LAS bf16x8*)(lds + PG8_SA(b, h) + aoff + m * 2048 + k * 1024); } while (0)
; #define PG8_LDB(dst, b, h) do { _Pragma("unroll") for (int n = 0; n < 2; ++n) _Pragma("unroll") for (int k = 0; k < 2; ++k) dst[n][k] = *(const PG8_LAS bf16x8*)(lds + PG8_SB(b, h) + boff + n * 2048 + k * 1024); } while (0)
; #define PG8_MMA(ai, bj, At, Bt) do { __builtin_amdgcn_s_setprio(1); _Pragma("unroll") for (int m = 0; m < 4; ++m) _Pragma("unroll") for (int n = 0; n < 2; ++n) _Pragma("unroll") for (int k = 0; k < 2; ++k) \
;         acc[ai][bj][m][n] = __builtin_amdgcn_mfma_f32_16x16x32_bf16(Bt[n][k], At[m][k], acc[ai][bj][m][n], 0, 0, 0); __builtin_amdgcn_s_setprio(0); } while (0)
; #define PG8_WAIT_V(n) asm volatile("s_waitcnt vmcnt(" #n ")" ::: "memory")
; #define PG8_WAIT_L(n) asm volatile("s_waitcnt lgkmcnt(" #n ")" ::: "memory")
; #define PG8_BAR __builtin_amdgcn_s_barrier()
; #define PG8_SCHED __builtin_amdgcn_sched_barrier(0)
; template <class Epi, class Sched, bool ALIGN_EPI = false>
; __device__ __forceinline__ void gemm_phase(PG8_LAS unsigned char* lds, const Gemm g, const Sched& S, const Epi& E) {
;     ...
;             PG8_LDB(B0, 0, 0); PG8_LDB(B1, 0, 1); PG8_SCHED; PG8_LDA(At, 0, 0); PG8_STAGE(PG8_SA(1, 1), a1 + hstepA, voffA);
;             PG8_WAIT_V(8); PG8_WAIT_L(0); PG8_BAR; PG8_MMA(0, 0, At, B0); PG8_MMA(0, 1, At, B1); PG8_BAR; PG8_SCHED;
;             PG8_LDA(At, 0, 1); PG8_STAGE(PG8_SB(0, 0), b2, voffB); PG8_STAGE(PG8_SB(0, 1), b2 + hstepB, voffB); PG8_STAGE(PG8_SA(0, 0), a2, voffA);
;             PG8_WAIT_V(8); PG8_WAIT_L(0); PG8_BAR; PG8_MMA(1, 0, At, B0); PG8_MMA(1, 1, At, B1); PG8_BAR; PG8_SCHED;
.LBB0_1544:
	ds_read_b128 v[130:133], v176
	ds_read_b128 v[134:137], v176 offset:1024
	ds_read_b128 v[138:141], v176 offset:2048
	ds_read_b128 v[142:145], v176 offset:3072
	ds_read_b128 v[164:167], v177
	ds_read_b128 v[168:171], v177 offset:1024
	ds_read_b128 v[172:175], v177 offset:2048
	ds_read_b128 v[180:183], v177 offset:3072
	s_add_u32 s6, s4, 0xfff00080
	s_addc_u32 s7, s5, -1
	s_cmp_eq_u32 s76, 60
	s_cselect_b32 s49, s43, s7
	s_cselect_b32 s48, s74, s6
	s_cselect_b32 s7, s41, s51
	s_cselect_b32 s6, s75, s50
	s_add_i32 m0, s61, 0xc000
	ds_read_b128 v[184:187], v178
	ds_read_b128 v[188:191], v178 offset:1024
	ds_read_b128 v[192:195], v178 offset:2048
	ds_read_b128 v[196:199], v178 offset:3072
	ds_read_b128 v[200:203], v178 offset:4096
	ds_read_b128 v[204:207], v178 offset:5120
	ds_read_b128 v[208:211], v178 offset:6144
	ds_read_b128 v[212:215], v178 offset:7168
	global_load_lds_dwordx4 v156, s[4:5]
	s_add_i32 m0, s61, 0xe000
	s_nop 0
	global_load_lds_dwordx4 v158, s[4:5]
	s_waitcnt vmcnt(8)
	s_waitcnt lgkmcnt(0)
	s_barrier
	s_waitcnt lgkmcnt(0)
	v_mfma_f32_16x16x32_bf16 v[90:93], v[130:133], v[184:187], v[90:93]
	v_mfma_f32_16x16x32_bf16 v[86:89], v[138:141], v[184:187], v[86:89]
	v_mfma_f32_16x16x32_bf16 v[126:129], v[130:133], v[192:195], v[126:129]
	v_mfma_f32_16x16x32_bf16 v[106:109], v[138:141], v[192:195], v[106:109]
	v_mfma_f32_16x16x32_bf16 v[122:125], v[130:133], v[200:203], v[122:125]
	v_mfma_f32_16x16x32_bf16 v[102:105], v[138:141], v[200:203], v[102:105]
	v_mfma_f32_16x16x32_bf16 v[70:73], v[130:133], v[208:211], v[70:73]
	v_mfma_f32_16x16x32_bf16 v[66:69], v[138:141], v[208:211], v[66:69]
	v_mfma_f32_16x16x32_bf16 v[90:93], v[134:137], v[188:191], v[90:93]
	v_mfma_f32_16x16x32_bf16 v[86:89], v[142:145], v[188:191], v[86:89]
	v_mfma_f32_16x16x32_bf16 v[126:129], v[134:137], v[196:199], v[126:129]
	v_mfma_f32_16x16x32_bf16 v[106:109], v[142:145], v[196:199], v[106:109]
	v_mfma_f32_16x16x32_bf16 v[122:125], v[134:137], v[204:207], v[122:125]
	v_mfma_f32_16x16x32_bf16 v[102:105], v[142:145], v[204:207], v[102:105]
	v_mfma_f32_16x16x32_bf16 v[70:73], v[134:137], v[212:215], v[70:73]
	v_mfma_f32_16x16x32_bf16 v[66:69], v[142:145], v[212:215], v[66:69]
	v_mfma_f32_16x16x32_bf16 v[78:81], v[164:167], v[184:187], v[78:81]
	v_mfma_f32_16x16x32_bf16 v[74:77], v[172:175], v[184:187], v[74:77]
	v_mfma_f32_16x16x32_bf16 v[118:121], v[164:167], v[192:195], v[118:121]
	v_mfma_f32_16x16x32_bf16 v[98:101], v[172:175], v[192:195], v[98:101]
	v_mfma_f32_16x16x32_bf16 v[114:117], v[164:167], v[200:203], v[114:117]
	v_mfma_f32_16x16x32_bf16 v[94:97], v[172:175], v[200:203], v[94:97]
	v_mfma_f32_16x16x32_bf16 v[110:113], v[164:167], v[208:211], v[110:113]
	v_mfma_f32_16x16x32_bf16 v[82:85], v[172:175], v[208:211], v[82:85]
	v_mfma_f32_16x16x32_bf16 v[78:81], v[168:171], v[188:191], v[78:81]
	v_mfma_f32_16x16x32_bf16 v[74:77], v[180:183], v[188:191], v[74:77]
	v_mfma_f32_16x16x32_bf16 v[118:121], v[168:171], v[196:199], v[118:121]
	v_mfma_f32_16x16x32_bf16 v[98:101], v[180:183], v[196:199], v[98:101]
	v_mfma_f32_16x16x32_bf16 v[114:117], v[168:171], v[204:207], v[114:117]
	v_mfma_f32_16x16x32_bf16 v[94:97], v[180:183], v[204:207], v[94:97]
	v_mfma_f32_16x16x32_bf16 v[110:113], v[168:171], v[212:215], v[110:113]
	v_mfma_f32_16x16x32_bf16 v[82:85], v[180:183], v[212:215], v[82:85]
	s_barrier
	s_add_i32 s77, s70, s54
	s_add_u32 s98, s6, s30
	s_addc_u32 s99, s7, s31
	s_mov_b32 m0, s77
	ds_read_b128 v[184:187], v178 offset:16384
	ds_read_b128 v[188:191], v178 offset:17408
	ds_read_b128 v[192:195], v178 offset:18432
	ds_read_b128 v[196:199], v178 offset:19456
	ds_read_b128 v[200:203], v178 offset:20480
	ds_read_b128 v[204:207], v178 offset:21504
	ds_read_b128 v[208:211], v178 offset:22528
	ds_read_b128 v[212:215], v178 offset:23552
	global_load_lds_dwordx4 v150, s[6:7]
	s_add_i32 m0, s77, 0x2000
	s_add_u32 s78, s6, 0x100000
	s_addc_u32 s79, s7, 0
	s_add_i32 s77, s71, s54
	global_load_lds_dwordx4 v146, s[6:7]
	s_mov_b32 m0, s77
	s_nop 0
	global_load_lds_dwordx4 v150, s[78:79]
	s_add_i32 m0, s77, 0x2000
	s_nop 0
	global_load_lds_dwordx4 v146, s[78:79]
	s_add_u32 s100, s48, s30
	s_addc_u32 s101, s49, s31
	s_mov_b32 m0, s61
	s_nop 0
	global_load_lds_dwordx4 v152, s[48:49]
	s_mov_b32 m0, s62
	s_nop 0
	global_load_lds_dwordx4 v148, s[48:49]
	s_waitcnt vmcnt(8)
	s_waitcnt lgkmcnt(0)
	s_barrier
	s_waitcnt lgkmcnt(0)
	v_mfma_f32_16x16x32_bf16 v[26:29], v[130:133], v[184:187], v[26:29]
	v_mfma_f32_16x16x32_bf16 v[22:25], v[138:141], v[184:187], v[22:25]
	v_mfma_f32_16x16x32_bf16 v[62:65], v[130:133], v[192:195], v[62:65]
	v_mfma_f32_16x16x32_bf16 v[42:45], v[138:141], v[192:195], v[42:45]
	v_mfma_f32_16x16x32_bf16 v[58:61], v[130:133], v[200:203], v[58:61]
	v_mfma_f32_16x16x32_bf16 v[38:41], v[138:141], v[200:203], v[38:41]
	v_mfma_f32_16x16x32_bf16 v[6:9], v[130:133], v[208:211], v[6:9]
	v_mfma_f32_16x16x32_bf16 v[2:5], v[138:141], v[208:211], v[2:5]
	v_mfma_f32_16x16x32_bf16 v[26:29], v[134:137], v[188:191], v[26:29]
	v_mfma_f32_16x16x32_bf16 v[22:25], v[142:145], v[188:191], v[22:25]
	v_mfma_f32_16x16x32_bf16 v[62:65], v[134:137], v[196:199], v[62:65]
	v_mfma_f32_16x16x32_bf16 v[42:45], v[142:145], v[196:199], v[42:45]
	v_mfma_f32_16x16x32_bf16 v[58:61], v[134:137], v[204:207], v[58:61]
	v_mfma_f32_16x16x32_bf16 v[38:41], v[142:145], v[204:207], v[38:41]
	v_mfma_f32_16x16x32_bf16 v[6:9], v[134:137], v[212:215], v[6:9]
	v_mfma_f32_16x16x32_bf16 v[2:5], v[142:145], v[212:215], v[2:5]
	v_mfma_f32_16x16x32_bf16 v[14:17], v[164:167], v[184:187], v[14:17]
	v_mfma_f32_16x16x32_bf16 v[10:13], v[172:175], v[184:187], v[10:13]
	v_mfma_f32_16x16x32_bf16 v[54:57], v[164:167], v[192:195], v[54:57]
	v_mfma_f32_16x16x32_bf16 v[34:37], v[172:175], v[192:195], v[34:37]
	v_mfma_f32_16x16x32_bf16 v[50:53], v[164:167], v[200:203], v[50:53]
	v_mfma_f32_16x16x32_bf16 v[30:33], v[172:175], v[200:203], v[30:33]
	v_mfma_f32_16x16x32_bf16 v[46:49], v[164:167], v[208:211], v[46:49]
	v_mfma_f32_16x16x32_bf16 v[18:21], v[172:175], v[208:211], v[18:21]
	v_mfma_f32_16x16x32_bf16 v[14:17], v[168:171], v[188:191], v[14:17]
	v_mfma_f32_16x16x32_bf16 v[10:13], v[180:183], v[188:191], v[10:13]
	v_mfma_f32_16x16x32_bf16 v[54:57], v[168:171], v[196:199], v[54:57]
	v_mfma_f32_16x16x32_bf16 v[34:37], v[180:183], v[196:199], v[34:37]
	v_mfma_f32_16x16x32_bf16 v[50:53], v[168:171], v[204:207], v[50:53]
	v_mfma_f32_16x16x32_bf16 v[30:33], v[180:183], v[204:207], v[30:33]
	v_mfma_f32_16x16x32_bf16 v[46:49], v[168:171], v[212:215], v[46:49]
	v_mfma_f32_16x16x32_bf16 v[18:21], v[180:183], v[212:215], v[18:21]
	s_barrier
; #define PG8_STAGE(bufoff, gbase, voff) do { _Pragma("unroll") for (int _i = 0; _i < 2; ++_i) \
;         __builtin_amdgcn_global_load_lds((const unsigned*)((const char*)(gbase) + (voff)[_i]), (PG8_LAS unsigned*)(lds + (bufoff) + ldsw + _i * 8192), 16, 0, 0); } while (0)
; #define PG8_LDA(dst, b, h) do { _Pragma("unroll") for (int m = 0; m < 4; ++m) _Pragma("unroll") for (int k = 0; k < 2; ++k) dst[m][k] = *(const PG8_LAS bf16x8*)(lds + PG8_SA(b, h) + aoff + m * 2048 + k * 1024); } while (0)
; #define PG8_LDB(dst, b, h) do { _Pragma("unroll") for (int n = 0; n < 2; ++n) _Pragma("unroll") for (int k = 0; k < 2; ++k) dst[n][k] = *(const PG8_LAS bf16x8*)(lds + PG8_SB(b, h) + boff + n * 2048 + k * 1024); } while (0)
; #define PG8_MMA(ai, bj, At, Bt) do { __builtin_amdgcn_s_setprio(1); _Pragma("unroll") for (int m = 0; m < 4; ++m) _Pragma("unroll") for (int n = 0; n < 2; ++n) _Pragma("unroll") for (int k = 0; k < 2; ++k) \
;         acc[ai][bj][m][n] = __builtin_amdgcn_mfma_f32_16x16x32_bf16(Bt[n][k], At[m][k], acc[ai][bj][m][n], 0, 0, 0); __builtin_amdgcn_s_setprio(0); } while (0)
; #define PG8_WAIT_V(n) asm volatile("s_waitcnt vmcnt(" #n ")" ::: "memory")
; #define PG8_WAIT_L(n) asm volatile("s_waitcnt lgkmcnt(" #n ")" ::: "memory")
; #define PG8_BAR __builtin_amdgcn_s_barrier()
; #define PG8_SCHED __builtin_amdgcn_sched_barrier(0)
; template <class Epi, class Sched, bool ALIGN_EPI = false>
; __device__ __forceinline__ void gemm_phase(PG8_LAS unsigned char* lds, const Gemm g, const Sched& S, const Epi& E) {
;     ...
;             PG8_LDB(B0, 1, 0); PG8_LDB(B1, 1, 1); PG8_SCHED; PG8_LDA(At, 1, 0); PG8_STAGE(PG8_SA(0, 1), a2 + hstepA, voffA);
;             PG8_WAIT_V(8); PG8_WAIT_L(0); PG8_BAR; PG8_MMA(0, 0, At, B0); PG8_MMA(0, 1, At, B1); PG8_BAR; PG8_SCHED;
;             PG8_LDA(At, 1, 1); PG8_STAGE(PG8_SB(1, 0), b3, voffB); PG8_STAGE(PG8_SB(1, 1), b3 + hstepB, voffB); PG8_STAGE(PG8_SA(1, 0), a3, voffA);
;             PG8_WAIT_V(8); PG8_WAIT_L(0); PG8_BAR; PG8_MMA(1, 0, At, B0); PG8_MMA(1, 1, At, B1); PG8_BAR; PG8_SCHED;
;         }
;         if constexpr (ALIGN_EPI) { if (wr == 0) PG8_BAR; }
	s_add_i32 s77, 0, 0x18000
	s_add_i32 s78, 0, 0x1c000
	v_add_u32_e32 v142, s77, v1
	v_add_u32_e32 v154, s78, v1
	ds_read_b128 v[130:133], v142
	ds_read_b128 v[134:137], v142 offset:1024
	ds_read_b128 v[138:141], v142 offset:2048
	ds_read_b128 v[142:145], v142 offset:3072
	ds_read_b128 v[164:167], v154
	ds_read_b128 v[168:171], v154 offset:1024
	ds_read_b128 v[172:175], v154 offset:2048
	ds_read_b128 v[180:183], v154 offset:3072
	s_add_u32 s48, s48, 0x100000
	s_addc_u32 s49, s49, 0
	s_mov_b32 m0, s63
	ds_read_b128 v[184:187], v178 offset:32768
	ds_read_b128 v[188:191], v178 offset:33792
	ds_read_b128 v[192:195], v178 offset:34816
	ds_read_b128 v[196:199], v178 offset:35840
	ds_read_b128 v[200:203], v178 offset:36864
	ds_read_b128 v[204:207], v178 offset:37888
	ds_read_b128 v[208:211], v178 offset:38912
	ds_read_b128 v[212:215], v178 offset:39936
	global_load_lds_dwordx4 v152, s[48:49]
	s_mov_b32 m0, s64
	s_nop 0
	global_load_lds_dwordx4 v148, s[48:49]
	s_waitcnt vmcnt(8)
	s_waitcnt lgkmcnt(0)
	s_barrier
	s_waitcnt lgkmcnt(0)
	v_mfma_f32_16x16x32_bf16 v[90:93], v[130:133], v[184:187], v[90:93]
	v_mfma_f32_16x16x32_bf16 v[86:89], v[138:141], v[184:187], v[86:89]
	v_mfma_f32_16x16x32_bf16 v[126:129], v[130:133], v[192:195], v[126:129]
	v_mfma_f32_16x16x32_bf16 v[106:109], v[138:141], v[192:195], v[106:109]
	v_mfma_f32_16x16x32_bf16 v[122:125], v[130:133], v[200:203], v[122:125]
	v_mfma_f32_16x16x32_bf16 v[102:105], v[138:141], v[200:203], v[102:105]
	v_mfma_f32_16x16x32_bf16 v[70:73], v[130:133], v[208:211], v[70:73]
	v_mfma_f32_16x16x32_bf16 v[66:69], v[138:141], v[208:211], v[66:69]
	v_mfma_f32_16x16x32_bf16 v[90:93], v[134:137], v[188:191], v[90:93]
	v_mfma_f32_16x16x32_bf16 v[86:89], v[142:145], v[188:191], v[86:89]
	v_mfma_f32_16x16x32_bf16 v[126:129], v[134:137], v[196:199], v[126:129]
	v_mfma_f32_16x16x32_bf16 v[106:109], v[142:145], v[196:199], v[106:109]
	v_mfma_f32_16x16x32_bf16 v[122:125], v[134:137], v[204:207], v[122:125]
	v_mfma_f32_16x16x32_bf16 v[102:105], v[142:145], v[204:207], v[102:105]
	v_mfma_f32_16x16x32_bf16 v[70:73], v[134:137], v[212:215], v[70:73]
	v_mfma_f32_16x16x32_bf16 v[66:69], v[142:145], v[212:215], v[66:69]
	v_mfma_f32_16x16x32_bf16 v[78:81], v[164:167], v[184:187], v[78:81]
	v_mfma_f32_16x16x32_bf16 v[74:77], v[172:175], v[184:187], v[74:77]
	v_mfma_f32_16x16x32_bf16 v[118:121], v[164:167], v[192:195], v[118:121]
	v_mfma_f32_16x16x32_bf16 v[98:101], v[172:175], v[192:195], v[98:101]
	v_mfma_f32_16x16x32_bf16 v[114:117], v[164:167], v[200:203], v[114:117]
	v_mfma_f32_16x16x32_bf16 v[94:97], v[172:175], v[200:203], v[94:97]
	v_mfma_f32_16x16x32_bf16 v[110:113], v[164:167], v[208:211], v[110:113]
	v_mfma_f32_16x16x32_bf16 v[82:85], v[172:175], v[208:211], v[82:85]
	v_mfma_f32_16x16x32_bf16 v[78:81], v[168:171], v[188:191], v[78:81]
	v_mfma_f32_16x16x32_bf16 v[74:77], v[180:183], v[188:191], v[74:77]
	v_mfma_f32_16x16x32_bf16 v[118:121], v[168:171], v[196:199], v[118:121]
	v_mfma_f32_16x16x32_bf16 v[98:101], v[180:183], v[196:199], v[98:101]
	v_mfma_f32_16x16x32_bf16 v[114:117], v[168:171], v[204:207], v[114:117]
	v_mfma_f32_16x16x32_bf16 v[94:97], v[180:183], v[204:207], v[94:97]
	v_mfma_f32_16x16x32_bf16 v[110:113], v[168:171], v[212:215], v[110:113]
	v_mfma_f32_16x16x32_bf16 v[82:85], v[180:183], v[212:215], v[82:85]
	s_barrier
	s_add_i32 s48, s77, s54
	s_mov_b32 m0, s48
	ds_read_b128 v[184:187], v178 offset:49152
	ds_read_b128 v[188:191], v178 offset:50176
	ds_read_b128 v[192:195], v178 offset:51200
	ds_read_b128 v[196:199], v178 offset:52224
	ds_read_b128 v[200:203], v178 offset:53248
	ds_read_b128 v[204:207], v178 offset:54272
	ds_read_b128 v[208:211], v178 offset:55296
	ds_read_b128 v[212:215], v178 offset:56320
	global_load_lds_dwordx4 v150, s[98:99]
	s_add_i32 m0, s48, 0x2000
	s_add_u32 s6, s6, 0x100080
	s_addc_u32 s7, s7, 0
	s_add_i32 s48, s78, s54
	global_load_lds_dwordx4 v146, s[98:99]
	s_mov_b32 m0, s48
	s_nop 0
	global_load_lds_dwordx4 v150, s[6:7]
	s_add_i32 m0, s48, 0x2000
	s_nop 0
	global_load_lds_dwordx4 v146, s[6:7]
	s_mov_b32 m0, s67
	s_nop 0
	global_load_lds_dwordx4 v152, s[100:101]
	s_mov_b32 m0, s68
	s_nop 0
	global_load_lds_dwordx4 v148, s[100:101]
	s_waitcnt vmcnt(8)
	s_waitcnt lgkmcnt(0)
	s_barrier
	s_waitcnt lgkmcnt(0)
	v_mfma_f32_16x16x32_bf16 v[26:29], v[130:133], v[184:187], v[26:29]
	v_mfma_f32_16x16x32_bf16 v[22:25], v[138:141], v[184:187], v[22:25]
	v_mfma_f32_16x16x32_bf16 v[62:65], v[130:133], v[192:195], v[62:65]
	v_mfma_f32_16x16x32_bf16 v[42:45], v[138:141], v[192:195], v[42:45]
	v_mfma_f32_16x16x32_bf16 v[58:61], v[130:133], v[200:203], v[58:61]
	v_mfma_f32_16x16x32_bf16 v[38:41], v[138:141], v[200:203], v[38:41]
	v_mfma_f32_16x16x32_bf16 v[6:9], v[130:133], v[208:211], v[6:9]
	v_mfma_f32_16x16x32_bf16 v[2:5], v[138:141], v[208:211], v[2:5]
	v_mfma_f32_16x16x32_bf16 v[26:29], v[134:137], v[188:191], v[26:29]
	v_mfma_f32_16x16x32_bf16 v[22:25], v[142:145], v[188:191], v[22:25]
	v_mfma_f32_16x16x32_bf16 v[62:65], v[134:137], v[196:199], v[62:65]
	v_mfma_f32_16x16x32_bf16 v[42:45], v[142:145], v[196:199], v[42:45]
	v_mfma_f32_16x16x32_bf16 v[58:61], v[134:137], v[204:207], v[58:61]
	v_mfma_f32_16x16x32_bf16 v[38:41], v[142:145], v[204:207], v[38:41]
	v_mfma_f32_16x16x32_bf16 v[6:9], v[134:137], v[212:215], v[6:9]
	v_mfma_f32_16x16x32_bf16 v[2:5], v[142:145], v[212:215], v[2:5]
	v_mfma_f32_16x16x32_bf16 v[14:17], v[164:167], v[184:187], v[14:17]
	v_mfma_f32_16x16x32_bf16 v[10:13], v[172:175], v[184:187], v[10:13]
	v_mfma_f32_16x16x32_bf16 v[54:57], v[164:167], v[192:195], v[54:57]
	v_mfma_f32_16x16x32_bf16 v[34:37], v[172:175], v[192:195], v[34:37]
	v_mfma_f32_16x16x32_bf16 v[50:53], v[164:167], v[200:203], v[50:53]
	v_mfma_f32_16x16x32_bf16 v[30:33], v[172:175], v[200:203], v[30:33]
	v_mfma_f32_16x16x32_bf16 v[46:49], v[164:167], v[208:211], v[46:49]
	v_mfma_f32_16x16x32_bf16 v[18:21], v[172:175], v[208:211], v[18:21]
	v_mfma_f32_16x16x32_bf16 v[14:17], v[168:171], v[188:191], v[14:17]
	v_mfma_f32_16x16x32_bf16 v[10:13], v[180:183], v[188:191], v[10:13]
	v_mfma_f32_16x16x32_bf16 v[54:57], v[168:171], v[196:199], v[54:57]
	v_mfma_f32_16x16x32_bf16 v[34:37], v[180:183], v[196:199], v[34:37]
	v_mfma_f32_16x16x32_bf16 v[50:53], v[168:171], v[204:207], v[50:53]
	v_mfma_f32_16x16x32_bf16 v[30:33], v[180:183], v[204:207], v[30:33]
	v_mfma_f32_16x16x32_bf16 v[46:49], v[168:171], v[212:215], v[46:49]
	v_mfma_f32_16x16x32_bf16 v[18:21], v[180:183], v[212:215], v[18:21]
	s_barrier
	s_add_i32 s76, s76, 2
	s_add_u32 s4, s4, 0x100
	s_addc_u32 s5, s5, 0
	s_add_u32 s50, s50, 0x100
	s_addc_u32 s51, s51, 0
	s_cmp_gt_u32 s76, 61
	s_cbranch_scc0 .LBB0_1544
	s_and_b64 vcc, exec, s[34:35]
	s_cbranch_vccz .LBB0_1547
	s_barrier

; __device__ __forceinline__ unsigned xb_ld(unsigned* p)              { return __hip_atomic_load(p, __ATOMIC_RELAXED, __HIP_MEMORY_SCOPE_AGENT); }
; __device__ __forceinline__ void xcd_barrier_complete(unsigned* bar, unsigned x, unsigned& nloc, unsigned& nx) {
;     const unsigned G = gridDim.x * gridDim.y * gridDim.z;
;     unsigned sum, cnt, mine, sp = 0u;
;     for (;;) {
;         sum = 0u; cnt = 0u; mine = 0u;
; #pragma unroll
;         for (unsigned j = 0; j < 16; ++j) { const unsigned c = xb_ld(&bar[XB_XCNT(j)]); sum += c; cnt += (c > 0u) ? 1u : 0u; mine = (j == x) ? c : mine; }
; __device__ __forceinline__ void xcd_barrier(const XcdBarrier& b) {
;     asm volatile("s_waitcnt vmcnt(0)" ::: "memory");
;     __syncthreads();
;     if (threadIdx.x == 0) {
;         unsigned* bar = b.bar;
;         __builtin_amdgcn_s_waitcnt(0);
;         unsigned nloc = b.st[0], nx = b.st[1];
;         if (nloc == 0u) { xcd_barrier_complete(bar, b.x, nloc, nx); b.st[0] = nloc; b.st[1] = nx; }
.LBB0_1563:
	s_setprio 0
	s_cmp_gt_i32 s59, 21
	s_cselect_b64 s[2:3], -1, 0
	s_and_b64 s[0:1], s[10:11], s[2:3]
	s_andn2_b64 vcc, exec, s[0:1]
	s_cbranch_vccnz .LBB0_1613
	s_waitcnt vmcnt(0)
	v_cmp_eq_u32_e32 vcc, 0, v0
	s_waitcnt vmcnt(0) lgkmcnt(0)
	s_barrier
	s_and_saveexec_b64 s[4:5], vcc
	s_cbranch_execz .LBB0_1612
	v_readlane_b32 s0, v228, 5
	s_waitcnt vmcnt(0) expcnt(0) lgkmcnt(0)
	s_nop 0
	v_mov_b32_e32 v1, s0
	ds_read_b32 v3, v1
	ds_read_b32 v1, v1 offset:4
	s_waitcnt lgkmcnt(1)
	v_cmp_ne_u32_e32 vcc, 0, v3
	s_cbranch_vccnz .LBB0_1580
	v_readlane_b32 s6, v228, 0
	v_readlane_b32 s7, v228, 1
	s_load_dwordx2 s[0:1], s[6:7], 0x4
	s_add_u32 s6, s56, 0x4200
	s_addc_u32 s7, s57, 0
	s_add_u32 s8, s56, 0x4400
	s_addc_u32 s9, s57, 0
	s_add_u32 s10, s56, 0x4500
	s_addc_u32 s11, s57, 0
	s_add_u32 s12, s56, 0x4600
	s_addc_u32 s13, s57, 0
	s_add_u32 s14, s56, 0x4700
	s_addc_u32 s15, s57, 0
	s_add_u32 s16, s56, 0x4800
	s_addc_u32 s17, s57, 0
	s_add_u32 s18, s56, 0x4900
	s_addc_u32 s19, s57, 0
	s_add_u32 s20, s56, 0x4a00
	s_addc_u32 s21, s57, 0
	s_add_u32 s22, s56, 0x4b00
	s_addc_u32 s23, s57, 0
	s_add_u32 s24, s56, 0x4c00
	s_addc_u32 s25, s57, 0
	s_add_u32 s26, s56, 0x4d00
	s_addc_u32 s27, s57, 0
	s_add_u32 s28, s56, 0x4e00
	s_addc_u32 s29, s57, 0
	s_add_u32 s30, s56, 0x4f00
	s_addc_u32 s31, s57, 0
	s_add_u32 s34, s56, 0x5000
	s_addc_u32 s35, s57, 0
	s_add_u32 s36, s56, 0x5100
	s_addc_u32 s37, s57, 0
	s_add_u32 s38, s56, 0x5200
	s_addc_u32 s39, s57, 0
	s_waitcnt lgkmcnt(0)
	s_mul_i32 s0, s0, s86
	s_add_u32 s40, s56, 0x5300
	s_mul_i32 s0, s0, s1
	s_addc_u32 s41, s57, 0
	s_mov_b32 s1, 1
	v_mov_b32_e32 v17, 0
	s_branch .LBB0_1568

; #define GEMM_RESB(RF32, Ap, lda_, Btp, K_, Rp) do { pg8::Gemm g{(const pg8::bf16_t*)(Ap), (const pg8::bf16_t*)(Btp), NTOK, DM, (K_), (lda_), (K_)}; \
;         pg8::StaticOrder S; S.init(NTOK, DM, G, bx); pg8::EpiResB<RF32> E{(pg8::bf16_t*)WSB(WS_X), (const void*)(Rp)}; \
;         pg8::gemm_phase<pg8::EpiResB<RF32>, pg8::StaticOrder, true>(ldsb + RING_OFF, g, S, E); } while (0)
;     __host__ __device__ bool next(int i, Unit& u) const {
;         const long L = (long)i * G + c; if (L >= nwg) return false;
;         int wgid = (int)L; { const int q = nwg / NXCD, r = nwg % NXCD, xcd = wgid % NXCD, off = wgid / NXCD; wgid = (xcd < r ? xcd * (q + 1) : r * (q + 1) + (xcd - r) * q) + off; }
;         const int nig = WGM * nN, gid = wgid / nig, fm = gid * WGM, gsz = (nM - fm) < WGM ? (nM - fm) : WGM;
;         u.pm = fm + ((wgid % nig) % gsz); u.pn = (wgid % nig) / gsz; return true;
; __global__ void __launch_bounds__(NTHREADS, 2) mk_fwd(Args args) {
;     ...
;     if (IN(22)) GEMM_RESB(false, WSB(WS_ACT), DFF, WSB(WS_WDOWN) + WDOWN_L, DFF, WSB(WS_X));
.LBB0_1678:
	s_cmp_lt_i32 s58, 23
	s_cselect_b64 s[0:1], -1, 0
	s_and_b64 s[6:7], s[0:1], s[2:3]
	s_andn2_b64 vcc, exec, s[6:7]
	s_cbranch_vccnz .LBB0_1707
	v_readfirstlane_b32 s98, v0
	s_nop 3
	s_lshr_b32 s98, s98, 8
	s_cmp_eq_u32 s98, 0
	s_cbranch_scc0 .Lmy_prio8
	s_setprio 1
.Lmy_prio8:
	v_mov_b32_e32 v1, v0
	s_cmpk_gt_i32 s33, 0x1ff
	v_readfirstlane_b32 s4, v1
	s_cbranch_scc1 .LBB0_1707
	s_ashr_i32 s0, s33, 31
	s_lshr_b32 s1, s0, 29
	s_add_i32 s8, s33, s1
	s_and_b32 s1, s8, -8
	s_sub_i32 s1, s33, s1
	s_cmp_gt_i32 s1, -1
	s_cbranch_scc0 .LBB0_1682
	s_lshl_b32 s5, s1, 6
	s_ashr_i32 s8, s8, 3
	s_cbranch_execz .LBB0_1683
	s_branch .LBB0_1684

; __device__ __forceinline__ unsigned xb_ld(unsigned* p)              { return __hip_atomic_load(p, __ATOMIC_RELAXED, __HIP_MEMORY_SCOPE_AGENT); }
; __device__ __forceinline__ void xcd_barrier_complete(unsigned* bar, unsigned x, unsigned& nloc, unsigned& nx) {
;     const unsigned G = gridDim.x * gridDim.y * gridDim.z;
;     unsigned sum, cnt, mine, sp = 0u;
;     for (;;) {
;         sum = 0u; cnt = 0u; mine = 0u;
; #pragma unroll
;         for (unsigned j = 0; j < 16; ++j) { const unsigned c = xb_ld(&bar[XB_XCNT(j)]); sum += c; cnt += (c > 0u) ? 1u : 0u; mine = (j == x) ? c : mine; }
; __device__ __forceinline__ void xcd_barrier(const XcdBarrier& b) {
;     asm volatile("s_waitcnt vmcnt(0)" ::: "memory");
;     __syncthreads();
;     if (threadIdx.x == 0) {
;         unsigned* bar = b.bar;
;         __builtin_amdgcn_s_waitcnt(0);
;         unsigned nloc = b.st[0], nx = b.st[1];
;         if (nloc == 0u) { xcd_barrier_complete(bar, b.x, nloc, nx); b.st[0] = nloc; b.st[1] = nx; }
.LBB0_1707:
	s_setprio 0
	s_cmp_gt_i32 s59, 23
	s_cselect_b64 s[2:3], -1, 0
	s_and_b64 s[0:1], s[6:7], s[2:3]
	s_andn2_b64 vcc, exec, s[0:1]
	s_cbranch_vccnz .LBB0_1757
	s_waitcnt vmcnt(0)
	v_cmp_eq_u32_e32 vcc, 0, v0
	s_waitcnt vmcnt(0) lgkmcnt(0)
	s_barrier
	s_and_saveexec_b64 s[4:5], vcc
	s_cbranch_execz .LBB0_1756
	v_readlane_b32 s0, v228, 5
	s_waitcnt vmcnt(0) expcnt(0) lgkmcnt(0)
	s_nop 0
	v_mov_b32_e32 v1, s0
	ds_read_b32 v3, v1
	ds_read_b32 v1, v1 offset:4
	s_waitcnt lgkmcnt(1)
	v_cmp_ne_u32_e32 vcc, 0, v3
	s_cbranch_vccnz .LBB0_1724
	v_readlane_b32 s6, v228, 0
	v_readlane_b32 s7, v228, 1
	s_load_dwordx2 s[0:1], s[6:7], 0x4
	s_add_u32 s6, s56, 0x4200
	s_addc_u32 s7, s57, 0
	s_add_u32 s8, s56, 0x4400
	s_addc_u32 s9, s57, 0
	s_add_u32 s10, s56, 0x4500
	s_addc_u32 s11, s57, 0
	s_add_u32 s12, s56, 0x4600
	s_addc_u32 s13, s57, 0
	s_add_u32 s14, s56, 0x4700
	s_addc_u32 s15, s57, 0
	s_add_u32 s16, s56, 0x4800
	s_addc_u32 s17, s57, 0
	s_add_u32 s18, s56, 0x4900
	s_addc_u32 s19, s57, 0
	s_add_u32 s20, s56, 0x4a00
	s_addc_u32 s21, s57, 0
	s_add_u32 s22, s56, 0x4b00
	s_addc_u32 s23, s57, 0
	s_add_u32 s24, s56, 0x4c00
	s_addc_u32 s25, s57, 0
	s_add_u32 s26, s56, 0x4d00
	s_addc_u32 s27, s57, 0
	s_add_u32 s28, s56, 0x4e00
	s_addc_u32 s29, s57, 0
	s_add_u32 s30, s56, 0x4f00
	s_addc_u32 s31, s57, 0
	s_add_u32 s34, s56, 0x5000
	s_addc_u32 s35, s57, 0
	s_add_u32 s36, s56, 0x5100
	s_addc_u32 s37, s57, 0
	s_add_u32 s38, s56, 0x5200
	s_addc_u32 s39, s57, 0
	s_waitcnt lgkmcnt(0)
	s_mul_i32 s0, s0, s86
	s_add_u32 s40, s56, 0x5300
	s_mul_i32 s0, s0, s1
	s_addc_u32 s41, s57, 0
	s_mov_b32 s1, 1
	v_mov_b32_e32 v17, 0
	s_branch .LBB0_1712
